# all three residual epilogues: f32 Y stores write 64B-contiguous row segments via permlane16+permlane32 lane exchange
# speedup vs baseline: 1.0030x; 1.0008x over previous
; __device__ __forceinline__ float xsum16(float v) { const auto r = __builtin_amdgcn_permlane16_swap(__float_as_uint(v), __float_as_uint(v), false, false); return __uint_as_float(r[0]) + __uint_as_float(r[1]); }
; __device__ __forceinline__ float xsum32(float v) { const auto r = __builtin_amdgcn_permlane32_swap(__float_as_uint(v), __float_as_uint(v), false, false); return __uint_as_float(r[0]) + __uint_as_float(r[1]); }
; __device__ __forceinline__ void row_stats4(const float* st, int rowb, int fq, float (&mu)[4], float (&rs)[4]) {
;     f32x4 a[4], b[4];
; #pragma unroll
;     for (int m = 0; m < 4; ++m) { const f32x4* p = (const f32x4*)(st + (size_t)(rowb + m * 16) * 32 + fq * 8); a[m] = p[0]; b[m] = p[1]; }
; #pragma unroll
;     for (int m = 0; m < 4; ++m) { float s1 = (a[m][0] + a[m][2]) + (b[m][0] + b[m][2]), s2 = (a[m][1] + a[m][3]) + (b[m][1] + b[m][3]);
;         s1 = xsum32(xsum16(s1)); s2 = xsum32(xsum16(s2));
;         const float mm = s1 * (1.0f / 1024.0f); mu[m] = mm; rs[m] = rsqrtf(fmaxf(s2 * (1.0f / 1024.0f) - mm * mm, 0.f) + LN_EPS_); }
;     asm volatile("" ::: "memory");
; }
;     __device__ __forceinline__ void operator()(const f32x4 (&acc)[2][2][4][2], const pg8::Unit& u, int wr, int wc, int fr, int fq) const {
;         const int row0 = u.pm * 256 + wr * 64 + fr, col0 = u.pn * 256 + wc * 32 + fq * 8;
; #pragma unroll
;         for (int ai = 0; ai < 2; ++ai) { float mu4[4], rs4[4]; row_stats4(stp, row0 + ai * 128, fq, mu4, rs4);
; #pragma unroll
;             for (int m = 0; m < 4; ++m) { const int row = row0 + ai * 128 + m * 16; const float mu = mu4[m], rs = rs4[m];
;                 f32x4 yv[2][2], gq[2][2], bq_[2][2];
; #pragma unroll
;                 for (int bj = 0; bj < 2; ++bj)
; #pragma unroll
;                     for (int n = 0; n < 2; ++n) { yv[bj][n] = *(const f32x4*)(Yin + (size_t)row * D_ + col0 + bj * 128 + 4 * n); gq[bj][n] = *(const f32x4*)(g + col0 + bj * 128 + 4 * n); bq_[bj][n] = *(const f32x4*)(b + col0 + bj * 128 + 4 * n); }
.LBB0_372:
	s_lshl_b32 s3, s3, 8
	s_add_i32 s3, s3, s53
	v_or_b32_e32 v158, s3, v182
	v_ashrrev_i32_e32 v159, 31, v158
	v_lshlrev_b64 v[130:131], 7, v[158:159]
	v_lshl_add_u64 v[136:137], v[146:147], 0, v[130:131]
	v_or_b32_e32 v180, 16, v158
	global_load_dwordx4 v[132:135], v[136:137], off
	global_load_dwordx4 v[166:169], v[136:137], off offset:16
	v_ashrrev_i32_e32 v181, 31, v180
	v_lshlrev_b64 v[172:173], 7, v[180:181]
	v_lshl_add_u64 v[136:137], v[146:147], 0, v[172:173]
	global_load_dwordx4 v[174:177], v[136:137], off
	global_load_dwordx4 v[186:189], v[136:137], off offset:16
	v_or_b32_e32 v170, 32, v158
	v_ashrrev_i32_e32 v171, 31, v170
	v_lshlrev_b64 v[164:165], 7, v[170:171]
	v_lshl_add_u64 v[136:137], v[146:147], 0, v[164:165]
	global_load_dwordx4 v[190:193], v[136:137], off
	global_load_dwordx4 v[196:199], v[136:137], off offset:16
	v_or_b32_e32 v162, 48, v158
	v_ashrrev_i32_e32 v163, 31, v162
	v_lshlrev_b64 v[160:161], 7, v[162:163]
	v_lshl_add_u64 v[204:205], v[146:147], 0, v[160:161]
	global_load_dwordx4 v[200:203], v[204:205], off
	s_nop 0
	global_load_dwordx4 v[204:207], v[204:205], off offset:16
	s_lshl_b32 s16, s2, 8
	s_lshl_b32 s17, s2, 3
	s_or_b32 s2, s16, s54
	v_or_b32_e32 v152, s2, v183
	v_ashrrev_i32_e32 v153, 31, v152
	v_lshlrev_b64 v[136:137], 12, v[158:159]
	v_lshlrev_b64 v[152:153], 2, v[152:153]
	v_lshl_add_u64 v[178:179], s[12:13], 0, v[136:137]
	v_lshl_add_u64 v[178:179], v[178:179], 0, v[152:153]
	v_lshl_add_u64 v[154:155], s[8:9], 0, v[152:153]
	v_lshl_add_u64 v[156:157], s[10:11], 0, v[152:153]
	global_load_dwordx4 v[208:211], v[178:179], off offset:16
	global_load_dwordx4 v[212:215], v[178:179], off
	global_load_dwordx4 v[216:219], v[154:155], off offset:16
	global_load_dwordx4 v[220:223], v[154:155], off
	global_load_dwordx4 v[234:237], v[156:157], off offset:16
	global_load_dwordx4 v[238:241], v[156:157], off
	s_mov_b32 s16, 0x3a800000
	s_mov_b32 s18, 0x3fd744fd
	s_load_dwordx16 s[60:75], s[34:35], 0x38
	s_or_b32 s24, s17, s57
	v_bitop3_b32 v194, s2, 56, v183 bitop3:0xc8
	s_ashr_i32 s40, s2, 6
	s_ashr_i32 s25, s24, 31
	s_waitcnt lgkmcnt(0)
	v_lshl_add_u64 v[136:137], s[74:75], 0, v[136:137]
	v_lshl_add_u64 v[136:137], v[136:137], 0, v[152:153]
	s_ashr_i32 s41, s40, 31
	s_waitcnt vmcnt(0)
	v_mov_b32_e32 v224, v132
	v_mov_b32_e32 v225, v166
	v_mov_b32_e32 v228, v134
	v_mov_b32_e32 v229, v168
	v_mov_b32_e32 v166, v133
	v_mov_b32_e32 v168, v135
	v_pk_add_f32 v[132:133], v[224:225], v[228:229]
	v_pk_add_f32 v[134:135], v[166:167], v[168:169]
	v_pk_add_f32 v[132:133], v[132:133], v[132:133] op_sel:[0,1] op_sel_hi:[1,0]
	v_pk_add_f32 v[134:135], v[134:135], v[134:135] op_sel:[0,1] op_sel_hi:[1,0]
	v_mov_b32_e32 v166, v174
	v_mov_b32_e32 v167, v186
	v_mov_b32_e32 v168, v176
	v_mov_b32_e32 v169, v188
	v_mov_b32_e32 v0, v132
	v_mov_b32_e32 v133, v134
	v_pk_add_f32 v[166:167], v[166:167], v[168:169]
	v_permlane16_swap_b32_e32 v132, v0
	v_permlane16_swap_b32_e32 v134, v133
	v_mov_b32_e32 v186, v175
	v_mov_b32_e32 v188, v177
	v_pk_add_f32 v[166:167], v[166:167], v[166:167] op_sel:[0,1] op_sel_hi:[1,0]
	v_add_f32_e32 v177, v132, v0
	v_add_f32_e32 v176, v134, v133
	v_pk_add_f32 v[168:169], v[186:187], v[188:189]
	v_mov_b32_e32 v135, v166
	v_mov_b32_e32 v187, v177
	v_mov_b32_e32 v186, v176
	v_permlane16_swap_b32_e32 v166, v135
	v_permlane32_swap_b32_e32 v177, v187
	v_permlane32_swap_b32_e32 v176, v186
	v_add_f32_e32 v133, v166, v135
	v_pk_add_f32 v[166:167], v[176:177], v[186:187]
	v_pk_add_f32 v[168:169], v[168:169], v[168:169] op_sel:[0,1] op_sel_hi:[1,0]
	v_pk_mul_f32 v[224:225], v[166:167], s[16:17] op_sel_hi:[1,0]
	v_mov_b32_e32 v159, v168
	v_fma_f32 v0, -v225, v225, v224
	v_max_f32_e32 v0, 0, v0
	v_permlane16_swap_b32_e32 v168, v159
	v_add_f32_e32 v0, 0x3727c5ac, v0
	s_mov_b32 s16, 0x800000
	v_add_f32_e32 v132, v168, v159
	v_mul_f32_e32 v159, 0x4b800000, v0
	v_cmp_gt_f32_e32 vcc, s16, v0
	v_mov_b32_e32 v174, v190
	v_mov_b32_e32 v175, v196
	v_cndmask_b32_e32 v0, v0, v159, vcc
	v_rsq_f32_e32 v0, v0
	v_mov_b32_e32 v166, v192
	v_mov_b32_e32 v167, v198
	v_pk_add_f32 v[166:167], v[174:175], v[166:167]
	v_mul_f32_e32 v159, 0x45800000, v0
	v_pk_add_f32 v[166:167], v[166:167], v[166:167] op_sel:[0,1] op_sel_hi:[1,0]
	v_mov_b32_e32 v196, v191
	v_mov_b32_e32 v198, v193
	v_cndmask_b32_e32 v0, v0, v159, vcc
	v_pk_add_f32 v[168:169], v[196:197], v[198:199]
	v_mov_b32_e32 v159, v166
	v_pk_add_f32 v[168:169], v[168:169], v[168:169] op_sel:[0,1] op_sel_hi:[1,0]
	s_nop 0
	v_permlane16_swap_b32_e32 v166, v159
	v_add_f32_e32 v175, v166, v159
	v_mov_b32_e32 v159, v168
	s_nop 1
	v_permlane16_swap_b32_e32 v168, v159
	global_load_dwordx4 v[186:189], v[178:179], off offset:528
	global_load_dwordx4 v[190:193], v[178:179], off offset:512
	v_add_f32_e32 v174, v168, v159
	v_mov_b32_e32 v166, v200
	v_mov_b32_e32 v167, v204
	v_mov_b32_e32 v168, v202
	v_mov_b32_e32 v169, v206
	v_mov_b32_e32 v204, v201
	v_mov_b32_e32 v206, v203
	v_pk_add_f32 v[166:167], v[166:167], v[168:169]
	v_pk_add_f32 v[168:169], v[204:205], v[206:207]
	global_load_dwordx4 v[196:199], v[154:155], off offset:528
	global_load_dwordx4 v[200:203], v[154:155], off offset:512
	global_load_dwordx4 v[204:207], v[156:157], off offset:528
	global_load_dwordx4 v[242:245], v[156:157], off offset:512
	v_sub_f32_e32 v179, v215, v225
	v_sub_f32_e32 v178, v214, v225
	v_sub_f32_e32 v213, v213, v225
	v_sub_f32_e32 v212, v212, v225
	v_pk_mul_f32 v[212:213], v[0:1], v[212:213] op_sel_hi:[0,1]
	v_pk_mul_f32 v[178:179], v[0:1], v[178:179] op_sel_hi:[0,1]
	v_pk_fma_f32 v[178:179], v[222:223], v[178:179], v[240:241]
	v_pk_fma_f32 v[212:213], v[220:221], v[212:213], v[238:239]
; __device__ __forceinline__ float xsum16(float v) { const auto r = __builtin_amdgcn_permlane16_swap(__float_as_uint(v), __float_as_uint(v), false, false); return __uint_as_float(r[0]) + __uint_as_float(r[1]); }
; __device__ __forceinline__ float xsum32(float v) { const auto r = __builtin_amdgcn_permlane32_swap(__float_as_uint(v), __float_as_uint(v), false, false); return __uint_as_float(r[0]) + __uint_as_float(r[1]); }
; __device__ __forceinline__ size_t blk_off(int r, int c, int K) { return (size_t)(r >> 8) * 256 * K + (size_t)(c >> 6) * (256 * 64) + (size_t)((r & 255) * 64 + (c & 63)); }
; __device__ __forceinline__ u32x4 pack8(const f32x4 a, const f32x4 b) { u32x4 w; w.x = cvt_pk_bf16(a[0], a[1]); w.y = cvt_pk_bf16(a[2], a[3]); w.z = cvt_pk_bf16(b[0], b[1]); w.w = cvt_pk_bf16(b[2], b[3]); return w; }
;     __device__ __forceinline__ void operator()(const f32x4 (&acc)[2][2][4][2], const pg8::Unit& u, int wr, int wc, int fr, int fq) const {
;     ...
;                     for (int n = 0; n < 2; ++n) { yv[bj][n] = *(const f32x4*)(Yin + (size_t)row * D_ + col0 + bj * 128 + 4 * n); gq[bj][n] = *(const f32x4*)(g + col0 + bj * 128 + 4 * n); bq_[bj][n] = *(const f32x4*)(b + col0 + bj * 128 + 4 * n); }
;                 asm volatile("" ::: "memory");
;                 float s1 = 0.f, s2 = 0.f;
; #pragma unroll
;                 for (int bj = 0; bj < 2; ++bj) { float* yp = Y + (size_t)row * D_ + col0 + bj * 128; f32x4 v[2];
; #pragma unroll
;                     for (int n = 0; n < 2; ++n) { v[n] = (((yv[bj][n] - mu) * rs) * gq[bj][n] + bq_[bj][n]) * ALPHA_ + acc[ai][bj][m][n] * sc;
;                         *(f32x4*)(yp + 4 * n) = v[n]; s1 += (v[n][0] + v[n][1]) + (v[n][2] + v[n][3]); s2 += (v[n][0] * v[n][0] + v[n][1] * v[n][1]) + (v[n][2] * v[n][2] + v[n][3] * v[n][3]); }
;                     *(u32x4*)(Yb + blk_off(row, col0 + bj * 128, D_)) = pack8(v[0], v[1]); }
;                 s1 = xsum32(xsum16(s1)); s2 = xsum32(xsum16(s2));
	v_pk_mul_f32 v[178:179], v[178:179], s[18:19] op_sel_hi:[1,0]
	v_pk_mul_f32 v[212:213], v[212:213], s[18:19] op_sel_hi:[1,0]
	v_pk_fma_f32 v[128:129], v[128:129], 0.5, v[178:179] op_sel_hi:[1,0,1]
	v_pk_fma_f32 v[126:127], v[126:127], 0.5, v[212:213] op_sel_hi:[1,0,1]
	v_add_f32_e32 v179, v128, v129
	v_add_f32_e32 v178, v126, v127
	v_add_f32_e32 v178, v178, v179
	v_add_f32_e32 v195, 0, v178
	v_mul_f32_e32 v178, v127, v127
	v_mul_f32_e32 v179, v129, v129
	v_fmac_f32_e32 v178, v126, v126
	v_fmac_f32_e32 v179, v128, v128
	v_add_f32_e32 v212, v178, v179
	v_sub_f32_e32 v179, v211, v225
	v_sub_f32_e32 v178, v210, v225
	v_sub_f32_e32 v209, v209, v225
	v_sub_f32_e32 v208, v208, v225
	v_pk_mul_f32 v[208:209], v[0:1], v[208:209] op_sel_hi:[0,1]
	v_pk_mul_f32 v[178:179], v[0:1], v[178:179] op_sel_hi:[0,1]
	v_pk_fma_f32 v[178:179], v[218:219], v[178:179], v[236:237]
	v_pk_fma_f32 v[208:209], v[216:217], v[208:209], v[234:235]
	v_pk_mul_f32 v[178:179], v[178:179], s[18:19] op_sel_hi:[1,0]
	v_pk_mul_f32 v[208:209], v[208:209], s[18:19] op_sel_hi:[1,0]
	v_pk_add_f32 v[166:167], v[166:167], v[166:167] op_sel:[0,1] op_sel_hi:[1,0]
	v_pk_fma_f32 v[124:125], v[124:125], 0.5, v[178:179] op_sel_hi:[1,0,1]
	v_pk_fma_f32 v[122:123], v[122:123], 0.5, v[208:209] op_sel_hi:[1,0,1]
	v_mov_b32_e32 v159, v166
	v_add_f32_e32 v178, v122, v123
	v_add_f32_e32 v179, v124, v125
	v_pk_add_f32 v[168:169], v[168:169], v[168:169] op_sel:[0,1] op_sel_hi:[1,0]
	v_permlane16_swap_b32_e32 v166, v159
	v_add_f32_e32 v178, v178, v179
	v_add_f32_e32 v167, v166, v159
	v_mov_b32_e32 v159, v168
	v_add_f32_e32 v178, v195, v178
	v_mul_f32_e32 v179, v123, v123
	v_mul_f32_e32 v195, v125, v125
	v_permlane16_swap_b32_e32 v168, v159
	s_ashr_i32 s16, s3, 8
	s_nop 0
	s_nop 1
	v_bfe_u32 v135, v227, 4, 2
	v_sub_u32_e32 v134, 0, v135
	v_lshlrev_b32_e32 v134, 4, v134
	v_ashrrev_i32_e32 v135, 31, v134
	v_lshl_add_u64 v[134:135], v[136:137], 0, v[134:135]
	v_permlane16_swap_b32_e32 v126, v122
	v_permlane16_swap_b32_e32 v127, v123
	v_permlane16_swap_b32_e32 v128, v124
	v_permlane16_swap_b32_e32 v129, v125
	v_permlane32_swap_b32_e32 v126, v122
	v_permlane32_swap_b32_e32 v127, v123
	v_permlane32_swap_b32_e32 v128, v124
	v_permlane32_swap_b32_e32 v129, v125
	global_store_dwordx4 v[134:135], v[126:129], off
	global_store_dwordx4 v[134:135], v[122:125], off offset:64
	s_nop 1
	v_permlane32_swap_b32_e32 v126, v122
	v_permlane32_swap_b32_e32 v127, v123
	v_permlane32_swap_b32_e32 v128, v124
	v_permlane32_swap_b32_e32 v129, v125
	v_permlane16_swap_b32_e32 v126, v122
	v_permlane16_swap_b32_e32 v127, v123
	v_permlane16_swap_b32_e32 v128, v124
	v_permlane16_swap_b32_e32 v129, v125
	v_fmac_f32_e32 v179, v122, v122
	v_fmac_f32_e32 v195, v124, v124
	v_cvt_pk_bf16_f32 v126, v126, v127
	v_cvt_pk_bf16_f32 v127, v128, v129
	v_cvt_pk_bf16_f32 v128, v122, v123
	v_cvt_pk_bf16_f32 v129, v124, v125
	v_add_f32_e32 v166, v168, v159
	s_ashr_i32 s17, s16, 31
	v_lshlrev_b32_e32 v159, 6, v158
	s_movk_i32 s3, 0x33c0
	s_lshl_b64 s[16:17], s[16:17], 19
	v_and_or_b32 v159, v159, s3, v194
	v_readlane_b32 s2, v253, 59
	v_readlane_b32 s3, v253, 60
	s_add_u32 s16, s2, s16
	s_addc_u32 s17, s3, s17
	s_lshl_b64 s[28:29], s[40:41], 15
	s_waitcnt vmcnt(6)
	v_sub_f32_e32 v123, v193, v225
	v_sub_f32_e32 v122, v192, v225
	v_sub_f32_e32 v125, v191, v225
	v_sub_f32_e32 v124, v190, v225
	v_pk_mul_f32 v[124:125], v[0:1], v[124:125] op_sel_hi:[0,1]
	v_pk_mul_f32 v[122:123], v[0:1], v[122:123] op_sel_hi:[0,1]
	s_add_u32 s50, s16, s28
	s_addc_u32 s51, s17, s29
	v_lshlrev_b32_e32 v159, 1, v159
	global_store_dwordx4 v159, v[126:129], s[50:51]
	s_waitcnt vmcnt(3)
	v_pk_fma_f32 v[122:123], v[202:203], v[122:123], v[244:245]
	v_pk_fma_f32 v[124:125], v[200:201], v[124:125], v[242:243]
	v_pk_mul_f32 v[122:123], v[122:123], s[18:19] op_sel_hi:[1,0]
	v_pk_mul_f32 v[124:125], v[124:125], s[18:19] op_sel_hi:[1,0]
	v_pk_fma_f32 v[120:121], v[120:121], 0.5, v[122:123] op_sel_hi:[1,0,1]
	v_pk_fma_f32 v[118:119], v[118:119], 0.5, v[124:125] op_sel_hi:[1,0,1]
	v_add_f32_e32 v123, v120, v121
	v_add_f32_e32 v122, v118, v119
	v_add_f32_e32 v122, v122, v123
	v_add_f32_e32 v126, v178, v122
	v_mul_f32_e32 v122, v119, v119
	v_mul_f32_e32 v123, v121, v121
	v_add_f32_e32 v179, v179, v195
	v_fmac_f32_e32 v122, v118, v118
	v_fmac_f32_e32 v123, v120, v120
	v_add_f32_e32 v179, v212, v179
	v_add_f32_e32 v122, v122, v123
	v_add_f32_e32 v127, v179, v122
	v_sub_f32_e32 v123, v189, v225
	v_sub_f32_e32 v122, v188, v225
	v_sub_f32_e32 v125, v187, v225
	v_sub_f32_e32 v124, v186, v225
	v_pk_mul_f32 v[124:125], v[0:1], v[124:125] op_sel_hi:[0,1]
	v_pk_mul_f32 v[122:123], v[0:1], v[122:123] op_sel_hi:[0,1]
	v_pk_fma_f32 v[122:123], v[198:199], v[122:123], v[206:207]
	v_pk_fma_f32 v[124:125], v[196:197], v[124:125], v[204:205]
	v_pk_mul_f32 v[122:123], v[122:123], s[18:19] op_sel_hi:[1,0]
	v_pk_mul_f32 v[124:125], v[124:125], s[18:19] op_sel_hi:[1,0]
	v_pk_fma_f32 v[116:117], v[116:117], 0.5, v[122:123] op_sel_hi:[1,0,1]
	v_pk_fma_f32 v[114:115], v[114:115], 0.5, v[124:125] op_sel_hi:[1,0,1]
	v_add_f32_e32 v122, v116, v117
	v_add_f32_e32 v0, v114, v115
	v_add_f32_e32 v0, v0, v122
	v_mul_f32_e32 v122, v115, v115
	v_mul_f32_e32 v123, v117, v117
	v_add_f32_e32 v0, v126, v0
	v_fmac_f32_e32 v122, v114, v114
	v_fmac_f32_e32 v123, v116, v116
	s_nop 0
	s_nop 1
	v_bfe_u32 v125, v227, 4, 2
	v_sub_u32_e32 v124, 0, v125
	v_lshlrev_b32_e32 v124, 4, v124
	v_ashrrev_i32_e32 v125, 31, v124
	v_lshl_add_u64 v[124:125], v[136:137], 0, v[124:125]
	v_permlane16_swap_b32_e32 v118, v114
	v_permlane16_swap_b32_e32 v119, v115
	v_permlane16_swap_b32_e32 v120, v116
	v_permlane16_swap_b32_e32 v121, v117
; __device__ __forceinline__ float xsum16(float v) { const auto r = __builtin_amdgcn_permlane16_swap(__float_as_uint(v), __float_as_uint(v), false, false); return __uint_as_float(r[0]) + __uint_as_float(r[1]); }
; __device__ __forceinline__ float xsum32(float v) { const auto r = __builtin_amdgcn_permlane32_swap(__float_as_uint(v), __float_as_uint(v), false, false); return __uint_as_float(r[0]) + __uint_as_float(r[1]); }
; __device__ __forceinline__ size_t blk_off(int r, int c, int K) { return (size_t)(r >> 8) * 256 * K + (size_t)(c >> 6) * (256 * 64) + (size_t)((r & 255) * 64 + (c & 63)); }
; __device__ __forceinline__ u32x4 pack8(const f32x4 a, const f32x4 b) { u32x4 w; w.x = cvt_pk_bf16(a[0], a[1]); w.y = cvt_pk_bf16(a[2], a[3]); w.z = cvt_pk_bf16(b[0], b[1]); w.w = cvt_pk_bf16(b[2], b[3]); return w; }
;     __device__ __forceinline__ void operator()(const f32x4 (&acc)[2][2][4][2], const pg8::Unit& u, int wr, int wc, int fr, int fq) const {
;     ...
;             for (int m = 0; m < 4; ++m) { const int row = row0 + ai * 128 + m * 16; const float mu = mu4[m], rs = rs4[m];
;                 f32x4 yv[2][2], gq[2][2], bq_[2][2];
; #pragma unroll
;                 for (int bj = 0; bj < 2; ++bj)
; #pragma unroll
;                     for (int n = 0; n < 2; ++n) { yv[bj][n] = *(const f32x4*)(Yin + (size_t)row * D_ + col0 + bj * 128 + 4 * n); gq[bj][n] = *(const f32x4*)(g + col0 + bj * 128 + 4 * n); bq_[bj][n] = *(const f32x4*)(b + col0 + bj * 128 + 4 * n); }
;                 asm volatile("" ::: "memory");
;                 float s1 = 0.f, s2 = 0.f;
; #pragma unroll
;                 for (int bj = 0; bj < 2; ++bj) { float* yp = Y + (size_t)row * D_ + col0 + bj * 128; f32x4 v[2];
; #pragma unroll
;                     for (int n = 0; n < 2; ++n) { v[n] = (((yv[bj][n] - mu) * rs) * gq[bj][n] + bq_[bj][n]) * ALPHA_ + acc[ai][bj][m][n] * sc;
;                         *(f32x4*)(yp + 4 * n) = v[n]; s1 += (v[n][0] + v[n][1]) + (v[n][2] + v[n][3]); s2 += (v[n][0] * v[n][0] + v[n][1] * v[n][1]) + (v[n][2] * v[n][2] + v[n][3] * v[n][3]); }
;                     *(u32x4*)(Yb + blk_off(row, col0 + bj * 128, D_)) = pack8(v[0], v[1]); }
;                 s1 = xsum32(xsum16(s1)); s2 = xsum32(xsum16(s2));
;                 if (fq == 0) *(f32x2*)(stn + (size_t)row * 32 + (u.pn * 4 + wc) * 2) = (f32x2){s1, s2}; asm volatile("" ::: "memory"); } }
	v_permlane32_swap_b32_e32 v118, v114
	v_permlane32_swap_b32_e32 v119, v115
	v_permlane32_swap_b32_e32 v120, v116
	v_permlane32_swap_b32_e32 v121, v117
	global_store_dwordx4 v[124:125], v[118:121], off offset:512
	global_store_dwordx4 v[124:125], v[114:117], off offset:576
	s_nop 1
	v_permlane32_swap_b32_e32 v118, v114
	v_permlane32_swap_b32_e32 v119, v115
	v_permlane32_swap_b32_e32 v120, v116
	v_permlane32_swap_b32_e32 v121, v117
	v_permlane16_swap_b32_e32 v118, v114
	v_permlane16_swap_b32_e32 v119, v115
	v_permlane16_swap_b32_e32 v120, v116
	v_permlane16_swap_b32_e32 v121, v117
	v_add_f32_e32 v122, v122, v123
	v_cvt_pk_bf16_f32 v118, v118, v119
	v_cvt_pk_bf16_f32 v119, v120, v121
	v_cvt_pk_bf16_f32 v120, v114, v115
	v_mov_b32_e32 v114, v0
	v_add_f32_e32 v122, v127, v122
	s_nop 0
	v_permlane16_swap_b32_e32 v0, v114
	s_or_b32 s2, s40, 2
	v_add_f32_e32 v114, v0, v114
	v_mov_b32_e32 v0, v122
	s_ashr_i32 s3, s2, 31
	s_nop 0
	v_permlane16_swap_b32_e32 v122, v0
	s_lshl_b64 s[40:41], s[2:3], 15
	v_add_f32_e32 v115, v122, v0
	v_mov_b32_e32 v135, v133
	v_mov_b32_e32 v134, v132
	v_mov_b32_e32 v177, v175
	v_mov_b32_e32 v176, v174
	v_mov_b32_e32 v169, v167
	v_mov_b32_e32 v168, v166
	v_cvt_pk_bf16_f32 v121, v116, v117
	s_add_u32 s42, s16, s40
	v_mov_b32_e32 v116, v114
	v_mov_b32_e32 v117, v115
	v_permlane32_swap_b32_e32 v133, v135
	v_permlane32_swap_b32_e32 v132, v134
	v_permlane32_swap_b32_e32 v175, v177
	v_permlane32_swap_b32_e32 v174, v176
	v_permlane32_swap_b32_e32 v167, v169
	v_permlane32_swap_b32_e32 v166, v168
	s_addc_u32 s43, s17, s41
	v_permlane32_swap_b32_e32 v114, v116
	v_permlane32_swap_b32_e32 v115, v117
	global_store_dwordx4 v159, v[118:121], s[42:43]
	s_and_saveexec_b64 s[26:27], s[44:45]
	s_cbranch_execz .LBB0_374
	v_pk_add_f32 v[114:115], v[114:115], v[116:117]
	v_lshl_add_u64 v[116:117], s[30:31], 0, v[130:131]
	v_lshl_add_u64 v[116:117], s[24:25], 2, v[116:117]
	global_store_dwordx2 v[116:117], v[114:115], off
.LBB0_374:
	s_or_b64 exec, exec, s[26:27]
	v_pk_add_f32 v[114:115], v[132:133], v[134:135]
	s_mov_b32 s2, 0x3a800000
	v_pk_mul_f32 v[178:179], v[114:115], s[2:3] op_sel_hi:[1,0]
	s_mov_b32 s2, 0x800000
	v_fma_f32 v0, -v179, v179, v178
	v_max_f32_e32 v0, 0, v0
	v_add_f32_e32 v0, 0x3727c5ac, v0
	v_cmp_gt_f32_e32 vcc, s2, v0
	v_mul_f32_e32 v114, 0x4b800000, v0
	v_lshlrev_b64 v[212:213], 12, v[180:181]
	v_cndmask_b32_e32 v0, v0, v114, vcc
	v_rsq_f32_e32 v0, v0
	v_lshlrev_b32_e32 v159, 6, v180
	s_movk_i32 s2, 0x37c0
	v_mul_f32_e32 v114, 0x45800000, v0
	v_cndmask_b32_e32 v0, v0, v114, vcc
	v_lshl_add_u64 v[114:115], s[12:13], 0, v[212:213]
	v_lshl_add_u64 v[118:119], v[114:115], 0, v[152:153]
	global_load_dwordx4 v[186:189], v[118:119], off offset:16
	global_load_dwordx4 v[190:193], v[118:119], off
	global_load_dwordx4 v[196:199], v[154:155], off offset:16
	global_load_dwordx4 v[200:203], v[154:155], off
	global_load_dwordx4 v[204:207], v[156:157], off offset:16
	global_load_dwordx4 v[208:211], v[156:157], off
	global_load_dwordx4 v[114:117], v[118:119], off offset:528
	global_load_dwordx4 v[134:137], v[118:119], off offset:512
	s_nop 0
	global_load_dwordx4 v[118:121], v[154:155], off offset:528
	global_load_dwordx4 v[126:129], v[154:155], off offset:512
	global_load_dwordx4 v[122:125], v[156:157], off offset:528
	global_load_dwordx4 v[130:133], v[156:157], off offset:512
	v_and_or_b32 v159, v159, s2, v194
	s_load_dwordx16 s[60:75], s[34:35], 0x38
	s_mov_b32 s2, 0x3fd744fd
	v_lshlrev_b32_e32 v159, 1, v159
	s_waitcnt lgkmcnt(0)
	v_lshl_add_u64 v[180:181], s[74:75], 0, v[212:213]
	v_lshl_add_u64 v[180:181], v[180:181], 0, v[152:153]
	s_waitcnt vmcnt(11)
	v_sub_f32_e32 v189, v189, v179
	s_waitcnt vmcnt(10)
	v_sub_f32_e32 v193, v193, v179
	v_sub_f32_e32 v192, v192, v179
	v_sub_f32_e32 v191, v191, v179
	v_sub_f32_e32 v190, v190, v179
	v_pk_mul_f32 v[190:191], v[0:1], v[190:191] op_sel_hi:[0,1]
	v_pk_mul_f32 v[192:193], v[0:1], v[192:193] op_sel_hi:[0,1]
	v_sub_f32_e32 v188, v188, v179
	v_sub_f32_e32 v187, v187, v179
	v_sub_f32_e32 v186, v186, v179
	s_waitcnt vmcnt(6)
	v_pk_fma_f32 v[192:193], v[202:203], v[192:193], v[210:211]
	v_pk_fma_f32 v[190:191], v[200:201], v[190:191], v[208:209]
	v_pk_mul_f32 v[186:187], v[0:1], v[186:187] op_sel_hi:[0,1]
	v_pk_mul_f32 v[188:189], v[0:1], v[188:189] op_sel_hi:[0,1]
	v_pk_mul_f32 v[190:191], v[190:191], s[2:3] op_sel_hi:[1,0]
	v_pk_mul_f32 v[192:193], v[192:193], s[2:3] op_sel_hi:[1,0]
	v_pk_fma_f32 v[188:189], v[198:199], v[188:189], v[206:207]
	v_pk_fma_f32 v[186:187], v[196:197], v[186:187], v[204:205]
	v_pk_fma_f32 v[112:113], v[112:113], 0.5, v[192:193] op_sel_hi:[1,0,1]
	v_pk_fma_f32 v[110:111], v[110:111], 0.5, v[190:191] op_sel_hi:[1,0,1]
	v_pk_mul_f32 v[186:187], v[186:187], s[2:3] op_sel_hi:[1,0]
	v_pk_mul_f32 v[188:189], v[188:189], s[2:3] op_sel_hi:[1,0]
	v_add_f32_e32 v178, v110, v111
	v_add_f32_e32 v190, v112, v113
	v_pk_fma_f32 v[108:109], v[108:109], 0.5, v[188:189] op_sel_hi:[1,0,1]
	v_pk_fma_f32 v[106:107], v[106:107], 0.5, v[186:187] op_sel_hi:[1,0,1]
	v_add_f32_e32 v178, v178, v190
	v_add_f32_e32 v186, v106, v107
	v_add_f32_e32 v187, v108, v109
	v_add_f32_e32 v178, 0, v178
	v_add_f32_e32 v186, v186, v187
	v_mul_f32_e32 v190, v111, v111
	v_mul_f32_e32 v191, v113, v113
	v_add_f32_e32 v178, v178, v186
	v_mul_f32_e32 v186, v107, v107
	v_mul_f32_e32 v187, v109, v109
	s_nop 0
	v_fmac_f32_e32 v190, v110, v110
	v_fmac_f32_e32 v191, v112, v112
	s_nop 1
	v_bfe_u32 v189, v227, 4, 2
	v_sub_u32_e32 v188, 0, v189
	v_lshlrev_b32_e32 v188, 4, v188
	v_ashrrev_i32_e32 v189, 31, v188
	v_lshl_add_u64 v[188:189], v[180:181], 0, v[188:189]
	v_permlane16_swap_b32_e32 v110, v106
	v_permlane16_swap_b32_e32 v111, v107
	v_permlane16_swap_b32_e32 v112, v108
	v_permlane16_swap_b32_e32 v113, v109
	v_permlane32_swap_b32_e32 v110, v106
	v_permlane32_swap_b32_e32 v111, v107
	v_permlane32_swap_b32_e32 v112, v108
	v_permlane32_swap_b32_e32 v113, v109
	global_store_dwordx4 v[188:189], v[110:113], off
	global_store_dwordx4 v[188:189], v[106:109], off offset:64
	s_nop 1
	v_permlane32_swap_b32_e32 v110, v106
	v_permlane32_swap_b32_e32 v111, v107
	v_permlane32_swap_b32_e32 v112, v108
	v_permlane32_swap_b32_e32 v113, v109
	v_permlane16_swap_b32_e32 v110, v106
	v_permlane16_swap_b32_e32 v111, v107
	v_permlane16_swap_b32_e32 v112, v108
	v_permlane16_swap_b32_e32 v113, v109
	v_fmac_f32_e32 v186, v106, v106
	v_fmac_f32_e32 v187, v108, v108
	v_cvt_pk_bf16_f32 v110, v110, v111
	v_cvt_pk_bf16_f32 v111, v112, v113
	v_cvt_pk_bf16_f32 v112, v106, v107
	v_cvt_pk_bf16_f32 v113, v108, v109
	s_waitcnt vmcnt(6)
; __device__ __forceinline__ float xsum16(float v) { const auto r = __builtin_amdgcn_permlane16_swap(__float_as_uint(v), __float_as_uint(v), false, false); return __uint_as_float(r[0]) + __uint_as_float(r[1]); }
; __device__ __forceinline__ float xsum32(float v) { const auto r = __builtin_amdgcn_permlane32_swap(__float_as_uint(v), __float_as_uint(v), false, false); return __uint_as_float(r[0]) + __uint_as_float(r[1]); }
; __device__ __forceinline__ size_t blk_off(int r, int c, int K) { return (size_t)(r >> 8) * 256 * K + (size_t)(c >> 6) * (256 * 64) + (size_t)((r & 255) * 64 + (c & 63)); }
; __device__ __forceinline__ u32x4 pack8(const f32x4 a, const f32x4 b) { u32x4 w; w.x = cvt_pk_bf16(a[0], a[1]); w.y = cvt_pk_bf16(a[2], a[3]); w.z = cvt_pk_bf16(b[0], b[1]); w.w = cvt_pk_bf16(b[2], b[3]); return w; }
;     __device__ __forceinline__ void operator()(const f32x4 (&acc)[2][2][4][2], const pg8::Unit& u, int wr, int wc, int fr, int fq) const {
;     ...
;             for (int m = 0; m < 4; ++m) { const int row = row0 + ai * 128 + m * 16; const float mu = mu4[m], rs = rs4[m];
;                 f32x4 yv[2][2], gq[2][2], bq_[2][2];
; #pragma unroll
;                 for (int bj = 0; bj < 2; ++bj)
; #pragma unroll
;                     for (int n = 0; n < 2; ++n) { yv[bj][n] = *(const f32x4*)(Yin + (size_t)row * D_ + col0 + bj * 128 + 4 * n); gq[bj][n] = *(const f32x4*)(g + col0 + bj * 128 + 4 * n); bq_[bj][n] = *(const f32x4*)(b + col0 + bj * 128 + 4 * n); }
;                 asm volatile("" ::: "memory");
;                 float s1 = 0.f, s2 = 0.f;
; #pragma unroll
;                 for (int bj = 0; bj < 2; ++bj) { float* yp = Y + (size_t)row * D_ + col0 + bj * 128; f32x4 v[2];
; #pragma unroll
;                     for (int n = 0; n < 2; ++n) { v[n] = (((yv[bj][n] - mu) * rs) * gq[bj][n] + bq_[bj][n]) * ALPHA_ + acc[ai][bj][m][n] * sc;
;                         *(f32x4*)(yp + 4 * n) = v[n]; s1 += (v[n][0] + v[n][1]) + (v[n][2] + v[n][3]); s2 += (v[n][0] * v[n][0] + v[n][1] * v[n][1]) + (v[n][2] * v[n][2] + v[n][3] * v[n][3]); }
;                     *(u32x4*)(Yb + blk_off(row, col0 + bj * 128, D_)) = pack8(v[0], v[1]); }
;                 s1 = xsum32(xsum16(s1)); s2 = xsum32(xsum16(s2));
;                 if (fq == 0) *(f32x2*)(stn + (size_t)row * 32 + (u.pn * 4 + wc) * 2) = (f32x2){s1, s2}; asm volatile("" ::: "memory"); } }
	v_sub_f32_e32 v107, v137, v179
	v_sub_f32_e32 v106, v136, v179
	v_sub_f32_e32 v109, v135, v179
	v_sub_f32_e32 v108, v134, v179
	v_pk_mul_f32 v[108:109], v[0:1], v[108:109] op_sel_hi:[0,1]
	v_pk_mul_f32 v[106:107], v[0:1], v[106:107] op_sel_hi:[0,1]
	s_waitcnt vmcnt(2)
	v_pk_fma_f32 v[106:107], v[128:129], v[106:107], v[132:133]
	v_pk_fma_f32 v[108:109], v[126:127], v[108:109], v[130:131]
	v_pk_mul_f32 v[106:107], v[106:107], s[2:3] op_sel_hi:[1,0]
	v_pk_mul_f32 v[108:109], v[108:109], s[2:3] op_sel_hi:[1,0]
	v_pk_fma_f32 v[104:105], v[104:105], 0.5, v[106:107] op_sel_hi:[1,0,1]
	v_pk_fma_f32 v[102:103], v[102:103], 0.5, v[108:109] op_sel_hi:[1,0,1]
	v_add_f32_e32 v107, v104, v105
	v_add_f32_e32 v106, v102, v103
	v_add_f32_e32 v106, v106, v107
	global_store_dwordx4 v159, v[110:113], s[50:51]
	v_mul_f32_e32 v107, v105, v105
	v_add_f32_e32 v190, v190, v191
	v_add_f32_e32 v110, v178, v106
	v_mul_f32_e32 v106, v103, v103
	v_add_f32_e32 v186, v186, v187
	v_fmac_f32_e32 v106, v102, v102
	v_fmac_f32_e32 v107, v104, v104
	v_add_f32_e32 v186, v190, v186
	v_add_f32_e32 v106, v106, v107
	v_add_f32_e32 v111, v186, v106
	v_sub_f32_e32 v107, v117, v179
	v_sub_f32_e32 v106, v116, v179
	v_sub_f32_e32 v109, v115, v179
	v_sub_f32_e32 v108, v114, v179
	v_pk_mul_f32 v[108:109], v[0:1], v[108:109] op_sel_hi:[0,1]
	v_pk_mul_f32 v[106:107], v[0:1], v[106:107] op_sel_hi:[0,1]
	v_pk_fma_f32 v[106:107], v[120:121], v[106:107], v[124:125]
	v_pk_fma_f32 v[108:109], v[118:119], v[108:109], v[122:123]
	v_pk_mul_f32 v[106:107], v[106:107], s[2:3] op_sel_hi:[1,0]
	v_pk_mul_f32 v[108:109], v[108:109], s[2:3] op_sel_hi:[1,0]
	v_pk_fma_f32 v[100:101], v[100:101], 0.5, v[106:107] op_sel_hi:[1,0,1]
	v_pk_fma_f32 v[98:99], v[98:99], 0.5, v[108:109] op_sel_hi:[1,0,1]
	v_add_f32_e32 v106, v100, v101
	v_add_f32_e32 v0, v98, v99
	v_add_f32_e32 v0, v0, v106
	v_mul_f32_e32 v106, v99, v99
	v_mul_f32_e32 v107, v101, v101
	v_add_f32_e32 v0, v110, v0
	v_fmac_f32_e32 v106, v98, v98
	v_fmac_f32_e32 v107, v100, v100
	s_nop 0
	s_nop 1
	v_bfe_u32 v109, v227, 4, 2
	v_sub_u32_e32 v108, 0, v109
	v_lshlrev_b32_e32 v108, 4, v108
	v_ashrrev_i32_e32 v109, 31, v108
	v_lshl_add_u64 v[108:109], v[180:181], 0, v[108:109]
	v_permlane16_swap_b32_e32 v102, v98
	v_permlane16_swap_b32_e32 v103, v99
	v_permlane16_swap_b32_e32 v104, v100
	v_permlane16_swap_b32_e32 v105, v101
	v_permlane32_swap_b32_e32 v102, v98
	v_permlane32_swap_b32_e32 v103, v99
	v_permlane32_swap_b32_e32 v104, v100
	v_permlane32_swap_b32_e32 v105, v101
	global_store_dwordx4 v[108:109], v[102:105], off offset:512
	global_store_dwordx4 v[108:109], v[98:101], off offset:576
	s_nop 1
	v_permlane32_swap_b32_e32 v102, v98
	v_permlane32_swap_b32_e32 v103, v99
	v_permlane32_swap_b32_e32 v104, v100
	v_permlane32_swap_b32_e32 v105, v101
	v_permlane16_swap_b32_e32 v102, v98
	v_permlane16_swap_b32_e32 v103, v99
	v_permlane16_swap_b32_e32 v104, v100
	v_permlane16_swap_b32_e32 v105, v101
	v_add_f32_e32 v106, v106, v107
	v_cvt_pk_bf16_f32 v102, v102, v103
	v_cvt_pk_bf16_f32 v103, v104, v105
	v_cvt_pk_bf16_f32 v104, v98, v99
	v_mov_b32_e32 v98, v0
	v_add_f32_e32 v106, v111, v106
	s_nop 0
	v_permlane16_swap_b32_e32 v0, v98
	v_add_f32_e32 v98, v0, v98
	v_mov_b32_e32 v0, v106
	s_nop 1
	v_permlane16_swap_b32_e32 v106, v0
	v_add_f32_e32 v99, v106, v0
	v_cvt_pk_bf16_f32 v105, v100, v101
	v_mov_b32_e32 v100, v98
	v_mov_b32_e32 v101, v99
	s_nop 0
	v_permlane32_swap_b32_e32 v98, v100
	v_permlane32_swap_b32_e32 v99, v101
	global_store_dwordx4 v159, v[102:105], s[42:43]
	s_and_saveexec_b64 s[26:27], s[44:45]
	s_cbranch_execz .LBB0_376
	v_pk_add_f32 v[98:99], v[98:99], v[100:101]
	v_lshl_add_u64 v[100:101], s[30:31], 0, v[172:173]
	v_lshl_add_u64 v[100:101], s[24:25], 2, v[100:101]
	global_store_dwordx2 v[100:101], v[98:99], off
.LBB0_376:
	s_or_b64 exec, exec, s[26:27]
	v_pk_add_f32 v[98:99], v[174:175], v[176:177]
	s_mov_b32 s2, 0x3a800000
	v_pk_mul_f32 v[122:123], v[98:99], s[2:3] op_sel_hi:[1,0]
	s_mov_b32 s2, 0x800000
	v_fma_f32 v0, -v123, v123, v122
	v_max_f32_e32 v0, 0, v0
	v_add_f32_e32 v0, 0x3727c5ac, v0
	v_cmp_gt_f32_e32 vcc, s2, v0
	v_mul_f32_e32 v98, 0x4b800000, v0
	v_lshlrev_b64 v[124:125], 12, v[170:171]
	v_cndmask_b32_e32 v0, v0, v98, vcc
	v_rsq_f32_e32 v0, v0
	s_load_dwordx16 s[60:75], s[34:35], 0x38
	v_lshlrev_b32_e32 v122, 6, v170
	v_mul_f32_e32 v98, 0x45800000, v0
	v_cndmask_b32_e32 v0, v0, v98, vcc
	v_lshl_add_u64 v[98:99], s[12:13], 0, v[124:125]
	v_lshl_add_u64 v[102:103], v[98:99], 0, v[152:153]
	global_load_dwordx4 v[126:129], v[102:103], off offset:16
	global_load_dwordx4 v[130:133], v[102:103], off
	global_load_dwordx4 v[134:137], v[154:155], off offset:16
	global_load_dwordx4 v[172:175], v[154:155], off
	global_load_dwordx4 v[176:179], v[156:157], off offset:16
	global_load_dwordx4 v[186:189], v[156:157], off
	global_load_dwordx4 v[98:101], v[102:103], off offset:528
	global_load_dwordx4 v[118:121], v[102:103], off offset:512
	s_nop 0
	global_load_dwordx4 v[102:105], v[154:155], off offset:528
	global_load_dwordx4 v[110:113], v[154:155], off offset:512
	global_load_dwordx4 v[106:109], v[156:157], off offset:528
	global_load_dwordx4 v[114:117], v[156:157], off offset:512
	s_movk_i32 s2, 0x3bc0
	v_and_or_b32 v122, v122, s2, v194
	s_mov_b32 s2, 0x3fd744fd
	s_waitcnt lgkmcnt(0)
	v_lshl_add_u64 v[124:125], s[74:75], 0, v[124:125]
	v_lshl_add_u64 v[124:125], v[124:125], 0, v[152:153]
	v_lshlrev_b32_e32 v122, 1, v122
	s_waitcnt vmcnt(11)
	v_sub_f32_e32 v129, v129, v123
	s_waitcnt vmcnt(10)
; __device__ __forceinline__ float xsum16(float v) { const auto r = __builtin_amdgcn_permlane16_swap(__float_as_uint(v), __float_as_uint(v), false, false); return __uint_as_float(r[0]) + __uint_as_float(r[1]); }
; __device__ __forceinline__ float xsum32(float v) { const auto r = __builtin_amdgcn_permlane32_swap(__float_as_uint(v), __float_as_uint(v), false, false); return __uint_as_float(r[0]) + __uint_as_float(r[1]); }
; __device__ __forceinline__ size_t blk_off(int r, int c, int K) { return (size_t)(r >> 8) * 256 * K + (size_t)(c >> 6) * (256 * 64) + (size_t)((r & 255) * 64 + (c & 63)); }
; __device__ __forceinline__ u32x4 pack8(const f32x4 a, const f32x4 b) { u32x4 w; w.x = cvt_pk_bf16(a[0], a[1]); w.y = cvt_pk_bf16(a[2], a[3]); w.z = cvt_pk_bf16(b[0], b[1]); w.w = cvt_pk_bf16(b[2], b[3]); return w; }
;     __device__ __forceinline__ void operator()(const f32x4 (&acc)[2][2][4][2], const pg8::Unit& u, int wr, int wc, int fr, int fq) const {
;     ...
;             for (int m = 0; m < 4; ++m) { const int row = row0 + ai * 128 + m * 16; const float mu = mu4[m], rs = rs4[m];
;                 f32x4 yv[2][2], gq[2][2], bq_[2][2];
; #pragma unroll
;                 for (int bj = 0; bj < 2; ++bj)
; #pragma unroll
;                     for (int n = 0; n < 2; ++n) { yv[bj][n] = *(const f32x4*)(Yin + (size_t)row * D_ + col0 + bj * 128 + 4 * n); gq[bj][n] = *(const f32x4*)(g + col0 + bj * 128 + 4 * n); bq_[bj][n] = *(const f32x4*)(b + col0 + bj * 128 + 4 * n); }
;                 asm volatile("" ::: "memory");
;                 float s1 = 0.f, s2 = 0.f;
; #pragma unroll
;                 for (int bj = 0; bj < 2; ++bj) { float* yp = Y + (size_t)row * D_ + col0 + bj * 128; f32x4 v[2];
; #pragma unroll
;                     for (int n = 0; n < 2; ++n) { v[n] = (((yv[bj][n] - mu) * rs) * gq[bj][n] + bq_[bj][n]) * ALPHA_ + acc[ai][bj][m][n] * sc;
;                         *(f32x4*)(yp + 4 * n) = v[n]; s1 += (v[n][0] + v[n][1]) + (v[n][2] + v[n][3]); s2 += (v[n][0] * v[n][0] + v[n][1] * v[n][1]) + (v[n][2] * v[n][2] + v[n][3] * v[n][3]); }
;                     *(u32x4*)(Yb + blk_off(row, col0 + bj * 128, D_)) = pack8(v[0], v[1]); }
;                 s1 = xsum32(xsum16(s1)); s2 = xsum32(xsum16(s2));
;                 if (fq == 0) *(f32x2*)(stn + (size_t)row * 32 + (u.pn * 4 + wc) * 2) = (f32x2){s1, s2}; asm volatile("" ::: "memory"); } }
	v_sub_f32_e32 v133, v133, v123
	v_sub_f32_e32 v132, v132, v123
	v_sub_f32_e32 v131, v131, v123
	v_sub_f32_e32 v130, v130, v123
	v_sub_f32_e32 v128, v128, v123
	v_sub_f32_e32 v127, v127, v123
	v_sub_f32_e32 v126, v126, v123
	v_pk_mul_f32 v[130:131], v[0:1], v[130:131] op_sel_hi:[0,1]
	v_pk_mul_f32 v[132:133], v[0:1], v[132:133] op_sel_hi:[0,1]
	v_pk_mul_f32 v[126:127], v[0:1], v[126:127] op_sel_hi:[0,1]
	v_pk_mul_f32 v[128:129], v[0:1], v[128:129] op_sel_hi:[0,1]
	s_waitcnt vmcnt(6)
	v_pk_fma_f32 v[132:133], v[174:175], v[132:133], v[188:189]
	v_pk_fma_f32 v[130:131], v[172:173], v[130:131], v[186:187]
	v_pk_fma_f32 v[128:129], v[136:137], v[128:129], v[178:179]
	v_pk_fma_f32 v[126:127], v[134:135], v[126:127], v[176:177]
	v_pk_mul_f32 v[130:131], v[130:131], s[2:3] op_sel_hi:[1,0]
	v_pk_mul_f32 v[132:133], v[132:133], s[2:3] op_sel_hi:[1,0]
	v_pk_mul_f32 v[126:127], v[126:127], s[2:3] op_sel_hi:[1,0]
	v_pk_mul_f32 v[128:129], v[128:129], s[2:3] op_sel_hi:[1,0]
	v_pk_fma_f32 v[96:97], v[96:97], 0.5, v[132:133] op_sel_hi:[1,0,1]
	v_pk_fma_f32 v[94:95], v[94:95], 0.5, v[130:131] op_sel_hi:[1,0,1]
	v_pk_fma_f32 v[92:93], v[92:93], 0.5, v[128:129] op_sel_hi:[1,0,1]
	v_pk_fma_f32 v[90:91], v[90:91], 0.5, v[126:127] op_sel_hi:[1,0,1]
	v_add_f32_e32 v130, v94, v95
	v_add_f32_e32 v131, v96, v97
	v_add_f32_e32 v126, v90, v91
	v_add_f32_e32 v127, v92, v93
	v_add_f32_e32 v130, v130, v131
	v_mul_f32_e32 v131, v95, v95
	v_mul_f32_e32 v132, v97, v97
	v_add_f32_e32 v126, v126, v127
	v_mul_f32_e32 v127, v91, v91
	v_mul_f32_e32 v128, v93, v93
	s_nop 0
	v_fmac_f32_e32 v131, v94, v94
	v_fmac_f32_e32 v132, v96, v96
	s_nop 1
	v_bfe_u32 v135, v227, 4, 2
	v_sub_u32_e32 v134, 0, v135
	v_lshlrev_b32_e32 v134, 4, v134
	v_ashrrev_i32_e32 v135, 31, v134
	v_lshl_add_u64 v[134:135], v[124:125], 0, v[134:135]
	v_permlane16_swap_b32_e32 v94, v90
	v_permlane16_swap_b32_e32 v95, v91
	v_permlane16_swap_b32_e32 v96, v92
	v_permlane16_swap_b32_e32 v97, v93
	v_permlane32_swap_b32_e32 v94, v90
	v_permlane32_swap_b32_e32 v95, v91
	v_permlane32_swap_b32_e32 v96, v92
	v_permlane32_swap_b32_e32 v97, v93
	global_store_dwordx4 v[134:135], v[94:97], off
	global_store_dwordx4 v[134:135], v[90:93], off offset:64
	s_nop 1
	v_permlane32_swap_b32_e32 v94, v90
	v_permlane32_swap_b32_e32 v95, v91
	v_permlane32_swap_b32_e32 v96, v92
	v_permlane32_swap_b32_e32 v97, v93
	v_permlane16_swap_b32_e32 v94, v90
	v_permlane16_swap_b32_e32 v95, v91
	v_permlane16_swap_b32_e32 v96, v92
	v_permlane16_swap_b32_e32 v97, v93
	v_fmac_f32_e32 v127, v90, v90
	v_fmac_f32_e32 v128, v92, v92
	v_cvt_pk_bf16_f32 v94, v94, v95
	v_cvt_pk_bf16_f32 v95, v96, v97
	v_cvt_pk_bf16_f32 v96, v90, v91
	v_cvt_pk_bf16_f32 v97, v92, v93
	s_waitcnt vmcnt(6)
	v_sub_f32_e32 v91, v121, v123
	v_sub_f32_e32 v90, v120, v123
	v_sub_f32_e32 v93, v119, v123
	v_sub_f32_e32 v92, v118, v123
	v_pk_mul_f32 v[92:93], v[0:1], v[92:93] op_sel_hi:[0,1]
	v_pk_mul_f32 v[90:91], v[0:1], v[90:91] op_sel_hi:[0,1]
	s_waitcnt vmcnt(2)
	v_pk_fma_f32 v[90:91], v[112:113], v[90:91], v[116:117]
	v_pk_fma_f32 v[92:93], v[110:111], v[92:93], v[114:115]
	v_pk_mul_f32 v[90:91], v[90:91], s[2:3] op_sel_hi:[1,0]
	v_pk_mul_f32 v[92:93], v[92:93], s[2:3] op_sel_hi:[1,0]
	v_pk_fma_f32 v[88:89], v[88:89], 0.5, v[90:91] op_sel_hi:[1,0,1]
	v_pk_fma_f32 v[86:87], v[86:87], 0.5, v[92:93] op_sel_hi:[1,0,1]
	v_add_f32_e32 v130, 0, v130
	v_add_f32_e32 v90, v86, v87
	v_add_f32_e32 v91, v88, v89
	v_add_f32_e32 v126, v130, v126
	v_add_f32_e32 v90, v90, v91
	global_store_dwordx4 v122, v[94:97], s[50:51]
	v_mul_f32_e32 v91, v89, v89
	v_add_f32_e32 v131, v131, v132
	v_add_f32_e32 v94, v126, v90
	v_mul_f32_e32 v90, v87, v87
	v_add_f32_e32 v127, v127, v128
	v_fmac_f32_e32 v90, v86, v86
	v_fmac_f32_e32 v91, v88, v88
	v_add_f32_e32 v127, v131, v127
	v_add_f32_e32 v90, v90, v91
	v_add_f32_e32 v95, v127, v90
	v_sub_f32_e32 v91, v101, v123
	v_sub_f32_e32 v90, v100, v123
	v_sub_f32_e32 v93, v99, v123
	v_sub_f32_e32 v92, v98, v123
	v_pk_mul_f32 v[92:93], v[0:1], v[92:93] op_sel_hi:[0,1]
	v_pk_mul_f32 v[90:91], v[0:1], v[90:91] op_sel_hi:[0,1]
	v_pk_fma_f32 v[90:91], v[104:105], v[90:91], v[108:109]
	v_pk_fma_f32 v[92:93], v[102:103], v[92:93], v[106:107]
	v_pk_mul_f32 v[90:91], v[90:91], s[2:3] op_sel_hi:[1,0]
	v_pk_mul_f32 v[92:93], v[92:93], s[2:3] op_sel_hi:[1,0]
	v_pk_fma_f32 v[84:85], v[84:85], 0.5, v[90:91] op_sel_hi:[1,0,1]
	v_pk_fma_f32 v[82:83], v[82:83], 0.5, v[92:93] op_sel_hi:[1,0,1]
	v_add_f32_e32 v90, v84, v85
	v_add_f32_e32 v0, v82, v83
	v_add_f32_e32 v0, v0, v90
	v_mul_f32_e32 v90, v83, v83
	v_mul_f32_e32 v91, v85, v85
	v_add_f32_e32 v0, v94, v0
	v_fmac_f32_e32 v90, v82, v82
	v_fmac_f32_e32 v91, v84, v84
	s_nop 0
	s_nop 1
	v_bfe_u32 v93, v227, 4, 2
	v_sub_u32_e32 v92, 0, v93
	v_lshlrev_b32_e32 v92, 4, v92
	v_ashrrev_i32_e32 v93, 31, v92
	v_lshl_add_u64 v[92:93], v[124:125], 0, v[92:93]
	v_permlane16_swap_b32_e32 v86, v82
	v_permlane16_swap_b32_e32 v87, v83
	v_permlane16_swap_b32_e32 v88, v84
	v_permlane16_swap_b32_e32 v89, v85
	v_permlane32_swap_b32_e32 v86, v82
	v_permlane32_swap_b32_e32 v87, v83
	v_permlane32_swap_b32_e32 v88, v84
	v_permlane32_swap_b32_e32 v89, v85
	global_store_dwordx4 v[92:93], v[86:89], off offset:512
	global_store_dwordx4 v[92:93], v[82:85], off offset:576
	s_nop 1
	v_permlane32_swap_b32_e32 v86, v82
	v_permlane32_swap_b32_e32 v87, v83
	v_permlane32_swap_b32_e32 v88, v84
	v_permlane32_swap_b32_e32 v89, v85
	v_permlane16_swap_b32_e32 v86, v82
	v_permlane16_swap_b32_e32 v87, v83
	v_permlane16_swap_b32_e32 v88, v84
	v_permlane16_swap_b32_e32 v89, v85
	v_add_f32_e32 v90, v90, v91
	v_cvt_pk_bf16_f32 v86, v86, v87
	v_cvt_pk_bf16_f32 v87, v88, v89
	v_cvt_pk_bf16_f32 v88, v82, v83
	v_mov_b32_e32 v82, v0
	v_add_f32_e32 v90, v95, v90
	s_nop 0
	v_permlane16_swap_b32_e32 v0, v82
	v_add_f32_e32 v82, v0, v82
	v_mov_b32_e32 v0, v90
	s_nop 1
	v_permlane16_swap_b32_e32 v90, v0
	v_add_f32_e32 v83, v90, v0
	v_cvt_pk_bf16_f32 v89, v84, v85
	v_mov_b32_e32 v84, v82
	v_mov_b32_e32 v85, v83
	s_nop 0
	v_permlane32_swap_b32_e32 v82, v84
	v_permlane32_swap_b32_e32 v83, v85
	global_store_dwordx4 v122, v[86:89], s[42:43]
	s_and_saveexec_b64 s[26:27], s[44:45]
	s_cbranch_execz .LBB0_378
	v_pk_add_f32 v[82:83], v[82:83], v[84:85]
	v_lshl_add_u64 v[84:85], s[30:31], 0, v[164:165]
	v_lshl_add_u64 v[84:85], s[24:25], 2, v[84:85]
	global_store_dwordx2 v[84:85], v[82:83], off
; __device__ __forceinline__ size_t blk_off(int r, int c, int K) { return (size_t)(r >> 8) * 256 * K + (size_t)(c >> 6) * (256 * 64) + (size_t)((r & 255) * 64 + (c & 63)); }
; __device__ __forceinline__ u32x4 pack8(const f32x4 a, const f32x4 b) { u32x4 w; w.x = cvt_pk_bf16(a[0], a[1]); w.y = cvt_pk_bf16(a[2], a[3]); w.z = cvt_pk_bf16(b[0], b[1]); w.w = cvt_pk_bf16(b[2], b[3]); return w; }
;     __device__ __forceinline__ void operator()(const f32x4 (&acc)[2][2][4][2], const pg8::Unit& u, int wr, int wc, int fr, int fq) const {
;     ...
;             for (int m = 0; m < 4; ++m) { const int row = row0 + ai * 128 + m * 16; const float mu = mu4[m], rs = rs4[m];
;                 f32x4 yv[2][2], gq[2][2], bq_[2][2];
; #pragma unroll
;                 for (int bj = 0; bj < 2; ++bj)
; #pragma unroll
;                     for (int n = 0; n < 2; ++n) { yv[bj][n] = *(const f32x4*)(Yin + (size_t)row * D_ + col0 + bj * 128 + 4 * n); gq[bj][n] = *(const f32x4*)(g + col0 + bj * 128 + 4 * n); bq_[bj][n] = *(const f32x4*)(b + col0 + bj * 128 + 4 * n); }
;                 asm volatile("" ::: "memory");
;                 float s1 = 0.f, s2 = 0.f;
; #pragma unroll
;                 for (int bj = 0; bj < 2; ++bj) { float* yp = Y + (size_t)row * D_ + col0 + bj * 128; f32x4 v[2];
; #pragma unroll
;                     for (int n = 0; n < 2; ++n) { v[n] = (((yv[bj][n] - mu) * rs) * gq[bj][n] + bq_[bj][n]) * ALPHA_ + acc[ai][bj][m][n] * sc;
;                         *(f32x4*)(yp + 4 * n) = v[n]; s1 += (v[n][0] + v[n][1]) + (v[n][2] + v[n][3]); s2 += (v[n][0] * v[n][0] + v[n][1] * v[n][1]) + (v[n][2] * v[n][2] + v[n][3] * v[n][3]); }
;                     *(u32x4*)(Yb + blk_off(row, col0 + bj * 128, D_)) = pack8(v[0], v[1]); }
.LBB0_378:
	s_or_b64 exec, exec, s[26:27]
	v_pk_add_f32 v[82:83], v[166:167], v[168:169]
	s_mov_b32 s2, 0x3a800000
	v_pk_mul_f32 v[106:107], v[82:83], s[2:3] op_sel_hi:[1,0]
	s_mov_b32 s2, 0x800000
	v_fma_f32 v0, -v107, v107, v106
	v_max_f32_e32 v0, 0, v0
	v_add_f32_e32 v0, 0x3727c5ac, v0
	v_cmp_gt_f32_e32 vcc, s2, v0
	v_mul_f32_e32 v82, 0x4b800000, v0
	v_lshlrev_b64 v[108:109], 12, v[162:163]
	v_cndmask_b32_e32 v0, v0, v82, vcc
	v_rsq_f32_e32 v0, v0
	s_load_dwordx16 s[60:75], s[34:35], 0x38
	v_lshlrev_b32_e32 v106, 6, v162
	v_mul_f32_e32 v82, 0x45800000, v0
	v_cndmask_b32_e32 v0, v0, v82, vcc
	v_lshl_add_u64 v[82:83], s[12:13], 0, v[108:109]
	v_lshl_add_u64 v[86:87], v[82:83], 0, v[152:153]
	global_load_dwordx4 v[110:113], v[86:87], off offset:16
	global_load_dwordx4 v[114:117], v[86:87], off
	global_load_dwordx4 v[118:121], v[154:155], off offset:16
	global_load_dwordx4 v[122:125], v[154:155], off
	global_load_dwordx4 v[126:129], v[156:157], off offset:16
	global_load_dwordx4 v[130:133], v[156:157], off
	global_load_dwordx4 v[82:85], v[86:87], off offset:528
	global_load_dwordx4 v[102:105], v[86:87], off offset:512
	s_nop 0
	global_load_dwordx4 v[86:89], v[154:155], off offset:528
	global_load_dwordx4 v[94:97], v[154:155], off offset:512
	global_load_dwordx4 v[90:93], v[156:157], off offset:528
	global_load_dwordx4 v[98:101], v[156:157], off offset:512
	s_movk_i32 s2, 0x3fc0
	v_and_or_b32 v106, v106, s2, v194
	s_mov_b32 s2, 0x3fd744fd
	s_waitcnt lgkmcnt(0)
	v_lshl_add_u64 v[108:109], s[74:75], 0, v[108:109]
	v_lshl_add_u64 v[108:109], v[108:109], 0, v[152:153]
	v_lshlrev_b32_e32 v106, 1, v106
	s_waitcnt vmcnt(11)
	v_sub_f32_e32 v113, v113, v107
	s_waitcnt vmcnt(10)
	v_sub_f32_e32 v117, v117, v107
	v_sub_f32_e32 v116, v116, v107
	v_sub_f32_e32 v115, v115, v107
	v_sub_f32_e32 v114, v114, v107
	v_sub_f32_e32 v112, v112, v107
	v_sub_f32_e32 v111, v111, v107
	v_sub_f32_e32 v110, v110, v107
	v_pk_mul_f32 v[114:115], v[0:1], v[114:115] op_sel_hi:[0,1]
	v_pk_mul_f32 v[116:117], v[0:1], v[116:117] op_sel_hi:[0,1]
	v_pk_mul_f32 v[110:111], v[0:1], v[110:111] op_sel_hi:[0,1]
	v_pk_mul_f32 v[112:113], v[0:1], v[112:113] op_sel_hi:[0,1]
	s_waitcnt vmcnt(6)
	v_pk_fma_f32 v[116:117], v[124:125], v[116:117], v[132:133]
	v_pk_fma_f32 v[114:115], v[122:123], v[114:115], v[130:131]
	v_pk_fma_f32 v[112:113], v[120:121], v[112:113], v[128:129]
	v_pk_fma_f32 v[110:111], v[118:119], v[110:111], v[126:127]
	v_pk_mul_f32 v[114:115], v[114:115], s[2:3] op_sel_hi:[1,0]
	v_pk_mul_f32 v[116:117], v[116:117], s[2:3] op_sel_hi:[1,0]
	v_pk_mul_f32 v[110:111], v[110:111], s[2:3] op_sel_hi:[1,0]
	v_pk_mul_f32 v[112:113], v[112:113], s[2:3] op_sel_hi:[1,0]
	v_pk_fma_f32 v[80:81], v[80:81], 0.5, v[116:117] op_sel_hi:[1,0,1]
	v_pk_fma_f32 v[78:79], v[78:79], 0.5, v[114:115] op_sel_hi:[1,0,1]
	v_pk_fma_f32 v[76:77], v[76:77], 0.5, v[112:113] op_sel_hi:[1,0,1]
	v_pk_fma_f32 v[74:75], v[74:75], 0.5, v[110:111] op_sel_hi:[1,0,1]
	v_add_f32_e32 v114, v78, v79
	v_add_f32_e32 v115, v80, v81
	v_add_f32_e32 v110, v74, v75
	v_add_f32_e32 v111, v76, v77
	v_add_f32_e32 v114, v114, v115
	v_mul_f32_e32 v115, v79, v79
	v_mul_f32_e32 v116, v81, v81
	v_add_f32_e32 v110, v110, v111
	v_mul_f32_e32 v111, v75, v75
	v_mul_f32_e32 v112, v77, v77
	s_nop 0
	v_fmac_f32_e32 v115, v78, v78
	v_fmac_f32_e32 v116, v80, v80
	s_nop 1
	v_bfe_u32 v119, v227, 4, 2
	v_sub_u32_e32 v118, 0, v119
	v_lshlrev_b32_e32 v118, 4, v118
	v_ashrrev_i32_e32 v119, 31, v118
	v_lshl_add_u64 v[118:119], v[108:109], 0, v[118:119]
	v_permlane16_swap_b32_e32 v78, v74
	v_permlane16_swap_b32_e32 v79, v75
	v_permlane16_swap_b32_e32 v80, v76
	v_permlane16_swap_b32_e32 v81, v77
	v_permlane32_swap_b32_e32 v78, v74
	v_permlane32_swap_b32_e32 v79, v75
	v_permlane32_swap_b32_e32 v80, v76
	v_permlane32_swap_b32_e32 v81, v77
	global_store_dwordx4 v[118:119], v[78:81], off
	global_store_dwordx4 v[118:119], v[74:77], off offset:64
	s_nop 1
	v_permlane32_swap_b32_e32 v78, v74
	v_permlane32_swap_b32_e32 v79, v75
	v_permlane32_swap_b32_e32 v80, v76
	v_permlane32_swap_b32_e32 v81, v77
	v_permlane16_swap_b32_e32 v78, v74
	v_permlane16_swap_b32_e32 v79, v75
	v_permlane16_swap_b32_e32 v80, v76
	v_permlane16_swap_b32_e32 v81, v77
	v_fmac_f32_e32 v111, v74, v74
	v_fmac_f32_e32 v112, v76, v76
	v_cvt_pk_bf16_f32 v78, v78, v79
	v_cvt_pk_bf16_f32 v79, v80, v81
	v_cvt_pk_bf16_f32 v80, v74, v75
	v_cvt_pk_bf16_f32 v81, v76, v77
	s_waitcnt vmcnt(6)
	v_sub_f32_e32 v75, v105, v107
	v_sub_f32_e32 v74, v104, v107
	v_sub_f32_e32 v77, v103, v107
	v_sub_f32_e32 v76, v102, v107
	v_pk_mul_f32 v[76:77], v[0:1], v[76:77] op_sel_hi:[0,1]
	v_pk_mul_f32 v[74:75], v[0:1], v[74:75] op_sel_hi:[0,1]
	s_waitcnt vmcnt(2)
; __device__ __forceinline__ float xsum16(float v) { const auto r = __builtin_amdgcn_permlane16_swap(__float_as_uint(v), __float_as_uint(v), false, false); return __uint_as_float(r[0]) + __uint_as_float(r[1]); }
; __device__ __forceinline__ void row_stats4(const float* st, int rowb, int fq, float (&mu)[4], float (&rs)[4]) {
;     ...
;     for (int m = 0; m < 4; ++m) { const f32x4* p = (const f32x4*)(st + (size_t)(rowb + m * 16) * 32 + fq * 8); a[m] = p[0]; b[m] = p[1]; }
; #pragma unroll
;     for (int m = 0; m < 4; ++m) { float s1 = (a[m][0] + a[m][2]) + (b[m][0] + b[m][2]), s2 = (a[m][1] + a[m][3]) + (b[m][1] + b[m][3]);
;         s1 = xsum32(xsum16(s1)); s2 = xsum32(xsum16(s2));
;         const float mm = s1 * (1.0f / 1024.0f); mu[m] = mm; rs[m] = rsqrtf(fmaxf(s2 * (1.0f / 1024.0f) - mm * mm, 0.f) + LN_EPS_); }
;     __device__ __forceinline__ void operator()(const f32x4 (&acc)[2][2][4][2], const pg8::Unit& u, int wr, int wc, int fr, int fq) const {
;     ...
;             for (int m = 0; m < 4; ++m) { const int row = row0 + ai * 128 + m * 16; const float mu = mu4[m], rs = rs4[m];
;                 f32x4 yv[2][2], gq[2][2], bq_[2][2];
; #pragma unroll
;                 for (int bj = 0; bj < 2; ++bj)
; #pragma unroll
;                     for (int n = 0; n < 2; ++n) { yv[bj][n] = *(const f32x4*)(Yin + (size_t)row * D_ + col0 + bj * 128 + 4 * n); gq[bj][n] = *(const f32x4*)(g + col0 + bj * 128 + 4 * n); bq_[bj][n] = *(const f32x4*)(b + col0 + bj * 128 + 4 * n); }
;                 asm volatile("" ::: "memory");
;                 float s1 = 0.f, s2 = 0.f;
; #pragma unroll
;                 for (int bj = 0; bj < 2; ++bj) { float* yp = Y + (size_t)row * D_ + col0 + bj * 128; f32x4 v[2];
; #pragma unroll
;                     for (int n = 0; n < 2; ++n) { v[n] = (((yv[bj][n] - mu) * rs) * gq[bj][n] + bq_[bj][n]) * ALPHA_ + acc[ai][bj][m][n] * sc;
;                         *(f32x4*)(yp + 4 * n) = v[n]; s1 += (v[n][0] + v[n][1]) + (v[n][2] + v[n][3]); s2 += (v[n][0] * v[n][0] + v[n][1] * v[n][1]) + (v[n][2] * v[n][2] + v[n][3] * v[n][3]); }
;                     *(u32x4*)(Yb + blk_off(row, col0 + bj * 128, D_)) = pack8(v[0], v[1]); }
;                 s1 = xsum32(xsum16(s1)); s2 = xsum32(xsum16(s2));
;                 if (fq == 0) *(f32x2*)(stn + (size_t)row * 32 + (u.pn * 4 + wc) * 2) = (f32x2){s1, s2}; asm volatile("" ::: "memory"); } }
	v_pk_fma_f32 v[74:75], v[96:97], v[74:75], v[100:101]
	v_pk_fma_f32 v[76:77], v[94:95], v[76:77], v[98:99]
	v_pk_mul_f32 v[74:75], v[74:75], s[2:3] op_sel_hi:[1,0]
	v_pk_mul_f32 v[76:77], v[76:77], s[2:3] op_sel_hi:[1,0]
	v_pk_fma_f32 v[72:73], v[72:73], 0.5, v[74:75] op_sel_hi:[1,0,1]
	v_pk_fma_f32 v[70:71], v[70:71], 0.5, v[76:77] op_sel_hi:[1,0,1]
	v_add_f32_e32 v114, 0, v114
	v_add_f32_e32 v74, v70, v71
	v_add_f32_e32 v75, v72, v73
	v_add_f32_e32 v110, v114, v110
	v_add_f32_e32 v74, v74, v75
	global_store_dwordx4 v106, v[78:81], s[50:51]
	v_mul_f32_e32 v75, v73, v73
	v_add_f32_e32 v115, v115, v116
	v_add_f32_e32 v78, v110, v74
	v_mul_f32_e32 v74, v71, v71
	v_add_f32_e32 v111, v111, v112
	v_fmac_f32_e32 v74, v70, v70
	v_fmac_f32_e32 v75, v72, v72
	v_add_f32_e32 v111, v115, v111
	v_add_f32_e32 v74, v74, v75
	v_add_f32_e32 v79, v111, v74
	v_sub_f32_e32 v75, v85, v107
	v_sub_f32_e32 v74, v84, v107
	v_sub_f32_e32 v77, v83, v107
	v_sub_f32_e32 v76, v82, v107
	v_pk_mul_f32 v[76:77], v[0:1], v[76:77] op_sel_hi:[0,1]
	v_pk_mul_f32 v[74:75], v[0:1], v[74:75] op_sel_hi:[0,1]
	v_pk_fma_f32 v[74:75], v[88:89], v[74:75], v[92:93]
	v_pk_fma_f32 v[76:77], v[86:87], v[76:77], v[90:91]
	v_pk_mul_f32 v[74:75], v[74:75], s[2:3] op_sel_hi:[1,0]
	v_pk_mul_f32 v[76:77], v[76:77], s[2:3] op_sel_hi:[1,0]
	v_pk_fma_f32 v[68:69], v[68:69], 0.5, v[74:75] op_sel_hi:[1,0,1]
	v_pk_fma_f32 v[66:67], v[66:67], 0.5, v[76:77] op_sel_hi:[1,0,1]
	v_add_f32_e32 v74, v68, v69
	v_add_f32_e32 v0, v66, v67
	v_add_f32_e32 v0, v0, v74
	v_mul_f32_e32 v74, v67, v67
	v_mul_f32_e32 v75, v69, v69
	v_add_f32_e32 v0, v78, v0
	v_fmac_f32_e32 v74, v66, v66
	v_fmac_f32_e32 v75, v68, v68
	s_nop 0
	s_nop 1
	v_bfe_u32 v77, v227, 4, 2
	v_sub_u32_e32 v76, 0, v77
	v_lshlrev_b32_e32 v76, 4, v76
	v_ashrrev_i32_e32 v77, 31, v76
	v_lshl_add_u64 v[76:77], v[108:109], 0, v[76:77]
	v_permlane16_swap_b32_e32 v70, v66
	v_permlane16_swap_b32_e32 v71, v67
	v_permlane16_swap_b32_e32 v72, v68
	v_permlane16_swap_b32_e32 v73, v69
	v_permlane32_swap_b32_e32 v70, v66
	v_permlane32_swap_b32_e32 v71, v67
	v_permlane32_swap_b32_e32 v72, v68
	v_permlane32_swap_b32_e32 v73, v69
	global_store_dwordx4 v[76:77], v[70:73], off offset:512
	global_store_dwordx4 v[76:77], v[66:69], off offset:576
	s_nop 1
	v_permlane32_swap_b32_e32 v70, v66
	v_permlane32_swap_b32_e32 v71, v67
	v_permlane32_swap_b32_e32 v72, v68
	v_permlane32_swap_b32_e32 v73, v69
	v_permlane16_swap_b32_e32 v70, v66
	v_permlane16_swap_b32_e32 v71, v67
	v_permlane16_swap_b32_e32 v72, v68
	v_permlane16_swap_b32_e32 v73, v69
	v_add_f32_e32 v74, v74, v75
	v_cvt_pk_bf16_f32 v70, v70, v71
	v_cvt_pk_bf16_f32 v71, v72, v73
	v_cvt_pk_bf16_f32 v72, v66, v67
	v_mov_b32_e32 v66, v0
	v_add_f32_e32 v74, v79, v74
	s_nop 0
	v_permlane16_swap_b32_e32 v0, v66
	v_add_f32_e32 v66, v0, v66
	v_mov_b32_e32 v0, v74
	s_nop 1
	v_permlane16_swap_b32_e32 v74, v0
	v_add_f32_e32 v67, v74, v0
	v_cvt_pk_bf16_f32 v73, v68, v69
	v_mov_b32_e32 v68, v66
	v_mov_b32_e32 v69, v67
	s_nop 0
	v_permlane32_swap_b32_e32 v66, v68
	v_permlane32_swap_b32_e32 v67, v69
	global_store_dwordx4 v106, v[70:73], s[42:43]
	s_and_saveexec_b64 s[26:27], s[44:45]
	s_cbranch_execz .LBB0_380
	v_pk_add_f32 v[66:67], v[66:67], v[68:69]
	v_lshl_add_u64 v[68:69], s[30:31], 0, v[160:161]
	v_lshl_add_u64 v[68:69], s[24:25], 2, v[68:69]
	global_store_dwordx2 v[68:69], v[66:67], off
.LBB0_380:
	s_or_b64 exec, exec, s[26:27]
	v_add_u32_e32 v68, 0x80, v158
	v_ashrrev_i32_e32 v69, 31, v68
	v_add_u32_e32 v94, 0x90, v158
	v_lshlrev_b64 v[66:67], 7, v[68:69]
	v_ashrrev_i32_e32 v95, 31, v94
	v_lshl_add_u64 v[74:75], v[146:147], 0, v[66:67]
	v_lshlrev_b64 v[86:87], 7, v[94:95]
	v_add_u32_e32 v76, 0xa0, v158
	global_load_dwordx4 v[70:73], v[74:75], off
	global_load_dwordx4 v[78:81], v[74:75], off offset:16
	v_lshl_add_u64 v[74:75], v[146:147], 0, v[86:87]
	v_ashrrev_i32_e32 v77, 31, v76
	global_load_dwordx4 v[82:85], v[74:75], off
	global_load_dwordx4 v[88:91], v[74:75], off offset:16
	v_lshlrev_b64 v[74:75], 7, v[76:77]
	v_lshl_add_u64 v[74:75], v[146:147], 0, v[74:75]
	global_load_dwordx4 v[96:99], v[74:75], off
	global_load_dwordx4 v[100:103], v[74:75], off offset:16
	v_add_u32_e32 v74, 0xb0, v158
	v_ashrrev_i32_e32 v75, 31, v74
	v_lshlrev_b64 v[92:93], 7, v[74:75]
	v_lshl_add_u64 v[92:93], v[146:147], 0, v[92:93]
	global_load_dwordx4 v[104:107], v[92:93], off
	global_load_dwordx4 v[108:111], v[92:93], off offset:16
	v_lshlrev_b64 v[136:137], 12, v[68:69]
	v_lshl_add_u64 v[112:113], s[12:13], 0, v[136:137]
	v_lshl_add_u64 v[92:93], v[112:113], 0, v[152:153]
	global_load_dwordx4 v[112:115], v[92:93], off offset:16
	global_load_dwordx4 v[116:119], v[92:93], off
	global_load_dwordx4 v[120:123], v[154:155], off offset:16
	global_load_dwordx4 v[124:127], v[154:155], off
	global_load_dwordx4 v[128:131], v[156:157], off offset:16
	global_load_dwordx4 v[132:135], v[156:157], off
	s_mov_b32 s2, 0x3a800000
	s_mov_b32 s16, 0x3fd744fd
	s_load_dwordx16 s[60:75], s[34:35], 0x38
	s_waitcnt vmcnt(13)
	v_mov_b32_e32 v158, v70
	s_waitcnt vmcnt(12)
	v_mov_b32_e32 v159, v78
	v_mov_b32_e32 v160, v72
	v_mov_b32_e32 v161, v80
	v_mov_b32_e32 v78, v71
	v_mov_b32_e32 v80, v73
	s_waitcnt vmcnt(11)
	v_mov_b32_e32 v70, v82
	s_waitcnt vmcnt(10)
	v_mov_b32_e32 v71, v88
	v_mov_b32_e32 v72, v84
	v_mov_b32_e32 v73, v90
	v_mov_b32_e32 v88, v83
	v_mov_b32_e32 v90, v85
	s_waitcnt vmcnt(9)
	v_mov_b32_e32 v82, v96
	s_waitcnt vmcnt(8)
; __device__ __forceinline__ float xsum16(float v) { const auto r = __builtin_amdgcn_permlane16_swap(__float_as_uint(v), __float_as_uint(v), false, false); return __uint_as_float(r[0]) + __uint_as_float(r[1]); }
; __device__ __forceinline__ float xsum32(float v) { const auto r = __builtin_amdgcn_permlane32_swap(__float_as_uint(v), __float_as_uint(v), false, false); return __uint_as_float(r[0]) + __uint_as_float(r[1]); }
; __device__ __forceinline__ size_t blk_off(int r, int c, int K) { return (size_t)(r >> 8) * 256 * K + (size_t)(c >> 6) * (256 * 64) + (size_t)((r & 255) * 64 + (c & 63)); }
; __device__ __forceinline__ void row_stats4(const float* st, int rowb, int fq, float (&mu)[4], float (&rs)[4]) {
;     ...
;     for (int m = 0; m < 4; ++m) { const f32x4* p = (const f32x4*)(st + (size_t)(rowb + m * 16) * 32 + fq * 8); a[m] = p[0]; b[m] = p[1]; }
; #pragma unroll
;     for (int m = 0; m < 4; ++m) { float s1 = (a[m][0] + a[m][2]) + (b[m][0] + b[m][2]), s2 = (a[m][1] + a[m][3]) + (b[m][1] + b[m][3]);
;         s1 = xsum32(xsum16(s1)); s2 = xsum32(xsum16(s2));
;         const float mm = s1 * (1.0f / 1024.0f); mu[m] = mm; rs[m] = rsqrtf(fmaxf(s2 * (1.0f / 1024.0f) - mm * mm, 0.f) + LN_EPS_); }
;     __device__ __forceinline__ void operator()(const f32x4 (&acc)[2][2][4][2], const pg8::Unit& u, int wr, int wc, int fr, int fq) const {
;     ...
;                     for (int n = 0; n < 2; ++n) { yv[bj][n] = *(const f32x4*)(Yin + (size_t)row * D_ + col0 + bj * 128 + 4 * n); gq[bj][n] = *(const f32x4*)(g + col0 + bj * 128 + 4 * n); bq_[bj][n] = *(const f32x4*)(b + col0 + bj * 128 + 4 * n); }
;                 asm volatile("" ::: "memory");
;                 float s1 = 0.f, s2 = 0.f;
; #pragma unroll
;                 for (int bj = 0; bj < 2; ++bj) { float* yp = Y + (size_t)row * D_ + col0 + bj * 128; f32x4 v[2];
; #pragma unroll
;                     for (int n = 0; n < 2; ++n) { v[n] = (((yv[bj][n] - mu) * rs) * gq[bj][n] + bq_[bj][n]) * ALPHA_ + acc[ai][bj][m][n] * sc;
;                         *(f32x4*)(yp + 4 * n) = v[n]; s1 += (v[n][0] + v[n][1]) + (v[n][2] + v[n][3]); s2 += (v[n][0] * v[n][0] + v[n][1] * v[n][1]) + (v[n][2] * v[n][2] + v[n][3] * v[n][3]); }
;                     *(u32x4*)(Yb + blk_off(row, col0 + bj * 128, D_)) = pack8(v[0], v[1]); }
	v_mov_b32_e32 v83, v100
	v_mov_b32_e32 v84, v98
	v_mov_b32_e32 v85, v102
	v_mov_b32_e32 v100, v97
	v_pk_add_f32 v[96:97], v[158:159], v[160:161]
	v_pk_add_f32 v[78:79], v[78:79], v[80:81]
	v_pk_add_f32 v[80:81], v[82:83], v[84:85]
	v_pk_add_f32 v[84:85], v[96:97], v[96:97] op_sel:[0,1] op_sel_hi:[1,0]
	v_pk_add_f32 v[78:79], v[78:79], v[78:79] op_sel:[0,1] op_sel_hi:[1,0]
	v_mov_b32_e32 v0, v84
	v_mov_b32_e32 v69, v78
	s_nop 0
	v_permlane16_swap_b32_e32 v84, v0
	v_permlane16_swap_b32_e32 v78, v69
	v_add_f32_e32 v79, v84, v0
	v_add_f32_e32 v78, v78, v69
	v_mov_b32_e32 v85, v79
	v_mov_b32_e32 v84, v78
	s_nop 0
	v_permlane32_swap_b32_e32 v79, v85
	v_permlane32_swap_b32_e32 v78, v84
	v_pk_add_f32 v[78:79], v[78:79], v[84:85]
	v_mov_b32_e32 v102, v99
	v_pk_mul_f32 v[78:79], v[78:79], s[2:3] op_sel_hi:[1,0]
	s_mov_b32 s2, 0x800000
	v_fma_f32 v0, -v79, v79, v78
	v_max_f32_e32 v0, 0, v0
	v_add_f32_e32 v0, 0x3727c5ac, v0
	v_mul_f32_e32 v69, 0x4b800000, v0
	v_cmp_gt_f32_e32 vcc, s2, v0
	v_pk_add_f32 v[82:83], v[100:101], v[102:103]
	v_pk_add_f32 v[80:81], v[80:81], v[80:81] op_sel:[0,1] op_sel_hi:[1,0]
	v_cndmask_b32_e32 v0, v0, v69, vcc
	v_rsq_f32_e32 v0, v0
	v_pk_add_f32 v[82:83], v[82:83], v[82:83] op_sel:[0,1] op_sel_hi:[1,0]
	v_mov_b32_e32 v81, v80
	s_nop 1
	v_permlane16_swap_b32_e32 v80, v81
	v_mul_f32_e32 v69, 0x45800000, v0
	v_cndmask_b32_e32 v78, v0, v69, vcc
	v_mov_b32_e32 v0, v82
	s_nop 1
	v_permlane16_swap_b32_e32 v82, v0
	global_load_dwordx4 v[96:99], v[92:93], off offset:528
	global_load_dwordx4 v[100:103], v[92:93], off offset:512
	v_pk_add_f32 v[70:71], v[70:71], v[72:73]
	v_pk_add_f32 v[72:73], v[88:89], v[90:91]
	v_add_f32_e32 v89, v80, v81
	v_add_f32_e32 v88, v82, v0
	s_waitcnt vmcnt(9)
	v_mov_b32_e32 v80, v104
	s_waitcnt vmcnt(8)
	v_mov_b32_e32 v81, v108
	v_mov_b32_e32 v82, v106
	v_mov_b32_e32 v83, v110
	v_mov_b32_e32 v108, v105
	v_mov_b32_e32 v110, v107
	v_pk_add_f32 v[80:81], v[80:81], v[82:83]
	v_pk_add_f32 v[82:83], v[108:109], v[110:111]
	global_load_dwordx4 v[104:107], v[154:155], off offset:528
	global_load_dwordx4 v[108:111], v[154:155], off offset:512
	global_load_dwordx4 v[158:161], v[156:157], off offset:528
	global_load_dwordx4 v[162:165], v[156:157], off offset:512
	s_waitcnt vmcnt(10)
	v_sub_f32_e32 v93, v119, v79
	v_sub_f32_e32 v92, v118, v79
	v_sub_f32_e32 v117, v117, v79
	v_sub_f32_e32 v116, v116, v79
	v_pk_mul_f32 v[116:117], v[78:79], v[116:117] op_sel_hi:[0,1]
	v_pk_mul_f32 v[92:93], v[78:79], v[92:93] op_sel_hi:[0,1]
	s_waitcnt vmcnt(6)
	v_pk_fma_f32 v[92:93], v[126:127], v[92:93], v[134:135]
	v_pk_fma_f32 v[116:117], v[124:125], v[116:117], v[132:133]
	v_pk_mul_f32 v[92:93], v[92:93], s[16:17] op_sel_hi:[1,0]
	v_pk_mul_f32 v[116:117], v[116:117], s[16:17] op_sel_hi:[1,0]
	v_pk_fma_f32 v[64:65], v[64:65], 0.5, v[92:93] op_sel_hi:[1,0,1]
	v_pk_fma_f32 v[62:63], v[62:63], 0.5, v[116:117] op_sel_hi:[1,0,1]
	v_add_f32_e32 v93, v64, v65
	v_add_f32_e32 v92, v62, v63
	v_add_f32_e32 v92, v92, v93
	v_add_f32_e32 v116, 0, v92
	v_mul_f32_e32 v92, v63, v63
	v_mul_f32_e32 v93, v65, v65
	v_pk_add_f32 v[80:81], v[80:81], v[80:81] op_sel:[0,1] op_sel_hi:[1,0]
	v_fmac_f32_e32 v92, v62, v62
	v_fmac_f32_e32 v93, v64, v64
	v_mov_b32_e32 v0, v80
	v_add_f32_e32 v117, v92, v93
	v_sub_f32_e32 v93, v115, v79
	v_sub_f32_e32 v92, v114, v79
	v_sub_f32_e32 v113, v113, v79
	v_sub_f32_e32 v112, v112, v79
	v_pk_add_f32 v[82:83], v[82:83], v[82:83] op_sel:[0,1] op_sel_hi:[1,0]
	v_permlane16_swap_b32_e32 v80, v0
	v_pk_mul_f32 v[112:113], v[78:79], v[112:113] op_sel_hi:[0,1]
	v_pk_mul_f32 v[92:93], v[78:79], v[92:93] op_sel_hi:[0,1]
	v_add_f32_e32 v83, v80, v0
	v_mov_b32_e32 v0, v82
	v_pk_fma_f32 v[92:93], v[122:123], v[92:93], v[130:131]
	v_pk_fma_f32 v[112:113], v[120:121], v[112:113], v[128:129]
	v_permlane16_swap_b32_e32 v82, v0
	v_pk_mul_f32 v[112:113], v[112:113], s[16:17] op_sel_hi:[1,0]
	v_pk_mul_f32 v[92:93], v[92:93], s[16:17] op_sel_hi:[1,0]
	v_add_f32_e32 v82, v82, v0
	v_ashrrev_i32_e32 v80, 8, v68
	v_lshlrev_b32_e32 v0, 6, v68
	s_movk_i32 s2, 0x33c0
	v_pk_fma_f32 v[60:61], v[60:61], 0.5, v[92:93] op_sel_hi:[1,0,1]
	v_pk_fma_f32 v[58:59], v[58:59], 0.5, v[112:113] op_sel_hi:[1,0,1]
	v_ashrrev_i32_e32 v81, 31, v80
	v_and_or_b32 v0, v0, s2, v194
	s_waitcnt lgkmcnt(0)
	v_lshl_add_u64 v[68:69], s[74:75], 0, v[136:137]
	v_add_f32_e32 v92, v58, v59
	v_add_f32_e32 v93, v60, v61
	v_readlane_b32 s2, v253, 59
	v_lshlrev_b64 v[80:81], 19, v[80:81]
	v_lshl_add_u64 v[68:69], v[68:69], 0, v[152:153]
	v_add_f32_e32 v92, v92, v93
	v_mul_f32_e32 v93, v59, v59
	v_readlane_b32 s3, v253, 60
	s_nop 0
	s_nop 1
	v_bfe_u32 v85, v227, 4, 2
	v_sub_u32_e32 v84, 0, v85
	v_lshlrev_b32_e32 v84, 4, v84
	v_ashrrev_i32_e32 v85, 31, v84
	v_lshl_add_u64 v[84:85], v[68:69], 0, v[84:85]
	v_permlane16_swap_b32_e32 v62, v58
	v_permlane16_swap_b32_e32 v63, v59
	v_permlane16_swap_b32_e32 v64, v60
	v_permlane16_swap_b32_e32 v65, v61
	v_permlane32_swap_b32_e32 v62, v58
	v_permlane32_swap_b32_e32 v63, v59
	v_permlane32_swap_b32_e32 v64, v60
	v_permlane32_swap_b32_e32 v65, v61
	global_store_dwordx4 v[84:85], v[62:65], off
	global_store_dwordx4 v[84:85], v[58:61], off offset:64
	s_nop 1
	v_permlane32_swap_b32_e32 v62, v58
	v_permlane32_swap_b32_e32 v63, v59
	v_permlane32_swap_b32_e32 v64, v60
	v_permlane32_swap_b32_e32 v65, v61
	v_permlane16_swap_b32_e32 v62, v58
	v_permlane16_swap_b32_e32 v63, v59
	v_permlane16_swap_b32_e32 v64, v60
	v_permlane16_swap_b32_e32 v65, v61
	v_fmac_f32_e32 v93, v58, v58
	v_cvt_pk_bf16_f32 v62, v62, v63
	v_cvt_pk_bf16_f32 v63, v64, v65
	v_cvt_pk_bf16_f32 v64, v58, v59
	v_lshl_add_u64 v[58:59], s[2:3], 0, v[80:81]
	v_mul_f32_e32 v112, v61, v61
	v_lshl_add_u64 v[80:81], v[58:59], 0, s[28:29]
	v_lshlrev_b32_e32 v0, 1, v0
	v_fmac_f32_e32 v112, v60, v60
	v_cvt_pk_bf16_f32 v65, v60, v61
	v_lshl_add_u64 v[60:61], v[80:81], 0, v[0:1]
	global_store_dwordx4 v[60:61], v[62:65], off
	s_waitcnt vmcnt(7)
; __device__ __forceinline__ float xsum16(float v) { const auto r = __builtin_amdgcn_permlane16_swap(__float_as_uint(v), __float_as_uint(v), false, false); return __uint_as_float(r[0]) + __uint_as_float(r[1]); }
; __device__ __forceinline__ float xsum32(float v) { const auto r = __builtin_amdgcn_permlane32_swap(__float_as_uint(v), __float_as_uint(v), false, false); return __uint_as_float(r[0]) + __uint_as_float(r[1]); }
; __device__ __forceinline__ size_t blk_off(int r, int c, int K) { return (size_t)(r >> 8) * 256 * K + (size_t)(c >> 6) * (256 * 64) + (size_t)((r & 255) * 64 + (c & 63)); }
; __device__ __forceinline__ u32x4 pack8(const f32x4 a, const f32x4 b) { u32x4 w; w.x = cvt_pk_bf16(a[0], a[1]); w.y = cvt_pk_bf16(a[2], a[3]); w.z = cvt_pk_bf16(b[0], b[1]); w.w = cvt_pk_bf16(b[2], b[3]); return w; }
;     __device__ __forceinline__ void operator()(const f32x4 (&acc)[2][2][4][2], const pg8::Unit& u, int wr, int wc, int fr, int fq) const {
;     ...
;                     for (int n = 0; n < 2; ++n) { yv[bj][n] = *(const f32x4*)(Yin + (size_t)row * D_ + col0 + bj * 128 + 4 * n); gq[bj][n] = *(const f32x4*)(g + col0 + bj * 128 + 4 * n); bq_[bj][n] = *(const f32x4*)(b + col0 + bj * 128 + 4 * n); }
;                 asm volatile("" ::: "memory");
;                 float s1 = 0.f, s2 = 0.f;
; #pragma unroll
;                 for (int bj = 0; bj < 2; ++bj) { float* yp = Y + (size_t)row * D_ + col0 + bj * 128; f32x4 v[2];
; #pragma unroll
;                     for (int n = 0; n < 2; ++n) { v[n] = (((yv[bj][n] - mu) * rs) * gq[bj][n] + bq_[bj][n]) * ALPHA_ + acc[ai][bj][m][n] * sc;
;                         *(f32x4*)(yp + 4 * n) = v[n]; s1 += (v[n][0] + v[n][1]) + (v[n][2] + v[n][3]); s2 += (v[n][0] * v[n][0] + v[n][1] * v[n][1]) + (v[n][2] * v[n][2] + v[n][3] * v[n][3]); }
;                     *(u32x4*)(Yb + blk_off(row, col0 + bj * 128, D_)) = pack8(v[0], v[1]); }
;                 s1 = xsum32(xsum16(s1)); s2 = xsum32(xsum16(s2));
;                 if (fq == 0) *(f32x2*)(stn + (size_t)row * 32 + (u.pn * 4 + wc) * 2) = (f32x2){s1, s2}; asm volatile("" ::: "memory"); } }
	v_sub_f32_e32 v61, v103, v79
	v_sub_f32_e32 v60, v102, v79
	v_sub_f32_e32 v63, v101, v79
	v_sub_f32_e32 v62, v100, v79
	v_pk_mul_f32 v[62:63], v[78:79], v[62:63] op_sel_hi:[0,1]
	v_pk_mul_f32 v[60:61], v[78:79], v[60:61] op_sel_hi:[0,1]
	v_add_f32_e32 v92, v116, v92
	s_waitcnt vmcnt(3)
	v_pk_fma_f32 v[60:61], v[110:111], v[60:61], v[164:165]
	v_pk_fma_f32 v[62:63], v[108:109], v[62:63], v[162:163]
	v_pk_mul_f32 v[60:61], v[60:61], s[16:17] op_sel_hi:[1,0]
	v_pk_mul_f32 v[62:63], v[62:63], s[16:17] op_sel_hi:[1,0]
	v_pk_fma_f32 v[56:57], v[56:57], 0.5, v[60:61] op_sel_hi:[1,0,1]
	v_pk_fma_f32 v[54:55], v[54:55], 0.5, v[62:63] op_sel_hi:[1,0,1]
	v_add_f32_e32 v61, v56, v57
	v_add_f32_e32 v60, v54, v55
	v_add_f32_e32 v60, v60, v61
	v_add_f32_e32 v64, v92, v60
	v_mul_f32_e32 v60, v55, v55
	v_mul_f32_e32 v61, v57, v57
	v_add_f32_e32 v93, v93, v112
	v_fmac_f32_e32 v60, v54, v54
	v_fmac_f32_e32 v61, v56, v56
	v_add_f32_e32 v93, v117, v93
	v_add_f32_e32 v60, v60, v61
	v_add_f32_e32 v65, v93, v60
	v_sub_f32_e32 v61, v99, v79
	v_sub_f32_e32 v60, v98, v79
	v_sub_f32_e32 v63, v97, v79
	v_sub_f32_e32 v62, v96, v79
	v_pk_mul_f32 v[62:63], v[78:79], v[62:63] op_sel_hi:[0,1]
	v_pk_mul_f32 v[60:61], v[78:79], v[60:61] op_sel_hi:[0,1]
	v_pk_fma_f32 v[60:61], v[106:107], v[60:61], v[160:161]
	v_pk_fma_f32 v[62:63], v[104:105], v[62:63], v[158:159]
	v_pk_mul_f32 v[60:61], v[60:61], s[16:17] op_sel_hi:[1,0]
	v_pk_mul_f32 v[62:63], v[62:63], s[16:17] op_sel_hi:[1,0]
	v_pk_fma_f32 v[52:53], v[52:53], 0.5, v[60:61] op_sel_hi:[1,0,1]
	v_pk_fma_f32 v[50:51], v[50:51], 0.5, v[62:63] op_sel_hi:[1,0,1]
	v_add_f32_e32 v61, v52, v53
	v_add_f32_e32 v60, v50, v51
	v_add_f32_e32 v60, v60, v61
	v_mul_f32_e32 v61, v51, v51
	v_mul_f32_e32 v62, v53, v53
	v_add_f32_e32 v60, v64, v60
	v_fmac_f32_e32 v61, v50, v50
	v_fmac_f32_e32 v62, v52, v52
	v_lshl_add_u64 v[78:79], v[58:59], 0, s[40:41]
	s_nop 0
	s_nop 1
	v_bfe_u32 v85, v227, 4, 2
	v_sub_u32_e32 v84, 0, v85
	v_lshlrev_b32_e32 v84, 4, v84
	v_ashrrev_i32_e32 v85, 31, v84
	v_lshl_add_u64 v[84:85], v[68:69], 0, v[84:85]
	v_permlane16_swap_b32_e32 v54, v50
	v_permlane16_swap_b32_e32 v55, v51
	v_permlane16_swap_b32_e32 v56, v52
	v_permlane16_swap_b32_e32 v57, v53
	v_permlane32_swap_b32_e32 v54, v50
	v_permlane32_swap_b32_e32 v55, v51
	v_permlane32_swap_b32_e32 v56, v52
	v_permlane32_swap_b32_e32 v57, v53
	global_store_dwordx4 v[84:85], v[54:57], off offset:512
	global_store_dwordx4 v[84:85], v[50:53], off offset:576
	s_nop 1
	v_permlane32_swap_b32_e32 v54, v50
	v_permlane32_swap_b32_e32 v55, v51
	v_permlane32_swap_b32_e32 v56, v52
	v_permlane32_swap_b32_e32 v57, v53
	v_permlane16_swap_b32_e32 v54, v50
	v_permlane16_swap_b32_e32 v55, v51
	v_permlane16_swap_b32_e32 v56, v52
	v_permlane16_swap_b32_e32 v57, v53
	v_add_f32_e32 v61, v61, v62
	v_cvt_pk_bf16_f32 v54, v54, v55
	v_cvt_pk_bf16_f32 v55, v56, v57
	v_cvt_pk_bf16_f32 v56, v50, v51
	v_lshl_add_u64 v[50:51], v[78:79], 0, v[0:1]
	v_mov_b32_e32 v0, v60
	v_pk_add_f32 v[70:71], v[70:71], v[70:71] op_sel:[0,1] op_sel_hi:[1,0]
	v_pk_add_f32 v[72:73], v[72:73], v[72:73] op_sel:[0,1] op_sel_hi:[1,0]
	v_add_f32_e32 v61, v65, v61
	v_cvt_pk_bf16_f32 v57, v52, v53
	v_permlane16_swap_b32_e32 v60, v0
	v_mov_b32_e32 v71, v70
	v_mov_b32_e32 v73, v72
	global_store_dwordx4 v[50:51], v[54:57], off
	v_add_f32_e32 v50, v60, v0
	v_mov_b32_e32 v0, v61
	v_permlane16_swap_b32_e32 v70, v71
	v_permlane16_swap_b32_e32 v72, v73
	v_permlane16_swap_b32_e32 v61, v0
	v_add_f32_e32 v71, v70, v71
	v_add_f32_e32 v70, v72, v73
	v_add_f32_e32 v51, v61, v0
	v_mov_b32_e32 v73, v71
	v_mov_b32_e32 v72, v70
	v_mov_b32_e32 v91, v89
	v_mov_b32_e32 v90, v88
	v_mov_b32_e32 v85, v83
	v_mov_b32_e32 v84, v82
	v_mov_b32_e32 v52, v50
	v_mov_b32_e32 v53, v51
	v_permlane32_swap_b32_e32 v71, v73
	v_permlane32_swap_b32_e32 v70, v72
	v_permlane32_swap_b32_e32 v89, v91
	v_permlane32_swap_b32_e32 v88, v90
	v_permlane32_swap_b32_e32 v83, v85
	v_permlane32_swap_b32_e32 v82, v84
	v_permlane32_swap_b32_e32 v50, v52
	v_permlane32_swap_b32_e32 v51, v53
	s_and_saveexec_b64 s[26:27], s[44:45]
	s_cbranch_execz .LBB0_382
	v_pk_add_f32 v[50:51], v[50:51], v[52:53]
	v_lshl_add_u64 v[52:53], s[30:31], 0, v[66:67]
	v_lshl_add_u64 v[52:53], s[24:25], 2, v[52:53]
	global_store_dwordx2 v[52:53], v[50:51], off
; __device__ __forceinline__ size_t blk_off(int r, int c, int K) { return (size_t)(r >> 8) * 256 * K + (size_t)(c >> 6) * (256 * 64) + (size_t)((r & 255) * 64 + (c & 63)); }
; __device__ __forceinline__ u32x4 pack8(const f32x4 a, const f32x4 b) { u32x4 w; w.x = cvt_pk_bf16(a[0], a[1]); w.y = cvt_pk_bf16(a[2], a[3]); w.z = cvt_pk_bf16(b[0], b[1]); w.w = cvt_pk_bf16(b[2], b[3]); return w; }
;     __device__ __forceinline__ void operator()(const f32x4 (&acc)[2][2][4][2], const pg8::Unit& u, int wr, int wc, int fr, int fq) const {
;     ...
;             for (int m = 0; m < 4; ++m) { const int row = row0 + ai * 128 + m * 16; const float mu = mu4[m], rs = rs4[m];
;                 f32x4 yv[2][2], gq[2][2], bq_[2][2];
; #pragma unroll
;                 for (int bj = 0; bj < 2; ++bj)
; #pragma unroll
;                     for (int n = 0; n < 2; ++n) { yv[bj][n] = *(const f32x4*)(Yin + (size_t)row * D_ + col0 + bj * 128 + 4 * n); gq[bj][n] = *(const f32x4*)(g + col0 + bj * 128 + 4 * n); bq_[bj][n] = *(const f32x4*)(b + col0 + bj * 128 + 4 * n); }
;                 asm volatile("" ::: "memory");
;                 float s1 = 0.f, s2 = 0.f;
; #pragma unroll
;                 for (int bj = 0; bj < 2; ++bj) { float* yp = Y + (size_t)row * D_ + col0 + bj * 128; f32x4 v[2];
; #pragma unroll
;                     for (int n = 0; n < 2; ++n) { v[n] = (((yv[bj][n] - mu) * rs) * gq[bj][n] + bq_[bj][n]) * ALPHA_ + acc[ai][bj][m][n] * sc;
;                         *(f32x4*)(yp + 4 * n) = v[n]; s1 += (v[n][0] + v[n][1]) + (v[n][2] + v[n][3]); s2 += (v[n][0] * v[n][0] + v[n][1] * v[n][1]) + (v[n][2] * v[n][2] + v[n][3] * v[n][3]); }
;                     *(u32x4*)(Yb + blk_off(row, col0 + bj * 128, D_)) = pack8(v[0], v[1]); }
.LBB0_382:
	s_or_b64 exec, exec, s[26:27]
	v_pk_add_f32 v[50:51], v[70:71], v[72:73]
	s_mov_b32 s2, 0x3a800000
	v_pk_mul_f32 v[92:93], v[50:51], s[2:3] op_sel_hi:[1,0]
	s_mov_b32 s2, 0x800000
	v_fma_f32 v0, -v93, v93, v92
	v_max_f32_e32 v0, 0, v0
	v_add_f32_e32 v0, 0x3727c5ac, v0
	v_cmp_gt_f32_e32 vcc, s2, v0
	v_mul_f32_e32 v50, 0x4b800000, v0
	v_lshlrev_b64 v[120:121], 12, v[94:95]
	v_cndmask_b32_e32 v0, v0, v50, vcc
	v_rsq_f32_e32 v0, v0
	s_movk_i32 s2, 0x37c0
	s_load_dwordx16 s[60:75], s[34:35], 0x38
	v_mul_f32_e32 v50, 0x45800000, v0
	v_cndmask_b32_e32 v92, v0, v50, vcc
	v_lshl_add_u64 v[50:51], s[12:13], 0, v[120:121]
	v_lshl_add_u64 v[54:55], v[50:51], 0, v[152:153]
	global_load_dwordx4 v[96:99], v[54:55], off offset:16
	global_load_dwordx4 v[100:103], v[54:55], off
	global_load_dwordx4 v[104:107], v[154:155], off offset:16
	global_load_dwordx4 v[108:111], v[154:155], off
	global_load_dwordx4 v[112:115], v[156:157], off offset:16
	global_load_dwordx4 v[116:119], v[156:157], off
	global_load_dwordx4 v[50:53], v[54:55], off offset:528
	global_load_dwordx4 v[70:73], v[54:55], off offset:512
	s_nop 0
	global_load_dwordx4 v[54:57], v[154:155], off offset:528
	global_load_dwordx4 v[62:65], v[154:155], off offset:512
	global_load_dwordx4 v[58:61], v[156:157], off offset:528
	global_load_dwordx4 v[66:69], v[156:157], off offset:512
	v_lshlrev_b32_e32 v0, 6, v94
	v_and_or_b32 v0, v0, s2, v194
	s_mov_b32 s2, 0x3fd744fd
	s_waitcnt lgkmcnt(0)
	v_lshl_add_u64 v[94:95], s[74:75], 0, v[120:121]
	v_lshlrev_b32_e32 v0, 1, v0
	v_lshl_add_u64 v[94:95], v[94:95], 0, v[152:153]
	s_waitcnt vmcnt(10)
	v_sub_f32_e32 v103, v103, v93
	v_sub_f32_e32 v102, v102, v93
	v_sub_f32_e32 v101, v101, v93
	v_sub_f32_e32 v100, v100, v93
	v_pk_mul_f32 v[100:101], v[92:93], v[100:101] op_sel_hi:[0,1]
	v_pk_mul_f32 v[102:103], v[92:93], v[102:103] op_sel_hi:[0,1]
	s_waitcnt vmcnt(6)
	v_pk_fma_f32 v[102:103], v[110:111], v[102:103], v[118:119]
	v_pk_fma_f32 v[100:101], v[108:109], v[100:101], v[116:117]
	v_pk_mul_f32 v[102:103], v[102:103], s[2:3] op_sel_hi:[1,0]
	v_pk_mul_f32 v[100:101], v[100:101], s[2:3] op_sel_hi:[1,0]
	v_pk_fma_f32 v[102:103], v[48:49], 0.5, v[102:103] op_sel_hi:[1,0,1]
	v_pk_fma_f32 v[100:101], v[46:47], 0.5, v[100:101] op_sel_hi:[1,0,1]
	v_add_f32_e32 v47, v102, v103
	v_add_f32_e32 v46, v100, v101
	v_add_f32_e32 v46, v46, v47
	v_add_f32_e32 v108, 0, v46
	v_mul_f32_e32 v46, v101, v101
	v_mul_f32_e32 v47, v103, v103
	v_fmac_f32_e32 v46, v100, v100
	v_fmac_f32_e32 v47, v102, v102
	v_add_f32_e32 v109, v46, v47
	v_sub_f32_e32 v47, v99, v93
	v_sub_f32_e32 v46, v98, v93
	v_sub_f32_e32 v49, v97, v93
	v_sub_f32_e32 v48, v96, v93
	v_pk_mul_f32 v[48:49], v[92:93], v[48:49] op_sel_hi:[0,1]
	v_pk_mul_f32 v[46:47], v[92:93], v[46:47] op_sel_hi:[0,1]
	v_pk_fma_f32 v[46:47], v[106:107], v[46:47], v[114:115]
	v_pk_fma_f32 v[48:49], v[104:105], v[48:49], v[112:113]
	v_pk_mul_f32 v[46:47], v[46:47], s[2:3] op_sel_hi:[1,0]
	v_pk_mul_f32 v[48:49], v[48:49], s[2:3] op_sel_hi:[1,0]
	v_pk_fma_f32 v[98:99], v[44:45], 0.5, v[46:47] op_sel_hi:[1,0,1]
	v_pk_fma_f32 v[96:97], v[42:43], 0.5, v[48:49] op_sel_hi:[1,0,1]
	v_add_f32_e32 v43, v98, v99
	v_add_f32_e32 v42, v96, v97
	v_add_f32_e32 v42, v42, v43
	v_add_f32_e32 v47, v108, v42
	v_mul_f32_e32 v42, v97, v97
	v_mul_f32_e32 v43, v99, v99
	v_fmac_f32_e32 v42, v96, v96
	v_fmac_f32_e32 v43, v98, v98
	v_add_f32_e32 v42, v42, v43
	v_add_f32_e32 v46, v109, v42
	v_cvt_pk_bf16_f32 v42, v100, v101
	v_cvt_pk_bf16_f32 v43, v102, v103
	v_cvt_pk_bf16_f32 v44, v96, v97
	v_cvt_pk_bf16_f32 v45, v98, v99
	v_lshl_add_u64 v[48:49], v[80:81], 0, v[0:1]
	s_nop 0
	s_nop 1
	v_bfe_u32 v105, v227, 4, 2
	v_sub_u32_e32 v104, 0, v105
	v_lshlrev_b32_e32 v104, 4, v104
	v_ashrrev_i32_e32 v105, 31, v104
	v_lshl_add_u64 v[104:105], v[94:95], 0, v[104:105]
	v_permlane16_swap_b32_e32 v100, v96
	v_permlane16_swap_b32_e32 v101, v97
	v_permlane16_swap_b32_e32 v102, v98
	v_permlane16_swap_b32_e32 v103, v99
	v_permlane32_swap_b32_e32 v100, v96
	v_permlane32_swap_b32_e32 v101, v97
	v_permlane32_swap_b32_e32 v102, v98
	v_permlane32_swap_b32_e32 v103, v99
	global_store_dwordx4 v[104:105], v[100:103], off
	global_store_dwordx4 v[104:105], v[96:99], off offset:64
	s_nop 1
	v_permlane32_swap_b32_e32 v100, v96
	v_permlane32_swap_b32_e32 v101, v97
	v_permlane32_swap_b32_e32 v102, v98
	v_permlane32_swap_b32_e32 v103, v99
	v_permlane16_swap_b32_e32 v100, v96
	v_permlane16_swap_b32_e32 v101, v97
	v_permlane16_swap_b32_e32 v102, v98
	v_permlane16_swap_b32_e32 v103, v99
	global_store_dwordx4 v[48:49], v[42:45], off
	s_waitcnt vmcnt(7)
	s_nop 0
	v_sub_f32_e32 v43, v73, v93
	v_sub_f32_e32 v42, v72, v93
	v_sub_f32_e32 v45, v71, v93
	v_sub_f32_e32 v44, v70, v93
	v_pk_mul_f32 v[44:45], v[92:93], v[44:45] op_sel_hi:[0,1]
	v_pk_mul_f32 v[42:43], v[92:93], v[42:43] op_sel_hi:[0,1]
	s_waitcnt vmcnt(3)
; __device__ __forceinline__ float xsum16(float v) { const auto r = __builtin_amdgcn_permlane16_swap(__float_as_uint(v), __float_as_uint(v), false, false); return __uint_as_float(r[0]) + __uint_as_float(r[1]); }
; __device__ __forceinline__ float xsum32(float v) { const auto r = __builtin_amdgcn_permlane32_swap(__float_as_uint(v), __float_as_uint(v), false, false); return __uint_as_float(r[0]) + __uint_as_float(r[1]); }
; __device__ __forceinline__ size_t blk_off(int r, int c, int K) { return (size_t)(r >> 8) * 256 * K + (size_t)(c >> 6) * (256 * 64) + (size_t)((r & 255) * 64 + (c & 63)); }
; __device__ __forceinline__ u32x4 pack8(const f32x4 a, const f32x4 b) { u32x4 w; w.x = cvt_pk_bf16(a[0], a[1]); w.y = cvt_pk_bf16(a[2], a[3]); w.z = cvt_pk_bf16(b[0], b[1]); w.w = cvt_pk_bf16(b[2], b[3]); return w; }
;     __device__ __forceinline__ void operator()(const f32x4 (&acc)[2][2][4][2], const pg8::Unit& u, int wr, int wc, int fr, int fq) const {
;     ...
;             for (int m = 0; m < 4; ++m) { const int row = row0 + ai * 128 + m * 16; const float mu = mu4[m], rs = rs4[m];
;                 f32x4 yv[2][2], gq[2][2], bq_[2][2];
; #pragma unroll
;                 for (int bj = 0; bj < 2; ++bj)
; #pragma unroll
;                     for (int n = 0; n < 2; ++n) { yv[bj][n] = *(const f32x4*)(Yin + (size_t)row * D_ + col0 + bj * 128 + 4 * n); gq[bj][n] = *(const f32x4*)(g + col0 + bj * 128 + 4 * n); bq_[bj][n] = *(const f32x4*)(b + col0 + bj * 128 + 4 * n); }
;                 asm volatile("" ::: "memory");
;                 float s1 = 0.f, s2 = 0.f;
; #pragma unroll
;                 for (int bj = 0; bj < 2; ++bj) { float* yp = Y + (size_t)row * D_ + col0 + bj * 128; f32x4 v[2];
; #pragma unroll
;                     for (int n = 0; n < 2; ++n) { v[n] = (((yv[bj][n] - mu) * rs) * gq[bj][n] + bq_[bj][n]) * ALPHA_ + acc[ai][bj][m][n] * sc;
;                         *(f32x4*)(yp + 4 * n) = v[n]; s1 += (v[n][0] + v[n][1]) + (v[n][2] + v[n][3]); s2 += (v[n][0] * v[n][0] + v[n][1] * v[n][1]) + (v[n][2] * v[n][2] + v[n][3] * v[n][3]); }
;                     *(u32x4*)(Yb + blk_off(row, col0 + bj * 128, D_)) = pack8(v[0], v[1]); }
;                 s1 = xsum32(xsum16(s1)); s2 = xsum32(xsum16(s2));
;                 if (fq == 0) *(f32x2*)(stn + (size_t)row * 32 + (u.pn * 4 + wc) * 2) = (f32x2){s1, s2}; asm volatile("" ::: "memory"); } }
	v_pk_fma_f32 v[42:43], v[64:65], v[42:43], v[68:69]
	v_pk_fma_f32 v[44:45], v[62:63], v[44:45], v[66:67]
	v_pk_mul_f32 v[42:43], v[42:43], s[2:3] op_sel_hi:[1,0]
	v_pk_mul_f32 v[44:45], v[44:45], s[2:3] op_sel_hi:[1,0]
	v_pk_fma_f32 v[40:41], v[40:41], 0.5, v[42:43] op_sel_hi:[1,0,1]
	v_pk_fma_f32 v[38:39], v[38:39], 0.5, v[44:45] op_sel_hi:[1,0,1]
	v_add_f32_e32 v43, v40, v41
	v_add_f32_e32 v42, v38, v39
	v_add_f32_e32 v42, v42, v43
	v_add_f32_e32 v47, v47, v42
	v_mul_f32_e32 v42, v39, v39
	v_mul_f32_e32 v43, v41, v41
	v_fmac_f32_e32 v42, v38, v38
	v_fmac_f32_e32 v43, v40, v40
	v_add_f32_e32 v42, v42, v43
	v_add_f32_e32 v46, v46, v42
	v_sub_f32_e32 v43, v53, v93
	v_sub_f32_e32 v42, v52, v93
	v_sub_f32_e32 v45, v51, v93
	v_sub_f32_e32 v44, v50, v93
	v_pk_mul_f32 v[44:45], v[92:93], v[44:45] op_sel_hi:[0,1]
	v_pk_mul_f32 v[42:43], v[92:93], v[42:43] op_sel_hi:[0,1]
	v_pk_fma_f32 v[42:43], v[56:57], v[42:43], v[60:61]
	v_pk_fma_f32 v[44:45], v[54:55], v[44:45], v[58:59]
	v_pk_mul_f32 v[42:43], v[42:43], s[2:3] op_sel_hi:[1,0]
	v_pk_mul_f32 v[44:45], v[44:45], s[2:3] op_sel_hi:[1,0]
	v_pk_fma_f32 v[36:37], v[36:37], 0.5, v[42:43] op_sel_hi:[1,0,1]
	v_pk_fma_f32 v[34:35], v[34:35], 0.5, v[44:45] op_sel_hi:[1,0,1]
	v_add_f32_e32 v43, v36, v37
	v_add_f32_e32 v42, v34, v35
	v_add_f32_e32 v42, v42, v43
	v_mul_f32_e32 v43, v35, v35
	v_mul_f32_e32 v44, v37, v37
	v_add_f32_e32 v42, v47, v42
	v_fmac_f32_e32 v43, v34, v34
	v_fmac_f32_e32 v44, v36, v36
	s_nop 0
	s_nop 1
	v_bfe_u32 v49, v227, 4, 2
	v_sub_u32_e32 v48, 0, v49
	v_lshlrev_b32_e32 v48, 4, v48
	v_ashrrev_i32_e32 v49, 31, v48
	v_lshl_add_u64 v[48:49], v[94:95], 0, v[48:49]
	v_permlane16_swap_b32_e32 v38, v34
	v_permlane16_swap_b32_e32 v39, v35
	v_permlane16_swap_b32_e32 v40, v36
	v_permlane16_swap_b32_e32 v41, v37
	v_permlane32_swap_b32_e32 v38, v34
	v_permlane32_swap_b32_e32 v39, v35
	v_permlane32_swap_b32_e32 v40, v36
	v_permlane32_swap_b32_e32 v41, v37
	global_store_dwordx4 v[48:49], v[38:41], off offset:512
	global_store_dwordx4 v[48:49], v[34:37], off offset:576
	s_nop 1
	v_permlane32_swap_b32_e32 v38, v34
	v_permlane32_swap_b32_e32 v39, v35
	v_permlane32_swap_b32_e32 v40, v36
	v_permlane32_swap_b32_e32 v41, v37
	v_permlane16_swap_b32_e32 v38, v34
	v_permlane16_swap_b32_e32 v39, v35
	v_permlane16_swap_b32_e32 v40, v36
	v_permlane16_swap_b32_e32 v41, v37
	v_add_f32_e32 v43, v43, v44
	v_cvt_pk_bf16_f32 v38, v38, v39
	v_cvt_pk_bf16_f32 v39, v40, v41
	v_cvt_pk_bf16_f32 v40, v34, v35
	v_lshl_add_u64 v[34:35], v[78:79], 0, v[0:1]
	v_mov_b32_e32 v0, v42
	v_add_f32_e32 v43, v46, v43
	v_cvt_pk_bf16_f32 v41, v36, v37
	v_permlane16_swap_b32_e32 v42, v0
	global_store_dwordx4 v[34:35], v[38:41], off
	v_add_f32_e32 v34, v42, v0
	v_mov_b32_e32 v0, v43
	s_nop 1
	v_permlane16_swap_b32_e32 v43, v0
	v_add_f32_e32 v35, v43, v0
	v_mov_b32_e32 v36, v34
	v_mov_b32_e32 v37, v35
	s_nop 0
	v_permlane32_swap_b32_e32 v34, v36
	v_permlane32_swap_b32_e32 v35, v37
	s_and_saveexec_b64 s[26:27], s[44:45]
	s_cbranch_execz .LBB0_384
	v_pk_add_f32 v[34:35], v[34:35], v[36:37]
	v_lshl_add_u64 v[36:37], s[30:31], 0, v[86:87]
	v_lshl_add_u64 v[36:37], s[24:25], 2, v[36:37]
	global_store_dwordx2 v[36:37], v[34:35], off
.LBB0_384:
	s_or_b64 exec, exec, s[26:27]
	v_pk_add_f32 v[34:35], v[88:89], v[90:91]
	s_mov_b32 s2, 0x3a800000
	v_pk_mul_f32 v[58:59], v[34:35], s[2:3] op_sel_hi:[1,0]
	s_mov_b32 s2, 0x800000
	v_fma_f32 v0, -v59, v59, v58
	v_max_f32_e32 v0, 0, v0
	v_add_f32_e32 v0, 0x3727c5ac, v0
	v_cmp_gt_f32_e32 vcc, s2, v0
	v_mul_f32_e32 v34, 0x4b800000, v0
	v_lshlrev_b64 v[60:61], 12, v[76:77]
	v_cndmask_b32_e32 v0, v0, v34, vcc
	v_rsq_f32_e32 v0, v0
	s_movk_i32 s2, 0x3bc0
	s_load_dwordx16 s[60:75], s[34:35], 0x38
	v_mul_f32_e32 v34, 0x45800000, v0
	v_cndmask_b32_e32 v58, v0, v34, vcc
	v_lshl_add_u64 v[34:35], s[12:13], 0, v[60:61]
	v_lshl_add_u64 v[38:39], v[34:35], 0, v[152:153]
	global_load_dwordx4 v[62:65], v[38:39], off offset:16
	global_load_dwordx4 v[66:69], v[38:39], off
	global_load_dwordx4 v[70:73], v[154:155], off offset:16
	global_load_dwordx4 v[86:89], v[154:155], off
	global_load_dwordx4 v[90:93], v[156:157], off offset:16
	global_load_dwordx4 v[94:97], v[156:157], off
	global_load_dwordx4 v[34:37], v[38:39], off offset:528
	global_load_dwordx4 v[54:57], v[38:39], off offset:512
	s_nop 0
	global_load_dwordx4 v[38:41], v[154:155], off offset:528
	global_load_dwordx4 v[46:49], v[154:155], off offset:512
	global_load_dwordx4 v[42:45], v[156:157], off offset:528
	global_load_dwordx4 v[50:53], v[156:157], off offset:512
	v_lshlrev_b32_e32 v0, 6, v76
	v_and_or_b32 v0, v0, s2, v194
	s_mov_b32 s2, 0x3fd744fd
	s_waitcnt lgkmcnt(0)
	v_lshl_add_u64 v[60:61], s[74:75], 0, v[60:61]
	v_lshlrev_b32_e32 v0, 1, v0
	v_lshl_add_u64 v[60:61], v[60:61], 0, v[152:153]
	s_waitcnt vmcnt(10)
	v_sub_f32_e32 v69, v69, v59
	v_sub_f32_e32 v68, v68, v59
	v_sub_f32_e32 v67, v67, v59
	v_sub_f32_e32 v66, v66, v59
	v_pk_mul_f32 v[66:67], v[58:59], v[66:67] op_sel_hi:[0,1]
	v_pk_mul_f32 v[68:69], v[58:59], v[68:69] op_sel_hi:[0,1]
	s_waitcnt vmcnt(6)
; __device__ __forceinline__ float xsum16(float v) { const auto r = __builtin_amdgcn_permlane16_swap(__float_as_uint(v), __float_as_uint(v), false, false); return __uint_as_float(r[0]) + __uint_as_float(r[1]); }
; __device__ __forceinline__ float xsum32(float v) { const auto r = __builtin_amdgcn_permlane32_swap(__float_as_uint(v), __float_as_uint(v), false, false); return __uint_as_float(r[0]) + __uint_as_float(r[1]); }
; __device__ __forceinline__ size_t blk_off(int r, int c, int K) { return (size_t)(r >> 8) * 256 * K + (size_t)(c >> 6) * (256 * 64) + (size_t)((r & 255) * 64 + (c & 63)); }
; __device__ __forceinline__ u32x4 pack8(const f32x4 a, const f32x4 b) { u32x4 w; w.x = cvt_pk_bf16(a[0], a[1]); w.y = cvt_pk_bf16(a[2], a[3]); w.z = cvt_pk_bf16(b[0], b[1]); w.w = cvt_pk_bf16(b[2], b[3]); return w; }
;     __device__ __forceinline__ void operator()(const f32x4 (&acc)[2][2][4][2], const pg8::Unit& u, int wr, int wc, int fr, int fq) const {
;     ...
;             for (int m = 0; m < 4; ++m) { const int row = row0 + ai * 128 + m * 16; const float mu = mu4[m], rs = rs4[m];
;                 f32x4 yv[2][2], gq[2][2], bq_[2][2];
; #pragma unroll
;                 for (int bj = 0; bj < 2; ++bj)
; #pragma unroll
;                     for (int n = 0; n < 2; ++n) { yv[bj][n] = *(const f32x4*)(Yin + (size_t)row * D_ + col0 + bj * 128 + 4 * n); gq[bj][n] = *(const f32x4*)(g + col0 + bj * 128 + 4 * n); bq_[bj][n] = *(const f32x4*)(b + col0 + bj * 128 + 4 * n); }
;                 asm volatile("" ::: "memory");
;                 float s1 = 0.f, s2 = 0.f;
; #pragma unroll
;                 for (int bj = 0; bj < 2; ++bj) { float* yp = Y + (size_t)row * D_ + col0 + bj * 128; f32x4 v[2];
; #pragma unroll
;                     for (int n = 0; n < 2; ++n) { v[n] = (((yv[bj][n] - mu) * rs) * gq[bj][n] + bq_[bj][n]) * ALPHA_ + acc[ai][bj][m][n] * sc;
;                         *(f32x4*)(yp + 4 * n) = v[n]; s1 += (v[n][0] + v[n][1]) + (v[n][2] + v[n][3]); s2 += (v[n][0] * v[n][0] + v[n][1] * v[n][1]) + (v[n][2] * v[n][2] + v[n][3] * v[n][3]); }
;                     *(u32x4*)(Yb + blk_off(row, col0 + bj * 128, D_)) = pack8(v[0], v[1]); }
;                 s1 = xsum32(xsum16(s1)); s2 = xsum32(xsum16(s2));
;                 if (fq == 0) *(f32x2*)(stn + (size_t)row * 32 + (u.pn * 4 + wc) * 2) = (f32x2){s1, s2}; asm volatile("" ::: "memory"); } }
	v_pk_fma_f32 v[68:69], v[88:89], v[68:69], v[96:97]
	v_pk_fma_f32 v[66:67], v[86:87], v[66:67], v[94:95]
	v_pk_mul_f32 v[68:69], v[68:69], s[2:3] op_sel_hi:[1,0]
	v_pk_mul_f32 v[66:67], v[66:67], s[2:3] op_sel_hi:[1,0]
	v_pk_fma_f32 v[68:69], v[32:33], 0.5, v[68:69] op_sel_hi:[1,0,1]
	v_pk_fma_f32 v[66:67], v[30:31], 0.5, v[66:67] op_sel_hi:[1,0,1]
	v_add_f32_e32 v31, v68, v69
	v_add_f32_e32 v30, v66, v67
	v_add_f32_e32 v30, v30, v31
	v_add_f32_e32 v86, 0, v30
	v_mul_f32_e32 v30, v67, v67
	v_mul_f32_e32 v31, v69, v69
	v_fmac_f32_e32 v30, v66, v66
	v_fmac_f32_e32 v31, v68, v68
	v_add_f32_e32 v87, v30, v31
	v_sub_f32_e32 v31, v65, v59
	v_sub_f32_e32 v30, v64, v59
	v_sub_f32_e32 v33, v63, v59
	v_sub_f32_e32 v32, v62, v59
	v_pk_mul_f32 v[32:33], v[58:59], v[32:33] op_sel_hi:[0,1]
	v_pk_mul_f32 v[30:31], v[58:59], v[30:31] op_sel_hi:[0,1]
	v_pk_fma_f32 v[30:31], v[72:73], v[30:31], v[92:93]
	v_pk_fma_f32 v[32:33], v[70:71], v[32:33], v[90:91]
	v_pk_mul_f32 v[30:31], v[30:31], s[2:3] op_sel_hi:[1,0]
	v_pk_mul_f32 v[32:33], v[32:33], s[2:3] op_sel_hi:[1,0]
	v_pk_fma_f32 v[64:65], v[28:29], 0.5, v[30:31] op_sel_hi:[1,0,1]
	v_pk_fma_f32 v[62:63], v[26:27], 0.5, v[32:33] op_sel_hi:[1,0,1]
	v_add_f32_e32 v27, v64, v65
	v_add_f32_e32 v26, v62, v63
	v_add_f32_e32 v26, v26, v27
	v_add_f32_e32 v31, v86, v26
	v_mul_f32_e32 v26, v63, v63
	v_mul_f32_e32 v27, v65, v65
	v_fmac_f32_e32 v26, v62, v62
	v_fmac_f32_e32 v27, v64, v64
	v_add_f32_e32 v26, v26, v27
	v_add_f32_e32 v30, v87, v26
	v_cvt_pk_bf16_f32 v26, v66, v67
	v_cvt_pk_bf16_f32 v27, v68, v69
	v_cvt_pk_bf16_f32 v28, v62, v63
	v_cvt_pk_bf16_f32 v29, v64, v65
	v_lshl_add_u64 v[32:33], v[80:81], 0, v[0:1]
	s_nop 0
	s_nop 1
	v_bfe_u32 v71, v227, 4, 2
	v_sub_u32_e32 v70, 0, v71
	v_lshlrev_b32_e32 v70, 4, v70
	v_ashrrev_i32_e32 v71, 31, v70
	v_lshl_add_u64 v[70:71], v[60:61], 0, v[70:71]
	v_permlane16_swap_b32_e32 v66, v62
	v_permlane16_swap_b32_e32 v67, v63
	v_permlane16_swap_b32_e32 v68, v64
	v_permlane16_swap_b32_e32 v69, v65
	v_permlane32_swap_b32_e32 v66, v62
	v_permlane32_swap_b32_e32 v67, v63
	v_permlane32_swap_b32_e32 v68, v64
	v_permlane32_swap_b32_e32 v69, v65
	global_store_dwordx4 v[70:71], v[66:69], off
	global_store_dwordx4 v[70:71], v[62:65], off offset:64
	s_nop 1
	v_permlane32_swap_b32_e32 v66, v62
	v_permlane32_swap_b32_e32 v67, v63
	v_permlane32_swap_b32_e32 v68, v64
	v_permlane32_swap_b32_e32 v69, v65
	v_permlane16_swap_b32_e32 v66, v62
	v_permlane16_swap_b32_e32 v67, v63
	v_permlane16_swap_b32_e32 v68, v64
	v_permlane16_swap_b32_e32 v69, v65
	global_store_dwordx4 v[32:33], v[26:29], off
	s_waitcnt vmcnt(7)
	s_nop 0
	v_sub_f32_e32 v27, v57, v59
	v_sub_f32_e32 v26, v56, v59
	v_sub_f32_e32 v29, v55, v59
	v_sub_f32_e32 v28, v54, v59
	v_pk_mul_f32 v[28:29], v[58:59], v[28:29] op_sel_hi:[0,1]
	v_pk_mul_f32 v[26:27], v[58:59], v[26:27] op_sel_hi:[0,1]
	s_waitcnt vmcnt(3)
	v_pk_fma_f32 v[26:27], v[48:49], v[26:27], v[52:53]
	v_pk_fma_f32 v[28:29], v[46:47], v[28:29], v[50:51]
	v_pk_mul_f32 v[26:27], v[26:27], s[2:3] op_sel_hi:[1,0]
	v_pk_mul_f32 v[28:29], v[28:29], s[2:3] op_sel_hi:[1,0]
	v_pk_fma_f32 v[24:25], v[24:25], 0.5, v[26:27] op_sel_hi:[1,0,1]
	v_pk_fma_f32 v[22:23], v[22:23], 0.5, v[28:29] op_sel_hi:[1,0,1]
	v_add_f32_e32 v27, v24, v25
	v_add_f32_e32 v26, v22, v23
	v_add_f32_e32 v26, v26, v27
	v_add_f32_e32 v31, v31, v26
	v_mul_f32_e32 v26, v23, v23
	v_mul_f32_e32 v27, v25, v25
	v_fmac_f32_e32 v26, v22, v22
	v_fmac_f32_e32 v27, v24, v24
	v_add_f32_e32 v26, v26, v27
	v_add_f32_e32 v30, v30, v26
	v_sub_f32_e32 v27, v37, v59
	v_sub_f32_e32 v26, v36, v59
	v_sub_f32_e32 v29, v35, v59
	v_sub_f32_e32 v28, v34, v59
	v_pk_mul_f32 v[28:29], v[58:59], v[28:29] op_sel_hi:[0,1]
	v_pk_mul_f32 v[26:27], v[58:59], v[26:27] op_sel_hi:[0,1]
	v_pk_fma_f32 v[26:27], v[40:41], v[26:27], v[44:45]
	v_pk_fma_f32 v[28:29], v[38:39], v[28:29], v[42:43]
	v_pk_mul_f32 v[26:27], v[26:27], s[2:3] op_sel_hi:[1,0]
	v_pk_mul_f32 v[28:29], v[28:29], s[2:3] op_sel_hi:[1,0]
	v_pk_fma_f32 v[20:21], v[20:21], 0.5, v[26:27] op_sel_hi:[1,0,1]
	v_pk_fma_f32 v[18:19], v[18:19], 0.5, v[28:29] op_sel_hi:[1,0,1]
	v_add_f32_e32 v27, v20, v21
	v_add_f32_e32 v26, v18, v19
	v_add_f32_e32 v26, v26, v27
	v_mul_f32_e32 v27, v19, v19
	v_mul_f32_e32 v28, v21, v21
	v_add_f32_e32 v26, v31, v26
	v_fmac_f32_e32 v27, v18, v18
	v_fmac_f32_e32 v28, v20, v20
	s_nop 0
	s_nop 1
	v_bfe_u32 v33, v227, 4, 2
	v_sub_u32_e32 v32, 0, v33
	v_lshlrev_b32_e32 v32, 4, v32
	v_ashrrev_i32_e32 v33, 31, v32
	v_lshl_add_u64 v[32:33], v[60:61], 0, v[32:33]
	v_permlane16_swap_b32_e32 v22, v18
	v_permlane16_swap_b32_e32 v23, v19
	v_permlane16_swap_b32_e32 v24, v20
	v_permlane16_swap_b32_e32 v25, v21
	v_permlane32_swap_b32_e32 v22, v18
	v_permlane32_swap_b32_e32 v23, v19
	v_permlane32_swap_b32_e32 v24, v20
	v_permlane32_swap_b32_e32 v25, v21
	global_store_dwordx4 v[32:33], v[22:25], off offset:512
	global_store_dwordx4 v[32:33], v[18:21], off offset:576
	s_nop 1
	v_permlane32_swap_b32_e32 v22, v18
	v_permlane32_swap_b32_e32 v23, v19
	v_permlane32_swap_b32_e32 v24, v20
	v_permlane32_swap_b32_e32 v25, v21
	v_permlane16_swap_b32_e32 v22, v18
	v_permlane16_swap_b32_e32 v23, v19
	v_permlane16_swap_b32_e32 v24, v20
	v_permlane16_swap_b32_e32 v25, v21
	v_add_f32_e32 v27, v27, v28
	v_cvt_pk_bf16_f32 v22, v22, v23
	v_cvt_pk_bf16_f32 v23, v24, v25
	v_cvt_pk_bf16_f32 v24, v18, v19
	v_lshl_add_u64 v[18:19], v[78:79], 0, v[0:1]
	v_mov_b32_e32 v0, v26
	v_add_f32_e32 v27, v30, v27
	v_cvt_pk_bf16_f32 v25, v20, v21
	v_permlane16_swap_b32_e32 v26, v0
	global_store_dwordx4 v[18:19], v[22:25], off
	v_add_f32_e32 v18, v26, v0
	v_mov_b32_e32 v0, v27
	s_nop 1
	v_permlane16_swap_b32_e32 v27, v0
	v_add_f32_e32 v19, v27, v0
	v_mov_b32_e32 v20, v18
	v_mov_b32_e32 v21, v19
	s_nop 0
	v_permlane32_swap_b32_e32 v18, v20
	v_permlane32_swap_b32_e32 v19, v21
	s_and_saveexec_b64 s[26:27], s[44:45]
	s_cbranch_execz .LBB0_386
	v_pk_add_f32 v[18:19], v[18:19], v[20:21]
	v_lshlrev_b64 v[20:21], 7, v[76:77]
	v_lshl_add_u64 v[20:21], s[30:31], 0, v[20:21]
	v_lshl_add_u64 v[20:21], s[24:25], 2, v[20:21]
	global_store_dwordx2 v[20:21], v[18:19], off
; __device__ __forceinline__ float xsum16(float v) { const auto r = __builtin_amdgcn_permlane16_swap(__float_as_uint(v), __float_as_uint(v), false, false); return __uint_as_float(r[0]) + __uint_as_float(r[1]); }
; __device__ __forceinline__ float xsum32(float v) { const auto r = __builtin_amdgcn_permlane32_swap(__float_as_uint(v), __float_as_uint(v), false, false); return __uint_as_float(r[0]) + __uint_as_float(r[1]); }
; __device__ __forceinline__ size_t blk_off(int r, int c, int K) { return (size_t)(r >> 8) * 256 * K + (size_t)(c >> 6) * (256 * 64) + (size_t)((r & 255) * 64 + (c & 63)); }
; __device__ __forceinline__ u32x4 pack8(const f32x4 a, const f32x4 b) { u32x4 w; w.x = cvt_pk_bf16(a[0], a[1]); w.y = cvt_pk_bf16(a[2], a[3]); w.z = cvt_pk_bf16(b[0], b[1]); w.w = cvt_pk_bf16(b[2], b[3]); return w; }
;     __device__ __forceinline__ void operator()(const f32x4 (&acc)[2][2][4][2], const pg8::Unit& u, int wr, int wc, int fr, int fq) const {
;     ...
;             for (int m = 0; m < 4; ++m) { const int row = row0 + ai * 128 + m * 16; const float mu = mu4[m], rs = rs4[m];
;                 f32x4 yv[2][2], gq[2][2], bq_[2][2];
; #pragma unroll
;                 for (int bj = 0; bj < 2; ++bj)
; #pragma unroll
;                     for (int n = 0; n < 2; ++n) { yv[bj][n] = *(const f32x4*)(Yin + (size_t)row * D_ + col0 + bj * 128 + 4 * n); gq[bj][n] = *(const f32x4*)(g + col0 + bj * 128 + 4 * n); bq_[bj][n] = *(const f32x4*)(b + col0 + bj * 128 + 4 * n); }
;                 asm volatile("" ::: "memory");
;                 float s1 = 0.f, s2 = 0.f;
; #pragma unroll
;                 for (int bj = 0; bj < 2; ++bj) { float* yp = Y + (size_t)row * D_ + col0 + bj * 128; f32x4 v[2];
; #pragma unroll
;                     for (int n = 0; n < 2; ++n) { v[n] = (((yv[bj][n] - mu) * rs) * gq[bj][n] + bq_[bj][n]) * ALPHA_ + acc[ai][bj][m][n] * sc;
;                         *(f32x4*)(yp + 4 * n) = v[n]; s1 += (v[n][0] + v[n][1]) + (v[n][2] + v[n][3]); s2 += (v[n][0] * v[n][0] + v[n][1] * v[n][1]) + (v[n][2] * v[n][2] + v[n][3] * v[n][3]); }
;                     *(u32x4*)(Yb + blk_off(row, col0 + bj * 128, D_)) = pack8(v[0], v[1]); }
;                 s1 = xsum32(xsum16(s1)); s2 = xsum32(xsum16(s2));
;                 if (fq == 0) *(f32x2*)(stn + (size_t)row * 32 + (u.pn * 4 + wc) * 2) = (f32x2){s1, s2}; asm volatile("" ::: "memory"); } }
.LBB0_386:
	s_or_b64 exec, exec, s[26:27]
	v_lshlrev_b64 v[26:27], 12, v[74:75]
	v_lshl_add_u64 v[18:19], s[12:13], 0, v[26:27]
	v_lshl_add_u64 v[28:29], v[18:19], 0, v[152:153]
	global_load_dwordx4 v[34:37], v[28:29], off
	global_load_dwordx4 v[38:41], v[28:29], off offset:16
	global_load_dwordx4 v[42:45], v[28:29], off offset:512
	global_load_dwordx4 v[46:49], v[156:157], off
	global_load_dwordx4 v[50:53], v[154:155], off
	global_load_dwordx4 v[54:57], v[154:155], off offset:16
	global_load_dwordx4 v[58:61], v[156:157], off offset:16
	global_load_dwordx4 v[62:65], v[154:155], off offset:512
	global_load_dwordx4 v[66:69], v[156:157], off offset:512
	s_load_dwordx16 s[60:75], s[34:35], 0x38
	v_pk_add_f32 v[18:19], v[82:83], v[84:85]
	s_mov_b32 s2, 0x3a800000
	v_pk_mul_f32 v[32:33], v[18:19], s[2:3] op_sel_hi:[1,0]
	global_load_dwordx4 v[18:21], v[154:155], off offset:528
	global_load_dwordx4 v[22:25], v[156:157], off offset:528
	s_waitcnt lgkmcnt(0)
	v_lshl_add_u64 v[26:27], s[74:75], 0, v[26:27]
	v_lshl_add_u64 v[30:31], v[26:27], 0, v[152:153]
	global_load_dwordx4 v[26:29], v[28:29], off offset:528
	v_fma_f32 v32, -v33, v33, v32
	v_lshlrev_b32_e32 v0, 6, v74
	s_movk_i32 s2, 0x3fc0
	v_max_f32_e32 v32, 0, v32
	v_and_or_b32 v0, v0, s2, v194
	v_add_f32_e32 v32, 0x3727c5ac, v32
	s_mov_b32 s2, 0x800000
	v_mul_f32_e32 v70, 0x4b800000, v32
	v_cmp_gt_f32_e32 vcc, s2, v32
	s_mov_b32 s2, 0x3fd744fd
	v_lshlrev_b32_e32 v0, 1, v0
	v_cndmask_b32_e32 v32, v32, v70, vcc
	v_rsq_f32_e32 v32, v32
	v_lshl_add_u64 v[70:71], v[80:81], 0, v[0:1]
	v_mul_f32_e32 v72, 0x45800000, v32
	v_cndmask_b32_e32 v32, v32, v72, vcc
	s_waitcnt vmcnt(11)
	v_sub_f32_e32 v37, v37, v33
	v_sub_f32_e32 v36, v36, v33
	v_sub_f32_e32 v35, v35, v33
	v_sub_f32_e32 v34, v34, v33
	s_waitcnt vmcnt(10)
	v_sub_f32_e32 v41, v41, v33
	v_sub_f32_e32 v40, v40, v33
	v_sub_f32_e32 v39, v39, v33
	v_sub_f32_e32 v38, v38, v33
	v_pk_mul_f32 v[34:35], v[32:33], v[34:35] op_sel_hi:[0,1]
	v_pk_mul_f32 v[36:37], v[32:33], v[36:37] op_sel_hi:[0,1]
	v_pk_mul_f32 v[38:39], v[32:33], v[38:39] op_sel_hi:[0,1]
	v_pk_mul_f32 v[40:41], v[32:33], v[40:41] op_sel_hi:[0,1]
	s_waitcnt vmcnt(7)
	v_pk_fma_f32 v[36:37], v[52:53], v[36:37], v[48:49]
	v_pk_fma_f32 v[34:35], v[50:51], v[34:35], v[46:47]
	s_waitcnt vmcnt(5)
	v_pk_fma_f32 v[40:41], v[56:57], v[40:41], v[60:61]
	v_pk_fma_f32 v[38:39], v[54:55], v[38:39], v[58:59]
	v_pk_mul_f32 v[34:35], v[34:35], s[2:3] op_sel_hi:[1,0]
	v_pk_mul_f32 v[36:37], v[36:37], s[2:3] op_sel_hi:[1,0]
	v_pk_mul_f32 v[38:39], v[38:39], s[2:3] op_sel_hi:[1,0]
	v_pk_mul_f32 v[40:41], v[40:41], s[2:3] op_sel_hi:[1,0]
	v_pk_fma_f32 v[16:17], v[16:17], 0.5, v[36:37] op_sel_hi:[1,0,1]
	v_pk_fma_f32 v[14:15], v[14:15], 0.5, v[34:35] op_sel_hi:[1,0,1]
	v_pk_fma_f32 v[12:13], v[12:13], 0.5, v[40:41] op_sel_hi:[1,0,1]
	v_pk_fma_f32 v[10:11], v[10:11], 0.5, v[38:39] op_sel_hi:[1,0,1]
	v_sub_f32_e32 v45, v45, v33
	v_sub_f32_e32 v44, v44, v33
	v_sub_f32_e32 v43, v43, v33
	v_sub_f32_e32 v42, v42, v33
	v_add_f32_e32 v38, v14, v15
	v_add_f32_e32 v39, v16, v17
	v_mul_f32_e32 v40, v15, v15
	v_mul_f32_e32 v41, v17, v17
	v_mul_f32_e32 v48, v11, v11
	v_mul_f32_e32 v49, v13, v13
	v_pk_mul_f32 v[42:43], v[32:33], v[42:43] op_sel_hi:[0,1]
	v_pk_mul_f32 v[44:45], v[32:33], v[44:45] op_sel_hi:[0,1]
	global_store_dwordx4 v[30:31], v[10:13], off offset:16
	v_add_f32_e32 v46, v10, v11
	v_add_f32_e32 v47, v12, v13
	v_cvt_pk_bf16_f32 v36, v10, v11
	v_add_f32_e32 v11, v38, v39
	v_fmac_f32_e32 v40, v14, v14
	v_fmac_f32_e32 v41, v16, v16
	v_fmac_f32_e32 v48, v10, v10
	v_fmac_f32_e32 v49, v12, v12
	s_waitcnt vmcnt(4)
	v_pk_fma_f32 v[44:45], v[64:65], v[44:45], v[68:69]
	v_pk_fma_f32 v[42:43], v[62:63], v[42:43], v[66:67]
	v_cvt_pk_bf16_f32 v37, v12, v13
	v_add_f32_e32 v13, v46, v47
	v_add_f32_e32 v10, 0, v11
	v_add_f32_e32 v11, v40, v41
	v_add_f32_e32 v12, v48, v49
	global_store_dwordx4 v[30:31], v[14:17], off
	v_cvt_pk_bf16_f32 v34, v14, v15
	v_cvt_pk_bf16_f32 v35, v16, v17
	v_add_f32_e32 v14, v10, v13
	v_add_f32_e32 v15, v11, v12
	v_pk_mul_f32 v[10:11], v[42:43], s[2:3] op_sel_hi:[1,0]
	v_pk_mul_f32 v[12:13], v[44:45], s[2:3] op_sel_hi:[1,0]
	v_pk_fma_f32 v[6:7], v[6:7], 0.5, v[10:11] op_sel_hi:[1,0,1]
	v_pk_fma_f32 v[8:9], v[8:9], 0.5, v[12:13] op_sel_hi:[1,0,1]
	v_add_f32_e32 v10, v6, v7
	v_add_f32_e32 v11, v8, v9
	v_add_f32_e32 v10, v10, v11
	v_add_f32_e32 v14, v14, v10
	v_mul_f32_e32 v10, v7, v7
	v_mul_f32_e32 v11, v9, v9
	v_fmac_f32_e32 v10, v6, v6
	v_fmac_f32_e32 v11, v8, v8
	v_add_f32_e32 v10, v10, v11
	v_add_f32_e32 v15, v15, v10
	s_waitcnt vmcnt(2)
	v_sub_f32_e32 v11, v29, v33
	v_sub_f32_e32 v10, v28, v33
	v_sub_f32_e32 v13, v27, v33
	v_sub_f32_e32 v12, v26, v33
	v_pk_mul_f32 v[12:13], v[32:33], v[12:13] op_sel_hi:[0,1]
	v_pk_mul_f32 v[10:11], v[32:33], v[10:11] op_sel_hi:[0,1]
	v_pk_fma_f32 v[10:11], v[20:21], v[10:11], v[24:25]
	v_pk_fma_f32 v[12:13], v[18:19], v[12:13], v[22:23]
	v_pk_mul_f32 v[10:11], v[10:11], s[2:3] op_sel_hi:[1,0]
	v_pk_mul_f32 v[12:13], v[12:13], s[2:3] op_sel_hi:[1,0]
	v_pk_fma_f32 v[4:5], v[4:5], 0.5, v[10:11] op_sel_hi:[1,0,1]
	v_pk_fma_f32 v[2:3], v[2:3], 0.5, v[12:13] op_sel_hi:[1,0,1]
	v_add_f32_e32 v11, v4, v5
	v_add_f32_e32 v10, v2, v3
	v_add_f32_e32 v10, v10, v11
	v_mul_f32_e32 v11, v3, v3
	v_mul_f32_e32 v12, v5, v5
	v_add_f32_e32 v10, v14, v10
	v_fmac_f32_e32 v11, v2, v2
	v_fmac_f32_e32 v12, v4, v4
	global_store_dwordx4 v[70:71], v[34:37], off
	s_nop 0
	s_nop 1
	v_bfe_u32 v17, v227, 4, 2
	v_sub_u32_e32 v16, 0, v17
	v_lshlrev_b32_e32 v16, 4, v16
	v_ashrrev_i32_e32 v17, 31, v16
	v_lshl_add_u64 v[16:17], v[30:31], 0, v[16:17]
	v_permlane16_swap_b32_e32 v6, v2
	v_permlane16_swap_b32_e32 v7, v3
	v_permlane16_swap_b32_e32 v8, v4
	v_permlane16_swap_b32_e32 v9, v5
	v_permlane32_swap_b32_e32 v6, v2
	v_permlane32_swap_b32_e32 v7, v3
	v_permlane32_swap_b32_e32 v8, v4
	v_permlane32_swap_b32_e32 v9, v5
	global_store_dwordx4 v[16:17], v[6:9], off offset:512
	global_store_dwordx4 v[16:17], v[2:5], off offset:576
	s_nop 1
	v_permlane32_swap_b32_e32 v6, v2
	v_permlane32_swap_b32_e32 v7, v3
	v_permlane32_swap_b32_e32 v8, v4
	v_permlane32_swap_b32_e32 v9, v5
	v_permlane16_swap_b32_e32 v6, v2
	v_permlane16_swap_b32_e32 v7, v3
	v_permlane16_swap_b32_e32 v8, v4
	v_permlane16_swap_b32_e32 v9, v5
	v_add_f32_e32 v11, v11, v12
	v_cvt_pk_bf16_f32 v6, v6, v7
	v_cvt_pk_bf16_f32 v7, v8, v9
	v_cvt_pk_bf16_f32 v8, v2, v3
	v_lshl_add_u64 v[2:3], v[78:79], 0, v[0:1]
	v_mov_b32_e32 v0, v10
	v_add_f32_e32 v11, v15, v11
	v_cvt_pk_bf16_f32 v9, v4, v5
	v_permlane16_swap_b32_e32 v10, v0
	global_store_dwordx4 v[2:3], v[6:9], off
	v_add_f32_e32 v2, v10, v0
	v_mov_b32_e32 v0, v11
	s_nop 1
	v_permlane16_swap_b32_e32 v11, v0
	v_add_f32_e32 v3, v11, v0
	v_mov_b32_e32 v4, v2
	v_mov_b32_e32 v5, v3
	s_nop 0
	v_permlane32_swap_b32_e32 v2, v4
	v_permlane32_swap_b32_e32 v3, v5
	s_and_saveexec_b64 s[26:27], s[44:45]
	s_cbranch_execz .LBB0_388
;     __device__ __forceinline__ void operator()(const f32x4 (&acc)[2][2][4][2], const pg8::Unit& u, int wr, int wc, int fr, int fq) const {
;     ...
;                 if (fq == 0) *(f32x2*)(stn + (size_t)row * 32 + (u.pn * 4 + wc) * 2) = (f32x2){s1, s2}; asm volatile("" ::: "memory"); } }
	v_pk_add_f32 v[2:3], v[2:3], v[4:5]
	v_lshlrev_b64 v[4:5], 7, v[74:75]
	v_lshl_add_u64 v[4:5], s[30:31], 0, v[4:5]
	v_lshl_add_u64 v[4:5], s[24:25], 2, v[4:5]
	global_store_dwordx2 v[4:5], v[2:3], off

; __device__ __forceinline__ float xsum16(float v) { const auto r = __builtin_amdgcn_permlane16_swap(__float_as_uint(v), __float_as_uint(v), false, false); return __uint_as_float(r[0]) + __uint_as_float(r[1]); }
; __device__ __forceinline__ float xsum32(float v) { const auto r = __builtin_amdgcn_permlane32_swap(__float_as_uint(v), __float_as_uint(v), false, false); return __uint_as_float(r[0]) + __uint_as_float(r[1]); }
; __device__ __forceinline__ void row_stats4(const float* st, int rowb, int fq, float (&mu)[4], float (&rs)[4]) {
;     ...
;     for (int m = 0; m < 4; ++m) { const f32x4* p = (const f32x4*)(st + (size_t)(rowb + m * 16) * 32 + fq * 8); a[m] = p[0]; b[m] = p[1]; }
; #pragma unroll
;     for (int m = 0; m < 4; ++m) { float s1 = (a[m][0] + a[m][2]) + (b[m][0] + b[m][2]), s2 = (a[m][1] + a[m][3]) + (b[m][1] + b[m][3]);
;         s1 = xsum32(xsum16(s1)); s2 = xsum32(xsum16(s2));
;         const float mm = s1 * (1.0f / 1024.0f); mu[m] = mm; rs[m] = rsqrtf(fmaxf(s2 * (1.0f / 1024.0f) - mm * mm, 0.f) + LN_EPS_); }
;     __device__ __forceinline__ void operator()(const f32x4 (&acc)[2][2][4][2], const pg8::Unit& u, int wr, int wc, int fr, int fq) const {
;         const int row0 = u.pm * 256 + wr * 64 + fr, col0 = u.pn * 256 + wc * 32 + fq * 8;
; #pragma unroll
;         for (int ai = 0; ai < 2; ++ai) { float mu4[4], rs4[4]; row_stats4(stp, row0 + ai * 128, fq, mu4, rs4);
; #pragma unroll
;             for (int m = 0; m < 4; ++m) { const int row = row0 + ai * 128 + m * 16; const float mu = mu4[m], rs = rs4[m];
;                 f32x4 yv[2][2], gq[2][2], bq_[2][2];
; #pragma unroll
;                 for (int bj = 0; bj < 2; ++bj)
; #pragma unroll
;                     for (int n = 0; n < 2; ++n) { yv[bj][n] = *(const f32x4*)(Yin + (size_t)row * D_ + col0 + bj * 128 + 4 * n); gq[bj][n] = *(const f32x4*)(g + col0 + bj * 128 + 4 * n); bq_[bj][n] = *(const f32x4*)(b + col0 + bj * 128 + 4 * n); }
.LBB0_1535:
	s_lshl_b32 s3, s3, 8
	s_add_i32 s3, s3, s0
	v_or_b32_e32 v158, s3, v184
	v_ashrrev_i32_e32 v159, 31, v158
	v_lshlrev_b64 v[130:131], 7, v[158:159]
	v_lshl_add_u64 v[136:137], v[146:147], 0, v[130:131]
	v_or_b32_e32 v180, 16, v158
	global_load_dwordx4 v[132:135], v[136:137], off
	global_load_dwordx4 v[166:169], v[136:137], off offset:16
	v_ashrrev_i32_e32 v181, 31, v180
	v_lshlrev_b64 v[172:173], 7, v[180:181]
	v_lshl_add_u64 v[136:137], v[146:147], 0, v[172:173]
	global_load_dwordx4 v[174:177], v[136:137], off
	global_load_dwordx4 v[186:189], v[136:137], off offset:16
	v_or_b32_e32 v170, 32, v158
	v_ashrrev_i32_e32 v171, 31, v170
	v_lshlrev_b64 v[164:165], 7, v[170:171]
	v_lshl_add_u64 v[136:137], v[146:147], 0, v[164:165]
	global_load_dwordx4 v[190:193], v[136:137], off
	global_load_dwordx4 v[198:201], v[136:137], off offset:16
	v_or_b32_e32 v162, 48, v158
	v_ashrrev_i32_e32 v163, 31, v162
	v_lshlrev_b64 v[160:161], 7, v[162:163]
	v_lshl_add_u64 v[182:183], v[146:147], 0, v[160:161]
	global_load_dwordx4 v[202:205], v[182:183], off
	global_load_dwordx4 v[206:209], v[182:183], off offset:16
	s_load_dwordx16 s[64:79], s[34:35], 0x38
	s_lshl_b32 s1, s2, 8
	s_lshl_b32 s14, s2, 3
	s_or_b32 s2, s1, s57
	v_or_b32_e32 v152, s2, v185
	v_ashrrev_i32_e32 v153, 31, v152
	v_lshlrev_b64 v[136:137], 12, v[158:159]
	v_lshlrev_b64 v[178:179], 2, v[152:153]
	s_waitcnt lgkmcnt(0)
	v_lshl_add_u64 v[136:137], s[78:79], 0, v[136:137]
	v_lshl_add_u64 v[156:157], s[8:9], 0, v[178:179]
	v_lshl_add_u64 v[154:155], s[10:11], 0, v[178:179]
	v_lshl_add_u64 v[136:137], v[136:137], 0, v[178:179]
	s_or_b32 s52, s14, s61
	s_mov_b32 s14, 0x3a800000
	global_load_dwordx4 v[210:213], v[136:137], off offset:16
	global_load_dwordx4 v[214:217], v[136:137], off
	global_load_dwordx4 v[218:221], v[156:157], off offset:16
	global_load_dwordx4 v[222:225], v[156:157], off
	global_load_dwordx4 v[234:237], v[154:155], off offset:16
	global_load_dwordx4 v[238:241], v[154:155], off
	s_mov_b32 s1, 0x800000
	s_mov_b32 s18, 0x3fd744fd
	v_bitop3_b32 v196, s2, 56, v185 bitop3:0xc8
	s_ashr_i32 s2, s2, 6
	s_ashr_i32 s53, s52, 31
	v_readlane_b32 s16, v253, 59
	v_readlane_b32 s17, v253, 60
	s_waitcnt vmcnt(0)
	v_mov_b32_e32 v178, v132
	v_mov_b32_e32 v179, v166
	v_mov_b32_e32 v182, v134
	v_mov_b32_e32 v183, v168
	v_mov_b32_e32 v166, v133
	v_mov_b32_e32 v168, v135
	v_pk_add_f32 v[132:133], v[178:179], v[182:183]
	v_pk_add_f32 v[134:135], v[166:167], v[168:169]
	v_pk_add_f32 v[132:133], v[132:133], v[132:133] op_sel:[0,1] op_sel_hi:[1,0]
	v_pk_add_f32 v[134:135], v[134:135], v[134:135] op_sel:[0,1] op_sel_hi:[1,0]
	v_mov_b32_e32 v166, v174
	v_mov_b32_e32 v167, v186
	v_mov_b32_e32 v168, v176
	v_mov_b32_e32 v169, v188
	v_mov_b32_e32 v0, v132
	v_mov_b32_e32 v133, v134
	v_pk_add_f32 v[166:167], v[166:167], v[168:169]
	v_permlane16_swap_b32_e32 v132, v0
	v_permlane16_swap_b32_e32 v134, v133
	v_mov_b32_e32 v188, v177
	v_pk_add_f32 v[166:167], v[166:167], v[166:167] op_sel:[0,1] op_sel_hi:[1,0]
	v_add_f32_e32 v177, v132, v0
	v_add_f32_e32 v176, v134, v133
	v_mov_b32_e32 v135, v166
	v_mov_b32_e32 v179, v177
	v_mov_b32_e32 v178, v176
	v_permlane16_swap_b32_e32 v166, v135
	v_permlane32_swap_b32_e32 v177, v179
	v_permlane32_swap_b32_e32 v176, v178
	v_mov_b32_e32 v186, v175
	v_add_f32_e32 v133, v166, v135
	v_pk_add_f32 v[166:167], v[176:177], v[178:179]
	v_pk_add_f32 v[168:169], v[186:187], v[188:189]
	v_pk_mul_f32 v[178:179], v[166:167], s[14:15] op_sel_hi:[1,0]
	v_pk_add_f32 v[168:169], v[168:169], v[168:169] op_sel:[0,1] op_sel_hi:[1,0]
	v_fma_f32 v0, -v179, v179, v178
	v_mov_b32_e32 v159, v168
	v_max_f32_e32 v0, 0, v0
	s_nop 0
	v_permlane16_swap_b32_e32 v168, v159
	v_add_f32_e32 v0, 0x3727c5ac, v0
	v_add_f32_e32 v132, v168, v159
	v_mul_f32_e32 v159, 0x4b800000, v0
	v_cmp_gt_f32_e32 vcc, s1, v0
	v_mov_b32_e32 v174, v190
	v_mov_b32_e32 v175, v198
	v_cndmask_b32_e32 v0, v0, v159, vcc
	v_rsq_f32_e32 v0, v0
	v_mov_b32_e32 v166, v192
	v_mov_b32_e32 v167, v200
	v_pk_add_f32 v[166:167], v[174:175], v[166:167]
	v_mul_f32_e32 v159, 0x45800000, v0
	v_pk_add_f32 v[166:167], v[166:167], v[166:167] op_sel:[0,1] op_sel_hi:[1,0]
	v_mov_b32_e32 v198, v191
	v_mov_b32_e32 v200, v193
	v_cndmask_b32_e32 v0, v0, v159, vcc
	v_pk_add_f32 v[168:169], v[198:199], v[200:201]
	v_mov_b32_e32 v159, v166
	v_pk_add_f32 v[168:169], v[168:169], v[168:169] op_sel:[0,1] op_sel_hi:[1,0]
	s_nop 0
	v_permlane16_swap_b32_e32 v166, v159
	v_add_f32_e32 v175, v166, v159
	v_mov_b32_e32 v159, v168
	s_nop 1
	v_permlane16_swap_b32_e32 v168, v159
	global_load_dwordx4 v[186:189], v[136:137], off offset:528
	global_load_dwordx4 v[190:193], v[136:137], off offset:512
	v_add_f32_e32 v174, v168, v159
	v_mov_b32_e32 v166, v202
	v_mov_b32_e32 v167, v206
	v_mov_b32_e32 v168, v204
	v_mov_b32_e32 v169, v208
	v_mov_b32_e32 v206, v203
	v_mov_b32_e32 v208, v205
	v_pk_add_f32 v[166:167], v[166:167], v[168:169]
	v_pk_add_f32 v[168:169], v[206:207], v[208:209]
	global_load_dwordx4 v[198:201], v[156:157], off offset:528
	global_load_dwordx4 v[202:205], v[156:157], off offset:512
	global_load_dwordx4 v[206:209], v[154:155], off offset:528
	global_load_dwordx4 v[242:245], v[154:155], off offset:512
	v_sub_f32_e32 v183, v215, v179
	v_sub_f32_e32 v182, v214, v179
	v_sub_f32_e32 v215, v217, v179
	v_sub_f32_e32 v214, v216, v179
	v_pk_mul_f32 v[214:215], v[0:1], v[214:215] op_sel_hi:[0,1]
	v_pk_mul_f32 v[182:183], v[0:1], v[182:183] op_sel_hi:[0,1]
	v_pk_fma_f32 v[182:183], v[222:223], v[182:183], v[238:239]
	v_pk_fma_f32 v[214:215], v[224:225], v[214:215], v[240:241]
	v_pk_fma_f32 v[126:127], v[182:183], s[18:19], v[126:127] op_sel_hi:[1,0,1]
; __device__ __forceinline__ float xsum16(float v) { const auto r = __builtin_amdgcn_permlane16_swap(__float_as_uint(v), __float_as_uint(v), false, false); return __uint_as_float(r[0]) + __uint_as_float(r[1]); }
; __device__ __forceinline__ float xsum32(float v) { const auto r = __builtin_amdgcn_permlane32_swap(__float_as_uint(v), __float_as_uint(v), false, false); return __uint_as_float(r[0]) + __uint_as_float(r[1]); }
; __device__ __forceinline__ size_t blk_off(int r, int c, int K) { return (size_t)(r >> 8) * 256 * K + (size_t)(c >> 6) * (256 * 64) + (size_t)((r & 255) * 64 + (c & 63)); }
; __device__ __forceinline__ u32x4 pack8(const f32x4 a, const f32x4 b) { u32x4 w; w.x = cvt_pk_bf16(a[0], a[1]); w.y = cvt_pk_bf16(a[2], a[3]); w.z = cvt_pk_bf16(b[0], b[1]); w.w = cvt_pk_bf16(b[2], b[3]); return w; }
;     __device__ __forceinline__ void operator()(const f32x4 (&acc)[2][2][4][2], const pg8::Unit& u, int wr, int wc, int fr, int fq) const {
;     ...
;                     for (int n = 0; n < 2; ++n) { yv[bj][n] = *(const f32x4*)(Yin + (size_t)row * D_ + col0 + bj * 128 + 4 * n); gq[bj][n] = *(const f32x4*)(g + col0 + bj * 128 + 4 * n); bq_[bj][n] = *(const f32x4*)(b + col0 + bj * 128 + 4 * n); }
;                 asm volatile("" ::: "memory");
;                 float s1 = 0.f, s2 = 0.f;
; #pragma unroll
;                 for (int bj = 0; bj < 2; ++bj) { float* yp = Y + (size_t)row * D_ + col0 + bj * 128; f32x4 v[2];
; #pragma unroll
;                     for (int n = 0; n < 2; ++n) { v[n] = (((yv[bj][n] - mu) * rs) * gq[bj][n] + bq_[bj][n]) * ALPHA_ + acc[ai][bj][m][n] * sc;
;                         *(f32x4*)(yp + 4 * n) = v[n]; s1 += (v[n][0] + v[n][1]) + (v[n][2] + v[n][3]); s2 += (v[n][0] * v[n][0] + v[n][1] * v[n][1]) + (v[n][2] * v[n][2] + v[n][3] * v[n][3]); }
;                     *(u32x4*)(Yb + blk_off(row, col0 + bj * 128, D_)) = pack8(v[0], v[1]); }
;                 s1 = xsum32(xsum16(s1)); s2 = xsum32(xsum16(s2));
;                 if (fq == 0) *(f32x2*)(stn + (size_t)row * 32 + (u.pn * 4 + wc) * 2) = (f32x2){s1, s2}; asm volatile("" ::: "memory"); } }
	v_pk_fma_f32 v[128:129], v[214:215], s[18:19], v[128:129] op_sel_hi:[1,0,1]
	v_add_f32_e32 v178, v126, v127
	v_add_f32_e32 v182, v128, v129
	v_add_f32_e32 v178, v178, v182
	v_mul_f32_e32 v182, v127, v127
	v_mul_f32_e32 v183, v129, v129
	v_fmac_f32_e32 v182, v126, v126
	v_fmac_f32_e32 v183, v128, v128
	v_add_f32_e32 v197, v182, v183
	v_sub_f32_e32 v183, v211, v179
	v_sub_f32_e32 v182, v210, v179
	v_sub_f32_e32 v211, v213, v179
	v_sub_f32_e32 v210, v212, v179
	v_pk_mul_f32 v[210:211], v[0:1], v[210:211] op_sel_hi:[0,1]
	v_pk_mul_f32 v[182:183], v[0:1], v[182:183] op_sel_hi:[0,1]
	v_pk_fma_f32 v[182:183], v[218:219], v[182:183], v[234:235]
	v_pk_fma_f32 v[210:211], v[220:221], v[210:211], v[236:237]
	v_pk_add_f32 v[166:167], v[166:167], v[166:167] op_sel:[0,1] op_sel_hi:[1,0]
	v_pk_fma_f32 v[124:125], v[210:211], s[18:19], v[124:125] op_sel_hi:[1,0,1]
	v_pk_fma_f32 v[122:123], v[182:183], s[18:19], v[122:123] op_sel_hi:[1,0,1]
	v_mov_b32_e32 v159, v166
	v_add_f32_e32 v182, v122, v123
	v_add_f32_e32 v183, v124, v125
	v_pk_add_f32 v[168:169], v[168:169], v[168:169] op_sel:[0,1] op_sel_hi:[1,0]
	v_permlane16_swap_b32_e32 v166, v159
	v_add_f32_e32 v178, 0, v178
	v_add_f32_e32 v182, v182, v183
	v_add_f32_e32 v167, v166, v159
	v_mov_b32_e32 v159, v168
	s_ashr_i32 s14, s3, 8
	v_add_f32_e32 v178, v178, v182
	v_mul_f32_e32 v182, v123, v123
	v_mul_f32_e32 v183, v125, v125
	v_permlane16_swap_b32_e32 v168, v159
	s_ashr_i32 s15, s14, 31
	s_nop 0
	s_nop 1
	v_bfe_u32 v135, v227, 4, 2
	v_sub_u32_e32 v134, 0, v135
	v_lshlrev_b32_e32 v134, 4, v134
	v_ashrrev_i32_e32 v135, 31, v134
	v_lshl_add_u64 v[134:135], v[136:137], 0, v[134:135]
	v_permlane16_swap_b32_e32 v126, v122
	v_permlane16_swap_b32_e32 v127, v123
	v_permlane16_swap_b32_e32 v128, v124
	v_permlane16_swap_b32_e32 v129, v125
	v_permlane32_swap_b32_e32 v126, v122
	v_permlane32_swap_b32_e32 v127, v123
	v_permlane32_swap_b32_e32 v128, v124
	v_permlane32_swap_b32_e32 v129, v125
	global_store_dwordx4 v[134:135], v[126:129], off
	global_store_dwordx4 v[134:135], v[122:125], off offset:64
	s_nop 1
	v_permlane32_swap_b32_e32 v126, v122
	v_permlane32_swap_b32_e32 v127, v123
	v_permlane32_swap_b32_e32 v128, v124
	v_permlane32_swap_b32_e32 v129, v125
	v_permlane16_swap_b32_e32 v126, v122
	v_permlane16_swap_b32_e32 v127, v123
	v_permlane16_swap_b32_e32 v128, v124
	v_permlane16_swap_b32_e32 v129, v125
	v_fmac_f32_e32 v182, v122, v122
	v_fmac_f32_e32 v183, v124, v124
	v_cvt_pk_bf16_f32 v126, v126, v127
	v_cvt_pk_bf16_f32 v127, v128, v129
	v_cvt_pk_bf16_f32 v128, v122, v123
	v_cvt_pk_bf16_f32 v129, v124, v125
	v_add_f32_e32 v166, v168, v159
	s_lshl_b64 s[14:15], s[14:15], 19
	v_lshlrev_b32_e32 v159, 6, v158
	s_movk_i32 s1, 0x33c0
	s_ashr_i32 s3, s2, 31
	v_and_or_b32 v159, v159, s1, v196
	s_add_u32 s1, s16, s14
	s_addc_u32 s14, s17, s15
	s_lshl_b64 s[24:25], s[2:3], 15
	s_add_u32 s42, s1, s24
	s_addc_u32 s43, s14, s25
	v_lshlrev_b32_e32 v159, 1, v159
	global_store_dwordx4 v159, v[126:129], s[42:43]
	v_add_f32_e32 v182, v182, v183
	s_waitcnt vmcnt(7)
	v_sub_f32_e32 v123, v191, v179
	v_sub_f32_e32 v122, v190, v179
	v_sub_f32_e32 v125, v193, v179
	v_sub_f32_e32 v124, v192, v179
	v_pk_mul_f32 v[124:125], v[0:1], v[124:125] op_sel_hi:[0,1]
	v_pk_mul_f32 v[122:123], v[0:1], v[122:123] op_sel_hi:[0,1]
	v_add_f32_e32 v182, v197, v182
	s_or_b32 s2, s2, 2
	s_ashr_i32 s3, s2, 31
	s_lshl_b64 s[28:29], s[2:3], 15
	s_waitcnt vmcnt(3)
	v_pk_fma_f32 v[122:123], v[202:203], v[122:123], v[242:243]
	v_pk_fma_f32 v[124:125], v[204:205], v[124:125], v[244:245]
	v_pk_fma_f32 v[118:119], v[122:123], s[18:19], v[118:119] op_sel_hi:[1,0,1]
	v_pk_fma_f32 v[120:121], v[124:125], s[18:19], v[120:121] op_sel_hi:[1,0,1]
	v_add_f32_e32 v122, v118, v119
	v_add_f32_e32 v123, v120, v121
	v_add_f32_e32 v122, v122, v123
	v_add_f32_e32 v126, v178, v122
	v_mul_f32_e32 v122, v119, v119
	v_mul_f32_e32 v123, v121, v121
	v_fmac_f32_e32 v122, v118, v118
	v_fmac_f32_e32 v123, v120, v120
	v_add_f32_e32 v122, v122, v123
	v_add_f32_e32 v127, v182, v122
	v_sub_f32_e32 v123, v187, v179
	v_sub_f32_e32 v122, v186, v179
	v_sub_f32_e32 v125, v189, v179
	v_sub_f32_e32 v124, v188, v179
	v_pk_mul_f32 v[124:125], v[0:1], v[124:125] op_sel_hi:[0,1]
	v_pk_mul_f32 v[122:123], v[0:1], v[122:123] op_sel_hi:[0,1]
	v_pk_fma_f32 v[122:123], v[198:199], v[122:123], v[206:207]
	v_pk_fma_f32 v[124:125], v[200:201], v[124:125], v[208:209]
	v_pk_fma_f32 v[114:115], v[122:123], s[18:19], v[114:115] op_sel_hi:[1,0,1]
	v_pk_fma_f32 v[116:117], v[124:125], s[18:19], v[116:117] op_sel_hi:[1,0,1]
	v_add_f32_e32 v0, v114, v115
	v_add_f32_e32 v122, v116, v117
	v_add_f32_e32 v0, v0, v122
	v_mul_f32_e32 v122, v115, v115
	v_mul_f32_e32 v123, v117, v117
	v_add_f32_e32 v0, v126, v0
	v_fmac_f32_e32 v122, v114, v114
	v_fmac_f32_e32 v123, v116, v116
	s_nop 0
	s_nop 1
	v_bfe_u32 v125, v227, 4, 2
	v_sub_u32_e32 v124, 0, v125
	v_lshlrev_b32_e32 v124, 4, v124
	v_ashrrev_i32_e32 v125, 31, v124
	v_lshl_add_u64 v[124:125], v[136:137], 0, v[124:125]
	v_permlane16_swap_b32_e32 v118, v114
	v_permlane16_swap_b32_e32 v119, v115
	v_permlane16_swap_b32_e32 v120, v116
	v_permlane16_swap_b32_e32 v121, v117
	v_permlane32_swap_b32_e32 v118, v114
	v_permlane32_swap_b32_e32 v119, v115
	v_permlane32_swap_b32_e32 v120, v116
	v_permlane32_swap_b32_e32 v121, v117
	global_store_dwordx4 v[124:125], v[118:121], off offset:512
	global_store_dwordx4 v[124:125], v[114:117], off offset:576
	s_nop 1
	v_permlane32_swap_b32_e32 v118, v114
	v_permlane32_swap_b32_e32 v119, v115
	v_permlane32_swap_b32_e32 v120, v116
	v_permlane32_swap_b32_e32 v121, v117
	v_permlane16_swap_b32_e32 v118, v114
	v_permlane16_swap_b32_e32 v119, v115
	v_permlane16_swap_b32_e32 v120, v116
	v_permlane16_swap_b32_e32 v121, v117
	v_add_f32_e32 v122, v122, v123
	v_cvt_pk_bf16_f32 v118, v118, v119
	v_cvt_pk_bf16_f32 v119, v120, v121
	v_cvt_pk_bf16_f32 v120, v114, v115
	v_mov_b32_e32 v114, v0
	v_add_f32_e32 v122, v127, v122
	s_nop 0
	v_permlane16_swap_b32_e32 v0, v114
	v_add_f32_e32 v114, v0, v114
	v_mov_b32_e32 v0, v122
	s_nop 1
	v_permlane16_swap_b32_e32 v122, v0
	v_add_f32_e32 v115, v122, v0
	v_mov_b32_e32 v135, v133
	v_mov_b32_e32 v134, v132
	v_mov_b32_e32 v177, v175
	v_mov_b32_e32 v176, v174
	v_mov_b32_e32 v169, v167
	v_mov_b32_e32 v168, v166
	v_cvt_pk_bf16_f32 v121, v116, v117
	s_add_u32 s40, s1, s28
	v_mov_b32_e32 v116, v114
	v_mov_b32_e32 v117, v115
	v_permlane32_swap_b32_e32 v133, v135
	v_permlane32_swap_b32_e32 v132, v134
	v_permlane32_swap_b32_e32 v175, v177
	v_permlane32_swap_b32_e32 v174, v176
	v_permlane32_swap_b32_e32 v167, v169
	v_permlane32_swap_b32_e32 v166, v168
	s_addc_u32 s41, s14, s29
	v_permlane32_swap_b32_e32 v114, v116
	v_permlane32_swap_b32_e32 v115, v117
	global_store_dwordx4 v159, v[118:121], s[40:41]
	s_and_saveexec_b64 s[26:27], s[44:45]
	s_cbranch_execz .LBB0_1537
	v_pk_add_f32 v[114:115], v[114:115], v[116:117]
	v_lshl_add_u64 v[116:117], s[6:7], 0, v[130:131]
	v_lshl_add_u64 v[116:117], s[52:53], 2, v[116:117]
	global_store_dwordx2 v[116:117], v[114:115], off
; __device__ __forceinline__ size_t blk_off(int r, int c, int K) { return (size_t)(r >> 8) * 256 * K + (size_t)(c >> 6) * (256 * 64) + (size_t)((r & 255) * 64 + (c & 63)); }
; __device__ __forceinline__ u32x4 pack8(const f32x4 a, const f32x4 b) { u32x4 w; w.x = cvt_pk_bf16(a[0], a[1]); w.y = cvt_pk_bf16(a[2], a[3]); w.z = cvt_pk_bf16(b[0], b[1]); w.w = cvt_pk_bf16(b[2], b[3]); return w; }
;     __device__ __forceinline__ void operator()(const f32x4 (&acc)[2][2][4][2], const pg8::Unit& u, int wr, int wc, int fr, int fq) const {
;     ...
;             for (int m = 0; m < 4; ++m) { const int row = row0 + ai * 128 + m * 16; const float mu = mu4[m], rs = rs4[m];
;                 f32x4 yv[2][2], gq[2][2], bq_[2][2];
; #pragma unroll
;                 for (int bj = 0; bj < 2; ++bj)
; #pragma unroll
;                     for (int n = 0; n < 2; ++n) { yv[bj][n] = *(const f32x4*)(Yin + (size_t)row * D_ + col0 + bj * 128 + 4 * n); gq[bj][n] = *(const f32x4*)(g + col0 + bj * 128 + 4 * n); bq_[bj][n] = *(const f32x4*)(b + col0 + bj * 128 + 4 * n); }
;                 asm volatile("" ::: "memory");
;                 float s1 = 0.f, s2 = 0.f;
; #pragma unroll
;                 for (int bj = 0; bj < 2; ++bj) { float* yp = Y + (size_t)row * D_ + col0 + bj * 128; f32x4 v[2];
; #pragma unroll
;                     for (int n = 0; n < 2; ++n) { v[n] = (((yv[bj][n] - mu) * rs) * gq[bj][n] + bq_[bj][n]) * ALPHA_ + acc[ai][bj][m][n] * sc;
;                         *(f32x4*)(yp + 4 * n) = v[n]; s1 += (v[n][0] + v[n][1]) + (v[n][2] + v[n][3]); s2 += (v[n][0] * v[n][0] + v[n][1] * v[n][1]) + (v[n][2] * v[n][2] + v[n][3] * v[n][3]); }
;                     *(u32x4*)(Yb + blk_off(row, col0 + bj * 128, D_)) = pack8(v[0], v[1]); }
.LBB0_1537:
	s_or_b64 exec, exec, s[26:27]
	v_pk_add_f32 v[114:115], v[132:133], v[134:135]
	s_mov_b32 s2, 0x3a800000
	v_pk_mul_f32 v[178:179], v[114:115], s[2:3] op_sel_hi:[1,0]
	s_mov_b32 s1, 0x800000
	v_fma_f32 v0, -v179, v179, v178
	v_max_f32_e32 v0, 0, v0
	v_add_f32_e32 v0, 0x3727c5ac, v0
	v_cmp_gt_f32_e32 vcc, s1, v0
	v_mul_f32_e32 v114, 0x4b800000, v0
	s_load_dwordx16 s[64:79], s[34:35], 0x38
	v_cndmask_b32_e32 v0, v0, v114, vcc
	v_rsq_f32_e32 v0, v0
	v_lshlrev_b32_e32 v159, 6, v180
	s_mov_b32 s2, 0x3fd744fd
	v_mul_f32_e32 v114, 0x45800000, v0
	v_cndmask_b32_e32 v0, v0, v114, vcc
	v_lshlrev_b64 v[114:115], 12, v[180:181]
	s_waitcnt lgkmcnt(0)
	v_lshl_add_u64 v[114:115], s[78:79], 0, v[114:115]
	v_lshl_add_u64 v[182:183], v[152:153], 2, v[114:115]
	global_load_dwordx4 v[186:189], v[182:183], off offset:16
	global_load_dwordx4 v[190:193], v[182:183], off
	global_load_dwordx4 v[198:201], v[156:157], off offset:16
	global_load_dwordx4 v[202:205], v[156:157], off
	global_load_dwordx4 v[206:209], v[154:155], off offset:16
	global_load_dwordx4 v[210:213], v[154:155], off
	global_load_dwordx4 v[114:117], v[182:183], off offset:528
	global_load_dwordx4 v[134:137], v[182:183], off offset:512
	global_load_dwordx4 v[118:121], v[156:157], off offset:528
	global_load_dwordx4 v[126:129], v[156:157], off offset:512
	global_load_dwordx4 v[122:125], v[154:155], off offset:528
	global_load_dwordx4 v[130:133], v[154:155], off offset:512
	s_movk_i32 s1, 0x37c0
	v_and_or_b32 v159, v159, s1, v196
	v_lshlrev_b32_e32 v159, 1, v159
	s_waitcnt vmcnt(10)
	v_sub_f32_e32 v181, v191, v179
	v_sub_f32_e32 v180, v190, v179
	v_sub_f32_e32 v191, v193, v179
	v_sub_f32_e32 v190, v192, v179
	v_pk_mul_f32 v[190:191], v[0:1], v[190:191] op_sel_hi:[0,1]
	v_pk_mul_f32 v[180:181], v[0:1], v[180:181] op_sel_hi:[0,1]
	s_waitcnt vmcnt(6)
	v_pk_fma_f32 v[180:181], v[202:203], v[180:181], v[210:211]
	v_pk_fma_f32 v[190:191], v[204:205], v[190:191], v[212:213]
	v_pk_fma_f32 v[110:111], v[180:181], s[2:3], v[110:111] op_sel_hi:[1,0,1]
	v_pk_fma_f32 v[112:113], v[190:191], s[2:3], v[112:113] op_sel_hi:[1,0,1]
	v_add_f32_e32 v178, v110, v111
	v_add_f32_e32 v180, v112, v113
	v_add_f32_e32 v178, v178, v180
	v_mul_f32_e32 v180, v111, v111
	v_mul_f32_e32 v181, v113, v113
	v_fmac_f32_e32 v180, v110, v110
	v_fmac_f32_e32 v181, v112, v112
	v_add_f32_e32 v190, v180, v181
	v_sub_f32_e32 v181, v187, v179
	v_sub_f32_e32 v180, v186, v179
	v_sub_f32_e32 v187, v189, v179
	v_sub_f32_e32 v186, v188, v179
	v_pk_mul_f32 v[186:187], v[0:1], v[186:187] op_sel_hi:[0,1]
	v_pk_mul_f32 v[180:181], v[0:1], v[180:181] op_sel_hi:[0,1]
	v_pk_fma_f32 v[180:181], v[198:199], v[180:181], v[206:207]
	v_pk_fma_f32 v[186:187], v[200:201], v[186:187], v[208:209]
	v_pk_fma_f32 v[106:107], v[180:181], s[2:3], v[106:107] op_sel_hi:[1,0,1]
	v_pk_fma_f32 v[108:109], v[186:187], s[2:3], v[108:109] op_sel_hi:[1,0,1]
	v_add_f32_e32 v180, v106, v107
	v_add_f32_e32 v181, v108, v109
	v_add_f32_e32 v178, 0, v178
	v_add_f32_e32 v180, v180, v181
	v_add_f32_e32 v178, v178, v180
	v_mul_f32_e32 v180, v107, v107
	v_mul_f32_e32 v181, v109, v109
	s_nop 0
	s_nop 1
	v_bfe_u32 v187, v227, 4, 2
	v_sub_u32_e32 v186, 0, v187
	v_lshlrev_b32_e32 v186, 4, v186
	v_ashrrev_i32_e32 v187, 31, v186
	v_lshl_add_u64 v[186:187], v[182:183], 0, v[186:187]
	v_permlane16_swap_b32_e32 v110, v106
	v_permlane16_swap_b32_e32 v111, v107
	v_permlane16_swap_b32_e32 v112, v108
	v_permlane16_swap_b32_e32 v113, v109
	v_permlane32_swap_b32_e32 v110, v106
	v_permlane32_swap_b32_e32 v111, v107
	v_permlane32_swap_b32_e32 v112, v108
	v_permlane32_swap_b32_e32 v113, v109
	global_store_dwordx4 v[186:187], v[110:113], off
	global_store_dwordx4 v[186:187], v[106:109], off offset:64
	s_nop 1
	v_permlane32_swap_b32_e32 v110, v106
	v_permlane32_swap_b32_e32 v111, v107
	v_permlane32_swap_b32_e32 v112, v108
	v_permlane32_swap_b32_e32 v113, v109
	v_permlane16_swap_b32_e32 v110, v106
	v_permlane16_swap_b32_e32 v111, v107
	v_permlane16_swap_b32_e32 v112, v108
	v_permlane16_swap_b32_e32 v113, v109
	v_fmac_f32_e32 v180, v106, v106
	v_fmac_f32_e32 v181, v108, v108
	v_cvt_pk_bf16_f32 v110, v110, v111
	v_cvt_pk_bf16_f32 v111, v112, v113
	v_cvt_pk_bf16_f32 v112, v106, v107
	v_cvt_pk_bf16_f32 v113, v108, v109
	s_waitcnt vmcnt(6)
	v_sub_f32_e32 v107, v135, v179
	v_sub_f32_e32 v106, v134, v179
	v_sub_f32_e32 v109, v137, v179
	v_sub_f32_e32 v108, v136, v179
	v_pk_mul_f32 v[108:109], v[0:1], v[108:109] op_sel_hi:[0,1]
	v_pk_mul_f32 v[106:107], v[0:1], v[106:107] op_sel_hi:[0,1]
	s_waitcnt vmcnt(2)
; __device__ __forceinline__ float xsum16(float v) { const auto r = __builtin_amdgcn_permlane16_swap(__float_as_uint(v), __float_as_uint(v), false, false); return __uint_as_float(r[0]) + __uint_as_float(r[1]); }
; __device__ __forceinline__ float xsum32(float v) { const auto r = __builtin_amdgcn_permlane32_swap(__float_as_uint(v), __float_as_uint(v), false, false); return __uint_as_float(r[0]) + __uint_as_float(r[1]); }
; __device__ __forceinline__ size_t blk_off(int r, int c, int K) { return (size_t)(r >> 8) * 256 * K + (size_t)(c >> 6) * (256 * 64) + (size_t)((r & 255) * 64 + (c & 63)); }
; __device__ __forceinline__ u32x4 pack8(const f32x4 a, const f32x4 b) { u32x4 w; w.x = cvt_pk_bf16(a[0], a[1]); w.y = cvt_pk_bf16(a[2], a[3]); w.z = cvt_pk_bf16(b[0], b[1]); w.w = cvt_pk_bf16(b[2], b[3]); return w; }
;     __device__ __forceinline__ void operator()(const f32x4 (&acc)[2][2][4][2], const pg8::Unit& u, int wr, int wc, int fr, int fq) const {
;     ...
;             for (int m = 0; m < 4; ++m) { const int row = row0 + ai * 128 + m * 16; const float mu = mu4[m], rs = rs4[m];
;                 f32x4 yv[2][2], gq[2][2], bq_[2][2];
; #pragma unroll
;                 for (int bj = 0; bj < 2; ++bj)
; #pragma unroll
;                     for (int n = 0; n < 2; ++n) { yv[bj][n] = *(const f32x4*)(Yin + (size_t)row * D_ + col0 + bj * 128 + 4 * n); gq[bj][n] = *(const f32x4*)(g + col0 + bj * 128 + 4 * n); bq_[bj][n] = *(const f32x4*)(b + col0 + bj * 128 + 4 * n); }
;                 asm volatile("" ::: "memory");
;                 float s1 = 0.f, s2 = 0.f;
; #pragma unroll
;                 for (int bj = 0; bj < 2; ++bj) { float* yp = Y + (size_t)row * D_ + col0 + bj * 128; f32x4 v[2];
; #pragma unroll
;                     for (int n = 0; n < 2; ++n) { v[n] = (((yv[bj][n] - mu) * rs) * gq[bj][n] + bq_[bj][n]) * ALPHA_ + acc[ai][bj][m][n] * sc;
;                         *(f32x4*)(yp + 4 * n) = v[n]; s1 += (v[n][0] + v[n][1]) + (v[n][2] + v[n][3]); s2 += (v[n][0] * v[n][0] + v[n][1] * v[n][1]) + (v[n][2] * v[n][2] + v[n][3] * v[n][3]); }
;                     *(u32x4*)(Yb + blk_off(row, col0 + bj * 128, D_)) = pack8(v[0], v[1]); }
;                 s1 = xsum32(xsum16(s1)); s2 = xsum32(xsum16(s2));
;                 if (fq == 0) *(f32x2*)(stn + (size_t)row * 32 + (u.pn * 4 + wc) * 2) = (f32x2){s1, s2}; asm volatile("" ::: "memory"); } }
	v_pk_fma_f32 v[106:107], v[126:127], v[106:107], v[130:131]
	v_pk_fma_f32 v[108:109], v[128:129], v[108:109], v[132:133]
	v_pk_fma_f32 v[102:103], v[106:107], s[2:3], v[102:103] op_sel_hi:[1,0,1]
	v_pk_fma_f32 v[104:105], v[108:109], s[2:3], v[104:105] op_sel_hi:[1,0,1]
	v_add_f32_e32 v106, v102, v103
	v_add_f32_e32 v107, v104, v105
	v_add_f32_e32 v106, v106, v107
	global_store_dwordx4 v159, v[110:113], s[42:43]
	v_mul_f32_e32 v107, v105, v105
	v_add_f32_e32 v180, v180, v181
	v_add_f32_e32 v110, v178, v106
	v_mul_f32_e32 v106, v103, v103
	v_fmac_f32_e32 v106, v102, v102
	v_fmac_f32_e32 v107, v104, v104
	v_add_f32_e32 v180, v190, v180
	v_add_f32_e32 v106, v106, v107
	v_add_f32_e32 v111, v180, v106
	v_sub_f32_e32 v107, v115, v179
	v_sub_f32_e32 v106, v114, v179
	v_sub_f32_e32 v109, v117, v179
	v_sub_f32_e32 v108, v116, v179
	v_pk_mul_f32 v[108:109], v[0:1], v[108:109] op_sel_hi:[0,1]
	v_pk_mul_f32 v[106:107], v[0:1], v[106:107] op_sel_hi:[0,1]
	v_pk_fma_f32 v[106:107], v[118:119], v[106:107], v[122:123]
	v_pk_fma_f32 v[108:109], v[120:121], v[108:109], v[124:125]
	v_pk_fma_f32 v[98:99], v[106:107], s[2:3], v[98:99] op_sel_hi:[1,0,1]
	v_pk_fma_f32 v[100:101], v[108:109], s[2:3], v[100:101] op_sel_hi:[1,0,1]
	v_add_f32_e32 v0, v98, v99
	v_add_f32_e32 v106, v100, v101
	v_add_f32_e32 v0, v0, v106
	v_mul_f32_e32 v106, v99, v99
	v_mul_f32_e32 v107, v101, v101
	v_add_f32_e32 v0, v110, v0
	v_fmac_f32_e32 v106, v98, v98
	v_fmac_f32_e32 v107, v100, v100
	s_nop 0
	s_nop 1
	v_bfe_u32 v109, v227, 4, 2
	v_sub_u32_e32 v108, 0, v109
	v_lshlrev_b32_e32 v108, 4, v108
	v_ashrrev_i32_e32 v109, 31, v108
	v_lshl_add_u64 v[108:109], v[182:183], 0, v[108:109]
	v_permlane16_swap_b32_e32 v102, v98
	v_permlane16_swap_b32_e32 v103, v99
	v_permlane16_swap_b32_e32 v104, v100
	v_permlane16_swap_b32_e32 v105, v101
	v_permlane32_swap_b32_e32 v102, v98
	v_permlane32_swap_b32_e32 v103, v99
	v_permlane32_swap_b32_e32 v104, v100
	v_permlane32_swap_b32_e32 v105, v101
	global_store_dwordx4 v[108:109], v[102:105], off offset:512
	global_store_dwordx4 v[108:109], v[98:101], off offset:576
	s_nop 1
	v_permlane32_swap_b32_e32 v102, v98
	v_permlane32_swap_b32_e32 v103, v99
	v_permlane32_swap_b32_e32 v104, v100
	v_permlane32_swap_b32_e32 v105, v101
	v_permlane16_swap_b32_e32 v102, v98
	v_permlane16_swap_b32_e32 v103, v99
	v_permlane16_swap_b32_e32 v104, v100
	v_permlane16_swap_b32_e32 v105, v101
	v_add_f32_e32 v106, v106, v107
	v_cvt_pk_bf16_f32 v102, v102, v103
	v_cvt_pk_bf16_f32 v103, v104, v105
	v_cvt_pk_bf16_f32 v104, v98, v99
	v_mov_b32_e32 v98, v0
	v_add_f32_e32 v106, v111, v106
	s_nop 0
	v_permlane16_swap_b32_e32 v0, v98
	v_add_f32_e32 v98, v0, v98
	v_mov_b32_e32 v0, v106
	s_nop 1
	v_permlane16_swap_b32_e32 v106, v0
	v_add_f32_e32 v99, v106, v0
	v_cvt_pk_bf16_f32 v105, v100, v101
	v_mov_b32_e32 v100, v98
	v_mov_b32_e32 v101, v99
	s_nop 0
	v_permlane32_swap_b32_e32 v98, v100
	v_permlane32_swap_b32_e32 v99, v101
	global_store_dwordx4 v159, v[102:105], s[40:41]
	s_and_saveexec_b64 s[26:27], s[44:45]
	s_cbranch_execz .LBB0_1539
	v_pk_add_f32 v[98:99], v[98:99], v[100:101]
	v_lshl_add_u64 v[100:101], s[6:7], 0, v[172:173]
	v_lshl_add_u64 v[100:101], s[52:53], 2, v[100:101]
	global_store_dwordx2 v[100:101], v[98:99], off
.LBB0_1539:
	s_or_b64 exec, exec, s[26:27]
	v_pk_add_f32 v[98:99], v[174:175], v[176:177]
	s_mov_b32 s2, 0x3a800000
	v_pk_mul_f32 v[122:123], v[98:99], s[2:3] op_sel_hi:[1,0]
	s_mov_b32 s1, 0x800000
	v_fma_f32 v0, -v123, v123, v122
	v_max_f32_e32 v0, 0, v0
	v_add_f32_e32 v0, 0x3727c5ac, v0
	v_cmp_gt_f32_e32 vcc, s1, v0
	v_mul_f32_e32 v98, 0x4b800000, v0
	s_load_dwordx16 s[64:79], s[34:35], 0x38
	v_cndmask_b32_e32 v0, v0, v98, vcc
	v_rsq_f32_e32 v0, v0
	s_mov_b32 s2, 0x3fd744fd
	v_lshlrev_b32_e32 v122, 6, v170
	v_mul_f32_e32 v98, 0x45800000, v0
	v_cndmask_b32_e32 v0, v0, v98, vcc
	v_lshlrev_b64 v[98:99], 12, v[170:171]
	s_waitcnt lgkmcnt(0)
	v_lshl_add_u64 v[98:99], s[78:79], 0, v[98:99]
	v_lshl_add_u64 v[124:125], v[152:153], 2, v[98:99]
	global_load_dwordx4 v[126:129], v[124:125], off offset:16
	global_load_dwordx4 v[130:133], v[124:125], off
	global_load_dwordx4 v[134:137], v[156:157], off offset:16
	global_load_dwordx4 v[172:175], v[156:157], off
	global_load_dwordx4 v[176:179], v[154:155], off offset:16
	global_load_dwordx4 v[180:183], v[154:155], off
	global_load_dwordx4 v[98:101], v[124:125], off offset:528
	global_load_dwordx4 v[118:121], v[124:125], off offset:512
	global_load_dwordx4 v[102:105], v[156:157], off offset:528
	global_load_dwordx4 v[110:113], v[156:157], off offset:512
	global_load_dwordx4 v[106:109], v[154:155], off offset:528
	global_load_dwordx4 v[114:117], v[154:155], off offset:512
	s_movk_i32 s1, 0x3bc0
	v_and_or_b32 v122, v122, s1, v196
	v_lshlrev_b32_e32 v122, 1, v122
	s_waitcnt vmcnt(11)
	v_sub_f32_e32 v127, v127, v123
	s_waitcnt vmcnt(10)
	v_sub_f32_e32 v131, v131, v123
	v_sub_f32_e32 v130, v130, v123
	v_sub_f32_e32 v133, v133, v123
	v_sub_f32_e32 v132, v132, v123
	v_sub_f32_e32 v126, v126, v123
	v_sub_f32_e32 v129, v129, v123
	v_sub_f32_e32 v128, v128, v123
	v_pk_mul_f32 v[132:133], v[0:1], v[132:133] op_sel_hi:[0,1]
	v_pk_mul_f32 v[130:131], v[0:1], v[130:131] op_sel_hi:[0,1]
	v_pk_mul_f32 v[128:129], v[0:1], v[128:129] op_sel_hi:[0,1]
	v_pk_mul_f32 v[126:127], v[0:1], v[126:127] op_sel_hi:[0,1]
	s_waitcnt vmcnt(6)
; __device__ __forceinline__ float xsum16(float v) { const auto r = __builtin_amdgcn_permlane16_swap(__float_as_uint(v), __float_as_uint(v), false, false); return __uint_as_float(r[0]) + __uint_as_float(r[1]); }
; __device__ __forceinline__ float xsum32(float v) { const auto r = __builtin_amdgcn_permlane32_swap(__float_as_uint(v), __float_as_uint(v), false, false); return __uint_as_float(r[0]) + __uint_as_float(r[1]); }
; __device__ __forceinline__ size_t blk_off(int r, int c, int K) { return (size_t)(r >> 8) * 256 * K + (size_t)(c >> 6) * (256 * 64) + (size_t)((r & 255) * 64 + (c & 63)); }
; __device__ __forceinline__ u32x4 pack8(const f32x4 a, const f32x4 b) { u32x4 w; w.x = cvt_pk_bf16(a[0], a[1]); w.y = cvt_pk_bf16(a[2], a[3]); w.z = cvt_pk_bf16(b[0], b[1]); w.w = cvt_pk_bf16(b[2], b[3]); return w; }
;     __device__ __forceinline__ void operator()(const f32x4 (&acc)[2][2][4][2], const pg8::Unit& u, int wr, int wc, int fr, int fq) const {
;     ...
;                     for (int n = 0; n < 2; ++n) { yv[bj][n] = *(const f32x4*)(Yin + (size_t)row * D_ + col0 + bj * 128 + 4 * n); gq[bj][n] = *(const f32x4*)(g + col0 + bj * 128 + 4 * n); bq_[bj][n] = *(const f32x4*)(b + col0 + bj * 128 + 4 * n); }
;                 asm volatile("" ::: "memory");
;                 float s1 = 0.f, s2 = 0.f;
; #pragma unroll
;                 for (int bj = 0; bj < 2; ++bj) { float* yp = Y + (size_t)row * D_ + col0 + bj * 128; f32x4 v[2];
; #pragma unroll
;                     for (int n = 0; n < 2; ++n) { v[n] = (((yv[bj][n] - mu) * rs) * gq[bj][n] + bq_[bj][n]) * ALPHA_ + acc[ai][bj][m][n] * sc;
;                         *(f32x4*)(yp + 4 * n) = v[n]; s1 += (v[n][0] + v[n][1]) + (v[n][2] + v[n][3]); s2 += (v[n][0] * v[n][0] + v[n][1] * v[n][1]) + (v[n][2] * v[n][2] + v[n][3] * v[n][3]); }
;                     *(u32x4*)(Yb + blk_off(row, col0 + bj * 128, D_)) = pack8(v[0], v[1]); }
;                 s1 = xsum32(xsum16(s1)); s2 = xsum32(xsum16(s2));
;                 if (fq == 0) *(f32x2*)(stn + (size_t)row * 32 + (u.pn * 4 + wc) * 2) = (f32x2){s1, s2}; asm volatile("" ::: "memory"); } }
	v_pk_fma_f32 v[130:131], v[172:173], v[130:131], v[180:181]
	v_pk_fma_f32 v[132:133], v[174:175], v[132:133], v[182:183]
	v_pk_fma_f32 v[126:127], v[134:135], v[126:127], v[176:177]
	v_pk_fma_f32 v[128:129], v[136:137], v[128:129], v[178:179]
	v_pk_fma_f32 v[96:97], v[132:133], s[2:3], v[96:97] op_sel_hi:[1,0,1]
	v_pk_fma_f32 v[94:95], v[130:131], s[2:3], v[94:95] op_sel_hi:[1,0,1]
	v_pk_fma_f32 v[92:93], v[128:129], s[2:3], v[92:93] op_sel_hi:[1,0,1]
	v_pk_fma_f32 v[90:91], v[126:127], s[2:3], v[90:91] op_sel_hi:[1,0,1]
	v_add_f32_e32 v130, v94, v95
	v_add_f32_e32 v131, v96, v97
	v_add_f32_e32 v126, v90, v91
	v_add_f32_e32 v127, v92, v93
	v_add_f32_e32 v130, v130, v131
	v_mul_f32_e32 v131, v95, v95
	v_mul_f32_e32 v132, v97, v97
	v_add_f32_e32 v126, v126, v127
	v_mul_f32_e32 v127, v91, v91
	v_mul_f32_e32 v128, v93, v93
	s_nop 0
	v_fmac_f32_e32 v131, v94, v94
	v_fmac_f32_e32 v132, v96, v96
	s_nop 1
	v_bfe_u32 v135, v227, 4, 2
	v_sub_u32_e32 v134, 0, v135
	v_lshlrev_b32_e32 v134, 4, v134
	v_ashrrev_i32_e32 v135, 31, v134
	v_lshl_add_u64 v[134:135], v[124:125], 0, v[134:135]
	v_permlane16_swap_b32_e32 v94, v90
	v_permlane16_swap_b32_e32 v95, v91
	v_permlane16_swap_b32_e32 v96, v92
	v_permlane16_swap_b32_e32 v97, v93
	v_permlane32_swap_b32_e32 v94, v90
	v_permlane32_swap_b32_e32 v95, v91
	v_permlane32_swap_b32_e32 v96, v92
	v_permlane32_swap_b32_e32 v97, v93
	global_store_dwordx4 v[134:135], v[94:97], off
	global_store_dwordx4 v[134:135], v[90:93], off offset:64
	s_nop 1
	v_permlane32_swap_b32_e32 v94, v90
	v_permlane32_swap_b32_e32 v95, v91
	v_permlane32_swap_b32_e32 v96, v92
	v_permlane32_swap_b32_e32 v97, v93
	v_permlane16_swap_b32_e32 v94, v90
	v_permlane16_swap_b32_e32 v95, v91
	v_permlane16_swap_b32_e32 v96, v92
	v_permlane16_swap_b32_e32 v97, v93
	v_fmac_f32_e32 v127, v90, v90
	v_fmac_f32_e32 v128, v92, v92
	v_cvt_pk_bf16_f32 v94, v94, v95
	v_cvt_pk_bf16_f32 v95, v96, v97
	v_cvt_pk_bf16_f32 v96, v90, v91
	v_cvt_pk_bf16_f32 v97, v92, v93
	s_waitcnt vmcnt(6)
	v_sub_f32_e32 v91, v119, v123
	v_sub_f32_e32 v90, v118, v123
	v_sub_f32_e32 v93, v121, v123
	v_sub_f32_e32 v92, v120, v123
	v_pk_mul_f32 v[92:93], v[0:1], v[92:93] op_sel_hi:[0,1]
	v_pk_mul_f32 v[90:91], v[0:1], v[90:91] op_sel_hi:[0,1]
	s_waitcnt vmcnt(2)
	v_pk_fma_f32 v[90:91], v[110:111], v[90:91], v[114:115]
	v_pk_fma_f32 v[92:93], v[112:113], v[92:93], v[116:117]
	v_pk_fma_f32 v[86:87], v[90:91], s[2:3], v[86:87] op_sel_hi:[1,0,1]
	v_pk_fma_f32 v[88:89], v[92:93], s[2:3], v[88:89] op_sel_hi:[1,0,1]
	v_add_f32_e32 v130, 0, v130
	v_add_f32_e32 v90, v86, v87
	v_add_f32_e32 v91, v88, v89
	v_add_f32_e32 v126, v130, v126
	v_add_f32_e32 v90, v90, v91
	global_store_dwordx4 v122, v[94:97], s[42:43]
	v_mul_f32_e32 v91, v89, v89
	v_add_f32_e32 v131, v131, v132
	v_add_f32_e32 v94, v126, v90
	v_mul_f32_e32 v90, v87, v87
	v_add_f32_e32 v127, v127, v128
	v_fmac_f32_e32 v90, v86, v86
	v_fmac_f32_e32 v91, v88, v88
	v_add_f32_e32 v127, v131, v127
	v_add_f32_e32 v90, v90, v91
	v_add_f32_e32 v95, v127, v90
	v_sub_f32_e32 v91, v99, v123
	v_sub_f32_e32 v90, v98, v123
	v_sub_f32_e32 v93, v101, v123
	v_sub_f32_e32 v92, v100, v123
	v_pk_mul_f32 v[92:93], v[0:1], v[92:93] op_sel_hi:[0,1]
	v_pk_mul_f32 v[90:91], v[0:1], v[90:91] op_sel_hi:[0,1]
	v_pk_fma_f32 v[90:91], v[102:103], v[90:91], v[106:107]
	v_pk_fma_f32 v[92:93], v[104:105], v[92:93], v[108:109]
	v_pk_fma_f32 v[82:83], v[90:91], s[2:3], v[82:83] op_sel_hi:[1,0,1]
	v_pk_fma_f32 v[84:85], v[92:93], s[2:3], v[84:85] op_sel_hi:[1,0,1]
	v_add_f32_e32 v0, v82, v83
	v_add_f32_e32 v90, v84, v85
	v_add_f32_e32 v0, v0, v90
	v_mul_f32_e32 v90, v83, v83
	v_mul_f32_e32 v91, v85, v85
	v_add_f32_e32 v0, v94, v0
	v_fmac_f32_e32 v90, v82, v82
	v_fmac_f32_e32 v91, v84, v84
	s_nop 0
	s_nop 1
	v_bfe_u32 v93, v227, 4, 2
	v_sub_u32_e32 v92, 0, v93
	v_lshlrev_b32_e32 v92, 4, v92
	v_ashrrev_i32_e32 v93, 31, v92
	v_lshl_add_u64 v[92:93], v[124:125], 0, v[92:93]
	v_permlane16_swap_b32_e32 v86, v82
	v_permlane16_swap_b32_e32 v87, v83
	v_permlane16_swap_b32_e32 v88, v84
	v_permlane16_swap_b32_e32 v89, v85
	v_permlane32_swap_b32_e32 v86, v82
	v_permlane32_swap_b32_e32 v87, v83
	v_permlane32_swap_b32_e32 v88, v84
	v_permlane32_swap_b32_e32 v89, v85
	global_store_dwordx4 v[92:93], v[86:89], off offset:512
	global_store_dwordx4 v[92:93], v[82:85], off offset:576
	s_nop 1
	v_permlane32_swap_b32_e32 v86, v82
	v_permlane32_swap_b32_e32 v87, v83
	v_permlane32_swap_b32_e32 v88, v84
	v_permlane32_swap_b32_e32 v89, v85
	v_permlane16_swap_b32_e32 v86, v82
	v_permlane16_swap_b32_e32 v87, v83
	v_permlane16_swap_b32_e32 v88, v84
	v_permlane16_swap_b32_e32 v89, v85
	v_add_f32_e32 v90, v90, v91
	v_cvt_pk_bf16_f32 v86, v86, v87
	v_cvt_pk_bf16_f32 v87, v88, v89
	v_cvt_pk_bf16_f32 v88, v82, v83
	v_mov_b32_e32 v82, v0
	v_add_f32_e32 v90, v95, v90
	s_nop 0
	v_permlane16_swap_b32_e32 v0, v82
	v_add_f32_e32 v82, v0, v82
	v_mov_b32_e32 v0, v90
	s_nop 1
	v_permlane16_swap_b32_e32 v90, v0
	v_add_f32_e32 v83, v90, v0
	v_cvt_pk_bf16_f32 v89, v84, v85
	v_mov_b32_e32 v84, v82
	v_mov_b32_e32 v85, v83
	s_nop 0
	v_permlane32_swap_b32_e32 v82, v84
	v_permlane32_swap_b32_e32 v83, v85
	global_store_dwordx4 v122, v[86:89], s[40:41]
	s_and_saveexec_b64 s[26:27], s[44:45]
	s_cbranch_execz .LBB0_1541
	v_pk_add_f32 v[82:83], v[82:83], v[84:85]
	v_lshl_add_u64 v[84:85], s[6:7], 0, v[164:165]
	v_lshl_add_u64 v[84:85], s[52:53], 2, v[84:85]
	global_store_dwordx2 v[84:85], v[82:83], off
; __device__ __forceinline__ size_t blk_off(int r, int c, int K) { return (size_t)(r >> 8) * 256 * K + (size_t)(c >> 6) * (256 * 64) + (size_t)((r & 255) * 64 + (c & 63)); }
; __device__ __forceinline__ u32x4 pack8(const f32x4 a, const f32x4 b) { u32x4 w; w.x = cvt_pk_bf16(a[0], a[1]); w.y = cvt_pk_bf16(a[2], a[3]); w.z = cvt_pk_bf16(b[0], b[1]); w.w = cvt_pk_bf16(b[2], b[3]); return w; }
;     __device__ __forceinline__ void operator()(const f32x4 (&acc)[2][2][4][2], const pg8::Unit& u, int wr, int wc, int fr, int fq) const {
;     ...
;             for (int m = 0; m < 4; ++m) { const int row = row0 + ai * 128 + m * 16; const float mu = mu4[m], rs = rs4[m];
;                 f32x4 yv[2][2], gq[2][2], bq_[2][2];
; #pragma unroll
;                 for (int bj = 0; bj < 2; ++bj)
; #pragma unroll
;                     for (int n = 0; n < 2; ++n) { yv[bj][n] = *(const f32x4*)(Yin + (size_t)row * D_ + col0 + bj * 128 + 4 * n); gq[bj][n] = *(const f32x4*)(g + col0 + bj * 128 + 4 * n); bq_[bj][n] = *(const f32x4*)(b + col0 + bj * 128 + 4 * n); }
;                 asm volatile("" ::: "memory");
;                 float s1 = 0.f, s2 = 0.f;
; #pragma unroll
;                 for (int bj = 0; bj < 2; ++bj) { float* yp = Y + (size_t)row * D_ + col0 + bj * 128; f32x4 v[2];
; #pragma unroll
;                     for (int n = 0; n < 2; ++n) { v[n] = (((yv[bj][n] - mu) * rs) * gq[bj][n] + bq_[bj][n]) * ALPHA_ + acc[ai][bj][m][n] * sc;
;                         *(f32x4*)(yp + 4 * n) = v[n]; s1 += (v[n][0] + v[n][1]) + (v[n][2] + v[n][3]); s2 += (v[n][0] * v[n][0] + v[n][1] * v[n][1]) + (v[n][2] * v[n][2] + v[n][3] * v[n][3]); }
;                     *(u32x4*)(Yb + blk_off(row, col0 + bj * 128, D_)) = pack8(v[0], v[1]); }
.LBB0_1541:
	s_or_b64 exec, exec, s[26:27]
	v_pk_add_f32 v[82:83], v[166:167], v[168:169]
	s_mov_b32 s2, 0x3a800000
	v_pk_mul_f32 v[106:107], v[82:83], s[2:3] op_sel_hi:[1,0]
	s_mov_b32 s1, 0x800000
	v_fma_f32 v0, -v107, v107, v106
	v_max_f32_e32 v0, 0, v0
	v_add_f32_e32 v0, 0x3727c5ac, v0
	v_cmp_gt_f32_e32 vcc, s1, v0
	v_mul_f32_e32 v82, 0x4b800000, v0
	s_load_dwordx16 s[64:79], s[34:35], 0x38
	v_cndmask_b32_e32 v0, v0, v82, vcc
	v_rsq_f32_e32 v0, v0
	s_mov_b32 s2, 0x3fd744fd
	v_lshlrev_b32_e32 v106, 6, v162
	v_mul_f32_e32 v82, 0x45800000, v0
	v_cndmask_b32_e32 v0, v0, v82, vcc
	v_lshlrev_b64 v[82:83], 12, v[162:163]
	s_waitcnt lgkmcnt(0)
	v_lshl_add_u64 v[82:83], s[78:79], 0, v[82:83]
	v_lshl_add_u64 v[108:109], v[152:153], 2, v[82:83]
	global_load_dwordx4 v[110:113], v[108:109], off offset:16
	global_load_dwordx4 v[114:117], v[108:109], off
	global_load_dwordx4 v[118:121], v[156:157], off offset:16
	global_load_dwordx4 v[122:125], v[156:157], off
	global_load_dwordx4 v[126:129], v[154:155], off offset:16
	global_load_dwordx4 v[130:133], v[154:155], off
	global_load_dwordx4 v[82:85], v[108:109], off offset:528
	global_load_dwordx4 v[102:105], v[108:109], off offset:512
	global_load_dwordx4 v[86:89], v[156:157], off offset:528
	global_load_dwordx4 v[94:97], v[156:157], off offset:512
	global_load_dwordx4 v[90:93], v[154:155], off offset:528
	global_load_dwordx4 v[98:101], v[154:155], off offset:512
	s_movk_i32 s1, 0x3fc0
	v_and_or_b32 v106, v106, s1, v196
	v_lshlrev_b32_e32 v106, 1, v106
	s_waitcnt vmcnt(11)
	v_sub_f32_e32 v111, v111, v107
	s_waitcnt vmcnt(10)
	v_sub_f32_e32 v115, v115, v107
	v_sub_f32_e32 v114, v114, v107
	v_sub_f32_e32 v117, v117, v107
	v_sub_f32_e32 v116, v116, v107
	v_sub_f32_e32 v110, v110, v107
	v_sub_f32_e32 v113, v113, v107
	v_sub_f32_e32 v112, v112, v107
	v_pk_mul_f32 v[116:117], v[0:1], v[116:117] op_sel_hi:[0,1]
	v_pk_mul_f32 v[114:115], v[0:1], v[114:115] op_sel_hi:[0,1]
	v_pk_mul_f32 v[112:113], v[0:1], v[112:113] op_sel_hi:[0,1]
	v_pk_mul_f32 v[110:111], v[0:1], v[110:111] op_sel_hi:[0,1]
	s_waitcnt vmcnt(6)
	v_pk_fma_f32 v[114:115], v[122:123], v[114:115], v[130:131]
	v_pk_fma_f32 v[116:117], v[124:125], v[116:117], v[132:133]
	v_pk_fma_f32 v[110:111], v[118:119], v[110:111], v[126:127]
	v_pk_fma_f32 v[112:113], v[120:121], v[112:113], v[128:129]
	v_pk_fma_f32 v[80:81], v[116:117], s[2:3], v[80:81] op_sel_hi:[1,0,1]
	v_pk_fma_f32 v[78:79], v[114:115], s[2:3], v[78:79] op_sel_hi:[1,0,1]
	v_pk_fma_f32 v[76:77], v[112:113], s[2:3], v[76:77] op_sel_hi:[1,0,1]
	v_pk_fma_f32 v[74:75], v[110:111], s[2:3], v[74:75] op_sel_hi:[1,0,1]
	v_add_f32_e32 v114, v78, v79
	v_add_f32_e32 v115, v80, v81
	v_add_f32_e32 v110, v74, v75
	v_add_f32_e32 v111, v76, v77
	v_add_f32_e32 v114, v114, v115
	v_mul_f32_e32 v115, v79, v79
	v_mul_f32_e32 v116, v81, v81
	v_add_f32_e32 v110, v110, v111
	v_mul_f32_e32 v111, v75, v75
	v_mul_f32_e32 v112, v77, v77
	s_nop 0
	v_fmac_f32_e32 v115, v78, v78
	v_fmac_f32_e32 v116, v80, v80
	s_nop 1
	v_bfe_u32 v119, v227, 4, 2
	v_sub_u32_e32 v118, 0, v119
	v_lshlrev_b32_e32 v118, 4, v118
	v_ashrrev_i32_e32 v119, 31, v118
	v_lshl_add_u64 v[118:119], v[108:109], 0, v[118:119]
	v_permlane16_swap_b32_e32 v78, v74
	v_permlane16_swap_b32_e32 v79, v75
	v_permlane16_swap_b32_e32 v80, v76
	v_permlane16_swap_b32_e32 v81, v77
	v_permlane32_swap_b32_e32 v78, v74
	v_permlane32_swap_b32_e32 v79, v75
	v_permlane32_swap_b32_e32 v80, v76
	v_permlane32_swap_b32_e32 v81, v77
	global_store_dwordx4 v[118:119], v[78:81], off
	global_store_dwordx4 v[118:119], v[74:77], off offset:64
	s_nop 1
	v_permlane32_swap_b32_e32 v78, v74
	v_permlane32_swap_b32_e32 v79, v75
	v_permlane32_swap_b32_e32 v80, v76
	v_permlane32_swap_b32_e32 v81, v77
	v_permlane16_swap_b32_e32 v78, v74
	v_permlane16_swap_b32_e32 v79, v75
	v_permlane16_swap_b32_e32 v80, v76
	v_permlane16_swap_b32_e32 v81, v77
	v_fmac_f32_e32 v111, v74, v74
	v_fmac_f32_e32 v112, v76, v76
	v_cvt_pk_bf16_f32 v78, v78, v79
	v_cvt_pk_bf16_f32 v79, v80, v81
	v_cvt_pk_bf16_f32 v80, v74, v75
	v_cvt_pk_bf16_f32 v81, v76, v77
	s_waitcnt vmcnt(6)
	v_sub_f32_e32 v75, v103, v107
	v_sub_f32_e32 v74, v102, v107
	v_sub_f32_e32 v77, v105, v107
	v_sub_f32_e32 v76, v104, v107
	v_pk_mul_f32 v[76:77], v[0:1], v[76:77] op_sel_hi:[0,1]
	v_pk_mul_f32 v[74:75], v[0:1], v[74:75] op_sel_hi:[0,1]
	s_waitcnt vmcnt(2)
; __device__ __forceinline__ float xsum16(float v) { const auto r = __builtin_amdgcn_permlane16_swap(__float_as_uint(v), __float_as_uint(v), false, false); return __uint_as_float(r[0]) + __uint_as_float(r[1]); }
; __device__ __forceinline__ float xsum32(float v) { const auto r = __builtin_amdgcn_permlane32_swap(__float_as_uint(v), __float_as_uint(v), false, false); return __uint_as_float(r[0]) + __uint_as_float(r[1]); }
; __device__ __forceinline__ void row_stats4(const float* st, int rowb, int fq, float (&mu)[4], float (&rs)[4]) {
;     ...
;     for (int m = 0; m < 4; ++m) { const f32x4* p = (const f32x4*)(st + (size_t)(rowb + m * 16) * 32 + fq * 8); a[m] = p[0]; b[m] = p[1]; }
; #pragma unroll
;     for (int m = 0; m < 4; ++m) { float s1 = (a[m][0] + a[m][2]) + (b[m][0] + b[m][2]), s2 = (a[m][1] + a[m][3]) + (b[m][1] + b[m][3]);
;         s1 = xsum32(xsum16(s1)); s2 = xsum32(xsum16(s2));
;         const float mm = s1 * (1.0f / 1024.0f); mu[m] = mm; rs[m] = rsqrtf(fmaxf(s2 * (1.0f / 1024.0f) - mm * mm, 0.f) + LN_EPS_); }
;     __device__ __forceinline__ void operator()(const f32x4 (&acc)[2][2][4][2], const pg8::Unit& u, int wr, int wc, int fr, int fq) const {
;     ...
;                     for (int n = 0; n < 2; ++n) { yv[bj][n] = *(const f32x4*)(Yin + (size_t)row * D_ + col0 + bj * 128 + 4 * n); gq[bj][n] = *(const f32x4*)(g + col0 + bj * 128 + 4 * n); bq_[bj][n] = *(const f32x4*)(b + col0 + bj * 128 + 4 * n); }
;                 asm volatile("" ::: "memory");
;                 float s1 = 0.f, s2 = 0.f;
; #pragma unroll
;                 for (int bj = 0; bj < 2; ++bj) { float* yp = Y + (size_t)row * D_ + col0 + bj * 128; f32x4 v[2];
; #pragma unroll
;                     for (int n = 0; n < 2; ++n) { v[n] = (((yv[bj][n] - mu) * rs) * gq[bj][n] + bq_[bj][n]) * ALPHA_ + acc[ai][bj][m][n] * sc;
;                         *(f32x4*)(yp + 4 * n) = v[n]; s1 += (v[n][0] + v[n][1]) + (v[n][2] + v[n][3]); s2 += (v[n][0] * v[n][0] + v[n][1] * v[n][1]) + (v[n][2] * v[n][2] + v[n][3] * v[n][3]); }
;                     *(u32x4*)(Yb + blk_off(row, col0 + bj * 128, D_)) = pack8(v[0], v[1]); }
;                 s1 = xsum32(xsum16(s1)); s2 = xsum32(xsum16(s2));
;                 if (fq == 0) *(f32x2*)(stn + (size_t)row * 32 + (u.pn * 4 + wc) * 2) = (f32x2){s1, s2}; asm volatile("" ::: "memory"); } }
	v_pk_fma_f32 v[74:75], v[94:95], v[74:75], v[98:99]
	v_pk_fma_f32 v[76:77], v[96:97], v[76:77], v[100:101]
	v_pk_fma_f32 v[70:71], v[74:75], s[2:3], v[70:71] op_sel_hi:[1,0,1]
	v_pk_fma_f32 v[72:73], v[76:77], s[2:3], v[72:73] op_sel_hi:[1,0,1]
	v_add_f32_e32 v114, 0, v114
	v_add_f32_e32 v74, v70, v71
	v_add_f32_e32 v75, v72, v73
	v_add_f32_e32 v110, v114, v110
	v_add_f32_e32 v74, v74, v75
	global_store_dwordx4 v106, v[78:81], s[42:43]
	v_mul_f32_e32 v75, v73, v73
	v_add_f32_e32 v115, v115, v116
	v_add_f32_e32 v78, v110, v74
	v_mul_f32_e32 v74, v71, v71
	v_add_f32_e32 v111, v111, v112
	v_fmac_f32_e32 v74, v70, v70
	v_fmac_f32_e32 v75, v72, v72
	v_add_f32_e32 v111, v115, v111
	v_add_f32_e32 v74, v74, v75
	v_add_f32_e32 v79, v111, v74
	v_sub_f32_e32 v75, v83, v107
	v_sub_f32_e32 v74, v82, v107
	v_sub_f32_e32 v77, v85, v107
	v_sub_f32_e32 v76, v84, v107
	v_pk_mul_f32 v[76:77], v[0:1], v[76:77] op_sel_hi:[0,1]
	v_pk_mul_f32 v[74:75], v[0:1], v[74:75] op_sel_hi:[0,1]
	v_pk_fma_f32 v[74:75], v[86:87], v[74:75], v[90:91]
	v_pk_fma_f32 v[76:77], v[88:89], v[76:77], v[92:93]
	v_pk_fma_f32 v[66:67], v[74:75], s[2:3], v[66:67] op_sel_hi:[1,0,1]
	v_pk_fma_f32 v[68:69], v[76:77], s[2:3], v[68:69] op_sel_hi:[1,0,1]
	v_add_f32_e32 v0, v66, v67
	v_add_f32_e32 v74, v68, v69
	v_add_f32_e32 v0, v0, v74
	v_mul_f32_e32 v74, v67, v67
	v_mul_f32_e32 v75, v69, v69
	v_add_f32_e32 v0, v78, v0
	v_fmac_f32_e32 v74, v66, v66
	v_fmac_f32_e32 v75, v68, v68
	s_nop 0
	s_nop 1
	v_bfe_u32 v77, v227, 4, 2
	v_sub_u32_e32 v76, 0, v77
	v_lshlrev_b32_e32 v76, 4, v76
	v_ashrrev_i32_e32 v77, 31, v76
	v_lshl_add_u64 v[76:77], v[108:109], 0, v[76:77]
	v_permlane16_swap_b32_e32 v70, v66
	v_permlane16_swap_b32_e32 v71, v67
	v_permlane16_swap_b32_e32 v72, v68
	v_permlane16_swap_b32_e32 v73, v69
	v_permlane32_swap_b32_e32 v70, v66
	v_permlane32_swap_b32_e32 v71, v67
	v_permlane32_swap_b32_e32 v72, v68
	v_permlane32_swap_b32_e32 v73, v69
	global_store_dwordx4 v[76:77], v[70:73], off offset:512
	global_store_dwordx4 v[76:77], v[66:69], off offset:576
	s_nop 1
	v_permlane32_swap_b32_e32 v70, v66
	v_permlane32_swap_b32_e32 v71, v67
	v_permlane32_swap_b32_e32 v72, v68
	v_permlane32_swap_b32_e32 v73, v69
	v_permlane16_swap_b32_e32 v70, v66
	v_permlane16_swap_b32_e32 v71, v67
	v_permlane16_swap_b32_e32 v72, v68
	v_permlane16_swap_b32_e32 v73, v69
	v_add_f32_e32 v74, v74, v75
	v_cvt_pk_bf16_f32 v70, v70, v71
	v_cvt_pk_bf16_f32 v71, v72, v73
	v_cvt_pk_bf16_f32 v72, v66, v67
	v_mov_b32_e32 v66, v0
	v_add_f32_e32 v74, v79, v74
	s_nop 0
	v_permlane16_swap_b32_e32 v0, v66
	v_add_f32_e32 v66, v0, v66
	v_mov_b32_e32 v0, v74
	s_nop 1
	v_permlane16_swap_b32_e32 v74, v0
	v_add_f32_e32 v67, v74, v0
	v_cvt_pk_bf16_f32 v73, v68, v69
	v_mov_b32_e32 v68, v66
	v_mov_b32_e32 v69, v67
	s_nop 0
	v_permlane32_swap_b32_e32 v66, v68
	v_permlane32_swap_b32_e32 v67, v69
	global_store_dwordx4 v106, v[70:73], s[40:41]
	s_and_saveexec_b64 s[26:27], s[44:45]
	s_cbranch_execz .LBB0_1543
	v_pk_add_f32 v[66:67], v[66:67], v[68:69]
	v_lshl_add_u64 v[68:69], s[6:7], 0, v[160:161]
	v_lshl_add_u64 v[68:69], s[52:53], 2, v[68:69]
	global_store_dwordx2 v[68:69], v[66:67], off
.LBB0_1543:
	s_or_b64 exec, exec, s[26:27]
	v_add_u32_e32 v118, 0x80, v158
	v_ashrrev_i32_e32 v119, 31, v118
	v_lshlrev_b64 v[110:111], 7, v[118:119]
	v_lshl_add_u64 v[70:71], v[146:147], 0, v[110:111]
	global_load_dwordx4 v[66:69], v[70:71], off
	s_nop 0
	global_load_dwordx4 v[70:73], v[70:71], off offset:16
	v_add_u32_e32 v108, 0x90, v158
	v_ashrrev_i32_e32 v109, 31, v108
	v_lshlrev_b64 v[102:103], 7, v[108:109]
	v_lshl_add_u64 v[78:79], v[146:147], 0, v[102:103]
	global_load_dwordx4 v[74:77], v[78:79], off
	s_nop 0
	global_load_dwordx4 v[78:81], v[78:79], off offset:16
	v_add_u32_e32 v96, 0xa0, v158
	v_ashrrev_i32_e32 v97, 31, v96
	v_lshlrev_b64 v[82:83], 7, v[96:97]
	v_lshl_add_u64 v[86:87], v[146:147], 0, v[82:83]
	global_load_dwordx4 v[82:85], v[86:87], off
	s_nop 0
	global_load_dwordx4 v[86:89], v[86:87], off offset:16
	v_add_u32_e32 v94, 0xb0, v158
	v_ashrrev_i32_e32 v95, 31, v94
	v_lshlrev_b64 v[90:91], 7, v[94:95]
	v_lshl_add_u64 v[98:99], v[146:147], 0, v[90:91]
	global_load_dwordx4 v[90:93], v[98:99], off
	s_nop 0
	global_load_dwordx4 v[98:101], v[98:99], off offset:16
	s_mov_b32 s2, 0x3a800000
	s_mov_b32 s1, 0x800000
	s_load_dwordx16 s[64:79], s[34:35], 0x38
	s_mov_b32 s14, 0x3fd744fd
	s_waitcnt vmcnt(7)
	v_mov_b32_e32 v104, v66
	s_waitcnt vmcnt(6)
	v_mov_b32_e32 v105, v70
	v_mov_b32_e32 v106, v68
	v_mov_b32_e32 v107, v72
	v_pk_add_f32 v[104:105], v[104:105], v[106:107]
	v_mov_b32_e32 v70, v67
	v_pk_add_f32 v[104:105], v[104:105], v[104:105] op_sel:[0,1] op_sel_hi:[1,0]
	v_mov_b32_e32 v72, v69
	v_pk_add_f32 v[66:67], v[70:71], v[72:73]
	v_mov_b32_e32 v0, v104
	v_pk_add_f32 v[66:67], v[66:67], v[66:67] op_sel:[0,1] op_sel_hi:[1,0]
	s_nop 0
	v_permlane16_swap_b32_e32 v104, v0
	v_add_f32_e32 v67, v104, v0
	v_mov_b32_e32 v0, v66
	s_nop 1
	v_permlane16_swap_b32_e32 v66, v0
	v_add_f32_e32 v66, v66, v0
	v_mov_b32_e32 v69, v67
	v_mov_b32_e32 v68, v66
	s_nop 0
	v_permlane32_swap_b32_e32 v67, v69
	v_permlane32_swap_b32_e32 v66, v68
	v_pk_add_f32 v[66:67], v[66:67], v[68:69]
	s_waitcnt vmcnt(5)
	v_mov_b32_e32 v68, v76
	v_pk_mul_f32 v[116:117], v[66:67], s[2:3] op_sel_hi:[1,0]
	s_waitcnt vmcnt(4)
; __device__ __forceinline__ float xsum16(float v) { const auto r = __builtin_amdgcn_permlane16_swap(__float_as_uint(v), __float_as_uint(v), false, false); return __uint_as_float(r[0]) + __uint_as_float(r[1]); }
; __device__ __forceinline__ float xsum32(float v) { const auto r = __builtin_amdgcn_permlane32_swap(__float_as_uint(v), __float_as_uint(v), false, false); return __uint_as_float(r[0]) + __uint_as_float(r[1]); }
; __device__ __forceinline__ size_t blk_off(int r, int c, int K) { return (size_t)(r >> 8) * 256 * K + (size_t)(c >> 6) * (256 * 64) + (size_t)((r & 255) * 64 + (c & 63)); }
; __device__ __forceinline__ void row_stats4(const float* st, int rowb, int fq, float (&mu)[4], float (&rs)[4]) {
;     ...
;     for (int m = 0; m < 4; ++m) { const f32x4* p = (const f32x4*)(st + (size_t)(rowb + m * 16) * 32 + fq * 8); a[m] = p[0]; b[m] = p[1]; }
; #pragma unroll
;     for (int m = 0; m < 4; ++m) { float s1 = (a[m][0] + a[m][2]) + (b[m][0] + b[m][2]), s2 = (a[m][1] + a[m][3]) + (b[m][1] + b[m][3]);
;         s1 = xsum32(xsum16(s1)); s2 = xsum32(xsum16(s2));
;         const float mm = s1 * (1.0f / 1024.0f); mu[m] = mm; rs[m] = rsqrtf(fmaxf(s2 * (1.0f / 1024.0f) - mm * mm, 0.f) + LN_EPS_); }
;     __device__ __forceinline__ void operator()(const f32x4 (&acc)[2][2][4][2], const pg8::Unit& u, int wr, int wc, int fr, int fq) const {
;     ...
;                     for (int n = 0; n < 2; ++n) { yv[bj][n] = *(const f32x4*)(Yin + (size_t)row * D_ + col0 + bj * 128 + 4 * n); gq[bj][n] = *(const f32x4*)(g + col0 + bj * 128 + 4 * n); bq_[bj][n] = *(const f32x4*)(b + col0 + bj * 128 + 4 * n); }
;                 asm volatile("" ::: "memory");
;                 float s1 = 0.f, s2 = 0.f;
; #pragma unroll
;                 for (int bj = 0; bj < 2; ++bj) { float* yp = Y + (size_t)row * D_ + col0 + bj * 128; f32x4 v[2];
; #pragma unroll
;                     for (int n = 0; n < 2; ++n) { v[n] = (((yv[bj][n] - mu) * rs) * gq[bj][n] + bq_[bj][n]) * ALPHA_ + acc[ai][bj][m][n] * sc;
;                         *(f32x4*)(yp + 4 * n) = v[n]; s1 += (v[n][0] + v[n][1]) + (v[n][2] + v[n][3]); s2 += (v[n][0] * v[n][0] + v[n][1] * v[n][1]) + (v[n][2] * v[n][2] + v[n][3] * v[n][3]); }
;                     *(u32x4*)(Yb + blk_off(row, col0 + bj * 128, D_)) = pack8(v[0], v[1]); }
	v_mov_b32_e32 v67, v78
	v_fma_f32 v0, -v117, v117, v116
	v_max_f32_e32 v0, 0, v0
	v_add_f32_e32 v0, 0x3727c5ac, v0
	v_cmp_gt_f32_e32 vcc, s1, v0
	v_mul_f32_e32 v66, 0x4b800000, v0
	v_mov_b32_e32 v69, v80
	v_cndmask_b32_e32 v0, v0, v66, vcc
	v_rsq_f32_e32 v0, v0
	v_mov_b32_e32 v78, v75
	v_mov_b32_e32 v80, v77
	v_readlane_b32 s2, v253, 59
	v_mul_f32_e32 v66, 0x45800000, v0
	v_cndmask_b32_e32 v116, v0, v66, vcc
	v_mov_b32_e32 v66, v74
	v_pk_add_f32 v[66:67], v[66:67], v[68:69]
	v_pk_add_f32 v[68:69], v[78:79], v[80:81]
	v_pk_add_f32 v[66:67], v[66:67], v[66:67] op_sel:[0,1] op_sel_hi:[1,0]
	v_pk_add_f32 v[68:69], v[68:69], v[68:69] op_sel:[0,1] op_sel_hi:[1,0]
	v_mov_b32_e32 v0, v66
	s_nop 1
	v_permlane16_swap_b32_e32 v66, v0
	v_add_f32_e32 v113, v66, v0
	v_mov_b32_e32 v0, v68
	s_nop 1
	v_permlane16_swap_b32_e32 v68, v0
	v_add_f32_e32 v112, v68, v0
	s_waitcnt vmcnt(3)
	v_mov_b32_e32 v66, v82
	s_waitcnt vmcnt(2)
	v_mov_b32_e32 v67, v86
	v_mov_b32_e32 v68, v84
	v_mov_b32_e32 v69, v88
	v_pk_add_f32 v[66:67], v[66:67], v[68:69]
	v_mov_b32_e32 v86, v83
	v_pk_add_f32 v[66:67], v[66:67], v[66:67] op_sel:[0,1] op_sel_hi:[1,0]
	v_mov_b32_e32 v88, v85
	v_pk_add_f32 v[68:69], v[86:87], v[88:89]
	v_mov_b32_e32 v0, v66
	v_pk_add_f32 v[68:69], v[68:69], v[68:69] op_sel:[0,1] op_sel_hi:[1,0]
	s_nop 0
	v_permlane16_swap_b32_e32 v66, v0
	v_add_f32_e32 v105, v66, v0
	v_mov_b32_e32 v0, v68
	s_nop 1
	v_permlane16_swap_b32_e32 v68, v0
	v_add_f32_e32 v104, v68, v0
	s_waitcnt vmcnt(1)
	v_mov_b32_e32 v66, v90
	s_waitcnt vmcnt(0)
	v_mov_b32_e32 v67, v98
	v_mov_b32_e32 v68, v92
	v_mov_b32_e32 v69, v100
	v_pk_add_f32 v[66:67], v[66:67], v[68:69]
	v_mov_b32_e32 v98, v91
	v_pk_add_f32 v[66:67], v[66:67], v[66:67] op_sel:[0,1] op_sel_hi:[1,0]
	v_mov_b32_e32 v100, v93
	v_mov_b32_e32 v0, v66
	s_nop 1
	v_permlane16_swap_b32_e32 v66, v0
	v_pk_add_f32 v[68:69], v[98:99], v[100:101]
	v_add_f32_e32 v99, v66, v0
	v_ashrrev_i32_e32 v66, 8, v118
	v_ashrrev_i32_e32 v67, 31, v66
	v_pk_add_f32 v[68:69], v[68:69], v[68:69] op_sel:[0,1] op_sel_hi:[1,0]
	v_lshlrev_b64 v[120:121], 19, v[66:67]
	v_lshlrev_b64 v[66:67], 12, v[118:119]
	v_mov_b32_e32 v0, v68
	s_waitcnt lgkmcnt(0)
	v_lshl_add_u64 v[66:67], s[78:79], 0, v[66:67]
	v_permlane16_swap_b32_e32 v68, v0
	v_lshl_add_u64 v[122:123], v[152:153], 2, v[66:67]
	v_add_f32_e32 v98, v68, v0
	global_load_dwordx4 v[74:77], v[122:123], off offset:16
	global_load_dwordx4 v[86:89], v[122:123], off
	global_load_dwordx4 v[66:69], v[156:157], off offset:16
	global_load_dwordx4 v[78:81], v[156:157], off
	global_load_dwordx4 v[70:73], v[154:155], off offset:16
	global_load_dwordx4 v[82:85], v[154:155], off
	global_load_dwordx4 v[90:93], v[122:123], off offset:528
	global_load_dwordx4 v[124:127], v[122:123], off offset:512
	global_load_dwordx4 v[128:131], v[156:157], off offset:528
	global_load_dwordx4 v[132:135], v[156:157], off offset:512
	global_load_dwordx4 v[158:161], v[154:155], off offset:528
	global_load_dwordx4 v[162:165], v[154:155], off offset:512
	v_lshlrev_b32_e32 v0, 6, v118
	s_movk_i32 s1, 0x33c0
	v_readlane_b32 s3, v253, 60
	v_and_or_b32 v0, v0, s1, v196
	v_lshlrev_b32_e32 v0, 1, v0
	v_mov_b32_e32 v115, v113
	v_mov_b32_e32 v114, v112
	v_mov_b32_e32 v107, v105
	v_mov_b32_e32 v106, v104
	v_mov_b32_e32 v101, v99
	v_mov_b32_e32 v100, v98
	v_permlane32_swap_b32_e32 v113, v115
	v_permlane32_swap_b32_e32 v112, v114
	v_permlane32_swap_b32_e32 v105, v107
	v_permlane32_swap_b32_e32 v104, v106
	v_permlane32_swap_b32_e32 v99, v101
	v_permlane32_swap_b32_e32 v98, v100
	s_waitcnt vmcnt(11)
	v_sub_f32_e32 v75, v75, v117
	s_waitcnt vmcnt(10)
	v_sub_f32_e32 v87, v87, v117
	v_sub_f32_e32 v86, v86, v117
	v_sub_f32_e32 v89, v89, v117
	v_sub_f32_e32 v88, v88, v117
	v_sub_f32_e32 v74, v74, v117
	v_sub_f32_e32 v77, v77, v117
	v_sub_f32_e32 v76, v76, v117
	v_pk_mul_f32 v[88:89], v[116:117], v[88:89] op_sel_hi:[0,1]
	v_pk_mul_f32 v[86:87], v[116:117], v[86:87] op_sel_hi:[0,1]
	v_pk_mul_f32 v[76:77], v[116:117], v[76:77] op_sel_hi:[0,1]
	v_pk_mul_f32 v[74:75], v[116:117], v[74:75] op_sel_hi:[0,1]
	s_waitcnt vmcnt(6)
	v_pk_fma_f32 v[78:79], v[78:79], v[86:87], v[82:83]
	v_pk_fma_f32 v[80:81], v[80:81], v[88:89], v[84:85]
	v_pk_fma_f32 v[66:67], v[66:67], v[74:75], v[70:71]
	v_pk_fma_f32 v[68:69], v[68:69], v[76:77], v[72:73]
	v_pk_fma_f32 v[64:65], v[80:81], s[14:15], v[64:65] op_sel_hi:[1,0,1]
	v_pk_fma_f32 v[62:63], v[78:79], s[14:15], v[62:63] op_sel_hi:[1,0,1]
	v_pk_fma_f32 v[60:61], v[68:69], s[14:15], v[60:61] op_sel_hi:[1,0,1]
	v_pk_fma_f32 v[58:59], v[66:67], s[14:15], v[58:59] op_sel_hi:[1,0,1]
	v_add_f32_e32 v78, v62, v63
	v_add_f32_e32 v79, v64, v65
	v_add_f32_e32 v66, v58, v59
	v_add_f32_e32 v67, v60, v61
	v_add_f32_e32 v78, v78, v79
	v_mul_f32_e32 v79, v63, v63
	v_mul_f32_e32 v80, v65, v65
	v_add_f32_e32 v66, v66, v67
	v_mul_f32_e32 v67, v59, v59
	s_nop 0
	v_fmac_f32_e32 v79, v62, v62
	v_fmac_f32_e32 v80, v64, v64
	s_nop 1
	v_bfe_u32 v69, v227, 4, 2
	v_sub_u32_e32 v68, 0, v69
	v_lshlrev_b32_e32 v68, 4, v68
	v_ashrrev_i32_e32 v69, 31, v68
	v_lshl_add_u64 v[68:69], v[122:123], 0, v[68:69]
	v_permlane16_swap_b32_e32 v62, v58
	v_permlane16_swap_b32_e32 v63, v59
	v_permlane16_swap_b32_e32 v64, v60
	v_permlane16_swap_b32_e32 v65, v61
	v_permlane32_swap_b32_e32 v62, v58
	v_permlane32_swap_b32_e32 v63, v59
	v_permlane32_swap_b32_e32 v64, v60
	v_permlane32_swap_b32_e32 v65, v61
	global_store_dwordx4 v[68:69], v[62:65], off
	global_store_dwordx4 v[68:69], v[58:61], off offset:64
	s_nop 1
	v_permlane32_swap_b32_e32 v62, v58
	v_permlane32_swap_b32_e32 v63, v59
	v_permlane32_swap_b32_e32 v64, v60
	v_permlane32_swap_b32_e32 v65, v61
	v_permlane16_swap_b32_e32 v62, v58
	v_permlane16_swap_b32_e32 v63, v59
	v_permlane16_swap_b32_e32 v64, v60
	v_permlane16_swap_b32_e32 v65, v61
	v_fmac_f32_e32 v67, v58, v58
	v_cvt_pk_bf16_f32 v62, v62, v63
	v_cvt_pk_bf16_f32 v63, v64, v65
	v_cvt_pk_bf16_f32 v64, v58, v59
	v_lshl_add_u64 v[58:59], s[2:3], 0, v[120:121]
	v_mul_f32_e32 v68, v61, v61
	v_lshl_add_u64 v[76:77], v[58:59], 0, s[24:25]
	v_fmac_f32_e32 v68, v60, v60
	v_cvt_pk_bf16_f32 v65, v60, v61
	v_lshl_add_u64 v[60:61], v[76:77], 0, v[0:1]
	global_store_dwordx4 v[60:61], v[62:65], off
	s_waitcnt vmcnt(7)
; __device__ __forceinline__ float xsum16(float v) { const auto r = __builtin_amdgcn_permlane16_swap(__float_as_uint(v), __float_as_uint(v), false, false); return __uint_as_float(r[0]) + __uint_as_float(r[1]); }
; __device__ __forceinline__ float xsum32(float v) { const auto r = __builtin_amdgcn_permlane32_swap(__float_as_uint(v), __float_as_uint(v), false, false); return __uint_as_float(r[0]) + __uint_as_float(r[1]); }
; __device__ __forceinline__ size_t blk_off(int r, int c, int K) { return (size_t)(r >> 8) * 256 * K + (size_t)(c >> 6) * (256 * 64) + (size_t)((r & 255) * 64 + (c & 63)); }
; __device__ __forceinline__ u32x4 pack8(const f32x4 a, const f32x4 b) { u32x4 w; w.x = cvt_pk_bf16(a[0], a[1]); w.y = cvt_pk_bf16(a[2], a[3]); w.z = cvt_pk_bf16(b[0], b[1]); w.w = cvt_pk_bf16(b[2], b[3]); return w; }
;     __device__ __forceinline__ void operator()(const f32x4 (&acc)[2][2][4][2], const pg8::Unit& u, int wr, int wc, int fr, int fq) const {
;     ...
;                     for (int n = 0; n < 2; ++n) { yv[bj][n] = *(const f32x4*)(Yin + (size_t)row * D_ + col0 + bj * 128 + 4 * n); gq[bj][n] = *(const f32x4*)(g + col0 + bj * 128 + 4 * n); bq_[bj][n] = *(const f32x4*)(b + col0 + bj * 128 + 4 * n); }
;                 asm volatile("" ::: "memory");
;                 float s1 = 0.f, s2 = 0.f;
; #pragma unroll
;                 for (int bj = 0; bj < 2; ++bj) { float* yp = Y + (size_t)row * D_ + col0 + bj * 128; f32x4 v[2];
; #pragma unroll
;                     for (int n = 0; n < 2; ++n) { v[n] = (((yv[bj][n] - mu) * rs) * gq[bj][n] + bq_[bj][n]) * ALPHA_ + acc[ai][bj][m][n] * sc;
;                         *(f32x4*)(yp + 4 * n) = v[n]; s1 += (v[n][0] + v[n][1]) + (v[n][2] + v[n][3]); s2 += (v[n][0] * v[n][0] + v[n][1] * v[n][1]) + (v[n][2] * v[n][2] + v[n][3] * v[n][3]); }
;                     *(u32x4*)(Yb + blk_off(row, col0 + bj * 128, D_)) = pack8(v[0], v[1]); }
;                 s1 = xsum32(xsum16(s1)); s2 = xsum32(xsum16(s2));
;                 if (fq == 0) *(f32x2*)(stn + (size_t)row * 32 + (u.pn * 4 + wc) * 2) = (f32x2){s1, s2}; asm volatile("" ::: "memory"); } }
	v_sub_f32_e32 v61, v125, v117
	v_sub_f32_e32 v60, v124, v117
	v_sub_f32_e32 v63, v127, v117
	v_sub_f32_e32 v62, v126, v117
	v_pk_mul_f32 v[62:63], v[116:117], v[62:63] op_sel_hi:[0,1]
	v_pk_mul_f32 v[60:61], v[116:117], v[60:61] op_sel_hi:[0,1]
	s_waitcnt vmcnt(3)
	v_pk_fma_f32 v[60:61], v[132:133], v[60:61], v[162:163]
	v_pk_fma_f32 v[62:63], v[134:135], v[62:63], v[164:165]
	v_pk_fma_f32 v[54:55], v[60:61], s[14:15], v[54:55] op_sel_hi:[1,0,1]
	v_pk_fma_f32 v[56:57], v[62:63], s[14:15], v[56:57] op_sel_hi:[1,0,1]
	v_add_f32_e32 v78, 0, v78
	v_add_f32_e32 v60, v54, v55
	v_add_f32_e32 v61, v56, v57
	v_add_f32_e32 v66, v78, v66
	v_add_f32_e32 v60, v60, v61
	v_add_f32_e32 v64, v66, v60
	v_mul_f32_e32 v60, v55, v55
	v_mul_f32_e32 v61, v57, v57
	v_add_f32_e32 v79, v79, v80
	v_add_f32_e32 v67, v67, v68
	v_fmac_f32_e32 v60, v54, v54
	v_fmac_f32_e32 v61, v56, v56
	v_add_f32_e32 v67, v79, v67
	v_add_f32_e32 v60, v60, v61
	v_add_f32_e32 v65, v67, v60
	v_sub_f32_e32 v61, v91, v117
	v_sub_f32_e32 v60, v90, v117
	v_sub_f32_e32 v63, v93, v117
	v_sub_f32_e32 v62, v92, v117
	v_pk_mul_f32 v[62:63], v[116:117], v[62:63] op_sel_hi:[0,1]
	v_pk_mul_f32 v[60:61], v[116:117], v[60:61] op_sel_hi:[0,1]
	v_pk_fma_f32 v[60:61], v[128:129], v[60:61], v[158:159]
	v_pk_fma_f32 v[62:63], v[130:131], v[62:63], v[160:161]
	v_pk_fma_f32 v[50:51], v[60:61], s[14:15], v[50:51] op_sel_hi:[1,0,1]
	v_pk_fma_f32 v[52:53], v[62:63], s[14:15], v[52:53] op_sel_hi:[1,0,1]
	v_add_f32_e32 v60, v50, v51
	v_add_f32_e32 v61, v52, v53
	v_add_f32_e32 v60, v60, v61
	v_mul_f32_e32 v61, v51, v51
	v_mul_f32_e32 v62, v53, v53
	v_add_f32_e32 v60, v64, v60
	v_fmac_f32_e32 v61, v50, v50
	v_fmac_f32_e32 v62, v52, v52
	v_lshl_add_u64 v[74:75], v[58:59], 0, s[28:29]
	s_nop 0
	s_nop 1
	v_bfe_u32 v67, v227, 4, 2
	v_sub_u32_e32 v66, 0, v67
	v_lshlrev_b32_e32 v66, 4, v66
	v_ashrrev_i32_e32 v67, 31, v66
	v_lshl_add_u64 v[66:67], v[122:123], 0, v[66:67]
	v_permlane16_swap_b32_e32 v54, v50
	v_permlane16_swap_b32_e32 v55, v51
	v_permlane16_swap_b32_e32 v56, v52
	v_permlane16_swap_b32_e32 v57, v53
	v_permlane32_swap_b32_e32 v54, v50
	v_permlane32_swap_b32_e32 v55, v51
	v_permlane32_swap_b32_e32 v56, v52
	v_permlane32_swap_b32_e32 v57, v53
	global_store_dwordx4 v[66:67], v[54:57], off offset:512
	global_store_dwordx4 v[66:67], v[50:53], off offset:576
	s_nop 1
	v_permlane32_swap_b32_e32 v54, v50
	v_permlane32_swap_b32_e32 v55, v51
	v_permlane32_swap_b32_e32 v56, v52
	v_permlane32_swap_b32_e32 v57, v53
	v_permlane16_swap_b32_e32 v54, v50
	v_permlane16_swap_b32_e32 v55, v51
	v_permlane16_swap_b32_e32 v56, v52
	v_permlane16_swap_b32_e32 v57, v53
	v_add_f32_e32 v61, v61, v62
	v_cvt_pk_bf16_f32 v54, v54, v55
	v_cvt_pk_bf16_f32 v55, v56, v57
	v_cvt_pk_bf16_f32 v56, v50, v51
	v_lshl_add_u64 v[50:51], v[74:75], 0, v[0:1]
	v_mov_b32_e32 v0, v60
	v_add_f32_e32 v61, v65, v61
	v_cvt_pk_bf16_f32 v57, v52, v53
	v_permlane16_swap_b32_e32 v60, v0
	global_store_dwordx4 v[50:51], v[54:57], off
	v_add_f32_e32 v50, v60, v0
	v_mov_b32_e32 v0, v61
	s_nop 1
	v_permlane16_swap_b32_e32 v61, v0
	v_add_f32_e32 v51, v61, v0
	v_mov_b32_e32 v52, v50
	v_mov_b32_e32 v53, v51
	s_nop 0
	v_permlane32_swap_b32_e32 v50, v52
	v_permlane32_swap_b32_e32 v51, v53
	s_and_saveexec_b64 s[24:25], s[44:45]
	s_cbranch_execz .LBB0_1545
	v_pk_add_f32 v[50:51], v[50:51], v[52:53]
	v_lshl_add_u64 v[52:53], s[6:7], 0, v[110:111]
	v_lshl_add_u64 v[52:53], s[52:53], 2, v[52:53]
	global_store_dwordx2 v[52:53], v[50:51], off
.LBB0_1545:
	s_or_b64 exec, exec, s[24:25]
	v_pk_add_f32 v[50:51], v[112:113], v[114:115]
	s_mov_b32 s2, 0x3a800000
	v_pk_mul_f32 v[78:79], v[50:51], s[2:3] op_sel_hi:[1,0]
	s_mov_b32 s1, 0x800000
	v_fma_f32 v0, -v79, v79, v78
	v_max_f32_e32 v0, 0, v0
	v_add_f32_e32 v0, 0x3727c5ac, v0
	v_cmp_gt_f32_e32 vcc, s1, v0
	v_mul_f32_e32 v50, 0x4b800000, v0
	s_load_dwordx16 s[64:79], s[34:35], 0x38
	v_cndmask_b32_e32 v0, v0, v50, vcc
	v_rsq_f32_e32 v0, v0
	s_mov_b32 s2, 0x3fd744fd
	s_movk_i32 s1, 0x37c0
	v_mul_f32_e32 v50, 0x45800000, v0
	v_cndmask_b32_e32 v78, v0, v50, vcc
	v_lshlrev_b64 v[50:51], 12, v[108:109]
	s_waitcnt lgkmcnt(0)
	v_lshl_add_u64 v[50:51], s[78:79], 0, v[50:51]
	v_lshl_add_u64 v[80:81], v[152:153], 2, v[50:51]
	global_load_dwordx4 v[82:85], v[80:81], off offset:16
	global_load_dwordx4 v[86:89], v[80:81], off
	global_load_dwordx4 v[90:93], v[156:157], off offset:16
	global_load_dwordx4 v[110:113], v[156:157], off
	global_load_dwordx4 v[114:117], v[154:155], off offset:16
	global_load_dwordx4 v[118:121], v[154:155], off
	global_load_dwordx4 v[50:53], v[80:81], off offset:528
	global_load_dwordx4 v[70:73], v[80:81], off offset:512
	global_load_dwordx4 v[54:57], v[156:157], off offset:528
	global_load_dwordx4 v[62:65], v[156:157], off offset:512
	global_load_dwordx4 v[58:61], v[154:155], off offset:528
	global_load_dwordx4 v[66:69], v[154:155], off offset:512
	v_lshlrev_b32_e32 v0, 6, v108
	v_and_or_b32 v0, v0, s1, v196
	v_lshlrev_b32_e32 v0, 1, v0
	s_waitcnt vmcnt(10)
	v_sub_f32_e32 v87, v87, v79
	v_sub_f32_e32 v86, v86, v79
	v_sub_f32_e32 v89, v89, v79
	v_sub_f32_e32 v88, v88, v79
	v_pk_mul_f32 v[88:89], v[78:79], v[88:89] op_sel_hi:[0,1]
	v_pk_mul_f32 v[86:87], v[78:79], v[86:87] op_sel_hi:[0,1]
	s_waitcnt vmcnt(6)
; __device__ __forceinline__ float xsum16(float v) { const auto r = __builtin_amdgcn_permlane16_swap(__float_as_uint(v), __float_as_uint(v), false, false); return __uint_as_float(r[0]) + __uint_as_float(r[1]); }
; __device__ __forceinline__ float xsum32(float v) { const auto r = __builtin_amdgcn_permlane32_swap(__float_as_uint(v), __float_as_uint(v), false, false); return __uint_as_float(r[0]) + __uint_as_float(r[1]); }
; __device__ __forceinline__ size_t blk_off(int r, int c, int K) { return (size_t)(r >> 8) * 256 * K + (size_t)(c >> 6) * (256 * 64) + (size_t)((r & 255) * 64 + (c & 63)); }
; __device__ __forceinline__ u32x4 pack8(const f32x4 a, const f32x4 b) { u32x4 w; w.x = cvt_pk_bf16(a[0], a[1]); w.y = cvt_pk_bf16(a[2], a[3]); w.z = cvt_pk_bf16(b[0], b[1]); w.w = cvt_pk_bf16(b[2], b[3]); return w; }
;     __device__ __forceinline__ void operator()(const f32x4 (&acc)[2][2][4][2], const pg8::Unit& u, int wr, int wc, int fr, int fq) const {
;     ...
;             for (int m = 0; m < 4; ++m) { const int row = row0 + ai * 128 + m * 16; const float mu = mu4[m], rs = rs4[m];
;                 f32x4 yv[2][2], gq[2][2], bq_[2][2];
; #pragma unroll
;                 for (int bj = 0; bj < 2; ++bj)
; #pragma unroll
;                     for (int n = 0; n < 2; ++n) { yv[bj][n] = *(const f32x4*)(Yin + (size_t)row * D_ + col0 + bj * 128 + 4 * n); gq[bj][n] = *(const f32x4*)(g + col0 + bj * 128 + 4 * n); bq_[bj][n] = *(const f32x4*)(b + col0 + bj * 128 + 4 * n); }
;                 asm volatile("" ::: "memory");
;                 float s1 = 0.f, s2 = 0.f;
; #pragma unroll
;                 for (int bj = 0; bj < 2; ++bj) { float* yp = Y + (size_t)row * D_ + col0 + bj * 128; f32x4 v[2];
; #pragma unroll
;                     for (int n = 0; n < 2; ++n) { v[n] = (((yv[bj][n] - mu) * rs) * gq[bj][n] + bq_[bj][n]) * ALPHA_ + acc[ai][bj][m][n] * sc;
;                         *(f32x4*)(yp + 4 * n) = v[n]; s1 += (v[n][0] + v[n][1]) + (v[n][2] + v[n][3]); s2 += (v[n][0] * v[n][0] + v[n][1] * v[n][1]) + (v[n][2] * v[n][2] + v[n][3] * v[n][3]); }
;                     *(u32x4*)(Yb + blk_off(row, col0 + bj * 128, D_)) = pack8(v[0], v[1]); }
;                 s1 = xsum32(xsum16(s1)); s2 = xsum32(xsum16(s2));
;                 if (fq == 0) *(f32x2*)(stn + (size_t)row * 32 + (u.pn * 4 + wc) * 2) = (f32x2){s1, s2}; asm volatile("" ::: "memory"); } }
	v_pk_fma_f32 v[86:87], v[110:111], v[86:87], v[118:119]
	v_pk_fma_f32 v[88:89], v[112:113], v[88:89], v[120:121]
	v_pk_fma_f32 v[86:87], v[86:87], s[2:3], v[46:47] op_sel_hi:[1,0,1]
	v_pk_fma_f32 v[88:89], v[88:89], s[2:3], v[48:49] op_sel_hi:[1,0,1]
	v_add_f32_e32 v46, v86, v87
	v_add_f32_e32 v47, v88, v89
	v_add_f32_e32 v46, v46, v47
	v_add_f32_e32 v108, 0, v46
	v_mul_f32_e32 v46, v87, v87
	v_mul_f32_e32 v47, v89, v89
	v_fmac_f32_e32 v46, v86, v86
	v_fmac_f32_e32 v47, v88, v88
	v_add_f32_e32 v109, v46, v47
	v_sub_f32_e32 v47, v83, v79
	v_sub_f32_e32 v46, v82, v79
	v_sub_f32_e32 v49, v85, v79
	v_sub_f32_e32 v48, v84, v79
	v_pk_mul_f32 v[48:49], v[78:79], v[48:49] op_sel_hi:[0,1]
	v_pk_mul_f32 v[46:47], v[78:79], v[46:47] op_sel_hi:[0,1]
	v_pk_fma_f32 v[46:47], v[90:91], v[46:47], v[114:115]
	v_pk_fma_f32 v[48:49], v[92:93], v[48:49], v[116:117]
	v_pk_fma_f32 v[82:83], v[46:47], s[2:3], v[42:43] op_sel_hi:[1,0,1]
	v_pk_fma_f32 v[84:85], v[48:49], s[2:3], v[44:45] op_sel_hi:[1,0,1]
	v_add_f32_e32 v42, v82, v83
	v_add_f32_e32 v43, v84, v85
	v_add_f32_e32 v42, v42, v43
	v_add_f32_e32 v47, v108, v42
	v_mul_f32_e32 v42, v83, v83
	v_mul_f32_e32 v43, v85, v85
	v_fmac_f32_e32 v42, v82, v82
	v_fmac_f32_e32 v43, v84, v84
	v_add_f32_e32 v42, v42, v43
	v_add_f32_e32 v46, v109, v42
	v_cvt_pk_bf16_f32 v42, v86, v87
	v_cvt_pk_bf16_f32 v43, v88, v89
	v_cvt_pk_bf16_f32 v44, v82, v83
	v_cvt_pk_bf16_f32 v45, v84, v85
	v_lshl_add_u64 v[48:49], v[76:77], 0, v[0:1]
	s_nop 0
	s_nop 1
	v_bfe_u32 v91, v227, 4, 2
	v_sub_u32_e32 v90, 0, v91
	v_lshlrev_b32_e32 v90, 4, v90
	v_ashrrev_i32_e32 v91, 31, v90
	v_lshl_add_u64 v[90:91], v[80:81], 0, v[90:91]
	v_permlane16_swap_b32_e32 v86, v82
	v_permlane16_swap_b32_e32 v87, v83
	v_permlane16_swap_b32_e32 v88, v84
	v_permlane16_swap_b32_e32 v89, v85
	v_permlane32_swap_b32_e32 v86, v82
	v_permlane32_swap_b32_e32 v87, v83
	v_permlane32_swap_b32_e32 v88, v84
	v_permlane32_swap_b32_e32 v89, v85
	global_store_dwordx4 v[90:91], v[86:89], off
	global_store_dwordx4 v[90:91], v[82:85], off offset:64
	s_nop 1
	v_permlane32_swap_b32_e32 v86, v82
	v_permlane32_swap_b32_e32 v87, v83
	v_permlane32_swap_b32_e32 v88, v84
	v_permlane32_swap_b32_e32 v89, v85
	v_permlane16_swap_b32_e32 v86, v82
	v_permlane16_swap_b32_e32 v87, v83
	v_permlane16_swap_b32_e32 v88, v84
	v_permlane16_swap_b32_e32 v89, v85
	global_store_dwordx4 v[48:49], v[42:45], off
	s_waitcnt vmcnt(7)
	s_nop 0
	v_sub_f32_e32 v43, v71, v79
	v_sub_f32_e32 v42, v70, v79
	v_sub_f32_e32 v45, v73, v79
	v_sub_f32_e32 v44, v72, v79
	v_pk_mul_f32 v[44:45], v[78:79], v[44:45] op_sel_hi:[0,1]
	v_pk_mul_f32 v[42:43], v[78:79], v[42:43] op_sel_hi:[0,1]
	s_waitcnt vmcnt(3)
	v_pk_fma_f32 v[42:43], v[62:63], v[42:43], v[66:67]
	v_pk_fma_f32 v[44:45], v[64:65], v[44:45], v[68:69]
	v_pk_fma_f32 v[38:39], v[42:43], s[2:3], v[38:39] op_sel_hi:[1,0,1]
	v_pk_fma_f32 v[40:41], v[44:45], s[2:3], v[40:41] op_sel_hi:[1,0,1]
	v_add_f32_e32 v42, v38, v39
	v_add_f32_e32 v43, v40, v41
	v_add_f32_e32 v42, v42, v43
	v_add_f32_e32 v47, v47, v42
	v_mul_f32_e32 v42, v39, v39
	v_mul_f32_e32 v43, v41, v41
	v_fmac_f32_e32 v42, v38, v38
	v_fmac_f32_e32 v43, v40, v40
	v_add_f32_e32 v42, v42, v43
	v_add_f32_e32 v46, v46, v42
	v_sub_f32_e32 v43, v51, v79
	v_sub_f32_e32 v42, v50, v79
	v_sub_f32_e32 v45, v53, v79
	v_sub_f32_e32 v44, v52, v79
	v_pk_mul_f32 v[44:45], v[78:79], v[44:45] op_sel_hi:[0,1]
	v_pk_mul_f32 v[42:43], v[78:79], v[42:43] op_sel_hi:[0,1]
	v_pk_fma_f32 v[42:43], v[54:55], v[42:43], v[58:59]
	v_pk_fma_f32 v[44:45], v[56:57], v[44:45], v[60:61]
	v_pk_fma_f32 v[34:35], v[42:43], s[2:3], v[34:35] op_sel_hi:[1,0,1]
	v_pk_fma_f32 v[36:37], v[44:45], s[2:3], v[36:37] op_sel_hi:[1,0,1]
	v_add_f32_e32 v42, v34, v35
	v_add_f32_e32 v43, v36, v37
	v_add_f32_e32 v42, v42, v43
	v_mul_f32_e32 v43, v35, v35
	v_mul_f32_e32 v44, v37, v37
	v_add_f32_e32 v42, v47, v42
	v_fmac_f32_e32 v43, v34, v34
	v_fmac_f32_e32 v44, v36, v36
	s_nop 0
	s_nop 1
	v_bfe_u32 v49, v227, 4, 2
	v_sub_u32_e32 v48, 0, v49
	v_lshlrev_b32_e32 v48, 4, v48
	v_ashrrev_i32_e32 v49, 31, v48
	v_lshl_add_u64 v[48:49], v[80:81], 0, v[48:49]
	v_permlane16_swap_b32_e32 v38, v34
	v_permlane16_swap_b32_e32 v39, v35
	v_permlane16_swap_b32_e32 v40, v36
	v_permlane16_swap_b32_e32 v41, v37
	v_permlane32_swap_b32_e32 v38, v34
	v_permlane32_swap_b32_e32 v39, v35
	v_permlane32_swap_b32_e32 v40, v36
	v_permlane32_swap_b32_e32 v41, v37
	global_store_dwordx4 v[48:49], v[38:41], off offset:512
	global_store_dwordx4 v[48:49], v[34:37], off offset:576
	s_nop 1
	v_permlane32_swap_b32_e32 v38, v34
	v_permlane32_swap_b32_e32 v39, v35
	v_permlane32_swap_b32_e32 v40, v36
	v_permlane32_swap_b32_e32 v41, v37
	v_permlane16_swap_b32_e32 v38, v34
	v_permlane16_swap_b32_e32 v39, v35
	v_permlane16_swap_b32_e32 v40, v36
	v_permlane16_swap_b32_e32 v41, v37
	v_add_f32_e32 v43, v43, v44
	v_cvt_pk_bf16_f32 v38, v38, v39
	v_cvt_pk_bf16_f32 v39, v40, v41
	v_cvt_pk_bf16_f32 v40, v34, v35
	v_lshl_add_u64 v[34:35], v[74:75], 0, v[0:1]
	v_mov_b32_e32 v0, v42
	v_add_f32_e32 v43, v46, v43
	v_cvt_pk_bf16_f32 v41, v36, v37
	v_permlane16_swap_b32_e32 v42, v0
	global_store_dwordx4 v[34:35], v[38:41], off
	v_add_f32_e32 v34, v42, v0
	v_mov_b32_e32 v0, v43
	s_nop 1
	v_permlane16_swap_b32_e32 v43, v0
	v_add_f32_e32 v35, v43, v0
	v_mov_b32_e32 v36, v34
	v_mov_b32_e32 v37, v35
	s_nop 0
	v_permlane32_swap_b32_e32 v34, v36
	v_permlane32_swap_b32_e32 v35, v37
	s_and_saveexec_b64 s[24:25], s[44:45]
	s_cbranch_execz .LBB0_1547
	v_pk_add_f32 v[34:35], v[34:35], v[36:37]
	v_lshl_add_u64 v[36:37], s[6:7], 0, v[102:103]
	v_lshl_add_u64 v[36:37], s[52:53], 2, v[36:37]
	global_store_dwordx2 v[36:37], v[34:35], off
; __device__ __forceinline__ float xsum16(float v) { const auto r = __builtin_amdgcn_permlane16_swap(__float_as_uint(v), __float_as_uint(v), false, false); return __uint_as_float(r[0]) + __uint_as_float(r[1]); }
; __device__ __forceinline__ float xsum32(float v) { const auto r = __builtin_amdgcn_permlane32_swap(__float_as_uint(v), __float_as_uint(v), false, false); return __uint_as_float(r[0]) + __uint_as_float(r[1]); }
; __device__ __forceinline__ size_t blk_off(int r, int c, int K) { return (size_t)(r >> 8) * 256 * K + (size_t)(c >> 6) * (256 * 64) + (size_t)((r & 255) * 64 + (c & 63)); }
; __device__ __forceinline__ u32x4 pack8(const f32x4 a, const f32x4 b) { u32x4 w; w.x = cvt_pk_bf16(a[0], a[1]); w.y = cvt_pk_bf16(a[2], a[3]); w.z = cvt_pk_bf16(b[0], b[1]); w.w = cvt_pk_bf16(b[2], b[3]); return w; }
;     __device__ __forceinline__ void operator()(const f32x4 (&acc)[2][2][4][2], const pg8::Unit& u, int wr, int wc, int fr, int fq) const {
;     ...
;             for (int m = 0; m < 4; ++m) { const int row = row0 + ai * 128 + m * 16; const float mu = mu4[m], rs = rs4[m];
;                 f32x4 yv[2][2], gq[2][2], bq_[2][2];
; #pragma unroll
;                 for (int bj = 0; bj < 2; ++bj)
; #pragma unroll
;                     for (int n = 0; n < 2; ++n) { yv[bj][n] = *(const f32x4*)(Yin + (size_t)row * D_ + col0 + bj * 128 + 4 * n); gq[bj][n] = *(const f32x4*)(g + col0 + bj * 128 + 4 * n); bq_[bj][n] = *(const f32x4*)(b + col0 + bj * 128 + 4 * n); }
;                 asm volatile("" ::: "memory");
;                 float s1 = 0.f, s2 = 0.f;
; #pragma unroll
;                 for (int bj = 0; bj < 2; ++bj) { float* yp = Y + (size_t)row * D_ + col0 + bj * 128; f32x4 v[2];
; #pragma unroll
;                     for (int n = 0; n < 2; ++n) { v[n] = (((yv[bj][n] - mu) * rs) * gq[bj][n] + bq_[bj][n]) * ALPHA_ + acc[ai][bj][m][n] * sc;
;                         *(f32x4*)(yp + 4 * n) = v[n]; s1 += (v[n][0] + v[n][1]) + (v[n][2] + v[n][3]); s2 += (v[n][0] * v[n][0] + v[n][1] * v[n][1]) + (v[n][2] * v[n][2] + v[n][3] * v[n][3]); }
;                     *(u32x4*)(Yb + blk_off(row, col0 + bj * 128, D_)) = pack8(v[0], v[1]); }
;                 s1 = xsum32(xsum16(s1)); s2 = xsum32(xsum16(s2));
;                 if (fq == 0) *(f32x2*)(stn + (size_t)row * 32 + (u.pn * 4 + wc) * 2) = (f32x2){s1, s2}; asm volatile("" ::: "memory"); } }
.LBB0_1547:
	s_or_b64 exec, exec, s[24:25]
	v_pk_add_f32 v[34:35], v[104:105], v[106:107]
	s_mov_b32 s2, 0x3a800000
	v_pk_mul_f32 v[58:59], v[34:35], s[2:3] op_sel_hi:[1,0]
	s_mov_b32 s1, 0x800000
	v_fma_f32 v0, -v59, v59, v58
	v_max_f32_e32 v0, 0, v0
	v_add_f32_e32 v0, 0x3727c5ac, v0
	v_cmp_gt_f32_e32 vcc, s1, v0
	v_mul_f32_e32 v34, 0x4b800000, v0
	s_load_dwordx16 s[64:79], s[34:35], 0x38
	v_cndmask_b32_e32 v0, v0, v34, vcc
	v_rsq_f32_e32 v0, v0
	s_mov_b32 s2, 0x3fd744fd
	s_movk_i32 s1, 0x3bc0
	v_mul_f32_e32 v34, 0x45800000, v0
	v_cndmask_b32_e32 v58, v0, v34, vcc
	v_lshlrev_b64 v[34:35], 12, v[96:97]
	s_waitcnt lgkmcnt(0)
	v_lshl_add_u64 v[34:35], s[78:79], 0, v[34:35]
	v_lshl_add_u64 v[60:61], v[152:153], 2, v[34:35]
	global_load_dwordx4 v[62:65], v[60:61], off offset:16
	global_load_dwordx4 v[66:69], v[60:61], off
	global_load_dwordx4 v[70:73], v[156:157], off offset:16
	global_load_dwordx4 v[78:81], v[156:157], off
	global_load_dwordx4 v[82:85], v[154:155], off offset:16
	global_load_dwordx4 v[86:89], v[154:155], off
	global_load_dwordx4 v[34:37], v[60:61], off offset:528
	global_load_dwordx4 v[54:57], v[60:61], off offset:512
	global_load_dwordx4 v[38:41], v[156:157], off offset:528
	global_load_dwordx4 v[46:49], v[156:157], off offset:512
	global_load_dwordx4 v[42:45], v[154:155], off offset:528
	global_load_dwordx4 v[50:53], v[154:155], off offset:512
	v_lshlrev_b32_e32 v0, 6, v96
	v_and_or_b32 v0, v0, s1, v196
	v_lshlrev_b32_e32 v0, 1, v0
	s_waitcnt vmcnt(10)
	v_sub_f32_e32 v67, v67, v59
	v_sub_f32_e32 v66, v66, v59
	v_sub_f32_e32 v69, v69, v59
	v_sub_f32_e32 v68, v68, v59
	v_pk_mul_f32 v[68:69], v[58:59], v[68:69] op_sel_hi:[0,1]
	v_pk_mul_f32 v[66:67], v[58:59], v[66:67] op_sel_hi:[0,1]
	s_waitcnt vmcnt(6)
	v_pk_fma_f32 v[66:67], v[78:79], v[66:67], v[86:87]
	v_pk_fma_f32 v[68:69], v[80:81], v[68:69], v[88:89]
	v_pk_fma_f32 v[66:67], v[66:67], s[2:3], v[30:31] op_sel_hi:[1,0,1]
	v_pk_fma_f32 v[68:69], v[68:69], s[2:3], v[32:33] op_sel_hi:[1,0,1]
	v_add_f32_e32 v30, v66, v67
	v_add_f32_e32 v31, v68, v69
	v_add_f32_e32 v30, v30, v31
	v_add_f32_e32 v78, 0, v30
	v_mul_f32_e32 v30, v67, v67
	v_mul_f32_e32 v31, v69, v69
	v_fmac_f32_e32 v30, v66, v66
	v_fmac_f32_e32 v31, v68, v68
	v_add_f32_e32 v79, v30, v31
	v_sub_f32_e32 v31, v63, v59
	v_sub_f32_e32 v30, v62, v59
	v_sub_f32_e32 v33, v65, v59
	v_sub_f32_e32 v32, v64, v59
	v_pk_mul_f32 v[32:33], v[58:59], v[32:33] op_sel_hi:[0,1]
	v_pk_mul_f32 v[30:31], v[58:59], v[30:31] op_sel_hi:[0,1]
	v_pk_fma_f32 v[30:31], v[70:71], v[30:31], v[82:83]
	v_pk_fma_f32 v[32:33], v[72:73], v[32:33], v[84:85]
	v_pk_fma_f32 v[62:63], v[30:31], s[2:3], v[26:27] op_sel_hi:[1,0,1]
	v_pk_fma_f32 v[64:65], v[32:33], s[2:3], v[28:29] op_sel_hi:[1,0,1]
	v_add_f32_e32 v26, v62, v63
	v_add_f32_e32 v27, v64, v65
	v_add_f32_e32 v26, v26, v27
	v_add_f32_e32 v31, v78, v26
	v_mul_f32_e32 v26, v63, v63
	v_mul_f32_e32 v27, v65, v65
	v_fmac_f32_e32 v26, v62, v62
	v_fmac_f32_e32 v27, v64, v64
	v_add_f32_e32 v26, v26, v27
	v_add_f32_e32 v30, v79, v26
	v_cvt_pk_bf16_f32 v26, v66, v67
	v_cvt_pk_bf16_f32 v27, v68, v69
	v_cvt_pk_bf16_f32 v28, v62, v63
	v_cvt_pk_bf16_f32 v29, v64, v65
	v_lshl_add_u64 v[32:33], v[76:77], 0, v[0:1]
	s_nop 0
	s_nop 1
	v_bfe_u32 v71, v227, 4, 2
	v_sub_u32_e32 v70, 0, v71
	v_lshlrev_b32_e32 v70, 4, v70
	v_ashrrev_i32_e32 v71, 31, v70
	v_lshl_add_u64 v[70:71], v[60:61], 0, v[70:71]
	v_permlane16_swap_b32_e32 v66, v62
	v_permlane16_swap_b32_e32 v67, v63
	v_permlane16_swap_b32_e32 v68, v64
	v_permlane16_swap_b32_e32 v69, v65
	v_permlane32_swap_b32_e32 v66, v62
	v_permlane32_swap_b32_e32 v67, v63
	v_permlane32_swap_b32_e32 v68, v64
	v_permlane32_swap_b32_e32 v69, v65
	global_store_dwordx4 v[70:71], v[66:69], off
	global_store_dwordx4 v[70:71], v[62:65], off offset:64
	s_nop 1
	v_permlane32_swap_b32_e32 v66, v62
	v_permlane32_swap_b32_e32 v67, v63
	v_permlane32_swap_b32_e32 v68, v64
	v_permlane32_swap_b32_e32 v69, v65
	v_permlane16_swap_b32_e32 v66, v62
	v_permlane16_swap_b32_e32 v67, v63
	v_permlane16_swap_b32_e32 v68, v64
	v_permlane16_swap_b32_e32 v69, v65
	global_store_dwordx4 v[32:33], v[26:29], off
	s_waitcnt vmcnt(7)
	s_nop 0
	v_sub_f32_e32 v27, v55, v59
	v_sub_f32_e32 v26, v54, v59
	v_sub_f32_e32 v29, v57, v59
	v_sub_f32_e32 v28, v56, v59
	v_pk_mul_f32 v[28:29], v[58:59], v[28:29] op_sel_hi:[0,1]
	v_pk_mul_f32 v[26:27], v[58:59], v[26:27] op_sel_hi:[0,1]
	s_waitcnt vmcnt(3)
; __device__ __forceinline__ float xsum16(float v) { const auto r = __builtin_amdgcn_permlane16_swap(__float_as_uint(v), __float_as_uint(v), false, false); return __uint_as_float(r[0]) + __uint_as_float(r[1]); }
; __device__ __forceinline__ float xsum32(float v) { const auto r = __builtin_amdgcn_permlane32_swap(__float_as_uint(v), __float_as_uint(v), false, false); return __uint_as_float(r[0]) + __uint_as_float(r[1]); }
; __device__ __forceinline__ size_t blk_off(int r, int c, int K) { return (size_t)(r >> 8) * 256 * K + (size_t)(c >> 6) * (256 * 64) + (size_t)((r & 255) * 64 + (c & 63)); }
; __device__ __forceinline__ u32x4 pack8(const f32x4 a, const f32x4 b) { u32x4 w; w.x = cvt_pk_bf16(a[0], a[1]); w.y = cvt_pk_bf16(a[2], a[3]); w.z = cvt_pk_bf16(b[0], b[1]); w.w = cvt_pk_bf16(b[2], b[3]); return w; }
;     __device__ __forceinline__ void operator()(const f32x4 (&acc)[2][2][4][2], const pg8::Unit& u, int wr, int wc, int fr, int fq) const {
;     ...
;             for (int m = 0; m < 4; ++m) { const int row = row0 + ai * 128 + m * 16; const float mu = mu4[m], rs = rs4[m];
;                 f32x4 yv[2][2], gq[2][2], bq_[2][2];
; #pragma unroll
;                 for (int bj = 0; bj < 2; ++bj)
; #pragma unroll
;                     for (int n = 0; n < 2; ++n) { yv[bj][n] = *(const f32x4*)(Yin + (size_t)row * D_ + col0 + bj * 128 + 4 * n); gq[bj][n] = *(const f32x4*)(g + col0 + bj * 128 + 4 * n); bq_[bj][n] = *(const f32x4*)(b + col0 + bj * 128 + 4 * n); }
;                 asm volatile("" ::: "memory");
;                 float s1 = 0.f, s2 = 0.f;
; #pragma unroll
;                 for (int bj = 0; bj < 2; ++bj) { float* yp = Y + (size_t)row * D_ + col0 + bj * 128; f32x4 v[2];
; #pragma unroll
;                     for (int n = 0; n < 2; ++n) { v[n] = (((yv[bj][n] - mu) * rs) * gq[bj][n] + bq_[bj][n]) * ALPHA_ + acc[ai][bj][m][n] * sc;
;                         *(f32x4*)(yp + 4 * n) = v[n]; s1 += (v[n][0] + v[n][1]) + (v[n][2] + v[n][3]); s2 += (v[n][0] * v[n][0] + v[n][1] * v[n][1]) + (v[n][2] * v[n][2] + v[n][3] * v[n][3]); }
;                     *(u32x4*)(Yb + blk_off(row, col0 + bj * 128, D_)) = pack8(v[0], v[1]); }
;                 s1 = xsum32(xsum16(s1)); s2 = xsum32(xsum16(s2));
;                 if (fq == 0) *(f32x2*)(stn + (size_t)row * 32 + (u.pn * 4 + wc) * 2) = (f32x2){s1, s2}; asm volatile("" ::: "memory"); } }
	v_pk_fma_f32 v[26:27], v[46:47], v[26:27], v[50:51]
	v_pk_fma_f32 v[28:29], v[48:49], v[28:29], v[52:53]
	v_pk_fma_f32 v[22:23], v[26:27], s[2:3], v[22:23] op_sel_hi:[1,0,1]
	v_pk_fma_f32 v[24:25], v[28:29], s[2:3], v[24:25] op_sel_hi:[1,0,1]
	v_add_f32_e32 v26, v22, v23
	v_add_f32_e32 v27, v24, v25
	v_add_f32_e32 v26, v26, v27
	v_add_f32_e32 v31, v31, v26
	v_mul_f32_e32 v26, v23, v23
	v_mul_f32_e32 v27, v25, v25
	v_fmac_f32_e32 v26, v22, v22
	v_fmac_f32_e32 v27, v24, v24
	v_add_f32_e32 v26, v26, v27
	v_add_f32_e32 v30, v30, v26
	v_sub_f32_e32 v27, v35, v59
	v_sub_f32_e32 v26, v34, v59
	v_sub_f32_e32 v29, v37, v59
	v_sub_f32_e32 v28, v36, v59
	v_pk_mul_f32 v[28:29], v[58:59], v[28:29] op_sel_hi:[0,1]
	v_pk_mul_f32 v[26:27], v[58:59], v[26:27] op_sel_hi:[0,1]
	v_pk_fma_f32 v[26:27], v[38:39], v[26:27], v[42:43]
	v_pk_fma_f32 v[28:29], v[40:41], v[28:29], v[44:45]
	v_pk_fma_f32 v[18:19], v[26:27], s[2:3], v[18:19] op_sel_hi:[1,0,1]
	v_pk_fma_f32 v[20:21], v[28:29], s[2:3], v[20:21] op_sel_hi:[1,0,1]
	v_add_f32_e32 v26, v18, v19
	v_add_f32_e32 v27, v20, v21
	v_add_f32_e32 v26, v26, v27
	v_mul_f32_e32 v27, v19, v19
	v_mul_f32_e32 v28, v21, v21
	v_add_f32_e32 v26, v31, v26
	v_fmac_f32_e32 v27, v18, v18
	v_fmac_f32_e32 v28, v20, v20
	s_nop 0
	s_nop 1
	v_bfe_u32 v33, v227, 4, 2
	v_sub_u32_e32 v32, 0, v33
	v_lshlrev_b32_e32 v32, 4, v32
	v_ashrrev_i32_e32 v33, 31, v32
	v_lshl_add_u64 v[32:33], v[60:61], 0, v[32:33]
	v_permlane16_swap_b32_e32 v22, v18
	v_permlane16_swap_b32_e32 v23, v19
	v_permlane16_swap_b32_e32 v24, v20
	v_permlane16_swap_b32_e32 v25, v21
	v_permlane32_swap_b32_e32 v22, v18
	v_permlane32_swap_b32_e32 v23, v19
	v_permlane32_swap_b32_e32 v24, v20
	v_permlane32_swap_b32_e32 v25, v21
	global_store_dwordx4 v[32:33], v[22:25], off offset:512
	global_store_dwordx4 v[32:33], v[18:21], off offset:576
	s_nop 1
	v_permlane32_swap_b32_e32 v22, v18
	v_permlane32_swap_b32_e32 v23, v19
	v_permlane32_swap_b32_e32 v24, v20
	v_permlane32_swap_b32_e32 v25, v21
	v_permlane16_swap_b32_e32 v22, v18
	v_permlane16_swap_b32_e32 v23, v19
	v_permlane16_swap_b32_e32 v24, v20
	v_permlane16_swap_b32_e32 v25, v21
	v_add_f32_e32 v27, v27, v28
	v_cvt_pk_bf16_f32 v22, v22, v23
	v_cvt_pk_bf16_f32 v23, v24, v25
	v_cvt_pk_bf16_f32 v24, v18, v19
	v_lshl_add_u64 v[18:19], v[74:75], 0, v[0:1]
	v_mov_b32_e32 v0, v26
	v_add_f32_e32 v27, v30, v27
	v_cvt_pk_bf16_f32 v25, v20, v21
	v_permlane16_swap_b32_e32 v26, v0
	global_store_dwordx4 v[18:19], v[22:25], off
	v_add_f32_e32 v18, v26, v0
	v_mov_b32_e32 v0, v27
	s_nop 1
	v_permlane16_swap_b32_e32 v27, v0
	v_add_f32_e32 v19, v27, v0
	v_mov_b32_e32 v20, v18
	v_mov_b32_e32 v21, v19
	s_nop 0
	v_permlane32_swap_b32_e32 v18, v20
	v_permlane32_swap_b32_e32 v19, v21
	s_and_saveexec_b64 s[24:25], s[44:45]
	s_cbranch_execz .LBB0_1549
	v_pk_add_f32 v[18:19], v[18:19], v[20:21]
	v_lshlrev_b64 v[20:21], 7, v[96:97]
	v_lshl_add_u64 v[20:21], s[6:7], 0, v[20:21]
	v_lshl_add_u64 v[20:21], s[52:53], 2, v[20:21]
	global_store_dwordx2 v[20:21], v[18:19], off
.LBB0_1549:
	s_or_b64 exec, exec, s[24:25]
	v_pk_add_f32 v[18:19], v[98:99], v[100:101]
	s_mov_b32 s2, 0x3a800000
	v_pk_mul_f32 v[42:43], v[18:19], s[2:3] op_sel_hi:[1,0]
	s_mov_b32 s1, 0x800000
	v_fma_f32 v0, -v43, v43, v42
	v_max_f32_e32 v0, 0, v0
	v_add_f32_e32 v0, 0x3727c5ac, v0
	v_cmp_gt_f32_e32 vcc, s1, v0
	v_mul_f32_e32 v18, 0x4b800000, v0
	s_load_dwordx16 s[64:79], s[34:35], 0x38
	v_cndmask_b32_e32 v0, v0, v18, vcc
	v_rsq_f32_e32 v0, v0
	s_mov_b32 s2, 0x3fd744fd
	s_movk_i32 s1, 0x3fc0
	v_mul_f32_e32 v18, 0x45800000, v0
	v_cndmask_b32_e32 v42, v0, v18, vcc
	v_lshlrev_b64 v[18:19], 12, v[94:95]
	s_waitcnt lgkmcnt(0)
	v_lshl_add_u64 v[18:19], s[78:79], 0, v[18:19]
	v_lshl_add_u64 v[44:45], v[152:153], 2, v[18:19]
	global_load_dwordx4 v[46:49], v[44:45], off offset:16
	global_load_dwordx4 v[50:53], v[44:45], off
	global_load_dwordx4 v[54:57], v[156:157], off offset:16
	global_load_dwordx4 v[58:61], v[156:157], off
	global_load_dwordx4 v[62:65], v[154:155], off offset:16
	global_load_dwordx4 v[66:69], v[154:155], off
	global_load_dwordx4 v[18:21], v[44:45], off offset:528
	global_load_dwordx4 v[38:41], v[44:45], off offset:512
	global_load_dwordx4 v[22:25], v[156:157], off offset:528
	global_load_dwordx4 v[30:33], v[156:157], off offset:512
	global_load_dwordx4 v[26:29], v[154:155], off offset:528
	global_load_dwordx4 v[34:37], v[154:155], off offset:512
	v_lshlrev_b32_e32 v0, 6, v94
	v_and_or_b32 v0, v0, s1, v196
	v_lshlrev_b32_e32 v0, 1, v0
	s_waitcnt vmcnt(10)
	v_sub_f32_e32 v51, v51, v43
	v_sub_f32_e32 v50, v50, v43
	v_sub_f32_e32 v53, v53, v43
	v_sub_f32_e32 v52, v52, v43
	v_pk_mul_f32 v[52:53], v[42:43], v[52:53] op_sel_hi:[0,1]
	v_pk_mul_f32 v[50:51], v[42:43], v[50:51] op_sel_hi:[0,1]
	s_waitcnt vmcnt(6)
; __device__ __forceinline__ float xsum16(float v) { const auto r = __builtin_amdgcn_permlane16_swap(__float_as_uint(v), __float_as_uint(v), false, false); return __uint_as_float(r[0]) + __uint_as_float(r[1]); }
; __device__ __forceinline__ float xsum32(float v) { const auto r = __builtin_amdgcn_permlane32_swap(__float_as_uint(v), __float_as_uint(v), false, false); return __uint_as_float(r[0]) + __uint_as_float(r[1]); }
; __device__ __forceinline__ size_t blk_off(int r, int c, int K) { return (size_t)(r >> 8) * 256 * K + (size_t)(c >> 6) * (256 * 64) + (size_t)((r & 255) * 64 + (c & 63)); }
; __device__ __forceinline__ u32x4 pack8(const f32x4 a, const f32x4 b) { u32x4 w; w.x = cvt_pk_bf16(a[0], a[1]); w.y = cvt_pk_bf16(a[2], a[3]); w.z = cvt_pk_bf16(b[0], b[1]); w.w = cvt_pk_bf16(b[2], b[3]); return w; }
;     __device__ __forceinline__ void operator()(const f32x4 (&acc)[2][2][4][2], const pg8::Unit& u, int wr, int wc, int fr, int fq) const {
;     ...
;             for (int m = 0; m < 4; ++m) { const int row = row0 + ai * 128 + m * 16; const float mu = mu4[m], rs = rs4[m];
;                 f32x4 yv[2][2], gq[2][2], bq_[2][2];
; #pragma unroll
;                 for (int bj = 0; bj < 2; ++bj)
; #pragma unroll
;                     for (int n = 0; n < 2; ++n) { yv[bj][n] = *(const f32x4*)(Yin + (size_t)row * D_ + col0 + bj * 128 + 4 * n); gq[bj][n] = *(const f32x4*)(g + col0 + bj * 128 + 4 * n); bq_[bj][n] = *(const f32x4*)(b + col0 + bj * 128 + 4 * n); }
;                 asm volatile("" ::: "memory");
;                 float s1 = 0.f, s2 = 0.f;
; #pragma unroll
;                 for (int bj = 0; bj < 2; ++bj) { float* yp = Y + (size_t)row * D_ + col0 + bj * 128; f32x4 v[2];
; #pragma unroll
;                     for (int n = 0; n < 2; ++n) { v[n] = (((yv[bj][n] - mu) * rs) * gq[bj][n] + bq_[bj][n]) * ALPHA_ + acc[ai][bj][m][n] * sc;
;                         *(f32x4*)(yp + 4 * n) = v[n]; s1 += (v[n][0] + v[n][1]) + (v[n][2] + v[n][3]); s2 += (v[n][0] * v[n][0] + v[n][1] * v[n][1]) + (v[n][2] * v[n][2] + v[n][3] * v[n][3]); }
;                     *(u32x4*)(Yb + blk_off(row, col0 + bj * 128, D_)) = pack8(v[0], v[1]); }
;                 s1 = xsum32(xsum16(s1)); s2 = xsum32(xsum16(s2));
;                 if (fq == 0) *(f32x2*)(stn + (size_t)row * 32 + (u.pn * 4 + wc) * 2) = (f32x2){s1, s2}; asm volatile("" ::: "memory"); } }
	v_pk_fma_f32 v[50:51], v[58:59], v[50:51], v[66:67]
	v_pk_fma_f32 v[52:53], v[60:61], v[52:53], v[68:69]
	v_pk_fma_f32 v[50:51], v[50:51], s[2:3], v[14:15] op_sel_hi:[1,0,1]
	v_pk_fma_f32 v[52:53], v[52:53], s[2:3], v[16:17] op_sel_hi:[1,0,1]
	v_add_f32_e32 v14, v50, v51
	v_add_f32_e32 v15, v52, v53
	v_add_f32_e32 v14, v14, v15
	v_add_f32_e32 v58, 0, v14
	v_mul_f32_e32 v14, v51, v51
	v_mul_f32_e32 v15, v53, v53
	v_fmac_f32_e32 v14, v50, v50
	v_fmac_f32_e32 v15, v52, v52
	v_add_f32_e32 v59, v14, v15
	v_sub_f32_e32 v15, v47, v43
	v_sub_f32_e32 v14, v46, v43
	v_sub_f32_e32 v17, v49, v43
	v_sub_f32_e32 v16, v48, v43
	v_pk_mul_f32 v[16:17], v[42:43], v[16:17] op_sel_hi:[0,1]
	v_pk_mul_f32 v[14:15], v[42:43], v[14:15] op_sel_hi:[0,1]
	v_pk_fma_f32 v[14:15], v[54:55], v[14:15], v[62:63]
	v_pk_fma_f32 v[16:17], v[56:57], v[16:17], v[64:65]
	v_pk_fma_f32 v[46:47], v[14:15], s[2:3], v[10:11] op_sel_hi:[1,0,1]
	v_pk_fma_f32 v[48:49], v[16:17], s[2:3], v[12:13] op_sel_hi:[1,0,1]
	v_add_f32_e32 v10, v46, v47
	v_add_f32_e32 v11, v48, v49
	v_add_f32_e32 v10, v10, v11
	v_add_f32_e32 v15, v58, v10
	v_mul_f32_e32 v10, v47, v47
	v_mul_f32_e32 v11, v49, v49
	v_fmac_f32_e32 v10, v46, v46
	v_fmac_f32_e32 v11, v48, v48
	v_add_f32_e32 v10, v10, v11
	v_add_f32_e32 v14, v59, v10
	v_cvt_pk_bf16_f32 v10, v50, v51
	v_cvt_pk_bf16_f32 v11, v52, v53
	v_cvt_pk_bf16_f32 v12, v46, v47
	v_cvt_pk_bf16_f32 v13, v48, v49
	v_lshl_add_u64 v[16:17], v[76:77], 0, v[0:1]
	s_nop 0
	s_nop 1
	v_bfe_u32 v55, v227, 4, 2
	v_sub_u32_e32 v54, 0, v55
	v_lshlrev_b32_e32 v54, 4, v54
	v_ashrrev_i32_e32 v55, 31, v54
	v_lshl_add_u64 v[54:55], v[44:45], 0, v[54:55]
	v_permlane16_swap_b32_e32 v50, v46
	v_permlane16_swap_b32_e32 v51, v47
	v_permlane16_swap_b32_e32 v52, v48
	v_permlane16_swap_b32_e32 v53, v49
	v_permlane32_swap_b32_e32 v50, v46
	v_permlane32_swap_b32_e32 v51, v47
	v_permlane32_swap_b32_e32 v52, v48
	v_permlane32_swap_b32_e32 v53, v49
	global_store_dwordx4 v[54:55], v[50:53], off
	global_store_dwordx4 v[54:55], v[46:49], off offset:64
	s_nop 1
	v_permlane32_swap_b32_e32 v50, v46
	v_permlane32_swap_b32_e32 v51, v47
	v_permlane32_swap_b32_e32 v52, v48
	v_permlane32_swap_b32_e32 v53, v49
	v_permlane16_swap_b32_e32 v50, v46
	v_permlane16_swap_b32_e32 v51, v47
	v_permlane16_swap_b32_e32 v52, v48
	v_permlane16_swap_b32_e32 v53, v49
	global_store_dwordx4 v[16:17], v[10:13], off
	s_waitcnt vmcnt(7)
	s_nop 0
	v_sub_f32_e32 v11, v39, v43
	v_sub_f32_e32 v10, v38, v43
	v_sub_f32_e32 v13, v41, v43
	v_sub_f32_e32 v12, v40, v43
	v_pk_mul_f32 v[12:13], v[42:43], v[12:13] op_sel_hi:[0,1]
	v_pk_mul_f32 v[10:11], v[42:43], v[10:11] op_sel_hi:[0,1]
	s_waitcnt vmcnt(3)
	v_pk_fma_f32 v[10:11], v[30:31], v[10:11], v[34:35]
	v_pk_fma_f32 v[12:13], v[32:33], v[12:13], v[36:37]
	v_pk_fma_f32 v[6:7], v[10:11], s[2:3], v[6:7] op_sel_hi:[1,0,1]
	v_pk_fma_f32 v[8:9], v[12:13], s[2:3], v[8:9] op_sel_hi:[1,0,1]
	v_add_f32_e32 v10, v6, v7
	v_add_f32_e32 v11, v8, v9
	v_add_f32_e32 v10, v10, v11
	v_add_f32_e32 v15, v15, v10
	v_mul_f32_e32 v10, v7, v7
	v_mul_f32_e32 v11, v9, v9
	v_fmac_f32_e32 v10, v6, v6
	v_fmac_f32_e32 v11, v8, v8
	v_add_f32_e32 v10, v10, v11
	v_add_f32_e32 v14, v14, v10
	v_sub_f32_e32 v11, v19, v43
	v_sub_f32_e32 v10, v18, v43
	v_sub_f32_e32 v13, v21, v43
	v_sub_f32_e32 v12, v20, v43
	v_pk_mul_f32 v[12:13], v[42:43], v[12:13] op_sel_hi:[0,1]
	v_pk_mul_f32 v[10:11], v[42:43], v[10:11] op_sel_hi:[0,1]
	v_pk_fma_f32 v[10:11], v[22:23], v[10:11], v[26:27]
	v_pk_fma_f32 v[12:13], v[24:25], v[12:13], v[28:29]
	v_pk_fma_f32 v[2:3], v[10:11], s[2:3], v[2:3] op_sel_hi:[1,0,1]
	v_pk_fma_f32 v[4:5], v[12:13], s[2:3], v[4:5] op_sel_hi:[1,0,1]
	v_add_f32_e32 v10, v2, v3
	v_add_f32_e32 v11, v4, v5
	v_add_f32_e32 v10, v10, v11
	v_mul_f32_e32 v11, v3, v3
	v_mul_f32_e32 v12, v5, v5
	v_add_f32_e32 v10, v15, v10
	v_fmac_f32_e32 v11, v2, v2
	v_fmac_f32_e32 v12, v4, v4
	s_nop 0
	s_nop 1
	v_bfe_u32 v17, v227, 4, 2
	v_sub_u32_e32 v16, 0, v17
	v_lshlrev_b32_e32 v16, 4, v16
	v_ashrrev_i32_e32 v17, 31, v16
	v_lshl_add_u64 v[16:17], v[44:45], 0, v[16:17]
	v_permlane16_swap_b32_e32 v6, v2
	v_permlane16_swap_b32_e32 v7, v3
	v_permlane16_swap_b32_e32 v8, v4
	v_permlane16_swap_b32_e32 v9, v5
	v_permlane32_swap_b32_e32 v6, v2
	v_permlane32_swap_b32_e32 v7, v3
	v_permlane32_swap_b32_e32 v8, v4
	v_permlane32_swap_b32_e32 v9, v5
	global_store_dwordx4 v[16:17], v[6:9], off offset:512
	global_store_dwordx4 v[16:17], v[2:5], off offset:576
	s_nop 1
	v_permlane32_swap_b32_e32 v6, v2
	v_permlane32_swap_b32_e32 v7, v3
	v_permlane32_swap_b32_e32 v8, v4
	v_permlane32_swap_b32_e32 v9, v5
	v_permlane16_swap_b32_e32 v6, v2
	v_permlane16_swap_b32_e32 v7, v3
	v_permlane16_swap_b32_e32 v8, v4
	v_permlane16_swap_b32_e32 v9, v5
	v_add_f32_e32 v11, v11, v12
	v_cvt_pk_bf16_f32 v6, v6, v7
	v_cvt_pk_bf16_f32 v7, v8, v9
	v_cvt_pk_bf16_f32 v8, v2, v3
	v_lshl_add_u64 v[2:3], v[74:75], 0, v[0:1]
	v_mov_b32_e32 v0, v10
	v_add_f32_e32 v11, v14, v11
	v_cvt_pk_bf16_f32 v9, v4, v5
	v_permlane16_swap_b32_e32 v10, v0
	global_store_dwordx4 v[2:3], v[6:9], off
	v_add_f32_e32 v2, v10, v0
	v_mov_b32_e32 v0, v11
	s_nop 1
	v_permlane16_swap_b32_e32 v11, v0
	v_add_f32_e32 v3, v11, v0
	v_mov_b32_e32 v4, v2
	v_mov_b32_e32 v5, v3
	s_nop 0
	v_permlane32_swap_b32_e32 v2, v4
	v_permlane32_swap_b32_e32 v3, v5
	s_and_saveexec_b64 s[24:25], s[44:45]
	s_cbranch_execz .LBB0_1551
	v_pk_add_f32 v[2:3], v[2:3], v[4:5]
	v_lshlrev_b64 v[4:5], 7, v[94:95]
	v_lshl_add_u64 v[4:5], s[6:7], 0, v[4:5]
	v_lshl_add_u64 v[4:5], s[52:53], 2, v[4:5]
	global_store_dwordx2 v[4:5], v[2:3], off

; __device__ __forceinline__ float xsum16(float v) { const auto r = __builtin_amdgcn_permlane16_swap(__float_as_uint(v), __float_as_uint(v), false, false); return __uint_as_float(r[0]) + __uint_as_float(r[1]); }
; __device__ __forceinline__ float xsum32(float v) { const auto r = __builtin_amdgcn_permlane32_swap(__float_as_uint(v), __float_as_uint(v), false, false); return __uint_as_float(r[0]) + __uint_as_float(r[1]); }
; __device__ __forceinline__ void row_stats4(const float* st, int rowb, int fq, float (&mu)[4], float (&rs)[4]) {
;     ...
;     for (int m = 0; m < 4; ++m) { const f32x4* p = (const f32x4*)(st + (size_t)(rowb + m * 16) * 32 + fq * 8); a[m] = p[0]; b[m] = p[1]; }
; #pragma unroll
;     for (int m = 0; m < 4; ++m) { float s1 = (a[m][0] + a[m][2]) + (b[m][0] + b[m][2]), s2 = (a[m][1] + a[m][3]) + (b[m][1] + b[m][3]);
;         s1 = xsum32(xsum16(s1)); s2 = xsum32(xsum16(s2));
;         const float mm = s1 * (1.0f / 1024.0f); mu[m] = mm; rs[m] = rsqrtf(fmaxf(s2 * (1.0f / 1024.0f) - mm * mm, 0.f) + LN_EPS_); }
;     __device__ __forceinline__ void operator()(const f32x4 (&acc)[2][2][4][2], const pg8::Unit& u, int wr, int wc, int fr, int fq) const {
;     ...
;         for (int ai = 0; ai < 2; ++ai) { float mu4[4], rs4[4]; row_stats4(stp, row0 + ai * 128, fq, mu4, rs4);
; #pragma unroll
;             for (int m = 0; m < 4; ++m) { const int row = row0 + ai * 128 + m * 16; const float mu = mu4[m], rs = rs4[m];
;                 f32x4 yv[2][2], gq[2][2], bq_[2][2];
; #pragma unroll
;                 for (int bj = 0; bj < 2; ++bj)
; #pragma unroll
;                     for (int n = 0; n < 2; ++n) { yv[bj][n] = *(const f32x4*)(Yin + (size_t)row * D_ + col0 + bj * 128 + 4 * n); gq[bj][n] = *(const f32x4*)(g + col0 + bj * 128 + 4 * n); bq_[bj][n] = *(const f32x4*)(b + col0 + bj * 128 + 4 * n); }
;                 asm volatile("" ::: "memory");
;                 float s1 = 0.f, s2 = 0.f;
; #pragma unroll
;                 for (int bj = 0; bj < 2; ++bj) { float* yp = Y + (size_t)row * D_ + col0 + bj * 128; f32x4 v[2];
; #pragma unroll
;                     for (int n = 0; n < 2; ++n) { v[n] = (((yv[bj][n] - mu) * rs) * gq[bj][n] + bq_[bj][n]) * ALPHA_ + acc[ai][bj][m][n] * sc;
;                         *(f32x4*)(yp + 4 * n) = v[n]; s1 += (v[n][0] + v[n][1]) + (v[n][2] + v[n][3]); s2 += (v[n][0] * v[n][0] + v[n][1] * v[n][1]) + (v[n][2] * v[n][2] + v[n][3] * v[n][3]); }
.LBB0_1703:
	s_lshl_b32 s3, s3, 8
	s_add_i32 s3, s3, s0
	v_or_b32_e32 v158, s3, v184
	v_ashrrev_i32_e32 v159, 31, v158
	v_lshlrev_b64 v[130:131], 7, v[158:159]
	v_lshl_add_u64 v[136:137], v[146:147], 0, v[130:131]
	v_or_b32_e32 v182, 16, v158
	global_load_dwordx4 v[132:135], v[136:137], off
	global_load_dwordx4 v[166:169], v[136:137], off offset:16
	v_ashrrev_i32_e32 v183, 31, v182
	v_lshlrev_b64 v[172:173], 7, v[182:183]
	v_lshl_add_u64 v[136:137], v[146:147], 0, v[172:173]
	global_load_dwordx4 v[174:177], v[136:137], off
	global_load_dwordx4 v[178:181], v[136:137], off offset:16
	v_or_b32_e32 v170, 32, v158
	v_ashrrev_i32_e32 v171, 31, v170
	v_lshlrev_b64 v[164:165], 7, v[170:171]
	v_lshl_add_u64 v[136:137], v[146:147], 0, v[164:165]
	global_load_dwordx4 v[186:189], v[136:137], off
	global_load_dwordx4 v[190:193], v[136:137], off offset:16
	s_load_dwordx16 s[60:75], s[34:35], 0x38
	s_lshl_b32 s1, s2, 8
	s_lshl_b32 s16, s2, 3
	s_or_b32 s2, s1, s53
	v_or_b32_e32 v162, 48, v158
	v_or_b32_e32 v152, s2, v185
	v_ashrrev_i32_e32 v163, 31, v162
	v_ashrrev_i32_e32 v153, 31, v152
	v_lshlrev_b64 v[136:137], 12, v[158:159]
	v_lshlrev_b64 v[160:161], 7, v[162:163]
	v_lshlrev_b64 v[198:199], 2, v[152:153]
	s_waitcnt lgkmcnt(0)
	v_lshl_add_u64 v[136:137], s[74:75], 0, v[136:137]
	v_lshl_add_u64 v[202:203], v[146:147], 0, v[160:161]
	v_lshl_add_u64 v[156:157], s[10:11], 0, v[198:199]
	v_lshl_add_u64 v[154:155], s[12:13], 0, v[198:199]
	v_lshl_add_u64 v[136:137], v[136:137], 0, v[198:199]
	global_load_dwordx4 v[198:201], v[202:203], off
	s_nop 0
	global_load_dwordx4 v[202:205], v[202:203], off offset:16
	s_or_b32 s38, s16, s15
	s_mov_b32 s16, 0x3a800000
	s_mov_b32 s1, 0x800000
	global_load_dwordx4 v[206:209], v[136:137], off offset:16
	global_load_dwordx4 v[210:213], v[136:137], off
	global_load_dwordx4 v[214:217], v[156:157], off offset:16
	global_load_dwordx4 v[218:221], v[156:157], off
	global_load_dwordx4 v[222:225], v[154:155], off offset:16
	global_load_dwordx4 v[234:237], v[154:155], off
	s_mov_b32 s18, 0x3fd744fd
	s_ashr_i32 s44, s2, 6
	v_bitop3_b32 v196, s2, 56, v185 bitop3:0xc8
	s_ashr_i32 s39, s38, 31
	s_ashr_i32 s45, s44, 31
	s_waitcnt vmcnt(0)
	v_mov_b32_e32 v228, v132
	v_mov_b32_e32 v229, v166
	v_mov_b32_e32 v238, v134
	v_mov_b32_e32 v239, v168
	v_mov_b32_e32 v166, v133
	v_mov_b32_e32 v168, v135
	v_pk_add_f32 v[132:133], v[228:229], v[238:239]
	v_pk_add_f32 v[134:135], v[166:167], v[168:169]
	v_pk_add_f32 v[132:133], v[132:133], v[132:133] op_sel:[0,1] op_sel_hi:[1,0]
	v_pk_add_f32 v[134:135], v[134:135], v[134:135] op_sel:[0,1] op_sel_hi:[1,0]
	v_mov_b32_e32 v166, v174
	v_mov_b32_e32 v167, v178
	v_mov_b32_e32 v168, v176
	v_mov_b32_e32 v169, v180
	v_mov_b32_e32 v0, v132
	v_mov_b32_e32 v133, v134
	v_pk_add_f32 v[166:167], v[166:167], v[168:169]
	v_permlane16_swap_b32_e32 v132, v0
	v_permlane16_swap_b32_e32 v134, v133
	v_mov_b32_e32 v178, v175
	v_mov_b32_e32 v180, v177
	v_pk_add_f32 v[166:167], v[166:167], v[166:167] op_sel:[0,1] op_sel_hi:[1,0]
	v_add_f32_e32 v177, v132, v0
	v_add_f32_e32 v176, v134, v133
	v_pk_add_f32 v[168:169], v[178:179], v[180:181]
	v_mov_b32_e32 v135, v166
	v_mov_b32_e32 v179, v177
	v_mov_b32_e32 v178, v176
	v_permlane16_swap_b32_e32 v166, v135
	v_permlane32_swap_b32_e32 v177, v179
	v_permlane32_swap_b32_e32 v176, v178
	v_add_f32_e32 v133, v166, v135
	v_pk_add_f32 v[166:167], v[176:177], v[178:179]
	v_pk_add_f32 v[168:169], v[168:169], v[168:169] op_sel:[0,1] op_sel_hi:[1,0]
	v_pk_mul_f32 v[228:229], v[166:167], s[16:17] op_sel_hi:[1,0]
	v_mov_b32_e32 v159, v168
	v_fma_f32 v0, -v229, v229, v228
	v_max_f32_e32 v0, 0, v0
	v_permlane16_swap_b32_e32 v168, v159
	v_add_f32_e32 v0, 0x3727c5ac, v0
	v_add_f32_e32 v132, v168, v159
	v_mul_f32_e32 v159, 0x4b800000, v0
	v_cmp_gt_f32_e32 vcc, s1, v0
	v_mov_b32_e32 v174, v186
	v_mov_b32_e32 v175, v190
	v_cndmask_b32_e32 v0, v0, v159, vcc
	v_rsq_f32_e32 v0, v0
	v_mov_b32_e32 v166, v188
	v_mov_b32_e32 v167, v192
	v_pk_add_f32 v[166:167], v[174:175], v[166:167]
	v_mul_f32_e32 v159, 0x45800000, v0
	v_pk_add_f32 v[166:167], v[166:167], v[166:167] op_sel:[0,1] op_sel_hi:[1,0]
	v_mov_b32_e32 v190, v187
	v_mov_b32_e32 v192, v189
	v_cndmask_b32_e32 v0, v0, v159, vcc
	v_pk_add_f32 v[168:169], v[190:191], v[192:193]
	v_mov_b32_e32 v159, v166
	v_pk_add_f32 v[168:169], v[168:169], v[168:169] op_sel:[0,1] op_sel_hi:[1,0]
	s_nop 0
	v_permlane16_swap_b32_e32 v166, v159
	v_add_f32_e32 v175, v166, v159
	v_mov_b32_e32 v159, v168
	s_nop 1
	v_permlane16_swap_b32_e32 v168, v159
	global_load_dwordx4 v[178:181], v[136:137], off offset:528
	global_load_dwordx4 v[186:189], v[136:137], off offset:512
	v_add_f32_e32 v174, v168, v159
	v_mov_b32_e32 v166, v198
	v_mov_b32_e32 v167, v202
	v_mov_b32_e32 v168, v200
	v_mov_b32_e32 v169, v204
	v_mov_b32_e32 v202, v199
	v_mov_b32_e32 v204, v201
	v_pk_add_f32 v[166:167], v[166:167], v[168:169]
	v_pk_add_f32 v[168:169], v[202:203], v[204:205]
	global_load_dwordx4 v[190:193], v[156:157], off offset:528
	global_load_dwordx4 v[198:201], v[156:157], off offset:512
	global_load_dwordx4 v[202:205], v[154:155], off offset:528
	global_load_dwordx4 v[238:241], v[154:155], off offset:512
	v_sub_f32_e32 v213, v213, v229
	v_sub_f32_e32 v212, v212, v229
	v_sub_f32_e32 v211, v211, v229
	v_sub_f32_e32 v210, v210, v229
	v_pk_mul_f32 v[210:211], v[0:1], v[210:211] op_sel_hi:[0,1]
	v_pk_mul_f32 v[212:213], v[0:1], v[212:213] op_sel_hi:[0,1]
	v_sub_f32_e32 v209, v209, v229
	v_sub_f32_e32 v208, v208, v229
	v_sub_f32_e32 v207, v207, v229
	v_sub_f32_e32 v206, v206, v229
	v_pk_fma_f32 v[212:213], v[220:221], v[212:213], v[236:237]
	v_pk_fma_f32 v[210:211], v[218:219], v[210:211], v[234:235]
; __device__ __forceinline__ size_t blk_off(int r, int c, int K) { return (size_t)(r >> 8) * 256 * K + (size_t)(c >> 6) * (256 * 64) + (size_t)((r & 255) * 64 + (c & 63)); }
; __device__ __forceinline__ u32x4 pack8(const f32x4 a, const f32x4 b) { u32x4 w; w.x = cvt_pk_bf16(a[0], a[1]); w.y = cvt_pk_bf16(a[2], a[3]); w.z = cvt_pk_bf16(b[0], b[1]); w.w = cvt_pk_bf16(b[2], b[3]); return w; }
;     __device__ __forceinline__ void operator()(const f32x4 (&acc)[2][2][4][2], const pg8::Unit& u, int wr, int wc, int fr, int fq) const {
;     ...
;                     for (int n = 0; n < 2; ++n) { yv[bj][n] = *(const f32x4*)(Yin + (size_t)row * D_ + col0 + bj * 128 + 4 * n); gq[bj][n] = *(const f32x4*)(g + col0 + bj * 128 + 4 * n); bq_[bj][n] = *(const f32x4*)(b + col0 + bj * 128 + 4 * n); }
;                 asm volatile("" ::: "memory");
;                 float s1 = 0.f, s2 = 0.f;
; #pragma unroll
;                 for (int bj = 0; bj < 2; ++bj) { float* yp = Y + (size_t)row * D_ + col0 + bj * 128; f32x4 v[2];
; #pragma unroll
;                     for (int n = 0; n < 2; ++n) { v[n] = (((yv[bj][n] - mu) * rs) * gq[bj][n] + bq_[bj][n]) * ALPHA_ + acc[ai][bj][m][n] * sc;
;                         *(f32x4*)(yp + 4 * n) = v[n]; s1 += (v[n][0] + v[n][1]) + (v[n][2] + v[n][3]); s2 += (v[n][0] * v[n][0] + v[n][1] * v[n][1]) + (v[n][2] * v[n][2] + v[n][3] * v[n][3]); }
;                     *(u32x4*)(Yb + blk_off(row, col0 + bj * 128, D_)) = pack8(v[0], v[1]); }
	v_pk_mul_f32 v[206:207], v[0:1], v[206:207] op_sel_hi:[0,1]
	v_pk_mul_f32 v[208:209], v[0:1], v[208:209] op_sel_hi:[0,1]
	v_pk_mul_f32 v[210:211], v[210:211], s[18:19] op_sel_hi:[1,0]
	v_pk_mul_f32 v[212:213], v[212:213], s[18:19] op_sel_hi:[1,0]
	v_pk_fma_f32 v[208:209], v[216:217], v[208:209], v[224:225]
	v_pk_fma_f32 v[206:207], v[214:215], v[206:207], v[222:223]
	v_pk_fma_f32 v[128:129], v[128:129], 0.5, v[212:213] op_sel_hi:[1,0,1]
	v_pk_fma_f32 v[126:127], v[126:127], 0.5, v[210:211] op_sel_hi:[1,0,1]
	v_pk_mul_f32 v[206:207], v[206:207], s[18:19] op_sel_hi:[1,0]
	v_pk_mul_f32 v[208:209], v[208:209], s[18:19] op_sel_hi:[1,0]
	v_add_f32_e32 v197, v126, v127
	v_add_f32_e32 v210, v128, v129
	v_pk_fma_f32 v[124:125], v[124:125], 0.5, v[208:209] op_sel_hi:[1,0,1]
	v_pk_fma_f32 v[122:123], v[122:123], 0.5, v[206:207] op_sel_hi:[1,0,1]
	v_pk_add_f32 v[166:167], v[166:167], v[166:167] op_sel:[0,1] op_sel_hi:[1,0]
	v_add_f32_e32 v197, v197, v210
	v_add_f32_e32 v206, v122, v123
	v_add_f32_e32 v207, v124, v125
	v_mov_b32_e32 v159, v166
	v_add_f32_e32 v197, 0, v197
	v_add_f32_e32 v206, v206, v207
	v_pk_add_f32 v[168:169], v[168:169], v[168:169] op_sel:[0,1] op_sel_hi:[1,0]
	v_permlane16_swap_b32_e32 v166, v159
	v_mul_f32_e32 v210, v127, v127
	v_mul_f32_e32 v211, v129, v129
	v_add_f32_e32 v197, v197, v206
	v_mul_f32_e32 v206, v123, v123
	v_mul_f32_e32 v207, v125, v125
	v_add_f32_e32 v167, v166, v159
	v_mov_b32_e32 v159, v168
	s_ashr_i32 s16, s3, 8
	s_nop 0
	v_fmac_f32_e32 v210, v126, v126
	v_fmac_f32_e32 v211, v128, v128
	s_nop 1
	v_bfe_u32 v135, v227, 4, 2
	v_sub_u32_e32 v134, 0, v135
	v_lshlrev_b32_e32 v134, 4, v134
	v_ashrrev_i32_e32 v135, 31, v134
	v_lshl_add_u64 v[134:135], v[136:137], 0, v[134:135]
	v_permlane16_swap_b32_e32 v126, v122
	v_permlane16_swap_b32_e32 v127, v123
	v_permlane16_swap_b32_e32 v128, v124
	v_permlane16_swap_b32_e32 v129, v125
	v_permlane32_swap_b32_e32 v126, v122
	v_permlane32_swap_b32_e32 v127, v123
	v_permlane32_swap_b32_e32 v128, v124
	v_permlane32_swap_b32_e32 v129, v125
	global_store_dwordx4 v[134:135], v[126:129], off
	global_store_dwordx4 v[134:135], v[122:125], off offset:64
	s_nop 1
	v_permlane32_swap_b32_e32 v126, v122
	v_permlane32_swap_b32_e32 v127, v123
	v_permlane32_swap_b32_e32 v128, v124
	v_permlane32_swap_b32_e32 v129, v125
	v_permlane16_swap_b32_e32 v126, v122
	v_permlane16_swap_b32_e32 v127, v123
	v_permlane16_swap_b32_e32 v128, v124
	v_permlane16_swap_b32_e32 v129, v125
	v_fmac_f32_e32 v206, v122, v122
	v_fmac_f32_e32 v207, v124, v124
	v_cvt_pk_bf16_f32 v126, v126, v127
	v_cvt_pk_bf16_f32 v127, v128, v129
	v_cvt_pk_bf16_f32 v128, v122, v123
	v_cvt_pk_bf16_f32 v129, v124, v125
	v_permlane16_swap_b32_e32 v168, v159
	s_ashr_i32 s17, s16, 31
	v_add_f32_e32 v166, v168, v159
	s_lshl_b64 s[16:17], s[16:17], 19
	v_lshlrev_b32_e32 v159, 6, v158
	s_movk_i32 s1, 0x33c0
	v_readlane_b32 s2, v253, 59
	v_and_or_b32 v159, v159, s1, v196
	v_readlane_b32 s3, v253, 60
	s_add_u32 s1, s2, s16
	s_addc_u32 s16, s3, s17
	s_lshl_b64 s[24:25], s[44:45], 15
	s_add_u32 s48, s1, s24
	s_waitcnt vmcnt(6)
	v_sub_f32_e32 v123, v189, v229
	v_sub_f32_e32 v122, v188, v229
	v_sub_f32_e32 v125, v187, v229
	v_sub_f32_e32 v124, v186, v229
	v_pk_mul_f32 v[124:125], v[0:1], v[124:125] op_sel_hi:[0,1]
	v_pk_mul_f32 v[122:123], v[0:1], v[122:123] op_sel_hi:[0,1]
	s_addc_u32 s49, s16, s25
	v_lshlrev_b32_e32 v159, 1, v159
	global_store_dwordx4 v159, v[126:129], s[48:49]
	v_add_f32_e32 v210, v210, v211
	s_waitcnt vmcnt(3)
	v_pk_fma_f32 v[122:123], v[200:201], v[122:123], v[240:241]
	v_pk_fma_f32 v[124:125], v[198:199], v[124:125], v[238:239]
	v_pk_mul_f32 v[122:123], v[122:123], s[18:19] op_sel_hi:[1,0]
	v_pk_mul_f32 v[124:125], v[124:125], s[18:19] op_sel_hi:[1,0]
	v_pk_fma_f32 v[120:121], v[120:121], 0.5, v[122:123] op_sel_hi:[1,0,1]
	v_pk_fma_f32 v[118:119], v[118:119], 0.5, v[124:125] op_sel_hi:[1,0,1]
	v_add_f32_e32 v123, v120, v121
	v_add_f32_e32 v122, v118, v119
	v_add_f32_e32 v122, v122, v123
	v_add_f32_e32 v126, v197, v122
	v_mul_f32_e32 v122, v119, v119
	v_mul_f32_e32 v123, v121, v121
	v_add_f32_e32 v206, v206, v207
	v_fmac_f32_e32 v122, v118, v118
	v_fmac_f32_e32 v123, v120, v120
	v_add_f32_e32 v206, v210, v206
	v_add_f32_e32 v122, v122, v123
	v_add_f32_e32 v127, v206, v122
	v_sub_f32_e32 v123, v181, v229
	v_sub_f32_e32 v122, v180, v229
	v_sub_f32_e32 v125, v179, v229
	v_sub_f32_e32 v124, v178, v229
	v_pk_mul_f32 v[124:125], v[0:1], v[124:125] op_sel_hi:[0,1]
	v_pk_mul_f32 v[122:123], v[0:1], v[122:123] op_sel_hi:[0,1]
	v_pk_fma_f32 v[122:123], v[192:193], v[122:123], v[204:205]
	v_pk_fma_f32 v[124:125], v[190:191], v[124:125], v[202:203]
	v_pk_mul_f32 v[122:123], v[122:123], s[18:19] op_sel_hi:[1,0]
	v_pk_mul_f32 v[124:125], v[124:125], s[18:19] op_sel_hi:[1,0]
	v_pk_fma_f32 v[116:117], v[116:117], 0.5, v[122:123] op_sel_hi:[1,0,1]
	v_pk_fma_f32 v[114:115], v[114:115], 0.5, v[124:125] op_sel_hi:[1,0,1]
	v_add_f32_e32 v122, v116, v117
	v_add_f32_e32 v0, v114, v115
	v_add_f32_e32 v0, v0, v122
	v_mul_f32_e32 v122, v115, v115
	v_mul_f32_e32 v123, v117, v117
	v_add_f32_e32 v0, v126, v0
	v_fmac_f32_e32 v122, v114, v114
	v_fmac_f32_e32 v123, v116, v116
	s_nop 0
	s_nop 1
	v_bfe_u32 v125, v227, 4, 2
	v_sub_u32_e32 v124, 0, v125
	v_lshlrev_b32_e32 v124, 4, v124
	v_ashrrev_i32_e32 v125, 31, v124
	v_lshl_add_u64 v[124:125], v[136:137], 0, v[124:125]
	v_permlane16_swap_b32_e32 v118, v114
	v_permlane16_swap_b32_e32 v119, v115
	v_permlane16_swap_b32_e32 v120, v116
	v_permlane16_swap_b32_e32 v121, v117
	v_permlane32_swap_b32_e32 v118, v114
	v_permlane32_swap_b32_e32 v119, v115
	v_permlane32_swap_b32_e32 v120, v116
	v_permlane32_swap_b32_e32 v121, v117
; __device__ __forceinline__ float xsum16(float v) { const auto r = __builtin_amdgcn_permlane16_swap(__float_as_uint(v), __float_as_uint(v), false, false); return __uint_as_float(r[0]) + __uint_as_float(r[1]); }
; __device__ __forceinline__ float xsum32(float v) { const auto r = __builtin_amdgcn_permlane32_swap(__float_as_uint(v), __float_as_uint(v), false, false); return __uint_as_float(r[0]) + __uint_as_float(r[1]); }
; __device__ __forceinline__ size_t blk_off(int r, int c, int K) { return (size_t)(r >> 8) * 256 * K + (size_t)(c >> 6) * (256 * 64) + (size_t)((r & 255) * 64 + (c & 63)); }
; __device__ __forceinline__ u32x4 pack8(const f32x4 a, const f32x4 b) { u32x4 w; w.x = cvt_pk_bf16(a[0], a[1]); w.y = cvt_pk_bf16(a[2], a[3]); w.z = cvt_pk_bf16(b[0], b[1]); w.w = cvt_pk_bf16(b[2], b[3]); return w; }
;     __device__ __forceinline__ void operator()(const f32x4 (&acc)[2][2][4][2], const pg8::Unit& u, int wr, int wc, int fr, int fq) const {
;     ...
;             for (int m = 0; m < 4; ++m) { const int row = row0 + ai * 128 + m * 16; const float mu = mu4[m], rs = rs4[m];
;                 f32x4 yv[2][2], gq[2][2], bq_[2][2];
; #pragma unroll
;                 for (int bj = 0; bj < 2; ++bj)
; #pragma unroll
;                     for (int n = 0; n < 2; ++n) { yv[bj][n] = *(const f32x4*)(Yin + (size_t)row * D_ + col0 + bj * 128 + 4 * n); gq[bj][n] = *(const f32x4*)(g + col0 + bj * 128 + 4 * n); bq_[bj][n] = *(const f32x4*)(b + col0 + bj * 128 + 4 * n); }
;                 asm volatile("" ::: "memory");
;                 float s1 = 0.f, s2 = 0.f;
; #pragma unroll
;                 for (int bj = 0; bj < 2; ++bj) { float* yp = Y + (size_t)row * D_ + col0 + bj * 128; f32x4 v[2];
; #pragma unroll
;                     for (int n = 0; n < 2; ++n) { v[n] = (((yv[bj][n] - mu) * rs) * gq[bj][n] + bq_[bj][n]) * ALPHA_ + acc[ai][bj][m][n] * sc;
;                         *(f32x4*)(yp + 4 * n) = v[n]; s1 += (v[n][0] + v[n][1]) + (v[n][2] + v[n][3]); s2 += (v[n][0] * v[n][0] + v[n][1] * v[n][1]) + (v[n][2] * v[n][2] + v[n][3] * v[n][3]); }
;                     *(u32x4*)(Yb + blk_off(row, col0 + bj * 128, D_)) = pack8(v[0], v[1]); }
;                 s1 = xsum32(xsum16(s1)); s2 = xsum32(xsum16(s2));
;                 if (fq == 0) *(f32x2*)(stn + (size_t)row * 32 + (u.pn * 4 + wc) * 2) = (f32x2){s1, s2}; asm volatile("" ::: "memory"); } }
	global_store_dwordx4 v[124:125], v[118:121], off offset:512
	global_store_dwordx4 v[124:125], v[114:117], off offset:576
	s_nop 1
	v_permlane32_swap_b32_e32 v118, v114
	v_permlane32_swap_b32_e32 v119, v115
	v_permlane32_swap_b32_e32 v120, v116
	v_permlane32_swap_b32_e32 v121, v117
	v_permlane16_swap_b32_e32 v118, v114
	v_permlane16_swap_b32_e32 v119, v115
	v_permlane16_swap_b32_e32 v120, v116
	v_permlane16_swap_b32_e32 v121, v117
	v_add_f32_e32 v122, v122, v123
	v_cvt_pk_bf16_f32 v118, v118, v119
	v_cvt_pk_bf16_f32 v119, v120, v121
	v_cvt_pk_bf16_f32 v120, v114, v115
	v_mov_b32_e32 v114, v0
	v_add_f32_e32 v122, v127, v122
	s_nop 0
	v_permlane16_swap_b32_e32 v0, v114
	s_or_b32 s2, s44, 2
	v_add_f32_e32 v114, v0, v114
	v_mov_b32_e32 v0, v122
	s_ashr_i32 s3, s2, 31
	s_nop 0
	v_permlane16_swap_b32_e32 v122, v0
	s_lshl_b64 s[44:45], s[2:3], 15
	v_add_f32_e32 v115, v122, v0
	v_mov_b32_e32 v135, v133
	v_mov_b32_e32 v134, v132
	v_mov_b32_e32 v177, v175
	v_mov_b32_e32 v176, v174
	v_mov_b32_e32 v169, v167
	v_mov_b32_e32 v168, v166
	v_cvt_pk_bf16_f32 v121, v116, v117
	s_add_u32 s46, s1, s44
	v_mov_b32_e32 v116, v114
	v_mov_b32_e32 v117, v115
	v_permlane32_swap_b32_e32 v133, v135
	v_permlane32_swap_b32_e32 v132, v134
	v_permlane32_swap_b32_e32 v175, v177
	v_permlane32_swap_b32_e32 v174, v176
	v_permlane32_swap_b32_e32 v167, v169
	v_permlane32_swap_b32_e32 v166, v168
	s_addc_u32 s47, s16, s45
	v_permlane32_swap_b32_e32 v114, v116
	v_permlane32_swap_b32_e32 v115, v117
	global_store_dwordx4 v159, v[118:121], s[46:47]
	s_and_saveexec_b64 s[26:27], s[40:41]
	s_cbranch_execz .LBB0_1705
	v_pk_add_f32 v[114:115], v[114:115], v[116:117]
	v_lshl_add_u64 v[116:117], s[8:9], 0, v[130:131]
	v_lshl_add_u64 v[116:117], s[38:39], 2, v[116:117]
	global_store_dwordx2 v[116:117], v[114:115], off
.LBB0_1705:
	s_or_b64 exec, exec, s[26:27]
	v_pk_add_f32 v[114:115], v[132:133], v[134:135]
	s_mov_b32 s2, 0x3a800000
	v_pk_mul_f32 v[178:179], v[114:115], s[2:3] op_sel_hi:[1,0]
	s_mov_b32 s1, 0x800000
	v_fma_f32 v0, -v179, v179, v178
	v_max_f32_e32 v0, 0, v0
	v_add_f32_e32 v0, 0x3727c5ac, v0
	v_cmp_gt_f32_e32 vcc, s1, v0
	v_mul_f32_e32 v114, 0x4b800000, v0
	s_load_dwordx16 s[60:75], s[34:35], 0x38
	v_cndmask_b32_e32 v0, v0, v114, vcc
	v_rsq_f32_e32 v0, v0
	v_lshlrev_b32_e32 v159, 6, v182
	s_mov_b32 s2, 0x3fd744fd
	v_mul_f32_e32 v114, 0x45800000, v0
	v_cndmask_b32_e32 v0, v0, v114, vcc
	v_lshlrev_b64 v[114:115], 12, v[182:183]
	s_waitcnt lgkmcnt(0)
	v_lshl_add_u64 v[114:115], s[74:75], 0, v[114:115]
	v_lshl_add_u64 v[180:181], v[152:153], 2, v[114:115]
	global_load_dwordx4 v[186:189], v[180:181], off offset:16
	global_load_dwordx4 v[190:193], v[180:181], off
	global_load_dwordx4 v[198:201], v[156:157], off offset:16
	global_load_dwordx4 v[202:205], v[156:157], off
	global_load_dwordx4 v[206:209], v[154:155], off offset:16
	global_load_dwordx4 v[210:213], v[154:155], off
	global_load_dwordx4 v[114:117], v[180:181], off offset:528
	global_load_dwordx4 v[134:137], v[180:181], off offset:512
	global_load_dwordx4 v[118:121], v[156:157], off offset:528
	global_load_dwordx4 v[126:129], v[156:157], off offset:512
	global_load_dwordx4 v[122:125], v[154:155], off offset:528
	global_load_dwordx4 v[130:133], v[154:155], off offset:512
	s_movk_i32 s1, 0x37c0
	v_and_or_b32 v159, v159, s1, v196
	v_lshlrev_b32_e32 v159, 1, v159
	s_waitcnt vmcnt(11)
	v_sub_f32_e32 v187, v187, v179
	s_waitcnt vmcnt(10)
	v_sub_f32_e32 v183, v193, v179
	v_sub_f32_e32 v182, v192, v179
	v_sub_f32_e32 v191, v191, v179
	v_sub_f32_e32 v190, v190, v179
	v_pk_mul_f32 v[190:191], v[0:1], v[190:191] op_sel_hi:[0,1]
	v_pk_mul_f32 v[182:183], v[0:1], v[182:183] op_sel_hi:[0,1]
	s_waitcnt vmcnt(6)
	v_pk_fma_f32 v[182:183], v[204:205], v[182:183], v[212:213]
	v_pk_fma_f32 v[190:191], v[202:203], v[190:191], v[210:211]
	v_pk_mul_f32 v[182:183], v[182:183], s[2:3] op_sel_hi:[1,0]
	v_pk_mul_f32 v[190:191], v[190:191], s[2:3] op_sel_hi:[1,0]
	v_pk_fma_f32 v[112:113], v[112:113], 0.5, v[182:183] op_sel_hi:[1,0,1]
	v_pk_fma_f32 v[110:111], v[110:111], 0.5, v[190:191] op_sel_hi:[1,0,1]
	v_add_f32_e32 v182, v112, v113
	v_add_f32_e32 v178, v110, v111
	v_add_f32_e32 v178, v178, v182
	v_mul_f32_e32 v182, v111, v111
	v_mul_f32_e32 v183, v113, v113
	v_fmac_f32_e32 v182, v110, v110
	v_fmac_f32_e32 v183, v112, v112
	v_add_f32_e32 v190, v182, v183
	v_sub_f32_e32 v183, v189, v179
	v_sub_f32_e32 v182, v188, v179
	v_sub_f32_e32 v186, v186, v179
	v_pk_mul_f32 v[186:187], v[0:1], v[186:187] op_sel_hi:[0,1]
	v_pk_mul_f32 v[182:183], v[0:1], v[182:183] op_sel_hi:[0,1]
	v_pk_fma_f32 v[182:183], v[200:201], v[182:183], v[208:209]
	v_pk_fma_f32 v[186:187], v[198:199], v[186:187], v[206:207]
	v_pk_mul_f32 v[182:183], v[182:183], s[2:3] op_sel_hi:[1,0]
	v_pk_mul_f32 v[186:187], v[186:187], s[2:3] op_sel_hi:[1,0]
	v_pk_fma_f32 v[108:109], v[108:109], 0.5, v[182:183] op_sel_hi:[1,0,1]
	v_pk_fma_f32 v[106:107], v[106:107], 0.5, v[186:187] op_sel_hi:[1,0,1]
	v_add_f32_e32 v183, v108, v109
	v_add_f32_e32 v182, v106, v107
	v_add_f32_e32 v178, 0, v178
	v_add_f32_e32 v182, v182, v183
	v_add_f32_e32 v178, v178, v182
	v_mul_f32_e32 v182, v107, v107
	v_mul_f32_e32 v183, v109, v109
	s_nop 0
	s_nop 1
	v_bfe_u32 v187, v227, 4, 2
	v_sub_u32_e32 v186, 0, v187
	v_lshlrev_b32_e32 v186, 4, v186
	v_ashrrev_i32_e32 v187, 31, v186
	v_lshl_add_u64 v[186:187], v[180:181], 0, v[186:187]
	v_permlane16_swap_b32_e32 v110, v106
	v_permlane16_swap_b32_e32 v111, v107
	v_permlane16_swap_b32_e32 v112, v108
	v_permlane16_swap_b32_e32 v113, v109
	v_permlane32_swap_b32_e32 v110, v106
	v_permlane32_swap_b32_e32 v111, v107
	v_permlane32_swap_b32_e32 v112, v108
	v_permlane32_swap_b32_e32 v113, v109
	global_store_dwordx4 v[186:187], v[110:113], off
	global_store_dwordx4 v[186:187], v[106:109], off offset:64
	s_nop 1
	v_permlane32_swap_b32_e32 v110, v106
	v_permlane32_swap_b32_e32 v111, v107
	v_permlane32_swap_b32_e32 v112, v108
	v_permlane32_swap_b32_e32 v113, v109
	v_permlane16_swap_b32_e32 v110, v106
	v_permlane16_swap_b32_e32 v111, v107
	v_permlane16_swap_b32_e32 v112, v108
	v_permlane16_swap_b32_e32 v113, v109
	v_fmac_f32_e32 v182, v106, v106
	v_fmac_f32_e32 v183, v108, v108
	v_cvt_pk_bf16_f32 v110, v110, v111
	v_cvt_pk_bf16_f32 v111, v112, v113
	v_cvt_pk_bf16_f32 v112, v106, v107
	v_cvt_pk_bf16_f32 v113, v108, v109
	s_waitcnt vmcnt(6)
; __device__ __forceinline__ float xsum16(float v) { const auto r = __builtin_amdgcn_permlane16_swap(__float_as_uint(v), __float_as_uint(v), false, false); return __uint_as_float(r[0]) + __uint_as_float(r[1]); }
; __device__ __forceinline__ float xsum32(float v) { const auto r = __builtin_amdgcn_permlane32_swap(__float_as_uint(v), __float_as_uint(v), false, false); return __uint_as_float(r[0]) + __uint_as_float(r[1]); }
; __device__ __forceinline__ size_t blk_off(int r, int c, int K) { return (size_t)(r >> 8) * 256 * K + (size_t)(c >> 6) * (256 * 64) + (size_t)((r & 255) * 64 + (c & 63)); }
; __device__ __forceinline__ u32x4 pack8(const f32x4 a, const f32x4 b) { u32x4 w; w.x = cvt_pk_bf16(a[0], a[1]); w.y = cvt_pk_bf16(a[2], a[3]); w.z = cvt_pk_bf16(b[0], b[1]); w.w = cvt_pk_bf16(b[2], b[3]); return w; }
;     __device__ __forceinline__ void operator()(const f32x4 (&acc)[2][2][4][2], const pg8::Unit& u, int wr, int wc, int fr, int fq) const {
;     ...
;             for (int m = 0; m < 4; ++m) { const int row = row0 + ai * 128 + m * 16; const float mu = mu4[m], rs = rs4[m];
;                 f32x4 yv[2][2], gq[2][2], bq_[2][2];
; #pragma unroll
;                 for (int bj = 0; bj < 2; ++bj)
; #pragma unroll
;                     for (int n = 0; n < 2; ++n) { yv[bj][n] = *(const f32x4*)(Yin + (size_t)row * D_ + col0 + bj * 128 + 4 * n); gq[bj][n] = *(const f32x4*)(g + col0 + bj * 128 + 4 * n); bq_[bj][n] = *(const f32x4*)(b + col0 + bj * 128 + 4 * n); }
;                 asm volatile("" ::: "memory");
;                 float s1 = 0.f, s2 = 0.f;
; #pragma unroll
;                 for (int bj = 0; bj < 2; ++bj) { float* yp = Y + (size_t)row * D_ + col0 + bj * 128; f32x4 v[2];
; #pragma unroll
;                     for (int n = 0; n < 2; ++n) { v[n] = (((yv[bj][n] - mu) * rs) * gq[bj][n] + bq_[bj][n]) * ALPHA_ + acc[ai][bj][m][n] * sc;
;                         *(f32x4*)(yp + 4 * n) = v[n]; s1 += (v[n][0] + v[n][1]) + (v[n][2] + v[n][3]); s2 += (v[n][0] * v[n][0] + v[n][1] * v[n][1]) + (v[n][2] * v[n][2] + v[n][3] * v[n][3]); }
;                     *(u32x4*)(Yb + blk_off(row, col0 + bj * 128, D_)) = pack8(v[0], v[1]); }
;                 s1 = xsum32(xsum16(s1)); s2 = xsum32(xsum16(s2));
;                 if (fq == 0) *(f32x2*)(stn + (size_t)row * 32 + (u.pn * 4 + wc) * 2) = (f32x2){s1, s2}; asm volatile("" ::: "memory"); } }
	v_sub_f32_e32 v107, v137, v179
	v_sub_f32_e32 v106, v136, v179
	v_sub_f32_e32 v109, v135, v179
	v_sub_f32_e32 v108, v134, v179
	v_pk_mul_f32 v[108:109], v[0:1], v[108:109] op_sel_hi:[0,1]
	v_pk_mul_f32 v[106:107], v[0:1], v[106:107] op_sel_hi:[0,1]
	s_waitcnt vmcnt(2)
	v_pk_fma_f32 v[106:107], v[128:129], v[106:107], v[132:133]
	v_pk_fma_f32 v[108:109], v[126:127], v[108:109], v[130:131]
	v_pk_mul_f32 v[106:107], v[106:107], s[2:3] op_sel_hi:[1,0]
	v_pk_mul_f32 v[108:109], v[108:109], s[2:3] op_sel_hi:[1,0]
	v_pk_fma_f32 v[104:105], v[104:105], 0.5, v[106:107] op_sel_hi:[1,0,1]
	v_pk_fma_f32 v[102:103], v[102:103], 0.5, v[108:109] op_sel_hi:[1,0,1]
	v_add_f32_e32 v107, v104, v105
	v_add_f32_e32 v106, v102, v103
	v_add_f32_e32 v106, v106, v107
	global_store_dwordx4 v159, v[110:113], s[48:49]
	v_mul_f32_e32 v107, v105, v105
	v_add_f32_e32 v182, v182, v183
	v_add_f32_e32 v110, v178, v106
	v_mul_f32_e32 v106, v103, v103
	v_fmac_f32_e32 v106, v102, v102
	v_fmac_f32_e32 v107, v104, v104
	v_add_f32_e32 v182, v190, v182
	v_add_f32_e32 v106, v106, v107
	v_add_f32_e32 v111, v182, v106
	v_sub_f32_e32 v107, v117, v179
	v_sub_f32_e32 v106, v116, v179
	v_sub_f32_e32 v109, v115, v179
	v_sub_f32_e32 v108, v114, v179
	v_pk_mul_f32 v[108:109], v[0:1], v[108:109] op_sel_hi:[0,1]
	v_pk_mul_f32 v[106:107], v[0:1], v[106:107] op_sel_hi:[0,1]
	v_pk_fma_f32 v[106:107], v[120:121], v[106:107], v[124:125]
	v_pk_fma_f32 v[108:109], v[118:119], v[108:109], v[122:123]
	v_pk_mul_f32 v[106:107], v[106:107], s[2:3] op_sel_hi:[1,0]
	v_pk_mul_f32 v[108:109], v[108:109], s[2:3] op_sel_hi:[1,0]
	v_pk_fma_f32 v[100:101], v[100:101], 0.5, v[106:107] op_sel_hi:[1,0,1]
	v_pk_fma_f32 v[98:99], v[98:99], 0.5, v[108:109] op_sel_hi:[1,0,1]
	v_add_f32_e32 v106, v100, v101
	v_add_f32_e32 v0, v98, v99
	v_add_f32_e32 v0, v0, v106
	v_mul_f32_e32 v106, v99, v99
	v_mul_f32_e32 v107, v101, v101
	v_add_f32_e32 v0, v110, v0
	v_fmac_f32_e32 v106, v98, v98
	v_fmac_f32_e32 v107, v100, v100
	s_nop 0
	s_nop 1
	v_bfe_u32 v109, v227, 4, 2
	v_sub_u32_e32 v108, 0, v109
	v_lshlrev_b32_e32 v108, 4, v108
	v_ashrrev_i32_e32 v109, 31, v108
	v_lshl_add_u64 v[108:109], v[180:181], 0, v[108:109]
	v_permlane16_swap_b32_e32 v102, v98
	v_permlane16_swap_b32_e32 v103, v99
	v_permlane16_swap_b32_e32 v104, v100
	v_permlane16_swap_b32_e32 v105, v101
	v_permlane32_swap_b32_e32 v102, v98
	v_permlane32_swap_b32_e32 v103, v99
	v_permlane32_swap_b32_e32 v104, v100
	v_permlane32_swap_b32_e32 v105, v101
	global_store_dwordx4 v[108:109], v[102:105], off offset:512
	global_store_dwordx4 v[108:109], v[98:101], off offset:576
	s_nop 1
	v_permlane32_swap_b32_e32 v102, v98
	v_permlane32_swap_b32_e32 v103, v99
	v_permlane32_swap_b32_e32 v104, v100
	v_permlane32_swap_b32_e32 v105, v101
	v_permlane16_swap_b32_e32 v102, v98
	v_permlane16_swap_b32_e32 v103, v99
	v_permlane16_swap_b32_e32 v104, v100
	v_permlane16_swap_b32_e32 v105, v101
	v_add_f32_e32 v106, v106, v107
	v_cvt_pk_bf16_f32 v102, v102, v103
	v_cvt_pk_bf16_f32 v103, v104, v105
	v_cvt_pk_bf16_f32 v104, v98, v99
	v_mov_b32_e32 v98, v0
	v_add_f32_e32 v106, v111, v106
	s_nop 0
	v_permlane16_swap_b32_e32 v0, v98
	v_add_f32_e32 v98, v0, v98
	v_mov_b32_e32 v0, v106
	s_nop 1
	v_permlane16_swap_b32_e32 v106, v0
	v_add_f32_e32 v99, v106, v0
	v_cvt_pk_bf16_f32 v105, v100, v101
	v_mov_b32_e32 v100, v98
	v_mov_b32_e32 v101, v99
	s_nop 0
	v_permlane32_swap_b32_e32 v98, v100
	v_permlane32_swap_b32_e32 v99, v101
	global_store_dwordx4 v159, v[102:105], s[46:47]
	s_and_saveexec_b64 s[26:27], s[40:41]
	s_cbranch_execz .LBB0_1707
	v_pk_add_f32 v[98:99], v[98:99], v[100:101]
	v_lshl_add_u64 v[100:101], s[8:9], 0, v[172:173]
	v_lshl_add_u64 v[100:101], s[38:39], 2, v[100:101]
	global_store_dwordx2 v[100:101], v[98:99], off
.LBB0_1707:
	s_or_b64 exec, exec, s[26:27]
	v_pk_add_f32 v[98:99], v[174:175], v[176:177]
	s_mov_b32 s2, 0x3a800000
	v_pk_mul_f32 v[122:123], v[98:99], s[2:3] op_sel_hi:[1,0]
	s_mov_b32 s1, 0x800000
	v_fma_f32 v0, -v123, v123, v122
	v_max_f32_e32 v0, 0, v0
	v_add_f32_e32 v0, 0x3727c5ac, v0
	v_cmp_gt_f32_e32 vcc, s1, v0
	v_mul_f32_e32 v98, 0x4b800000, v0
	s_load_dwordx16 s[60:75], s[34:35], 0x38
	v_cndmask_b32_e32 v0, v0, v98, vcc
	v_rsq_f32_e32 v0, v0
	s_mov_b32 s2, 0x3fd744fd
	v_lshlrev_b32_e32 v122, 6, v170
	v_mul_f32_e32 v98, 0x45800000, v0
	v_cndmask_b32_e32 v0, v0, v98, vcc
	v_lshlrev_b64 v[98:99], 12, v[170:171]
	s_waitcnt lgkmcnt(0)
	v_lshl_add_u64 v[98:99], s[74:75], 0, v[98:99]
	v_lshl_add_u64 v[124:125], v[152:153], 2, v[98:99]
	global_load_dwordx4 v[126:129], v[124:125], off offset:16
	global_load_dwordx4 v[130:133], v[124:125], off
	global_load_dwordx4 v[134:137], v[156:157], off offset:16
	global_load_dwordx4 v[172:175], v[156:157], off
	global_load_dwordx4 v[176:179], v[154:155], off offset:16
	global_load_dwordx4 v[180:183], v[154:155], off
	global_load_dwordx4 v[98:101], v[124:125], off offset:528
	global_load_dwordx4 v[118:121], v[124:125], off offset:512
	global_load_dwordx4 v[102:105], v[156:157], off offset:528
	global_load_dwordx4 v[110:113], v[156:157], off offset:512
	global_load_dwordx4 v[106:109], v[154:155], off offset:528
	global_load_dwordx4 v[114:117], v[154:155], off offset:512
	s_movk_i32 s1, 0x3bc0
	v_and_or_b32 v122, v122, s1, v196
	v_lshlrev_b32_e32 v122, 1, v122
	s_waitcnt vmcnt(11)
	v_sub_f32_e32 v129, v129, v123
	s_waitcnt vmcnt(10)
	v_sub_f32_e32 v133, v133, v123
	v_sub_f32_e32 v132, v132, v123
	v_sub_f32_e32 v131, v131, v123
	v_sub_f32_e32 v130, v130, v123
	v_sub_f32_e32 v128, v128, v123
	v_sub_f32_e32 v127, v127, v123
	v_sub_f32_e32 v126, v126, v123
	v_pk_mul_f32 v[130:131], v[0:1], v[130:131] op_sel_hi:[0,1]
	v_pk_mul_f32 v[132:133], v[0:1], v[132:133] op_sel_hi:[0,1]
	v_pk_mul_f32 v[126:127], v[0:1], v[126:127] op_sel_hi:[0,1]
	v_pk_mul_f32 v[128:129], v[0:1], v[128:129] op_sel_hi:[0,1]
	s_waitcnt vmcnt(6)
; __device__ __forceinline__ float xsum16(float v) { const auto r = __builtin_amdgcn_permlane16_swap(__float_as_uint(v), __float_as_uint(v), false, false); return __uint_as_float(r[0]) + __uint_as_float(r[1]); }
; __device__ __forceinline__ float xsum32(float v) { const auto r = __builtin_amdgcn_permlane32_swap(__float_as_uint(v), __float_as_uint(v), false, false); return __uint_as_float(r[0]) + __uint_as_float(r[1]); }
; __device__ __forceinline__ size_t blk_off(int r, int c, int K) { return (size_t)(r >> 8) * 256 * K + (size_t)(c >> 6) * (256 * 64) + (size_t)((r & 255) * 64 + (c & 63)); }
; __device__ __forceinline__ u32x4 pack8(const f32x4 a, const f32x4 b) { u32x4 w; w.x = cvt_pk_bf16(a[0], a[1]); w.y = cvt_pk_bf16(a[2], a[3]); w.z = cvt_pk_bf16(b[0], b[1]); w.w = cvt_pk_bf16(b[2], b[3]); return w; }
;     __device__ __forceinline__ void operator()(const f32x4 (&acc)[2][2][4][2], const pg8::Unit& u, int wr, int wc, int fr, int fq) const {
;     ...
;             for (int m = 0; m < 4; ++m) { const int row = row0 + ai * 128 + m * 16; const float mu = mu4[m], rs = rs4[m];
;                 f32x4 yv[2][2], gq[2][2], bq_[2][2];
; #pragma unroll
;                 for (int bj = 0; bj < 2; ++bj)
; #pragma unroll
;                     for (int n = 0; n < 2; ++n) { yv[bj][n] = *(const f32x4*)(Yin + (size_t)row * D_ + col0 + bj * 128 + 4 * n); gq[bj][n] = *(const f32x4*)(g + col0 + bj * 128 + 4 * n); bq_[bj][n] = *(const f32x4*)(b + col0 + bj * 128 + 4 * n); }
;                 asm volatile("" ::: "memory");
;                 float s1 = 0.f, s2 = 0.f;
; #pragma unroll
;                 for (int bj = 0; bj < 2; ++bj) { float* yp = Y + (size_t)row * D_ + col0 + bj * 128; f32x4 v[2];
; #pragma unroll
;                     for (int n = 0; n < 2; ++n) { v[n] = (((yv[bj][n] - mu) * rs) * gq[bj][n] + bq_[bj][n]) * ALPHA_ + acc[ai][bj][m][n] * sc;
;                         *(f32x4*)(yp + 4 * n) = v[n]; s1 += (v[n][0] + v[n][1]) + (v[n][2] + v[n][3]); s2 += (v[n][0] * v[n][0] + v[n][1] * v[n][1]) + (v[n][2] * v[n][2] + v[n][3] * v[n][3]); }
;                     *(u32x4*)(Yb + blk_off(row, col0 + bj * 128, D_)) = pack8(v[0], v[1]); }
;                 s1 = xsum32(xsum16(s1)); s2 = xsum32(xsum16(s2));
;                 if (fq == 0) *(f32x2*)(stn + (size_t)row * 32 + (u.pn * 4 + wc) * 2) = (f32x2){s1, s2}; asm volatile("" ::: "memory"); } }
	v_pk_fma_f32 v[132:133], v[174:175], v[132:133], v[182:183]
	v_pk_fma_f32 v[130:131], v[172:173], v[130:131], v[180:181]
	v_pk_fma_f32 v[128:129], v[136:137], v[128:129], v[178:179]
	v_pk_fma_f32 v[126:127], v[134:135], v[126:127], v[176:177]
	v_pk_mul_f32 v[130:131], v[130:131], s[2:3] op_sel_hi:[1,0]
	v_pk_mul_f32 v[132:133], v[132:133], s[2:3] op_sel_hi:[1,0]
	v_pk_mul_f32 v[126:127], v[126:127], s[2:3] op_sel_hi:[1,0]
	v_pk_mul_f32 v[128:129], v[128:129], s[2:3] op_sel_hi:[1,0]
	v_pk_fma_f32 v[96:97], v[96:97], 0.5, v[132:133] op_sel_hi:[1,0,1]
	v_pk_fma_f32 v[94:95], v[94:95], 0.5, v[130:131] op_sel_hi:[1,0,1]
	v_pk_fma_f32 v[92:93], v[92:93], 0.5, v[128:129] op_sel_hi:[1,0,1]
	v_pk_fma_f32 v[90:91], v[90:91], 0.5, v[126:127] op_sel_hi:[1,0,1]
	v_add_f32_e32 v130, v94, v95
	v_add_f32_e32 v131, v96, v97
	v_add_f32_e32 v126, v90, v91
	v_add_f32_e32 v127, v92, v93
	v_add_f32_e32 v130, v130, v131
	v_mul_f32_e32 v131, v95, v95
	v_mul_f32_e32 v132, v97, v97
	v_add_f32_e32 v126, v126, v127
	v_mul_f32_e32 v127, v91, v91
	v_mul_f32_e32 v128, v93, v93
	s_nop 0
	v_fmac_f32_e32 v131, v94, v94
	v_fmac_f32_e32 v132, v96, v96
	s_nop 1
	v_bfe_u32 v135, v227, 4, 2
	v_sub_u32_e32 v134, 0, v135
	v_lshlrev_b32_e32 v134, 4, v134
	v_ashrrev_i32_e32 v135, 31, v134
	v_lshl_add_u64 v[134:135], v[124:125], 0, v[134:135]
	v_permlane16_swap_b32_e32 v94, v90
	v_permlane16_swap_b32_e32 v95, v91
	v_permlane16_swap_b32_e32 v96, v92
	v_permlane16_swap_b32_e32 v97, v93
	v_permlane32_swap_b32_e32 v94, v90
	v_permlane32_swap_b32_e32 v95, v91
	v_permlane32_swap_b32_e32 v96, v92
	v_permlane32_swap_b32_e32 v97, v93
	global_store_dwordx4 v[134:135], v[94:97], off
	global_store_dwordx4 v[134:135], v[90:93], off offset:64
	s_nop 1
	v_permlane32_swap_b32_e32 v94, v90
	v_permlane32_swap_b32_e32 v95, v91
	v_permlane32_swap_b32_e32 v96, v92
	v_permlane32_swap_b32_e32 v97, v93
	v_permlane16_swap_b32_e32 v94, v90
	v_permlane16_swap_b32_e32 v95, v91
	v_permlane16_swap_b32_e32 v96, v92
	v_permlane16_swap_b32_e32 v97, v93
	v_fmac_f32_e32 v127, v90, v90
	v_fmac_f32_e32 v128, v92, v92
	v_cvt_pk_bf16_f32 v94, v94, v95
	v_cvt_pk_bf16_f32 v95, v96, v97
	v_cvt_pk_bf16_f32 v96, v90, v91
	v_cvt_pk_bf16_f32 v97, v92, v93
	s_waitcnt vmcnt(6)
	v_sub_f32_e32 v91, v121, v123
	v_sub_f32_e32 v90, v120, v123
	v_sub_f32_e32 v93, v119, v123
	v_sub_f32_e32 v92, v118, v123
	v_pk_mul_f32 v[92:93], v[0:1], v[92:93] op_sel_hi:[0,1]
	v_pk_mul_f32 v[90:91], v[0:1], v[90:91] op_sel_hi:[0,1]
	s_waitcnt vmcnt(2)
	v_pk_fma_f32 v[90:91], v[112:113], v[90:91], v[116:117]
	v_pk_fma_f32 v[92:93], v[110:111], v[92:93], v[114:115]
	v_pk_mul_f32 v[90:91], v[90:91], s[2:3] op_sel_hi:[1,0]
	v_pk_mul_f32 v[92:93], v[92:93], s[2:3] op_sel_hi:[1,0]
	v_pk_fma_f32 v[88:89], v[88:89], 0.5, v[90:91] op_sel_hi:[1,0,1]
	v_pk_fma_f32 v[86:87], v[86:87], 0.5, v[92:93] op_sel_hi:[1,0,1]
	v_add_f32_e32 v130, 0, v130
	v_add_f32_e32 v90, v86, v87
	v_add_f32_e32 v91, v88, v89
	v_add_f32_e32 v126, v130, v126
	v_add_f32_e32 v90, v90, v91
	global_store_dwordx4 v122, v[94:97], s[48:49]
	v_mul_f32_e32 v91, v89, v89
	v_add_f32_e32 v131, v131, v132
	v_add_f32_e32 v94, v126, v90
	v_mul_f32_e32 v90, v87, v87
	v_add_f32_e32 v127, v127, v128
	v_fmac_f32_e32 v90, v86, v86
	v_fmac_f32_e32 v91, v88, v88
	v_add_f32_e32 v127, v131, v127
	v_add_f32_e32 v90, v90, v91
	v_add_f32_e32 v95, v127, v90
	v_sub_f32_e32 v91, v101, v123
	v_sub_f32_e32 v90, v100, v123
	v_sub_f32_e32 v93, v99, v123
	v_sub_f32_e32 v92, v98, v123
	v_pk_mul_f32 v[92:93], v[0:1], v[92:93] op_sel_hi:[0,1]
	v_pk_mul_f32 v[90:91], v[0:1], v[90:91] op_sel_hi:[0,1]
	v_pk_fma_f32 v[90:91], v[104:105], v[90:91], v[108:109]
	v_pk_fma_f32 v[92:93], v[102:103], v[92:93], v[106:107]
	v_pk_mul_f32 v[90:91], v[90:91], s[2:3] op_sel_hi:[1,0]
	v_pk_mul_f32 v[92:93], v[92:93], s[2:3] op_sel_hi:[1,0]
	v_pk_fma_f32 v[84:85], v[84:85], 0.5, v[90:91] op_sel_hi:[1,0,1]
	v_pk_fma_f32 v[82:83], v[82:83], 0.5, v[92:93] op_sel_hi:[1,0,1]
	v_add_f32_e32 v90, v84, v85
	v_add_f32_e32 v0, v82, v83
	v_add_f32_e32 v0, v0, v90
	v_mul_f32_e32 v90, v83, v83
	v_mul_f32_e32 v91, v85, v85
	v_add_f32_e32 v0, v94, v0
	v_fmac_f32_e32 v90, v82, v82
	v_fmac_f32_e32 v91, v84, v84
	s_nop 0
	s_nop 1
	v_bfe_u32 v93, v227, 4, 2
	v_sub_u32_e32 v92, 0, v93
	v_lshlrev_b32_e32 v92, 4, v92
	v_ashrrev_i32_e32 v93, 31, v92
	v_lshl_add_u64 v[92:93], v[124:125], 0, v[92:93]
	v_permlane16_swap_b32_e32 v86, v82
	v_permlane16_swap_b32_e32 v87, v83
	v_permlane16_swap_b32_e32 v88, v84
	v_permlane16_swap_b32_e32 v89, v85
	v_permlane32_swap_b32_e32 v86, v82
	v_permlane32_swap_b32_e32 v87, v83
	v_permlane32_swap_b32_e32 v88, v84
	v_permlane32_swap_b32_e32 v89, v85
	global_store_dwordx4 v[92:93], v[86:89], off offset:512
	global_store_dwordx4 v[92:93], v[82:85], off offset:576
	s_nop 1
	v_permlane32_swap_b32_e32 v86, v82
	v_permlane32_swap_b32_e32 v87, v83
	v_permlane32_swap_b32_e32 v88, v84
	v_permlane32_swap_b32_e32 v89, v85
	v_permlane16_swap_b32_e32 v86, v82
	v_permlane16_swap_b32_e32 v87, v83
	v_permlane16_swap_b32_e32 v88, v84
	v_permlane16_swap_b32_e32 v89, v85
	v_add_f32_e32 v90, v90, v91
	v_cvt_pk_bf16_f32 v86, v86, v87
	v_cvt_pk_bf16_f32 v87, v88, v89
	v_cvt_pk_bf16_f32 v88, v82, v83
	v_mov_b32_e32 v82, v0
	v_add_f32_e32 v90, v95, v90
	s_nop 0
	v_permlane16_swap_b32_e32 v0, v82
	v_add_f32_e32 v82, v0, v82
	v_mov_b32_e32 v0, v90
	s_nop 1
	v_permlane16_swap_b32_e32 v90, v0
	v_add_f32_e32 v83, v90, v0
	v_cvt_pk_bf16_f32 v89, v84, v85
	v_mov_b32_e32 v84, v82
	v_mov_b32_e32 v85, v83
	s_nop 0
	v_permlane32_swap_b32_e32 v82, v84
	v_permlane32_swap_b32_e32 v83, v85
	global_store_dwordx4 v122, v[86:89], s[46:47]
	s_and_saveexec_b64 s[26:27], s[40:41]
	s_cbranch_execz .LBB0_1709
	v_pk_add_f32 v[82:83], v[82:83], v[84:85]
	v_lshl_add_u64 v[84:85], s[8:9], 0, v[164:165]
	v_lshl_add_u64 v[84:85], s[38:39], 2, v[84:85]
	global_store_dwordx2 v[84:85], v[82:83], off
; __device__ __forceinline__ float xsum16(float v) { const auto r = __builtin_amdgcn_permlane16_swap(__float_as_uint(v), __float_as_uint(v), false, false); return __uint_as_float(r[0]) + __uint_as_float(r[1]); }
; __device__ __forceinline__ float xsum32(float v) { const auto r = __builtin_amdgcn_permlane32_swap(__float_as_uint(v), __float_as_uint(v), false, false); return __uint_as_float(r[0]) + __uint_as_float(r[1]); }
; __device__ __forceinline__ size_t blk_off(int r, int c, int K) { return (size_t)(r >> 8) * 256 * K + (size_t)(c >> 6) * (256 * 64) + (size_t)((r & 255) * 64 + (c & 63)); }
; __device__ __forceinline__ u32x4 pack8(const f32x4 a, const f32x4 b) { u32x4 w; w.x = cvt_pk_bf16(a[0], a[1]); w.y = cvt_pk_bf16(a[2], a[3]); w.z = cvt_pk_bf16(b[0], b[1]); w.w = cvt_pk_bf16(b[2], b[3]); return w; }
;     __device__ __forceinline__ void operator()(const f32x4 (&acc)[2][2][4][2], const pg8::Unit& u, int wr, int wc, int fr, int fq) const {
;     ...
;             for (int m = 0; m < 4; ++m) { const int row = row0 + ai * 128 + m * 16; const float mu = mu4[m], rs = rs4[m];
;                 f32x4 yv[2][2], gq[2][2], bq_[2][2];
; #pragma unroll
;                 for (int bj = 0; bj < 2; ++bj)
; #pragma unroll
;                     for (int n = 0; n < 2; ++n) { yv[bj][n] = *(const f32x4*)(Yin + (size_t)row * D_ + col0 + bj * 128 + 4 * n); gq[bj][n] = *(const f32x4*)(g + col0 + bj * 128 + 4 * n); bq_[bj][n] = *(const f32x4*)(b + col0 + bj * 128 + 4 * n); }
;                 asm volatile("" ::: "memory");
;                 float s1 = 0.f, s2 = 0.f;
; #pragma unroll
;                 for (int bj = 0; bj < 2; ++bj) { float* yp = Y + (size_t)row * D_ + col0 + bj * 128; f32x4 v[2];
; #pragma unroll
;                     for (int n = 0; n < 2; ++n) { v[n] = (((yv[bj][n] - mu) * rs) * gq[bj][n] + bq_[bj][n]) * ALPHA_ + acc[ai][bj][m][n] * sc;
;                         *(f32x4*)(yp + 4 * n) = v[n]; s1 += (v[n][0] + v[n][1]) + (v[n][2] + v[n][3]); s2 += (v[n][0] * v[n][0] + v[n][1] * v[n][1]) + (v[n][2] * v[n][2] + v[n][3] * v[n][3]); }
;                     *(u32x4*)(Yb + blk_off(row, col0 + bj * 128, D_)) = pack8(v[0], v[1]); }
;                 s1 = xsum32(xsum16(s1)); s2 = xsum32(xsum16(s2));
;                 if (fq == 0) *(f32x2*)(stn + (size_t)row * 32 + (u.pn * 4 + wc) * 2) = (f32x2){s1, s2}; asm volatile("" ::: "memory"); } }
.LBB0_1709:
	s_or_b64 exec, exec, s[26:27]
	v_pk_add_f32 v[82:83], v[166:167], v[168:169]
	s_mov_b32 s2, 0x3a800000
	v_pk_mul_f32 v[106:107], v[82:83], s[2:3] op_sel_hi:[1,0]
	s_mov_b32 s1, 0x800000
	v_fma_f32 v0, -v107, v107, v106
	v_max_f32_e32 v0, 0, v0
	v_add_f32_e32 v0, 0x3727c5ac, v0
	v_cmp_gt_f32_e32 vcc, s1, v0
	v_mul_f32_e32 v82, 0x4b800000, v0
	s_load_dwordx16 s[60:75], s[34:35], 0x38
	v_cndmask_b32_e32 v0, v0, v82, vcc
	v_rsq_f32_e32 v0, v0
	s_mov_b32 s2, 0x3fd744fd
	v_lshlrev_b32_e32 v106, 6, v162
	v_mul_f32_e32 v82, 0x45800000, v0
	v_cndmask_b32_e32 v0, v0, v82, vcc
	v_lshlrev_b64 v[82:83], 12, v[162:163]
	s_waitcnt lgkmcnt(0)
	v_lshl_add_u64 v[82:83], s[74:75], 0, v[82:83]
	v_lshl_add_u64 v[108:109], v[152:153], 2, v[82:83]
	global_load_dwordx4 v[110:113], v[108:109], off offset:16
	global_load_dwordx4 v[114:117], v[108:109], off
	global_load_dwordx4 v[118:121], v[156:157], off offset:16
	global_load_dwordx4 v[122:125], v[156:157], off
	global_load_dwordx4 v[126:129], v[154:155], off offset:16
	global_load_dwordx4 v[130:133], v[154:155], off
	global_load_dwordx4 v[82:85], v[108:109], off offset:528
	global_load_dwordx4 v[102:105], v[108:109], off offset:512
	global_load_dwordx4 v[86:89], v[156:157], off offset:528
	global_load_dwordx4 v[94:97], v[156:157], off offset:512
	global_load_dwordx4 v[90:93], v[154:155], off offset:528
	global_load_dwordx4 v[98:101], v[154:155], off offset:512
	s_movk_i32 s1, 0x3fc0
	v_and_or_b32 v106, v106, s1, v196
	v_lshlrev_b32_e32 v106, 1, v106
	s_waitcnt vmcnt(11)
	v_sub_f32_e32 v113, v113, v107
	s_waitcnt vmcnt(10)
	v_sub_f32_e32 v117, v117, v107
	v_sub_f32_e32 v116, v116, v107
	v_sub_f32_e32 v115, v115, v107
	v_sub_f32_e32 v114, v114, v107
	v_sub_f32_e32 v112, v112, v107
	v_sub_f32_e32 v111, v111, v107
	v_sub_f32_e32 v110, v110, v107
	v_pk_mul_f32 v[114:115], v[0:1], v[114:115] op_sel_hi:[0,1]
	v_pk_mul_f32 v[116:117], v[0:1], v[116:117] op_sel_hi:[0,1]
	v_pk_mul_f32 v[110:111], v[0:1], v[110:111] op_sel_hi:[0,1]
	v_pk_mul_f32 v[112:113], v[0:1], v[112:113] op_sel_hi:[0,1]
	s_waitcnt vmcnt(6)
	v_pk_fma_f32 v[116:117], v[124:125], v[116:117], v[132:133]
	v_pk_fma_f32 v[114:115], v[122:123], v[114:115], v[130:131]
	v_pk_fma_f32 v[112:113], v[120:121], v[112:113], v[128:129]
	v_pk_fma_f32 v[110:111], v[118:119], v[110:111], v[126:127]
	v_pk_mul_f32 v[114:115], v[114:115], s[2:3] op_sel_hi:[1,0]
	v_pk_mul_f32 v[116:117], v[116:117], s[2:3] op_sel_hi:[1,0]
	v_pk_mul_f32 v[110:111], v[110:111], s[2:3] op_sel_hi:[1,0]
	v_pk_mul_f32 v[112:113], v[112:113], s[2:3] op_sel_hi:[1,0]
	v_pk_fma_f32 v[80:81], v[80:81], 0.5, v[116:117] op_sel_hi:[1,0,1]
	v_pk_fma_f32 v[78:79], v[78:79], 0.5, v[114:115] op_sel_hi:[1,0,1]
	v_pk_fma_f32 v[76:77], v[76:77], 0.5, v[112:113] op_sel_hi:[1,0,1]
	v_pk_fma_f32 v[74:75], v[74:75], 0.5, v[110:111] op_sel_hi:[1,0,1]
	v_add_f32_e32 v114, v78, v79
	v_add_f32_e32 v115, v80, v81
	v_add_f32_e32 v110, v74, v75
	v_add_f32_e32 v111, v76, v77
	v_add_f32_e32 v114, v114, v115
	v_mul_f32_e32 v115, v79, v79
	v_mul_f32_e32 v116, v81, v81
	v_add_f32_e32 v110, v110, v111
	v_mul_f32_e32 v111, v75, v75
	v_mul_f32_e32 v112, v77, v77
	s_nop 0
	v_fmac_f32_e32 v115, v78, v78
	v_fmac_f32_e32 v116, v80, v80
	s_nop 1
	v_bfe_u32 v119, v227, 4, 2
	v_sub_u32_e32 v118, 0, v119
	v_lshlrev_b32_e32 v118, 4, v118
	v_ashrrev_i32_e32 v119, 31, v118
	v_lshl_add_u64 v[118:119], v[108:109], 0, v[118:119]
	v_permlane16_swap_b32_e32 v78, v74
	v_permlane16_swap_b32_e32 v79, v75
	v_permlane16_swap_b32_e32 v80, v76
	v_permlane16_swap_b32_e32 v81, v77
	v_permlane32_swap_b32_e32 v78, v74
	v_permlane32_swap_b32_e32 v79, v75
	v_permlane32_swap_b32_e32 v80, v76
	v_permlane32_swap_b32_e32 v81, v77
	global_store_dwordx4 v[118:119], v[78:81], off
	global_store_dwordx4 v[118:119], v[74:77], off offset:64
	s_nop 1
	v_permlane32_swap_b32_e32 v78, v74
	v_permlane32_swap_b32_e32 v79, v75
	v_permlane32_swap_b32_e32 v80, v76
	v_permlane32_swap_b32_e32 v81, v77
	v_permlane16_swap_b32_e32 v78, v74
	v_permlane16_swap_b32_e32 v79, v75
	v_permlane16_swap_b32_e32 v80, v76
	v_permlane16_swap_b32_e32 v81, v77
	v_fmac_f32_e32 v111, v74, v74
	v_fmac_f32_e32 v112, v76, v76
	v_cvt_pk_bf16_f32 v78, v78, v79
	v_cvt_pk_bf16_f32 v79, v80, v81
	v_cvt_pk_bf16_f32 v80, v74, v75
	v_cvt_pk_bf16_f32 v81, v76, v77
	s_waitcnt vmcnt(6)
	v_sub_f32_e32 v75, v105, v107
	v_sub_f32_e32 v74, v104, v107
	v_sub_f32_e32 v77, v103, v107
	v_sub_f32_e32 v76, v102, v107
	v_pk_mul_f32 v[76:77], v[0:1], v[76:77] op_sel_hi:[0,1]
	v_pk_mul_f32 v[74:75], v[0:1], v[74:75] op_sel_hi:[0,1]
	s_waitcnt vmcnt(2)
; __device__ __forceinline__ float xsum16(float v) { const auto r = __builtin_amdgcn_permlane16_swap(__float_as_uint(v), __float_as_uint(v), false, false); return __uint_as_float(r[0]) + __uint_as_float(r[1]); }
; __device__ __forceinline__ void row_stats4(const float* st, int rowb, int fq, float (&mu)[4], float (&rs)[4]) {
;     ...
;     for (int m = 0; m < 4; ++m) { const f32x4* p = (const f32x4*)(st + (size_t)(rowb + m * 16) * 32 + fq * 8); a[m] = p[0]; b[m] = p[1]; }
; #pragma unroll
;     for (int m = 0; m < 4; ++m) { float s1 = (a[m][0] + a[m][2]) + (b[m][0] + b[m][2]), s2 = (a[m][1] + a[m][3]) + (b[m][1] + b[m][3]);
;         s1 = xsum32(xsum16(s1)); s2 = xsum32(xsum16(s2));
;         const float mm = s1 * (1.0f / 1024.0f); mu[m] = mm; rs[m] = rsqrtf(fmaxf(s2 * (1.0f / 1024.0f) - mm * mm, 0.f) + LN_EPS_); }
;     __device__ __forceinline__ void operator()(const f32x4 (&acc)[2][2][4][2], const pg8::Unit& u, int wr, int wc, int fr, int fq) const {
;     ...
;             for (int m = 0; m < 4; ++m) { const int row = row0 + ai * 128 + m * 16; const float mu = mu4[m], rs = rs4[m];
;                 f32x4 yv[2][2], gq[2][2], bq_[2][2];
; #pragma unroll
;                 for (int bj = 0; bj < 2; ++bj)
; #pragma unroll
;                     for (int n = 0; n < 2; ++n) { yv[bj][n] = *(const f32x4*)(Yin + (size_t)row * D_ + col0 + bj * 128 + 4 * n); gq[bj][n] = *(const f32x4*)(g + col0 + bj * 128 + 4 * n); bq_[bj][n] = *(const f32x4*)(b + col0 + bj * 128 + 4 * n); }
;                 asm volatile("" ::: "memory");
;                 float s1 = 0.f, s2 = 0.f;
; #pragma unroll
;                 for (int bj = 0; bj < 2; ++bj) { float* yp = Y + (size_t)row * D_ + col0 + bj * 128; f32x4 v[2];
; #pragma unroll
;                     for (int n = 0; n < 2; ++n) { v[n] = (((yv[bj][n] - mu) * rs) * gq[bj][n] + bq_[bj][n]) * ALPHA_ + acc[ai][bj][m][n] * sc;
;                         *(f32x4*)(yp + 4 * n) = v[n]; s1 += (v[n][0] + v[n][1]) + (v[n][2] + v[n][3]); s2 += (v[n][0] * v[n][0] + v[n][1] * v[n][1]) + (v[n][2] * v[n][2] + v[n][3] * v[n][3]); }
;                     *(u32x4*)(Yb + blk_off(row, col0 + bj * 128, D_)) = pack8(v[0], v[1]); }
;                 s1 = xsum32(xsum16(s1)); s2 = xsum32(xsum16(s2));
;                 if (fq == 0) *(f32x2*)(stn + (size_t)row * 32 + (u.pn * 4 + wc) * 2) = (f32x2){s1, s2}; asm volatile("" ::: "memory"); } }
	v_pk_fma_f32 v[74:75], v[96:97], v[74:75], v[100:101]
	v_pk_fma_f32 v[76:77], v[94:95], v[76:77], v[98:99]
	v_pk_mul_f32 v[74:75], v[74:75], s[2:3] op_sel_hi:[1,0]
	v_pk_mul_f32 v[76:77], v[76:77], s[2:3] op_sel_hi:[1,0]
	v_pk_fma_f32 v[72:73], v[72:73], 0.5, v[74:75] op_sel_hi:[1,0,1]
	v_pk_fma_f32 v[70:71], v[70:71], 0.5, v[76:77] op_sel_hi:[1,0,1]
	v_add_f32_e32 v114, 0, v114
	v_add_f32_e32 v74, v70, v71
	v_add_f32_e32 v75, v72, v73
	v_add_f32_e32 v110, v114, v110
	v_add_f32_e32 v74, v74, v75
	global_store_dwordx4 v106, v[78:81], s[48:49]
	v_mul_f32_e32 v75, v73, v73
	v_add_f32_e32 v115, v115, v116
	v_add_f32_e32 v78, v110, v74
	v_mul_f32_e32 v74, v71, v71
	v_add_f32_e32 v111, v111, v112
	v_fmac_f32_e32 v74, v70, v70
	v_fmac_f32_e32 v75, v72, v72
	v_add_f32_e32 v111, v115, v111
	v_add_f32_e32 v74, v74, v75
	v_add_f32_e32 v79, v111, v74
	v_sub_f32_e32 v75, v85, v107
	v_sub_f32_e32 v74, v84, v107
	v_sub_f32_e32 v77, v83, v107
	v_sub_f32_e32 v76, v82, v107
	v_pk_mul_f32 v[76:77], v[0:1], v[76:77] op_sel_hi:[0,1]
	v_pk_mul_f32 v[74:75], v[0:1], v[74:75] op_sel_hi:[0,1]
	v_pk_fma_f32 v[74:75], v[88:89], v[74:75], v[92:93]
	v_pk_fma_f32 v[76:77], v[86:87], v[76:77], v[90:91]
	v_pk_mul_f32 v[74:75], v[74:75], s[2:3] op_sel_hi:[1,0]
	v_pk_mul_f32 v[76:77], v[76:77], s[2:3] op_sel_hi:[1,0]
	v_pk_fma_f32 v[68:69], v[68:69], 0.5, v[74:75] op_sel_hi:[1,0,1]
	v_pk_fma_f32 v[66:67], v[66:67], 0.5, v[76:77] op_sel_hi:[1,0,1]
	v_add_f32_e32 v74, v68, v69
	v_add_f32_e32 v0, v66, v67
	v_add_f32_e32 v0, v0, v74
	v_mul_f32_e32 v74, v67, v67
	v_mul_f32_e32 v75, v69, v69
	v_add_f32_e32 v0, v78, v0
	v_fmac_f32_e32 v74, v66, v66
	v_fmac_f32_e32 v75, v68, v68
	s_nop 0
	s_nop 1
	v_bfe_u32 v77, v227, 4, 2
	v_sub_u32_e32 v76, 0, v77
	v_lshlrev_b32_e32 v76, 4, v76
	v_ashrrev_i32_e32 v77, 31, v76
	v_lshl_add_u64 v[76:77], v[108:109], 0, v[76:77]
	v_permlane16_swap_b32_e32 v70, v66
	v_permlane16_swap_b32_e32 v71, v67
	v_permlane16_swap_b32_e32 v72, v68
	v_permlane16_swap_b32_e32 v73, v69
	v_permlane32_swap_b32_e32 v70, v66
	v_permlane32_swap_b32_e32 v71, v67
	v_permlane32_swap_b32_e32 v72, v68
	v_permlane32_swap_b32_e32 v73, v69
	global_store_dwordx4 v[76:77], v[70:73], off offset:512
	global_store_dwordx4 v[76:77], v[66:69], off offset:576
	s_nop 1
	v_permlane32_swap_b32_e32 v70, v66
	v_permlane32_swap_b32_e32 v71, v67
	v_permlane32_swap_b32_e32 v72, v68
	v_permlane32_swap_b32_e32 v73, v69
	v_permlane16_swap_b32_e32 v70, v66
	v_permlane16_swap_b32_e32 v71, v67
	v_permlane16_swap_b32_e32 v72, v68
	v_permlane16_swap_b32_e32 v73, v69
	v_add_f32_e32 v74, v74, v75
	v_cvt_pk_bf16_f32 v70, v70, v71
	v_cvt_pk_bf16_f32 v71, v72, v73
	v_cvt_pk_bf16_f32 v72, v66, v67
	v_mov_b32_e32 v66, v0
	v_add_f32_e32 v74, v79, v74
	s_nop 0
	v_permlane16_swap_b32_e32 v0, v66
	v_add_f32_e32 v66, v0, v66
	v_mov_b32_e32 v0, v74
	s_nop 1
	v_permlane16_swap_b32_e32 v74, v0
	v_add_f32_e32 v67, v74, v0
	v_cvt_pk_bf16_f32 v73, v68, v69
	v_mov_b32_e32 v68, v66
	v_mov_b32_e32 v69, v67
	s_nop 0
	v_permlane32_swap_b32_e32 v66, v68
	v_permlane32_swap_b32_e32 v67, v69
	global_store_dwordx4 v106, v[70:73], s[46:47]
	s_and_saveexec_b64 s[26:27], s[40:41]
	s_cbranch_execz .LBB0_1711
	v_pk_add_f32 v[66:67], v[66:67], v[68:69]
	v_lshl_add_u64 v[68:69], s[8:9], 0, v[160:161]
	v_lshl_add_u64 v[68:69], s[38:39], 2, v[68:69]
	global_store_dwordx2 v[68:69], v[66:67], off
.LBB0_1711:
	s_or_b64 exec, exec, s[26:27]
	v_add_u32_e32 v68, 0x80, v158
	v_ashrrev_i32_e32 v69, 31, v68
	v_lshlrev_b64 v[66:67], 7, v[68:69]
	v_lshl_add_u64 v[74:75], v[146:147], 0, v[66:67]
	v_add_u32_e32 v96, 0x90, v158
	global_load_dwordx4 v[70:73], v[74:75], off
	global_load_dwordx4 v[82:85], v[74:75], off offset:16
	v_ashrrev_i32_e32 v97, 31, v96
	v_lshlrev_b64 v[86:87], 7, v[96:97]
	v_add_u32_e32 v80, 0xa0, v158
	v_lshl_add_u64 v[74:75], v[146:147], 0, v[86:87]
	v_ashrrev_i32_e32 v81, 31, v80
	global_load_dwordx4 v[88:91], v[74:75], off
	global_load_dwordx4 v[92:95], v[74:75], off offset:16
	v_lshlrev_b64 v[74:75], 7, v[80:81]
	v_lshl_add_u64 v[74:75], v[146:147], 0, v[74:75]
	global_load_dwordx4 v[98:101], v[74:75], off
	global_load_dwordx4 v[102:105], v[74:75], off offset:16
	v_add_u32_e32 v74, 0xb0, v158
	v_ashrrev_i32_e32 v75, 31, v74
	v_lshlrev_b64 v[76:77], 7, v[74:75]
	v_lshl_add_u64 v[76:77], v[146:147], 0, v[76:77]
	global_load_dwordx4 v[106:109], v[76:77], off
	global_load_dwordx4 v[110:113], v[76:77], off offset:16
	s_load_dwordx16 s[60:75], s[34:35], 0x38
	v_lshlrev_b64 v[78:79], 12, v[68:69]
	s_mov_b32 s2, 0x3a800000
	s_mov_b32 s1, 0x800000
	s_waitcnt lgkmcnt(0)
	v_lshl_add_u64 v[78:79], s[74:75], 0, v[78:79]
	v_lshl_add_u64 v[76:77], v[152:153], 2, v[78:79]
	global_load_dwordx4 v[114:117], v[76:77], off offset:16
	global_load_dwordx4 v[118:121], v[76:77], off
	global_load_dwordx4 v[122:125], v[156:157], off offset:16
	global_load_dwordx4 v[126:129], v[156:157], off
	global_load_dwordx4 v[130:133], v[154:155], off offset:16
	global_load_dwordx4 v[134:137], v[154:155], off
	s_mov_b32 s16, 0x3fd744fd
	s_waitcnt vmcnt(13)
	v_mov_b32_e32 v78, v70
	s_waitcnt vmcnt(12)
	v_mov_b32_e32 v79, v82
	v_mov_b32_e32 v158, v72
	v_mov_b32_e32 v159, v84
	v_mov_b32_e32 v82, v71
	v_mov_b32_e32 v84, v73
	v_pk_add_f32 v[78:79], v[78:79], v[158:159]
	v_pk_add_f32 v[82:83], v[82:83], v[84:85]
	v_pk_add_f32 v[78:79], v[78:79], v[78:79] op_sel:[0,1] op_sel_hi:[1,0]
	v_pk_add_f32 v[82:83], v[82:83], v[82:83] op_sel:[0,1] op_sel_hi:[1,0]
	v_mov_b32_e32 v0, v78
	v_mov_b32_e32 v69, v82
	s_nop 0
	v_permlane16_swap_b32_e32 v78, v0
	v_permlane16_swap_b32_e32 v82, v69
	v_add_f32_e32 v79, v78, v0
	v_add_f32_e32 v78, v82, v69
	v_mov_b32_e32 v83, v79
	v_mov_b32_e32 v82, v78
	s_waitcnt vmcnt(11)
; __device__ __forceinline__ float xsum16(float v) { const auto r = __builtin_amdgcn_permlane16_swap(__float_as_uint(v), __float_as_uint(v), false, false); return __uint_as_float(r[0]) + __uint_as_float(r[1]); }
; __device__ __forceinline__ float xsum32(float v) { const auto r = __builtin_amdgcn_permlane32_swap(__float_as_uint(v), __float_as_uint(v), false, false); return __uint_as_float(r[0]) + __uint_as_float(r[1]); }
; __device__ __forceinline__ size_t blk_off(int r, int c, int K) { return (size_t)(r >> 8) * 256 * K + (size_t)(c >> 6) * (256 * 64) + (size_t)((r & 255) * 64 + (c & 63)); }
; __device__ __forceinline__ u32x4 pack8(const f32x4 a, const f32x4 b) { u32x4 w; w.x = cvt_pk_bf16(a[0], a[1]); w.y = cvt_pk_bf16(a[2], a[3]); w.z = cvt_pk_bf16(b[0], b[1]); w.w = cvt_pk_bf16(b[2], b[3]); return w; }
;     __device__ __forceinline__ void operator()(const f32x4 (&acc)[2][2][4][2], const pg8::Unit& u, int wr, int wc, int fr, int fq) const {
;     ...
;             for (int m = 0; m < 4; ++m) { const int row = row0 + ai * 128 + m * 16; const float mu = mu4[m], rs = rs4[m];
;                 f32x4 yv[2][2], gq[2][2], bq_[2][2];
; #pragma unroll
;                 for (int bj = 0; bj < 2; ++bj)
; #pragma unroll
;                     for (int n = 0; n < 2; ++n) { yv[bj][n] = *(const f32x4*)(Yin + (size_t)row * D_ + col0 + bj * 128 + 4 * n); gq[bj][n] = *(const f32x4*)(g + col0 + bj * 128 + 4 * n); bq_[bj][n] = *(const f32x4*)(b + col0 + bj * 128 + 4 * n); }
;                 asm volatile("" ::: "memory");
;                 float s1 = 0.f, s2 = 0.f;
; #pragma unroll
;                 for (int bj = 0; bj < 2; ++bj) { float* yp = Y + (size_t)row * D_ + col0 + bj * 128; f32x4 v[2];
; #pragma unroll
;                     for (int n = 0; n < 2; ++n) { v[n] = (((yv[bj][n] - mu) * rs) * gq[bj][n] + bq_[bj][n]) * ALPHA_ + acc[ai][bj][m][n] * sc;
;                         *(f32x4*)(yp + 4 * n) = v[n]; s1 += (v[n][0] + v[n][1]) + (v[n][2] + v[n][3]); s2 += (v[n][0] * v[n][0] + v[n][1] * v[n][1]) + (v[n][2] * v[n][2] + v[n][3] * v[n][3]); }
;                     *(u32x4*)(Yb + blk_off(row, col0 + bj * 128, D_)) = pack8(v[0], v[1]); }
;                 s1 = xsum32(xsum16(s1)); s2 = xsum32(xsum16(s2));
;                 if (fq == 0) *(f32x2*)(stn + (size_t)row * 32 + (u.pn * 4 + wc) * 2) = (f32x2){s1, s2}; asm volatile("" ::: "memory"); } }
	v_mov_b32_e32 v70, v88
	s_waitcnt vmcnt(10)
	v_mov_b32_e32 v71, v92
	v_mov_b32_e32 v72, v90
	v_mov_b32_e32 v73, v94
	v_mov_b32_e32 v92, v89
	v_mov_b32_e32 v94, v91
	v_permlane32_swap_b32_e32 v79, v83
	v_permlane32_swap_b32_e32 v78, v82
	s_waitcnt vmcnt(9)
	v_mov_b32_e32 v88, v98
	s_waitcnt vmcnt(8)
	v_mov_b32_e32 v89, v102
	v_mov_b32_e32 v90, v100
	v_mov_b32_e32 v91, v104
	v_mov_b32_e32 v102, v99
	v_mov_b32_e32 v104, v101
	v_pk_add_f32 v[70:71], v[70:71], v[72:73]
	v_pk_add_f32 v[72:73], v[92:93], v[94:95]
	v_pk_add_f32 v[78:79], v[78:79], v[82:83]
	global_load_dwordx4 v[92:95], v[76:77], off offset:528
	global_load_dwordx4 v[98:101], v[76:77], off offset:512
	v_pk_mul_f32 v[162:163], v[78:79], s[2:3] op_sel_hi:[1,0]
	s_waitcnt vmcnt(9)
	v_mov_b32_e32 v78, v106
	s_waitcnt vmcnt(8)
	v_mov_b32_e32 v79, v110
	v_mov_b32_e32 v82, v108
	v_mov_b32_e32 v83, v112
	v_mov_b32_e32 v110, v107
	v_mov_b32_e32 v112, v109
	v_pk_add_f32 v[84:85], v[88:89], v[90:91]
	v_pk_add_f32 v[88:89], v[102:103], v[104:105]
	v_pk_add_f32 v[78:79], v[78:79], v[82:83]
	v_pk_add_f32 v[82:83], v[110:111], v[112:113]
	global_load_dwordx4 v[102:105], v[156:157], off offset:528
	global_load_dwordx4 v[106:109], v[156:157], off offset:512
	global_load_dwordx4 v[110:113], v[154:155], off offset:528
	global_load_dwordx4 v[158:161], v[154:155], off offset:512
	v_fma_f32 v0, -v163, v163, v162
	v_max_f32_e32 v0, 0, v0
	v_add_f32_e32 v0, 0x3727c5ac, v0
	v_mul_f32_e32 v69, 0x4b800000, v0
	v_cmp_gt_f32_e32 vcc, s1, v0
	v_pk_add_f32 v[88:89], v[88:89], v[88:89] op_sel:[0,1] op_sel_hi:[1,0]
	v_pk_add_f32 v[78:79], v[78:79], v[78:79] op_sel:[0,1] op_sel_hi:[1,0]
	v_cndmask_b32_e32 v0, v0, v69, vcc
	v_rsq_f32_e32 v0, v0
	v_pk_add_f32 v[82:83], v[82:83], v[82:83] op_sel:[0,1] op_sel_hi:[1,0]
	s_waitcnt vmcnt(10)
	v_sub_f32_e32 v119, v119, v163
	v_sub_f32_e32 v118, v118, v163
	v_mul_f32_e32 v69, 0x45800000, v0
	v_cndmask_b32_e32 v162, v0, v69, vcc
	v_mov_b32_e32 v0, v88
	s_nop 1
	v_permlane16_swap_b32_e32 v88, v0
	v_add_f32_e32 v88, v88, v0
	v_mov_b32_e32 v0, v78
	s_nop 1
	v_permlane16_swap_b32_e32 v78, v0
	v_add_f32_e32 v83, v78, v0
	v_mov_b32_e32 v0, v82
	s_nop 1
	v_permlane16_swap_b32_e32 v82, v0
	v_add_f32_e32 v82, v82, v0
	v_ashrrev_i32_e32 v78, 8, v68
	v_lshlrev_b32_e32 v0, 6, v68
	v_sub_f32_e32 v69, v121, v163
	v_sub_f32_e32 v68, v120, v163
	v_pk_mul_f32 v[118:119], v[162:163], v[118:119] op_sel_hi:[0,1]
	v_pk_mul_f32 v[68:69], v[162:163], v[68:69] op_sel_hi:[0,1]
	s_waitcnt vmcnt(6)
	v_pk_fma_f32 v[68:69], v[128:129], v[68:69], v[136:137]
	v_pk_fma_f32 v[118:119], v[126:127], v[118:119], v[134:135]
	v_pk_mul_f32 v[68:69], v[68:69], s[16:17] op_sel_hi:[1,0]
	v_pk_mul_f32 v[118:119], v[118:119], s[16:17] op_sel_hi:[1,0]
	v_pk_fma_f32 v[64:65], v[64:65], 0.5, v[68:69] op_sel_hi:[1,0,1]
	v_pk_fma_f32 v[62:63], v[62:63], 0.5, v[118:119] op_sel_hi:[1,0,1]
	v_add_f32_e32 v69, v64, v65
	v_add_f32_e32 v68, v62, v63
	v_add_f32_e32 v68, v68, v69
	v_add_f32_e32 v118, 0, v68
	v_mul_f32_e32 v68, v63, v63
	v_mul_f32_e32 v69, v65, v65
	v_fmac_f32_e32 v68, v62, v62
	v_fmac_f32_e32 v69, v64, v64
	v_add_f32_e32 v119, v68, v69
	v_sub_f32_e32 v69, v117, v163
	v_sub_f32_e32 v68, v116, v163
	v_sub_f32_e32 v115, v115, v163
	v_sub_f32_e32 v114, v114, v163
	v_pk_mul_f32 v[114:115], v[162:163], v[114:115] op_sel_hi:[0,1]
	v_pk_mul_f32 v[68:69], v[162:163], v[68:69] op_sel_hi:[0,1]
	v_pk_fma_f32 v[68:69], v[124:125], v[68:69], v[132:133]
	v_pk_fma_f32 v[114:115], v[122:123], v[114:115], v[130:131]
	v_pk_mul_f32 v[68:69], v[68:69], s[16:17] op_sel_hi:[1,0]
	v_pk_mul_f32 v[114:115], v[114:115], s[16:17] op_sel_hi:[1,0]
	v_pk_fma_f32 v[60:61], v[60:61], 0.5, v[68:69] op_sel_hi:[1,0,1]
	v_pk_fma_f32 v[58:59], v[58:59], 0.5, v[114:115] op_sel_hi:[1,0,1]
	v_ashrrev_i32_e32 v79, 31, v78
	v_add_f32_e32 v68, v58, v59
	v_add_f32_e32 v69, v60, v61
	v_readlane_b32 s2, v253, 59
	v_lshlrev_b64 v[78:79], 19, v[78:79]
	s_movk_i32 s1, 0x33c0
	v_add_f32_e32 v68, v68, v69
	v_mul_f32_e32 v69, v59, v59
	v_readlane_b32 s3, v253, 60
	v_and_or_b32 v0, v0, s1, v196
	s_nop 0
	s_nop 1
	v_bfe_u32 v91, v227, 4, 2
	v_sub_u32_e32 v90, 0, v91
	v_lshlrev_b32_e32 v90, 4, v90
	v_ashrrev_i32_e32 v91, 31, v90
	v_lshl_add_u64 v[90:91], v[76:77], 0, v[90:91]
	v_permlane16_swap_b32_e32 v62, v58
	v_permlane16_swap_b32_e32 v63, v59
	v_permlane16_swap_b32_e32 v64, v60
	v_permlane16_swap_b32_e32 v65, v61
	v_permlane32_swap_b32_e32 v62, v58
	v_permlane32_swap_b32_e32 v63, v59
	v_permlane32_swap_b32_e32 v64, v60
	v_permlane32_swap_b32_e32 v65, v61
	global_store_dwordx4 v[90:91], v[62:65], off
	global_store_dwordx4 v[90:91], v[58:61], off offset:64
	s_nop 1
	v_permlane32_swap_b32_e32 v62, v58
	v_permlane32_swap_b32_e32 v63, v59
	v_permlane32_swap_b32_e32 v64, v60
	v_permlane32_swap_b32_e32 v65, v61
	v_permlane16_swap_b32_e32 v62, v58
	v_permlane16_swap_b32_e32 v63, v59
	v_permlane16_swap_b32_e32 v64, v60
	v_permlane16_swap_b32_e32 v65, v61
	v_fmac_f32_e32 v69, v58, v58
	v_cvt_pk_bf16_f32 v62, v62, v63
	v_cvt_pk_bf16_f32 v63, v64, v65
	v_cvt_pk_bf16_f32 v64, v58, v59
	v_lshl_add_u64 v[58:59], s[2:3], 0, v[78:79]
	v_mul_f32_e32 v114, v61, v61
	v_lshl_add_u64 v[78:79], v[58:59], 0, s[24:25]
	v_lshlrev_b32_e32 v0, 1, v0
	v_fmac_f32_e32 v114, v60, v60
	v_cvt_pk_bf16_f32 v65, v60, v61
	v_lshl_add_u64 v[60:61], v[78:79], 0, v[0:1]
	global_store_dwordx4 v[60:61], v[62:65], off
	s_waitcnt vmcnt(7)
	v_sub_f32_e32 v61, v101, v163
	v_sub_f32_e32 v60, v100, v163
	v_sub_f32_e32 v63, v99, v163
	v_sub_f32_e32 v62, v98, v163
	v_pk_mul_f32 v[62:63], v[162:163], v[62:63] op_sel_hi:[0,1]
	v_pk_mul_f32 v[60:61], v[162:163], v[60:61] op_sel_hi:[0,1]
	s_waitcnt vmcnt(3)
; __device__ __forceinline__ float xsum16(float v) { const auto r = __builtin_amdgcn_permlane16_swap(__float_as_uint(v), __float_as_uint(v), false, false); return __uint_as_float(r[0]) + __uint_as_float(r[1]); }
; __device__ __forceinline__ float xsum32(float v) { const auto r = __builtin_amdgcn_permlane32_swap(__float_as_uint(v), __float_as_uint(v), false, false); return __uint_as_float(r[0]) + __uint_as_float(r[1]); }
; __device__ __forceinline__ size_t blk_off(int r, int c, int K) { return (size_t)(r >> 8) * 256 * K + (size_t)(c >> 6) * (256 * 64) + (size_t)((r & 255) * 64 + (c & 63)); }
; __device__ __forceinline__ u32x4 pack8(const f32x4 a, const f32x4 b) { u32x4 w; w.x = cvt_pk_bf16(a[0], a[1]); w.y = cvt_pk_bf16(a[2], a[3]); w.z = cvt_pk_bf16(b[0], b[1]); w.w = cvt_pk_bf16(b[2], b[3]); return w; }
;     __device__ __forceinline__ void operator()(const f32x4 (&acc)[2][2][4][2], const pg8::Unit& u, int wr, int wc, int fr, int fq) const {
;     ...
;             for (int m = 0; m < 4; ++m) { const int row = row0 + ai * 128 + m * 16; const float mu = mu4[m], rs = rs4[m];
;                 f32x4 yv[2][2], gq[2][2], bq_[2][2];
; #pragma unroll
;                 for (int bj = 0; bj < 2; ++bj)
; #pragma unroll
;                     for (int n = 0; n < 2; ++n) { yv[bj][n] = *(const f32x4*)(Yin + (size_t)row * D_ + col0 + bj * 128 + 4 * n); gq[bj][n] = *(const f32x4*)(g + col0 + bj * 128 + 4 * n); bq_[bj][n] = *(const f32x4*)(b + col0 + bj * 128 + 4 * n); }
;                 asm volatile("" ::: "memory");
;                 float s1 = 0.f, s2 = 0.f;
; #pragma unroll
;                 for (int bj = 0; bj < 2; ++bj) { float* yp = Y + (size_t)row * D_ + col0 + bj * 128; f32x4 v[2];
; #pragma unroll
;                     for (int n = 0; n < 2; ++n) { v[n] = (((yv[bj][n] - mu) * rs) * gq[bj][n] + bq_[bj][n]) * ALPHA_ + acc[ai][bj][m][n] * sc;
;                         *(f32x4*)(yp + 4 * n) = v[n]; s1 += (v[n][0] + v[n][1]) + (v[n][2] + v[n][3]); s2 += (v[n][0] * v[n][0] + v[n][1] * v[n][1]) + (v[n][2] * v[n][2] + v[n][3] * v[n][3]); }
;                     *(u32x4*)(Yb + blk_off(row, col0 + bj * 128, D_)) = pack8(v[0], v[1]); }
;                 s1 = xsum32(xsum16(s1)); s2 = xsum32(xsum16(s2));
;                 if (fq == 0) *(f32x2*)(stn + (size_t)row * 32 + (u.pn * 4 + wc) * 2) = (f32x2){s1, s2}; asm volatile("" ::: "memory"); } }
	v_pk_fma_f32 v[60:61], v[108:109], v[60:61], v[160:161]
	v_pk_fma_f32 v[62:63], v[106:107], v[62:63], v[158:159]
	v_pk_mul_f32 v[60:61], v[60:61], s[16:17] op_sel_hi:[1,0]
	v_pk_mul_f32 v[62:63], v[62:63], s[16:17] op_sel_hi:[1,0]
	v_pk_fma_f32 v[56:57], v[56:57], 0.5, v[60:61] op_sel_hi:[1,0,1]
	v_pk_fma_f32 v[54:55], v[54:55], 0.5, v[62:63] op_sel_hi:[1,0,1]
	v_add_f32_e32 v61, v56, v57
	v_add_f32_e32 v60, v54, v55
	v_add_f32_e32 v68, v118, v68
	v_add_f32_e32 v60, v60, v61
	v_add_f32_e32 v64, v68, v60
	v_mul_f32_e32 v60, v55, v55
	v_mul_f32_e32 v61, v57, v57
	v_add_f32_e32 v69, v69, v114
	v_fmac_f32_e32 v60, v54, v54
	v_fmac_f32_e32 v61, v56, v56
	v_add_f32_e32 v69, v119, v69
	v_add_f32_e32 v60, v60, v61
	v_add_f32_e32 v65, v69, v60
	v_sub_f32_e32 v61, v95, v163
	v_sub_f32_e32 v60, v94, v163
	v_sub_f32_e32 v63, v93, v163
	v_sub_f32_e32 v62, v92, v163
	v_pk_mul_f32 v[62:63], v[162:163], v[62:63] op_sel_hi:[0,1]
	v_pk_mul_f32 v[60:61], v[162:163], v[60:61] op_sel_hi:[0,1]
	v_pk_fma_f32 v[60:61], v[104:105], v[60:61], v[112:113]
	v_pk_fma_f32 v[62:63], v[102:103], v[62:63], v[110:111]
	v_pk_mul_f32 v[60:61], v[60:61], s[16:17] op_sel_hi:[1,0]
	v_pk_mul_f32 v[62:63], v[62:63], s[16:17] op_sel_hi:[1,0]
	v_pk_fma_f32 v[52:53], v[52:53], 0.5, v[60:61] op_sel_hi:[1,0,1]
	v_pk_fma_f32 v[50:51], v[50:51], 0.5, v[62:63] op_sel_hi:[1,0,1]
	v_add_f32_e32 v61, v52, v53
	v_add_f32_e32 v60, v50, v51
	v_add_f32_e32 v60, v60, v61
	v_mul_f32_e32 v61, v51, v51
	v_mul_f32_e32 v62, v53, v53
	s_nop 0
	s_nop 1
	v_bfe_u32 v69, v227, 4, 2
	v_sub_u32_e32 v68, 0, v69
	v_lshlrev_b32_e32 v68, 4, v68
	v_ashrrev_i32_e32 v69, 31, v68
	v_lshl_add_u64 v[68:69], v[76:77], 0, v[68:69]
	v_permlane16_swap_b32_e32 v54, v50
	v_permlane16_swap_b32_e32 v55, v51
	v_permlane16_swap_b32_e32 v56, v52
	v_permlane16_swap_b32_e32 v57, v53
	v_permlane32_swap_b32_e32 v54, v50
	v_permlane32_swap_b32_e32 v55, v51
	v_permlane32_swap_b32_e32 v56, v52
	v_permlane32_swap_b32_e32 v57, v53
	global_store_dwordx4 v[68:69], v[54:57], off offset:512
	global_store_dwordx4 v[68:69], v[50:53], off offset:576
	s_nop 1
	v_permlane32_swap_b32_e32 v54, v50
	v_permlane32_swap_b32_e32 v55, v51
	v_permlane32_swap_b32_e32 v56, v52
	v_permlane32_swap_b32_e32 v57, v53
	v_permlane16_swap_b32_e32 v54, v50
	v_permlane16_swap_b32_e32 v55, v51
	v_permlane16_swap_b32_e32 v56, v52
	v_permlane16_swap_b32_e32 v57, v53
	v_add_f32_e32 v60, v64, v60
	v_fmac_f32_e32 v61, v50, v50
	v_fmac_f32_e32 v62, v52, v52
	v_lshl_add_u64 v[76:77], v[58:59], 0, s[44:45]
	v_add_f32_e32 v61, v61, v62
	v_cvt_pk_bf16_f32 v54, v54, v55
	v_cvt_pk_bf16_f32 v55, v56, v57
	v_cvt_pk_bf16_f32 v56, v50, v51
	v_lshl_add_u64 v[50:51], v[76:77], 0, v[0:1]
	v_mov_b32_e32 v0, v60
	v_pk_add_f32 v[70:71], v[70:71], v[70:71] op_sel:[0,1] op_sel_hi:[1,0]
	v_pk_add_f32 v[72:73], v[72:73], v[72:73] op_sel:[0,1] op_sel_hi:[1,0]
	v_pk_add_f32 v[84:85], v[84:85], v[84:85] op_sel:[0,1] op_sel_hi:[1,0]
	v_add_f32_e32 v61, v65, v61
	v_cvt_pk_bf16_f32 v57, v52, v53
	v_permlane16_swap_b32_e32 v60, v0
	v_mov_b32_e32 v71, v70
	v_mov_b32_e32 v73, v72
	v_mov_b32_e32 v85, v84
	global_store_dwordx4 v[50:51], v[54:57], off
	v_add_f32_e32 v50, v60, v0
	v_mov_b32_e32 v0, v61
	v_permlane16_swap_b32_e32 v70, v71
	v_permlane16_swap_b32_e32 v72, v73
	v_permlane16_swap_b32_e32 v84, v85
	v_permlane16_swap_b32_e32 v61, v0
	v_add_f32_e32 v71, v70, v71
	v_add_f32_e32 v70, v72, v73
	v_add_f32_e32 v89, v84, v85
	v_add_f32_e32 v51, v61, v0
	v_mov_b32_e32 v73, v71
	v_mov_b32_e32 v72, v70
	v_mov_b32_e32 v91, v89
	v_mov_b32_e32 v90, v88
	v_mov_b32_e32 v85, v83
	v_mov_b32_e32 v84, v82
	v_mov_b32_e32 v52, v50
	v_mov_b32_e32 v53, v51
	v_permlane32_swap_b32_e32 v71, v73
	v_permlane32_swap_b32_e32 v70, v72
	v_permlane32_swap_b32_e32 v89, v91
	v_permlane32_swap_b32_e32 v88, v90
	v_permlane32_swap_b32_e32 v83, v85
	v_permlane32_swap_b32_e32 v82, v84
	v_permlane32_swap_b32_e32 v50, v52
	v_permlane32_swap_b32_e32 v51, v53
	s_and_saveexec_b64 s[24:25], s[40:41]
	s_cbranch_execz .LBB0_1713
	v_pk_add_f32 v[50:51], v[50:51], v[52:53]
	v_lshl_add_u64 v[52:53], s[8:9], 0, v[66:67]
	v_lshl_add_u64 v[52:53], s[38:39], 2, v[52:53]
	global_store_dwordx2 v[52:53], v[50:51], off
.LBB0_1713:
	s_or_b64 exec, exec, s[24:25]
	v_pk_add_f32 v[50:51], v[70:71], v[72:73]
	s_mov_b32 s2, 0x3a800000
	v_pk_mul_f32 v[92:93], v[50:51], s[2:3] op_sel_hi:[1,0]
	s_mov_b32 s1, 0x800000
	v_fma_f32 v0, -v93, v93, v92
	v_max_f32_e32 v0, 0, v0
	v_add_f32_e32 v0, 0x3727c5ac, v0
	v_cmp_gt_f32_e32 vcc, s1, v0
	v_mul_f32_e32 v50, 0x4b800000, v0
	s_load_dwordx16 s[60:75], s[34:35], 0x38
	v_cndmask_b32_e32 v0, v0, v50, vcc
	v_rsq_f32_e32 v0, v0
	s_mov_b32 s2, 0x3fd744fd
	s_movk_i32 s1, 0x37c0
	v_mul_f32_e32 v50, 0x45800000, v0
	v_cndmask_b32_e32 v92, v0, v50, vcc
	v_lshlrev_b64 v[50:51], 12, v[96:97]
	s_waitcnt lgkmcnt(0)
	v_lshl_add_u64 v[50:51], s[74:75], 0, v[50:51]
	v_lshl_add_u64 v[94:95], v[152:153], 2, v[50:51]
	global_load_dwordx4 v[98:101], v[94:95], off offset:16
	global_load_dwordx4 v[102:105], v[94:95], off
	global_load_dwordx4 v[106:109], v[156:157], off offset:16
	global_load_dwordx4 v[110:113], v[156:157], off
	global_load_dwordx4 v[114:117], v[154:155], off offset:16
	global_load_dwordx4 v[118:121], v[154:155], off
	global_load_dwordx4 v[50:53], v[94:95], off offset:528
	global_load_dwordx4 v[70:73], v[94:95], off offset:512
	global_load_dwordx4 v[54:57], v[156:157], off offset:528
	global_load_dwordx4 v[62:65], v[156:157], off offset:512
	global_load_dwordx4 v[58:61], v[154:155], off offset:528
	global_load_dwordx4 v[66:69], v[154:155], off offset:512
	v_lshlrev_b32_e32 v0, 6, v96
	v_and_or_b32 v0, v0, s1, v196
	v_lshlrev_b32_e32 v0, 1, v0
	s_waitcnt vmcnt(10)
; __device__ __forceinline__ float xsum16(float v) { const auto r = __builtin_amdgcn_permlane16_swap(__float_as_uint(v), __float_as_uint(v), false, false); return __uint_as_float(r[0]) + __uint_as_float(r[1]); }
; __device__ __forceinline__ float xsum32(float v) { const auto r = __builtin_amdgcn_permlane32_swap(__float_as_uint(v), __float_as_uint(v), false, false); return __uint_as_float(r[0]) + __uint_as_float(r[1]); }
; __device__ __forceinline__ size_t blk_off(int r, int c, int K) { return (size_t)(r >> 8) * 256 * K + (size_t)(c >> 6) * (256 * 64) + (size_t)((r & 255) * 64 + (c & 63)); }
; __device__ __forceinline__ u32x4 pack8(const f32x4 a, const f32x4 b) { u32x4 w; w.x = cvt_pk_bf16(a[0], a[1]); w.y = cvt_pk_bf16(a[2], a[3]); w.z = cvt_pk_bf16(b[0], b[1]); w.w = cvt_pk_bf16(b[2], b[3]); return w; }
;     __device__ __forceinline__ void operator()(const f32x4 (&acc)[2][2][4][2], const pg8::Unit& u, int wr, int wc, int fr, int fq) const {
;     ...
;             for (int m = 0; m < 4; ++m) { const int row = row0 + ai * 128 + m * 16; const float mu = mu4[m], rs = rs4[m];
;                 f32x4 yv[2][2], gq[2][2], bq_[2][2];
; #pragma unroll
;                 for (int bj = 0; bj < 2; ++bj)
; #pragma unroll
;                     for (int n = 0; n < 2; ++n) { yv[bj][n] = *(const f32x4*)(Yin + (size_t)row * D_ + col0 + bj * 128 + 4 * n); gq[bj][n] = *(const f32x4*)(g + col0 + bj * 128 + 4 * n); bq_[bj][n] = *(const f32x4*)(b + col0 + bj * 128 + 4 * n); }
;                 asm volatile("" ::: "memory");
;                 float s1 = 0.f, s2 = 0.f;
; #pragma unroll
;                 for (int bj = 0; bj < 2; ++bj) { float* yp = Y + (size_t)row * D_ + col0 + bj * 128; f32x4 v[2];
; #pragma unroll
;                     for (int n = 0; n < 2; ++n) { v[n] = (((yv[bj][n] - mu) * rs) * gq[bj][n] + bq_[bj][n]) * ALPHA_ + acc[ai][bj][m][n] * sc;
;                         *(f32x4*)(yp + 4 * n) = v[n]; s1 += (v[n][0] + v[n][1]) + (v[n][2] + v[n][3]); s2 += (v[n][0] * v[n][0] + v[n][1] * v[n][1]) + (v[n][2] * v[n][2] + v[n][3] * v[n][3]); }
;                     *(u32x4*)(Yb + blk_off(row, col0 + bj * 128, D_)) = pack8(v[0], v[1]); }
;                 s1 = xsum32(xsum16(s1)); s2 = xsum32(xsum16(s2));
;                 if (fq == 0) *(f32x2*)(stn + (size_t)row * 32 + (u.pn * 4 + wc) * 2) = (f32x2){s1, s2}; asm volatile("" ::: "memory"); } }
	v_sub_f32_e32 v97, v105, v93
	v_sub_f32_e32 v96, v104, v93
	v_sub_f32_e32 v103, v103, v93
	v_sub_f32_e32 v102, v102, v93
	v_pk_mul_f32 v[102:103], v[92:93], v[102:103] op_sel_hi:[0,1]
	v_pk_mul_f32 v[96:97], v[92:93], v[96:97] op_sel_hi:[0,1]
	s_waitcnt vmcnt(6)
	v_pk_fma_f32 v[96:97], v[112:113], v[96:97], v[120:121]
	v_pk_fma_f32 v[102:103], v[110:111], v[102:103], v[118:119]
	v_pk_mul_f32 v[96:97], v[96:97], s[2:3] op_sel_hi:[1,0]
	v_pk_mul_f32 v[102:103], v[102:103], s[2:3] op_sel_hi:[1,0]
	v_pk_fma_f32 v[104:105], v[48:49], 0.5, v[96:97] op_sel_hi:[1,0,1]
	v_pk_fma_f32 v[102:103], v[46:47], 0.5, v[102:103] op_sel_hi:[1,0,1]
	v_add_f32_e32 v47, v104, v105
	v_add_f32_e32 v46, v102, v103
	v_add_f32_e32 v46, v46, v47
	v_add_f32_e32 v110, 0, v46
	v_mul_f32_e32 v46, v103, v103
	v_mul_f32_e32 v47, v105, v105
	v_fmac_f32_e32 v46, v102, v102
	v_fmac_f32_e32 v47, v104, v104
	v_add_f32_e32 v111, v46, v47
	v_sub_f32_e32 v47, v101, v93
	v_sub_f32_e32 v46, v100, v93
	v_sub_f32_e32 v49, v99, v93
	v_sub_f32_e32 v48, v98, v93
	v_pk_mul_f32 v[48:49], v[92:93], v[48:49] op_sel_hi:[0,1]
	v_pk_mul_f32 v[46:47], v[92:93], v[46:47] op_sel_hi:[0,1]
	v_pk_fma_f32 v[46:47], v[108:109], v[46:47], v[116:117]
	v_pk_fma_f32 v[48:49], v[106:107], v[48:49], v[114:115]
	v_pk_mul_f32 v[46:47], v[46:47], s[2:3] op_sel_hi:[1,0]
	v_pk_mul_f32 v[48:49], v[48:49], s[2:3] op_sel_hi:[1,0]
	v_pk_fma_f32 v[98:99], v[44:45], 0.5, v[46:47] op_sel_hi:[1,0,1]
	v_pk_fma_f32 v[96:97], v[42:43], 0.5, v[48:49] op_sel_hi:[1,0,1]
	v_add_f32_e32 v43, v98, v99
	v_add_f32_e32 v42, v96, v97
	v_add_f32_e32 v42, v42, v43
	v_add_f32_e32 v47, v110, v42
	v_mul_f32_e32 v42, v97, v97
	v_mul_f32_e32 v43, v99, v99
	v_fmac_f32_e32 v42, v96, v96
	v_fmac_f32_e32 v43, v98, v98
	v_add_f32_e32 v42, v42, v43
	v_add_f32_e32 v46, v111, v42
	v_cvt_pk_bf16_f32 v42, v102, v103
	v_cvt_pk_bf16_f32 v43, v104, v105
	v_cvt_pk_bf16_f32 v44, v96, v97
	v_cvt_pk_bf16_f32 v45, v98, v99
	v_lshl_add_u64 v[48:49], v[78:79], 0, v[0:1]
	s_nop 0
	s_nop 1
	v_bfe_u32 v101, v227, 4, 2
	v_sub_u32_e32 v100, 0, v101
	v_lshlrev_b32_e32 v100, 4, v100
	v_ashrrev_i32_e32 v101, 31, v100
	v_lshl_add_u64 v[100:101], v[94:95], 0, v[100:101]
	v_permlane16_swap_b32_e32 v102, v96
	v_permlane16_swap_b32_e32 v103, v97
	v_permlane16_swap_b32_e32 v104, v98
	v_permlane16_swap_b32_e32 v105, v99
	v_permlane32_swap_b32_e32 v102, v96
	v_permlane32_swap_b32_e32 v103, v97
	v_permlane32_swap_b32_e32 v104, v98
	v_permlane32_swap_b32_e32 v105, v99
	global_store_dwordx4 v[100:101], v[102:105], off
	global_store_dwordx4 v[100:101], v[96:99], off offset:64
	s_nop 1
	v_permlane32_swap_b32_e32 v102, v96
	v_permlane32_swap_b32_e32 v103, v97
	v_permlane32_swap_b32_e32 v104, v98
	v_permlane32_swap_b32_e32 v105, v99
	v_permlane16_swap_b32_e32 v102, v96
	v_permlane16_swap_b32_e32 v103, v97
	v_permlane16_swap_b32_e32 v104, v98
	v_permlane16_swap_b32_e32 v105, v99
	global_store_dwordx4 v[48:49], v[42:45], off
	s_waitcnt vmcnt(7)
	s_nop 0
	v_sub_f32_e32 v43, v73, v93
	v_sub_f32_e32 v42, v72, v93
	v_sub_f32_e32 v45, v71, v93
	v_sub_f32_e32 v44, v70, v93
	v_pk_mul_f32 v[44:45], v[92:93], v[44:45] op_sel_hi:[0,1]
	v_pk_mul_f32 v[42:43], v[92:93], v[42:43] op_sel_hi:[0,1]
	s_waitcnt vmcnt(3)
	v_pk_fma_f32 v[42:43], v[64:65], v[42:43], v[68:69]
	v_pk_fma_f32 v[44:45], v[62:63], v[44:45], v[66:67]
	v_pk_mul_f32 v[42:43], v[42:43], s[2:3] op_sel_hi:[1,0]
	v_pk_mul_f32 v[44:45], v[44:45], s[2:3] op_sel_hi:[1,0]
	v_pk_fma_f32 v[40:41], v[40:41], 0.5, v[42:43] op_sel_hi:[1,0,1]
	v_pk_fma_f32 v[38:39], v[38:39], 0.5, v[44:45] op_sel_hi:[1,0,1]
	v_add_f32_e32 v43, v40, v41
	v_add_f32_e32 v42, v38, v39
	v_add_f32_e32 v42, v42, v43
	v_add_f32_e32 v47, v47, v42
	v_mul_f32_e32 v42, v39, v39
	v_mul_f32_e32 v43, v41, v41
	v_fmac_f32_e32 v42, v38, v38
	v_fmac_f32_e32 v43, v40, v40
	v_add_f32_e32 v42, v42, v43
	v_add_f32_e32 v46, v46, v42
	v_sub_f32_e32 v43, v53, v93
	v_sub_f32_e32 v42, v52, v93
	v_sub_f32_e32 v45, v51, v93
	v_sub_f32_e32 v44, v50, v93
	v_pk_mul_f32 v[44:45], v[92:93], v[44:45] op_sel_hi:[0,1]
	v_pk_mul_f32 v[42:43], v[92:93], v[42:43] op_sel_hi:[0,1]
	v_pk_fma_f32 v[42:43], v[56:57], v[42:43], v[60:61]
	v_pk_fma_f32 v[44:45], v[54:55], v[44:45], v[58:59]
	v_pk_mul_f32 v[42:43], v[42:43], s[2:3] op_sel_hi:[1,0]
	v_pk_mul_f32 v[44:45], v[44:45], s[2:3] op_sel_hi:[1,0]
	v_pk_fma_f32 v[36:37], v[36:37], 0.5, v[42:43] op_sel_hi:[1,0,1]
	v_pk_fma_f32 v[34:35], v[34:35], 0.5, v[44:45] op_sel_hi:[1,0,1]
	v_add_f32_e32 v43, v36, v37
	v_add_f32_e32 v42, v34, v35
	v_add_f32_e32 v42, v42, v43
	v_mul_f32_e32 v43, v35, v35
	v_mul_f32_e32 v44, v37, v37
	v_add_f32_e32 v42, v47, v42
	v_fmac_f32_e32 v43, v34, v34
	v_fmac_f32_e32 v44, v36, v36
	s_nop 0
	s_nop 1
	v_bfe_u32 v49, v227, 4, 2
	v_sub_u32_e32 v48, 0, v49
	v_lshlrev_b32_e32 v48, 4, v48
	v_ashrrev_i32_e32 v49, 31, v48
	v_lshl_add_u64 v[48:49], v[94:95], 0, v[48:49]
	v_permlane16_swap_b32_e32 v38, v34
	v_permlane16_swap_b32_e32 v39, v35
	v_permlane16_swap_b32_e32 v40, v36
	v_permlane16_swap_b32_e32 v41, v37
	v_permlane32_swap_b32_e32 v38, v34
	v_permlane32_swap_b32_e32 v39, v35
	v_permlane32_swap_b32_e32 v40, v36
	v_permlane32_swap_b32_e32 v41, v37
	global_store_dwordx4 v[48:49], v[38:41], off offset:512
	global_store_dwordx4 v[48:49], v[34:37], off offset:576
	s_nop 1
	v_permlane32_swap_b32_e32 v38, v34
	v_permlane32_swap_b32_e32 v39, v35
	v_permlane32_swap_b32_e32 v40, v36
	v_permlane32_swap_b32_e32 v41, v37
	v_permlane16_swap_b32_e32 v38, v34
	v_permlane16_swap_b32_e32 v39, v35
	v_permlane16_swap_b32_e32 v40, v36
	v_permlane16_swap_b32_e32 v41, v37
	v_add_f32_e32 v43, v43, v44
	v_cvt_pk_bf16_f32 v38, v38, v39
	v_cvt_pk_bf16_f32 v39, v40, v41
	v_cvt_pk_bf16_f32 v40, v34, v35
	v_lshl_add_u64 v[34:35], v[76:77], 0, v[0:1]
	v_mov_b32_e32 v0, v42
	v_add_f32_e32 v43, v46, v43
	v_cvt_pk_bf16_f32 v41, v36, v37
	v_permlane16_swap_b32_e32 v42, v0
	global_store_dwordx4 v[34:35], v[38:41], off
	v_add_f32_e32 v34, v42, v0
	v_mov_b32_e32 v0, v43
	s_nop 1
	v_permlane16_swap_b32_e32 v43, v0
	v_add_f32_e32 v35, v43, v0
	v_mov_b32_e32 v36, v34
	v_mov_b32_e32 v37, v35
	s_nop 0
	v_permlane32_swap_b32_e32 v34, v36
	v_permlane32_swap_b32_e32 v35, v37
	s_and_saveexec_b64 s[24:25], s[40:41]
	s_cbranch_execz .LBB0_1715
	v_pk_add_f32 v[34:35], v[34:35], v[36:37]
	v_lshl_add_u64 v[36:37], s[8:9], 0, v[86:87]
	v_lshl_add_u64 v[36:37], s[38:39], 2, v[36:37]
	global_store_dwordx2 v[36:37], v[34:35], off
; __device__ __forceinline__ float xsum16(float v) { const auto r = __builtin_amdgcn_permlane16_swap(__float_as_uint(v), __float_as_uint(v), false, false); return __uint_as_float(r[0]) + __uint_as_float(r[1]); }
; __device__ __forceinline__ float xsum32(float v) { const auto r = __builtin_amdgcn_permlane32_swap(__float_as_uint(v), __float_as_uint(v), false, false); return __uint_as_float(r[0]) + __uint_as_float(r[1]); }
; __device__ __forceinline__ size_t blk_off(int r, int c, int K) { return (size_t)(r >> 8) * 256 * K + (size_t)(c >> 6) * (256 * 64) + (size_t)((r & 255) * 64 + (c & 63)); }
; __device__ __forceinline__ u32x4 pack8(const f32x4 a, const f32x4 b) { u32x4 w; w.x = cvt_pk_bf16(a[0], a[1]); w.y = cvt_pk_bf16(a[2], a[3]); w.z = cvt_pk_bf16(b[0], b[1]); w.w = cvt_pk_bf16(b[2], b[3]); return w; }
;     __device__ __forceinline__ void operator()(const f32x4 (&acc)[2][2][4][2], const pg8::Unit& u, int wr, int wc, int fr, int fq) const {
;     ...
;             for (int m = 0; m < 4; ++m) { const int row = row0 + ai * 128 + m * 16; const float mu = mu4[m], rs = rs4[m];
;                 f32x4 yv[2][2], gq[2][2], bq_[2][2];
; #pragma unroll
;                 for (int bj = 0; bj < 2; ++bj)
; #pragma unroll
;                     for (int n = 0; n < 2; ++n) { yv[bj][n] = *(const f32x4*)(Yin + (size_t)row * D_ + col0 + bj * 128 + 4 * n); gq[bj][n] = *(const f32x4*)(g + col0 + bj * 128 + 4 * n); bq_[bj][n] = *(const f32x4*)(b + col0 + bj * 128 + 4 * n); }
;                 asm volatile("" ::: "memory");
;                 float s1 = 0.f, s2 = 0.f;
; #pragma unroll
;                 for (int bj = 0; bj < 2; ++bj) { float* yp = Y + (size_t)row * D_ + col0 + bj * 128; f32x4 v[2];
; #pragma unroll
;                     for (int n = 0; n < 2; ++n) { v[n] = (((yv[bj][n] - mu) * rs) * gq[bj][n] + bq_[bj][n]) * ALPHA_ + acc[ai][bj][m][n] * sc;
;                         *(f32x4*)(yp + 4 * n) = v[n]; s1 += (v[n][0] + v[n][1]) + (v[n][2] + v[n][3]); s2 += (v[n][0] * v[n][0] + v[n][1] * v[n][1]) + (v[n][2] * v[n][2] + v[n][3] * v[n][3]); }
;                     *(u32x4*)(Yb + blk_off(row, col0 + bj * 128, D_)) = pack8(v[0], v[1]); }
;                 s1 = xsum32(xsum16(s1)); s2 = xsum32(xsum16(s2));
;                 if (fq == 0) *(f32x2*)(stn + (size_t)row * 32 + (u.pn * 4 + wc) * 2) = (f32x2){s1, s2}; asm volatile("" ::: "memory"); } }
.LBB0_1715:
	s_or_b64 exec, exec, s[24:25]
	v_pk_add_f32 v[34:35], v[88:89], v[90:91]
	s_mov_b32 s2, 0x3a800000
	v_pk_mul_f32 v[58:59], v[34:35], s[2:3] op_sel_hi:[1,0]
	s_mov_b32 s1, 0x800000
	v_fma_f32 v0, -v59, v59, v58
	v_max_f32_e32 v0, 0, v0
	v_add_f32_e32 v0, 0x3727c5ac, v0
	v_cmp_gt_f32_e32 vcc, s1, v0
	v_mul_f32_e32 v34, 0x4b800000, v0
	s_load_dwordx16 s[60:75], s[34:35], 0x38
	v_cndmask_b32_e32 v0, v0, v34, vcc
	v_rsq_f32_e32 v0, v0
	s_mov_b32 s2, 0x3fd744fd
	s_movk_i32 s1, 0x3bc0
	v_mul_f32_e32 v34, 0x45800000, v0
	v_cndmask_b32_e32 v58, v0, v34, vcc
	v_lshlrev_b64 v[34:35], 12, v[80:81]
	s_waitcnt lgkmcnt(0)
	v_lshl_add_u64 v[34:35], s[74:75], 0, v[34:35]
	v_lshl_add_u64 v[60:61], v[152:153], 2, v[34:35]
	global_load_dwordx4 v[62:65], v[60:61], off offset:16
	global_load_dwordx4 v[66:69], v[60:61], off
	global_load_dwordx4 v[70:73], v[156:157], off offset:16
	global_load_dwordx4 v[86:89], v[156:157], off
	global_load_dwordx4 v[90:93], v[154:155], off offset:16
	global_load_dwordx4 v[94:97], v[154:155], off
	global_load_dwordx4 v[34:37], v[60:61], off offset:528
	global_load_dwordx4 v[54:57], v[60:61], off offset:512
	global_load_dwordx4 v[38:41], v[156:157], off offset:528
	global_load_dwordx4 v[46:49], v[156:157], off offset:512
	global_load_dwordx4 v[42:45], v[154:155], off offset:528
	global_load_dwordx4 v[50:53], v[154:155], off offset:512
	v_lshlrev_b32_e32 v0, 6, v80
	v_and_or_b32 v0, v0, s1, v196
	v_lshlrev_b32_e32 v0, 1, v0
	s_waitcnt vmcnt(10)
	v_sub_f32_e32 v69, v69, v59
	v_sub_f32_e32 v68, v68, v59
	v_sub_f32_e32 v67, v67, v59
	v_sub_f32_e32 v66, v66, v59
	v_pk_mul_f32 v[66:67], v[58:59], v[66:67] op_sel_hi:[0,1]
	v_pk_mul_f32 v[68:69], v[58:59], v[68:69] op_sel_hi:[0,1]
	s_waitcnt vmcnt(6)
	v_pk_fma_f32 v[68:69], v[88:89], v[68:69], v[96:97]
	v_pk_fma_f32 v[66:67], v[86:87], v[66:67], v[94:95]
	v_pk_mul_f32 v[68:69], v[68:69], s[2:3] op_sel_hi:[1,0]
	v_pk_mul_f32 v[66:67], v[66:67], s[2:3] op_sel_hi:[1,0]
	v_pk_fma_f32 v[68:69], v[32:33], 0.5, v[68:69] op_sel_hi:[1,0,1]
	v_pk_fma_f32 v[66:67], v[30:31], 0.5, v[66:67] op_sel_hi:[1,0,1]
	v_add_f32_e32 v31, v68, v69
	v_add_f32_e32 v30, v66, v67
	v_add_f32_e32 v30, v30, v31
	v_add_f32_e32 v86, 0, v30
	v_mul_f32_e32 v30, v67, v67
	v_mul_f32_e32 v31, v69, v69
	v_fmac_f32_e32 v30, v66, v66
	v_fmac_f32_e32 v31, v68, v68
	v_add_f32_e32 v87, v30, v31
	v_sub_f32_e32 v31, v65, v59
	v_sub_f32_e32 v30, v64, v59
	v_sub_f32_e32 v33, v63, v59
	v_sub_f32_e32 v32, v62, v59
	v_pk_mul_f32 v[32:33], v[58:59], v[32:33] op_sel_hi:[0,1]
	v_pk_mul_f32 v[30:31], v[58:59], v[30:31] op_sel_hi:[0,1]
	v_pk_fma_f32 v[30:31], v[72:73], v[30:31], v[92:93]
	v_pk_fma_f32 v[32:33], v[70:71], v[32:33], v[90:91]
	v_pk_mul_f32 v[30:31], v[30:31], s[2:3] op_sel_hi:[1,0]
	v_pk_mul_f32 v[32:33], v[32:33], s[2:3] op_sel_hi:[1,0]
	v_pk_fma_f32 v[64:65], v[28:29], 0.5, v[30:31] op_sel_hi:[1,0,1]
	v_pk_fma_f32 v[62:63], v[26:27], 0.5, v[32:33] op_sel_hi:[1,0,1]
	v_add_f32_e32 v27, v64, v65
	v_add_f32_e32 v26, v62, v63
	v_add_f32_e32 v26, v26, v27
	v_add_f32_e32 v31, v86, v26
	v_mul_f32_e32 v26, v63, v63
	v_mul_f32_e32 v27, v65, v65
	v_fmac_f32_e32 v26, v62, v62
	v_fmac_f32_e32 v27, v64, v64
	v_add_f32_e32 v26, v26, v27
	v_add_f32_e32 v30, v87, v26
	v_cvt_pk_bf16_f32 v26, v66, v67
	v_cvt_pk_bf16_f32 v27, v68, v69
	v_cvt_pk_bf16_f32 v28, v62, v63
	v_cvt_pk_bf16_f32 v29, v64, v65
	v_lshl_add_u64 v[32:33], v[78:79], 0, v[0:1]
	s_nop 0
	s_nop 1
	v_bfe_u32 v71, v227, 4, 2
	v_sub_u32_e32 v70, 0, v71
	v_lshlrev_b32_e32 v70, 4, v70
	v_ashrrev_i32_e32 v71, 31, v70
	v_lshl_add_u64 v[70:71], v[60:61], 0, v[70:71]
	v_permlane16_swap_b32_e32 v66, v62
	v_permlane16_swap_b32_e32 v67, v63
	v_permlane16_swap_b32_e32 v68, v64
	v_permlane16_swap_b32_e32 v69, v65
	v_permlane32_swap_b32_e32 v66, v62
	v_permlane32_swap_b32_e32 v67, v63
	v_permlane32_swap_b32_e32 v68, v64
	v_permlane32_swap_b32_e32 v69, v65
	global_store_dwordx4 v[70:71], v[66:69], off
	global_store_dwordx4 v[70:71], v[62:65], off offset:64
	s_nop 1
	v_permlane32_swap_b32_e32 v66, v62
	v_permlane32_swap_b32_e32 v67, v63
	v_permlane32_swap_b32_e32 v68, v64
	v_permlane32_swap_b32_e32 v69, v65
	v_permlane16_swap_b32_e32 v66, v62
	v_permlane16_swap_b32_e32 v67, v63
	v_permlane16_swap_b32_e32 v68, v64
	v_permlane16_swap_b32_e32 v69, v65
	global_store_dwordx4 v[32:33], v[26:29], off
	s_waitcnt vmcnt(7)
	s_nop 0
	v_sub_f32_e32 v27, v57, v59
	v_sub_f32_e32 v26, v56, v59
	v_sub_f32_e32 v29, v55, v59
	v_sub_f32_e32 v28, v54, v59
	v_pk_mul_f32 v[28:29], v[58:59], v[28:29] op_sel_hi:[0,1]
	v_pk_mul_f32 v[26:27], v[58:59], v[26:27] op_sel_hi:[0,1]
	s_waitcnt vmcnt(3)
; __device__ __forceinline__ float xsum16(float v) { const auto r = __builtin_amdgcn_permlane16_swap(__float_as_uint(v), __float_as_uint(v), false, false); return __uint_as_float(r[0]) + __uint_as_float(r[1]); }
; __device__ __forceinline__ float xsum32(float v) { const auto r = __builtin_amdgcn_permlane32_swap(__float_as_uint(v), __float_as_uint(v), false, false); return __uint_as_float(r[0]) + __uint_as_float(r[1]); }
; __device__ __forceinline__ size_t blk_off(int r, int c, int K) { return (size_t)(r >> 8) * 256 * K + (size_t)(c >> 6) * (256 * 64) + (size_t)((r & 255) * 64 + (c & 63)); }
; __device__ __forceinline__ u32x4 pack8(const f32x4 a, const f32x4 b) { u32x4 w; w.x = cvt_pk_bf16(a[0], a[1]); w.y = cvt_pk_bf16(a[2], a[3]); w.z = cvt_pk_bf16(b[0], b[1]); w.w = cvt_pk_bf16(b[2], b[3]); return w; }
;     __device__ __forceinline__ void operator()(const f32x4 (&acc)[2][2][4][2], const pg8::Unit& u, int wr, int wc, int fr, int fq) const {
;     ...
;             for (int m = 0; m < 4; ++m) { const int row = row0 + ai * 128 + m * 16; const float mu = mu4[m], rs = rs4[m];
;                 f32x4 yv[2][2], gq[2][2], bq_[2][2];
; #pragma unroll
;                 for (int bj = 0; bj < 2; ++bj)
; #pragma unroll
;                     for (int n = 0; n < 2; ++n) { yv[bj][n] = *(const f32x4*)(Yin + (size_t)row * D_ + col0 + bj * 128 + 4 * n); gq[bj][n] = *(const f32x4*)(g + col0 + bj * 128 + 4 * n); bq_[bj][n] = *(const f32x4*)(b + col0 + bj * 128 + 4 * n); }
;                 asm volatile("" ::: "memory");
;                 float s1 = 0.f, s2 = 0.f;
; #pragma unroll
;                 for (int bj = 0; bj < 2; ++bj) { float* yp = Y + (size_t)row * D_ + col0 + bj * 128; f32x4 v[2];
; #pragma unroll
;                     for (int n = 0; n < 2; ++n) { v[n] = (((yv[bj][n] - mu) * rs) * gq[bj][n] + bq_[bj][n]) * ALPHA_ + acc[ai][bj][m][n] * sc;
;                         *(f32x4*)(yp + 4 * n) = v[n]; s1 += (v[n][0] + v[n][1]) + (v[n][2] + v[n][3]); s2 += (v[n][0] * v[n][0] + v[n][1] * v[n][1]) + (v[n][2] * v[n][2] + v[n][3] * v[n][3]); }
;                     *(u32x4*)(Yb + blk_off(row, col0 + bj * 128, D_)) = pack8(v[0], v[1]); }
;                 s1 = xsum32(xsum16(s1)); s2 = xsum32(xsum16(s2));
;                 if (fq == 0) *(f32x2*)(stn + (size_t)row * 32 + (u.pn * 4 + wc) * 2) = (f32x2){s1, s2}; asm volatile("" ::: "memory"); } }
	v_pk_fma_f32 v[26:27], v[48:49], v[26:27], v[52:53]
	v_pk_fma_f32 v[28:29], v[46:47], v[28:29], v[50:51]
	v_pk_mul_f32 v[26:27], v[26:27], s[2:3] op_sel_hi:[1,0]
	v_pk_mul_f32 v[28:29], v[28:29], s[2:3] op_sel_hi:[1,0]
	v_pk_fma_f32 v[24:25], v[24:25], 0.5, v[26:27] op_sel_hi:[1,0,1]
	v_pk_fma_f32 v[22:23], v[22:23], 0.5, v[28:29] op_sel_hi:[1,0,1]
	v_add_f32_e32 v27, v24, v25
	v_add_f32_e32 v26, v22, v23
	v_add_f32_e32 v26, v26, v27
	v_add_f32_e32 v31, v31, v26
	v_mul_f32_e32 v26, v23, v23
	v_mul_f32_e32 v27, v25, v25
	v_fmac_f32_e32 v26, v22, v22
	v_fmac_f32_e32 v27, v24, v24
	v_add_f32_e32 v26, v26, v27
	v_add_f32_e32 v30, v30, v26
	v_sub_f32_e32 v27, v37, v59
	v_sub_f32_e32 v26, v36, v59
	v_sub_f32_e32 v29, v35, v59
	v_sub_f32_e32 v28, v34, v59
	v_pk_mul_f32 v[28:29], v[58:59], v[28:29] op_sel_hi:[0,1]
	v_pk_mul_f32 v[26:27], v[58:59], v[26:27] op_sel_hi:[0,1]
	v_pk_fma_f32 v[26:27], v[40:41], v[26:27], v[44:45]
	v_pk_fma_f32 v[28:29], v[38:39], v[28:29], v[42:43]
	v_pk_mul_f32 v[26:27], v[26:27], s[2:3] op_sel_hi:[1,0]
	v_pk_mul_f32 v[28:29], v[28:29], s[2:3] op_sel_hi:[1,0]
	v_pk_fma_f32 v[20:21], v[20:21], 0.5, v[26:27] op_sel_hi:[1,0,1]
	v_pk_fma_f32 v[18:19], v[18:19], 0.5, v[28:29] op_sel_hi:[1,0,1]
	v_add_f32_e32 v27, v20, v21
	v_add_f32_e32 v26, v18, v19
	v_add_f32_e32 v26, v26, v27
	v_mul_f32_e32 v27, v19, v19
	v_mul_f32_e32 v28, v21, v21
	v_add_f32_e32 v26, v31, v26
	v_fmac_f32_e32 v27, v18, v18
	v_fmac_f32_e32 v28, v20, v20
	s_nop 0
	s_nop 1
	v_bfe_u32 v33, v227, 4, 2
	v_sub_u32_e32 v32, 0, v33
	v_lshlrev_b32_e32 v32, 4, v32
	v_ashrrev_i32_e32 v33, 31, v32
	v_lshl_add_u64 v[32:33], v[60:61], 0, v[32:33]
	v_permlane16_swap_b32_e32 v22, v18
	v_permlane16_swap_b32_e32 v23, v19
	v_permlane16_swap_b32_e32 v24, v20
	v_permlane16_swap_b32_e32 v25, v21
	v_permlane32_swap_b32_e32 v22, v18
	v_permlane32_swap_b32_e32 v23, v19
	v_permlane32_swap_b32_e32 v24, v20
	v_permlane32_swap_b32_e32 v25, v21
	global_store_dwordx4 v[32:33], v[22:25], off offset:512
	global_store_dwordx4 v[32:33], v[18:21], off offset:576
	s_nop 1
	v_permlane32_swap_b32_e32 v22, v18
	v_permlane32_swap_b32_e32 v23, v19
	v_permlane32_swap_b32_e32 v24, v20
	v_permlane32_swap_b32_e32 v25, v21
	v_permlane16_swap_b32_e32 v22, v18
	v_permlane16_swap_b32_e32 v23, v19
	v_permlane16_swap_b32_e32 v24, v20
	v_permlane16_swap_b32_e32 v25, v21
	v_add_f32_e32 v27, v27, v28
	v_cvt_pk_bf16_f32 v22, v22, v23
	v_cvt_pk_bf16_f32 v23, v24, v25
	v_cvt_pk_bf16_f32 v24, v18, v19
	v_lshl_add_u64 v[18:19], v[76:77], 0, v[0:1]
	v_mov_b32_e32 v0, v26
	v_add_f32_e32 v27, v30, v27
	v_cvt_pk_bf16_f32 v25, v20, v21
	v_permlane16_swap_b32_e32 v26, v0
	global_store_dwordx4 v[18:19], v[22:25], off
	v_add_f32_e32 v18, v26, v0
	v_mov_b32_e32 v0, v27
	s_nop 1
	v_permlane16_swap_b32_e32 v27, v0
	v_add_f32_e32 v19, v27, v0
	v_mov_b32_e32 v20, v18
	v_mov_b32_e32 v21, v19
	s_nop 0
	v_permlane32_swap_b32_e32 v18, v20
	v_permlane32_swap_b32_e32 v19, v21
	s_and_saveexec_b64 s[24:25], s[40:41]
	s_cbranch_execz .LBB0_1717
	v_pk_add_f32 v[18:19], v[18:19], v[20:21]
	v_lshlrev_b64 v[20:21], 7, v[80:81]
	v_lshl_add_u64 v[20:21], s[8:9], 0, v[20:21]
	v_lshl_add_u64 v[20:21], s[38:39], 2, v[20:21]
	global_store_dwordx2 v[20:21], v[18:19], off
.LBB0_1717:
	s_or_b64 exec, exec, s[24:25]
	v_pk_add_f32 v[18:19], v[82:83], v[84:85]
	s_mov_b32 s2, 0x3a800000
	v_pk_mul_f32 v[42:43], v[18:19], s[2:3] op_sel_hi:[1,0]
	s_mov_b32 s1, 0x800000
	v_fma_f32 v0, -v43, v43, v42
	v_max_f32_e32 v0, 0, v0
	v_add_f32_e32 v0, 0x3727c5ac, v0
	v_cmp_gt_f32_e32 vcc, s1, v0
	v_mul_f32_e32 v18, 0x4b800000, v0
	s_load_dwordx16 s[60:75], s[34:35], 0x38
	v_cndmask_b32_e32 v0, v0, v18, vcc
	v_rsq_f32_e32 v0, v0
	s_mov_b32 s2, 0x3fd744fd
	s_movk_i32 s1, 0x3fc0
	v_mul_f32_e32 v18, 0x45800000, v0
	v_cndmask_b32_e32 v42, v0, v18, vcc
	v_lshlrev_b64 v[18:19], 12, v[74:75]
	s_waitcnt lgkmcnt(0)
	v_lshl_add_u64 v[18:19], s[74:75], 0, v[18:19]
	v_lshl_add_u64 v[44:45], v[152:153], 2, v[18:19]
	global_load_dwordx4 v[46:49], v[44:45], off offset:16
	global_load_dwordx4 v[50:53], v[44:45], off
	global_load_dwordx4 v[54:57], v[156:157], off offset:16
	global_load_dwordx4 v[58:61], v[156:157], off
	global_load_dwordx4 v[62:65], v[154:155], off offset:16
	global_load_dwordx4 v[66:69], v[154:155], off
	global_load_dwordx4 v[18:21], v[44:45], off offset:528
	global_load_dwordx4 v[38:41], v[44:45], off offset:512
	global_load_dwordx4 v[22:25], v[156:157], off offset:528
	global_load_dwordx4 v[30:33], v[156:157], off offset:512
	global_load_dwordx4 v[26:29], v[154:155], off offset:528
	global_load_dwordx4 v[34:37], v[154:155], off offset:512
	v_lshlrev_b32_e32 v0, 6, v74
	v_and_or_b32 v0, v0, s1, v196
	v_lshlrev_b32_e32 v0, 1, v0
	s_waitcnt vmcnt(10)
	v_sub_f32_e32 v53, v53, v43
	v_sub_f32_e32 v52, v52, v43
	v_sub_f32_e32 v51, v51, v43
	v_sub_f32_e32 v50, v50, v43
	v_pk_mul_f32 v[50:51], v[42:43], v[50:51] op_sel_hi:[0,1]
	v_pk_mul_f32 v[52:53], v[42:43], v[52:53] op_sel_hi:[0,1]
	s_waitcnt vmcnt(6)
; __device__ __forceinline__ float xsum16(float v) { const auto r = __builtin_amdgcn_permlane16_swap(__float_as_uint(v), __float_as_uint(v), false, false); return __uint_as_float(r[0]) + __uint_as_float(r[1]); }
; __device__ __forceinline__ float xsum32(float v) { const auto r = __builtin_amdgcn_permlane32_swap(__float_as_uint(v), __float_as_uint(v), false, false); return __uint_as_float(r[0]) + __uint_as_float(r[1]); }
; __device__ __forceinline__ size_t blk_off(int r, int c, int K) { return (size_t)(r >> 8) * 256 * K + (size_t)(c >> 6) * (256 * 64) + (size_t)((r & 255) * 64 + (c & 63)); }
; __device__ __forceinline__ u32x4 pack8(const f32x4 a, const f32x4 b) { u32x4 w; w.x = cvt_pk_bf16(a[0], a[1]); w.y = cvt_pk_bf16(a[2], a[3]); w.z = cvt_pk_bf16(b[0], b[1]); w.w = cvt_pk_bf16(b[2], b[3]); return w; }
;     __device__ __forceinline__ void operator()(const f32x4 (&acc)[2][2][4][2], const pg8::Unit& u, int wr, int wc, int fr, int fq) const {
;     ...
;             for (int m = 0; m < 4; ++m) { const int row = row0 + ai * 128 + m * 16; const float mu = mu4[m], rs = rs4[m];
;                 f32x4 yv[2][2], gq[2][2], bq_[2][2];
; #pragma unroll
;                 for (int bj = 0; bj < 2; ++bj)
; #pragma unroll
;                     for (int n = 0; n < 2; ++n) { yv[bj][n] = *(const f32x4*)(Yin + (size_t)row * D_ + col0 + bj * 128 + 4 * n); gq[bj][n] = *(const f32x4*)(g + col0 + bj * 128 + 4 * n); bq_[bj][n] = *(const f32x4*)(b + col0 + bj * 128 + 4 * n); }
;                 asm volatile("" ::: "memory");
;                 float s1 = 0.f, s2 = 0.f;
; #pragma unroll
;                 for (int bj = 0; bj < 2; ++bj) { float* yp = Y + (size_t)row * D_ + col0 + bj * 128; f32x4 v[2];
; #pragma unroll
;                     for (int n = 0; n < 2; ++n) { v[n] = (((yv[bj][n] - mu) * rs) * gq[bj][n] + bq_[bj][n]) * ALPHA_ + acc[ai][bj][m][n] * sc;
;                         *(f32x4*)(yp + 4 * n) = v[n]; s1 += (v[n][0] + v[n][1]) + (v[n][2] + v[n][3]); s2 += (v[n][0] * v[n][0] + v[n][1] * v[n][1]) + (v[n][2] * v[n][2] + v[n][3] * v[n][3]); }
;                     *(u32x4*)(Yb + blk_off(row, col0 + bj * 128, D_)) = pack8(v[0], v[1]); }
;                 s1 = xsum32(xsum16(s1)); s2 = xsum32(xsum16(s2));
;                 if (fq == 0) *(f32x2*)(stn + (size_t)row * 32 + (u.pn * 4 + wc) * 2) = (f32x2){s1, s2}; asm volatile("" ::: "memory"); } }
	v_pk_fma_f32 v[52:53], v[60:61], v[52:53], v[68:69]
	v_pk_fma_f32 v[50:51], v[58:59], v[50:51], v[66:67]
	v_pk_mul_f32 v[52:53], v[52:53], s[2:3] op_sel_hi:[1,0]
	v_pk_mul_f32 v[50:51], v[50:51], s[2:3] op_sel_hi:[1,0]
	v_pk_fma_f32 v[52:53], v[16:17], 0.5, v[52:53] op_sel_hi:[1,0,1]
	v_pk_fma_f32 v[50:51], v[14:15], 0.5, v[50:51] op_sel_hi:[1,0,1]
	v_add_f32_e32 v15, v52, v53
	v_add_f32_e32 v14, v50, v51
	v_add_f32_e32 v14, v14, v15
	v_add_f32_e32 v58, 0, v14
	v_mul_f32_e32 v14, v51, v51
	v_mul_f32_e32 v15, v53, v53
	v_fmac_f32_e32 v14, v50, v50
	v_fmac_f32_e32 v15, v52, v52
	v_add_f32_e32 v59, v14, v15
	v_sub_f32_e32 v15, v49, v43
	v_sub_f32_e32 v14, v48, v43
	v_sub_f32_e32 v17, v47, v43
	v_sub_f32_e32 v16, v46, v43
	v_pk_mul_f32 v[16:17], v[42:43], v[16:17] op_sel_hi:[0,1]
	v_pk_mul_f32 v[14:15], v[42:43], v[14:15] op_sel_hi:[0,1]
	v_pk_fma_f32 v[14:15], v[56:57], v[14:15], v[64:65]
	v_pk_fma_f32 v[16:17], v[54:55], v[16:17], v[62:63]
	v_pk_mul_f32 v[14:15], v[14:15], s[2:3] op_sel_hi:[1,0]
	v_pk_mul_f32 v[16:17], v[16:17], s[2:3] op_sel_hi:[1,0]
	v_pk_fma_f32 v[48:49], v[12:13], 0.5, v[14:15] op_sel_hi:[1,0,1]
	v_pk_fma_f32 v[46:47], v[10:11], 0.5, v[16:17] op_sel_hi:[1,0,1]
	v_add_f32_e32 v11, v48, v49
	v_add_f32_e32 v10, v46, v47
	v_add_f32_e32 v10, v10, v11
	v_add_f32_e32 v15, v58, v10
	v_mul_f32_e32 v10, v47, v47
	v_mul_f32_e32 v11, v49, v49
	v_fmac_f32_e32 v10, v46, v46
	v_fmac_f32_e32 v11, v48, v48
	v_add_f32_e32 v10, v10, v11
	v_add_f32_e32 v14, v59, v10
	v_cvt_pk_bf16_f32 v10, v50, v51
	v_cvt_pk_bf16_f32 v11, v52, v53
	v_cvt_pk_bf16_f32 v12, v46, v47
	v_cvt_pk_bf16_f32 v13, v48, v49
	v_lshl_add_u64 v[16:17], v[78:79], 0, v[0:1]
	s_nop 0
	s_nop 1
	v_bfe_u32 v55, v227, 4, 2
	v_sub_u32_e32 v54, 0, v55
	v_lshlrev_b32_e32 v54, 4, v54
	v_ashrrev_i32_e32 v55, 31, v54
	v_lshl_add_u64 v[54:55], v[44:45], 0, v[54:55]
	v_permlane16_swap_b32_e32 v50, v46
	v_permlane16_swap_b32_e32 v51, v47
	v_permlane16_swap_b32_e32 v52, v48
	v_permlane16_swap_b32_e32 v53, v49
	v_permlane32_swap_b32_e32 v50, v46
	v_permlane32_swap_b32_e32 v51, v47
	v_permlane32_swap_b32_e32 v52, v48
	v_permlane32_swap_b32_e32 v53, v49
	global_store_dwordx4 v[54:55], v[50:53], off
	global_store_dwordx4 v[54:55], v[46:49], off offset:64
	s_nop 1
	v_permlane32_swap_b32_e32 v50, v46
	v_permlane32_swap_b32_e32 v51, v47
	v_permlane32_swap_b32_e32 v52, v48
	v_permlane32_swap_b32_e32 v53, v49
	v_permlane16_swap_b32_e32 v50, v46
	v_permlane16_swap_b32_e32 v51, v47
	v_permlane16_swap_b32_e32 v52, v48
	v_permlane16_swap_b32_e32 v53, v49
	global_store_dwordx4 v[16:17], v[10:13], off
	s_waitcnt vmcnt(7)
	s_nop 0
	v_sub_f32_e32 v11, v41, v43
	v_sub_f32_e32 v10, v40, v43
	v_sub_f32_e32 v13, v39, v43
	v_sub_f32_e32 v12, v38, v43
	v_pk_mul_f32 v[12:13], v[42:43], v[12:13] op_sel_hi:[0,1]
	v_pk_mul_f32 v[10:11], v[42:43], v[10:11] op_sel_hi:[0,1]
	s_waitcnt vmcnt(3)
	v_pk_fma_f32 v[10:11], v[32:33], v[10:11], v[36:37]
	v_pk_fma_f32 v[12:13], v[30:31], v[12:13], v[34:35]
	v_pk_mul_f32 v[10:11], v[10:11], s[2:3] op_sel_hi:[1,0]
	v_pk_mul_f32 v[12:13], v[12:13], s[2:3] op_sel_hi:[1,0]
	v_pk_fma_f32 v[8:9], v[8:9], 0.5, v[10:11] op_sel_hi:[1,0,1]
	v_pk_fma_f32 v[6:7], v[6:7], 0.5, v[12:13] op_sel_hi:[1,0,1]
	v_add_f32_e32 v11, v8, v9
	v_add_f32_e32 v10, v6, v7
	v_add_f32_e32 v10, v10, v11
	v_add_f32_e32 v15, v15, v10
	v_mul_f32_e32 v10, v7, v7
	v_mul_f32_e32 v11, v9, v9
	v_fmac_f32_e32 v10, v6, v6
	v_fmac_f32_e32 v11, v8, v8
	v_add_f32_e32 v10, v10, v11
	v_add_f32_e32 v14, v14, v10
	v_sub_f32_e32 v11, v21, v43
	v_sub_f32_e32 v10, v20, v43
	v_sub_f32_e32 v13, v19, v43
	v_sub_f32_e32 v12, v18, v43
	v_pk_mul_f32 v[12:13], v[42:43], v[12:13] op_sel_hi:[0,1]
	v_pk_mul_f32 v[10:11], v[42:43], v[10:11] op_sel_hi:[0,1]
	v_pk_fma_f32 v[10:11], v[24:25], v[10:11], v[28:29]
	v_pk_fma_f32 v[12:13], v[22:23], v[12:13], v[26:27]
	v_pk_mul_f32 v[10:11], v[10:11], s[2:3] op_sel_hi:[1,0]
	v_pk_mul_f32 v[12:13], v[12:13], s[2:3] op_sel_hi:[1,0]
	v_pk_fma_f32 v[4:5], v[4:5], 0.5, v[10:11] op_sel_hi:[1,0,1]
	v_pk_fma_f32 v[2:3], v[2:3], 0.5, v[12:13] op_sel_hi:[1,0,1]
	v_add_f32_e32 v11, v4, v5
	v_add_f32_e32 v10, v2, v3
	v_add_f32_e32 v10, v10, v11
	v_mul_f32_e32 v11, v3, v3
	v_mul_f32_e32 v12, v5, v5
	v_add_f32_e32 v10, v15, v10
	v_fmac_f32_e32 v11, v2, v2
	v_fmac_f32_e32 v12, v4, v4
	s_nop 0
	s_nop 1
	v_bfe_u32 v17, v227, 4, 2
	v_sub_u32_e32 v16, 0, v17
	v_lshlrev_b32_e32 v16, 4, v16
	v_ashrrev_i32_e32 v17, 31, v16
	v_lshl_add_u64 v[16:17], v[44:45], 0, v[16:17]
	v_permlane16_swap_b32_e32 v6, v2
	v_permlane16_swap_b32_e32 v7, v3
	v_permlane16_swap_b32_e32 v8, v4
	v_permlane16_swap_b32_e32 v9, v5
	v_permlane32_swap_b32_e32 v6, v2
	v_permlane32_swap_b32_e32 v7, v3
	v_permlane32_swap_b32_e32 v8, v4
	v_permlane32_swap_b32_e32 v9, v5
	global_store_dwordx4 v[16:17], v[6:9], off offset:512
	global_store_dwordx4 v[16:17], v[2:5], off offset:576
	s_nop 1
	v_permlane32_swap_b32_e32 v6, v2
	v_permlane32_swap_b32_e32 v7, v3
	v_permlane32_swap_b32_e32 v8, v4
	v_permlane32_swap_b32_e32 v9, v5
	v_permlane16_swap_b32_e32 v6, v2
	v_permlane16_swap_b32_e32 v7, v3
	v_permlane16_swap_b32_e32 v8, v4
	v_permlane16_swap_b32_e32 v9, v5
	v_add_f32_e32 v11, v11, v12
	v_cvt_pk_bf16_f32 v6, v6, v7
	v_cvt_pk_bf16_f32 v7, v8, v9
	v_cvt_pk_bf16_f32 v8, v2, v3
	v_lshl_add_u64 v[2:3], v[76:77], 0, v[0:1]
	v_mov_b32_e32 v0, v10
	v_add_f32_e32 v11, v14, v11
	v_cvt_pk_bf16_f32 v9, v4, v5
	v_permlane16_swap_b32_e32 v10, v0
	global_store_dwordx4 v[2:3], v[6:9], off
	v_add_f32_e32 v2, v10, v0
	v_mov_b32_e32 v0, v11
	s_nop 1
	v_permlane16_swap_b32_e32 v11, v0
	v_add_f32_e32 v3, v11, v0
	v_mov_b32_e32 v4, v2
	v_mov_b32_e32 v5, v3
	s_nop 0
	v_permlane32_swap_b32_e32 v2, v4
	v_permlane32_swap_b32_e32 v3, v5
	s_and_saveexec_b64 s[24:25], s[40:41]
	s_cbranch_execz .LBB0_1719
	v_pk_add_f32 v[2:3], v[2:3], v[4:5]
	v_lshlrev_b64 v[4:5], 7, v[74:75]
	v_lshl_add_u64 v[4:5], s[8:9], 0, v[4:5]
	v_lshl_add_u64 v[4:5], s[38:39], 2, v[4:5]
	global_store_dwordx2 v[4:5], v[2:3], off
